# on top of scan+qkvb edits: GEMM K-loops without the per-segment s_setprio flips and without the duplicated lgkmcnt(0) waits
# speedup vs baseline: 1.0183x; 1.0127x over previous
; #define WAIT_V(n) asm volatile("s_waitcnt vmcnt(" #n ")" ::: "memory")
; #define WAIT_L(n) asm volatile("s_waitcnt lgkmcnt(" #n ")" ::: "memory")
; #define BAR __builtin_amdgcn_s_barrier()
; #define SCHED __builtin_amdgcn_sched_barrier(0)
; template <class Get, class Epi>
; DI void gemm_stream(LAS unsigned char* lds, const int K, const int ld, Get get, Epi epi) {
;     ...
;         for (int t = 0; t < nt; t += 2) {
;             const bool last = (t == nt - 2);
;             const char* a1 = cA + (size_t)(t + 1) * kstep;
;             const char* a2 = last ? nA : cA + (size_t)(t + 2) * kstep;
;             const char* b2 = last ? nB : cB + (size_t)(t + 2) * kstep;
;             const char* a3 = a2 + kstep;
;             const char* b3 = b2 + kstep;
;             LDB(B0, 0, 0); SCHED; LDA(At, 0, 0); STAGE(SAo(1, 1), a1 + hstep);
;             WAIT_L(8); BAR; WAIT_L(0); MMA(0, 0, At, B0); BAR; SCHED;
;             LDB(B1, 0, 1); STAGE(SBo(0, 0), b2);
;             BAR; WAIT_L(0); MMA(0, 1, At, B1); BAR;
;             LDA(At, 0, 1); STAGE(SAo(0, 0), a2);
;             BAR; WAIT_L(0); MMA(1, 0, At, B0); BAR; SCHED;
;             STAGE(SBo(0, 1), b2 + hstep);
;             WAIT_V(6); BAR; MMA(1, 1, At, B1); BAR;
;             LDB(B0, 1, 0); SCHED; LDA(At, 1, 0); STAGE(SAo(0, 1), a2 + hstep);
;             WAIT_L(8); BAR; WAIT_L(0); MMA(0, 0, At, B0); BAR; SCHED;
;             LDB(B1, 1, 1); STAGE(SBo(1, 0), b3);
;             BAR; WAIT_L(0); MMA(0, 1, At, B1); BAR;
;             LDA(At, 1, 1); STAGE(SAo(1, 0), a3);
;             BAR; WAIT_L(0); MMA(1, 0, At, B0); BAR; SCHED;
;             STAGE(SBo(1, 1), b3 + hstep);
;             WAIT_V(6); BAR; MMA(1, 1, At, B1); BAR;
;         }
.LBB0_726:
	ds_read_b128 v[128:131], v167
	ds_read_b128 v[132:135], v167 offset:1024
	ds_read_b128 v[136:139], v167 offset:2048
	ds_read_b128 v[154:157], v167 offset:3072
	s_add_u32 s6, s4, 0xfff80080
	s_addc_u32 s7, s5, -1
	s_cmp_eq_u32 vcc_lo, 28
	s_cselect_b32 s63, s59, s7
	s_cselect_b32 s62, s58, s6
	s_cselect_b32 s7, s61, s55
	s_cselect_b32 s6, s60, s29
	v_lshl_add_u64 v[140:141], s[4:5], 0, v[148:149]
	s_add_i32 m0, s74, 0xc000
	ds_read_b128 v[158:161], v168
	ds_read_b128 v[162:165], v168 offset:1024
	ds_read_b128 v[170:173], v168 offset:2048
	ds_read_b128 v[174:177], v168 offset:3072
	ds_read_b128 v[178:181], v168 offset:4096
	ds_read_b128 v[182:185], v168 offset:5120
	ds_read_b128 v[186:189], v168 offset:6144
	ds_read_b128 v[190:193], v168 offset:7168
	global_load_lds_dwordx4 v[140:141], off
	v_lshl_add_u64 v[140:141], s[4:5], 0, v[150:151]
	s_add_i32 m0, s74, 0xe000
	s_nop 0
	global_load_lds_dwordx4 v[140:141], off
	s_waitcnt lgkmcnt(8)
	s_barrier
	s_waitcnt lgkmcnt(0)
	v_mfma_f32_16x16x32_bf16 v[124:127], v[128:131], v[158:161], v[124:127]
	v_mfma_f32_16x16x32_bf16 v[120:123], v[136:139], v[158:161], v[120:123]
	v_mfma_f32_16x16x32_bf16 v[112:115], v[128:131], v[170:173], v[112:115]
	v_mfma_f32_16x16x32_bf16 v[108:111], v[136:139], v[170:173], v[108:111]
	v_mfma_f32_16x16x32_bf16 v[100:103], v[128:131], v[178:181], v[100:103]
	v_mfma_f32_16x16x32_bf16 v[92:95], v[136:139], v[178:181], v[92:95]
	v_mfma_f32_16x16x32_bf16 v[84:87], v[128:131], v[186:189], v[84:87]
	v_mfma_f32_16x16x32_bf16 v[76:79], v[136:139], v[186:189], v[76:79]
	v_mfma_f32_16x16x32_bf16 v[124:127], v[132:135], v[162:165], v[124:127]
	v_mfma_f32_16x16x32_bf16 v[120:123], v[154:157], v[162:165], v[120:123]
	v_mfma_f32_16x16x32_bf16 v[112:115], v[132:135], v[174:177], v[112:115]
	v_mfma_f32_16x16x32_bf16 v[108:111], v[154:157], v[174:177], v[108:111]
	v_mfma_f32_16x16x32_bf16 v[100:103], v[132:135], v[182:185], v[100:103]
	v_mfma_f32_16x16x32_bf16 v[92:95], v[154:157], v[182:185], v[92:95]
	v_mfma_f32_16x16x32_bf16 v[84:87], v[132:135], v[190:193], v[84:87]
	v_mfma_f32_16x16x32_bf16 v[76:79], v[154:157], v[190:193], v[76:79]
	s_barrier
	s_add_i32 s86, s85, s35
	v_lshl_add_u64 v[140:141], s[6:7], 0, v[142:143]
	s_mov_b32 m0, s86
	ds_read_b128 v[194:197], v169
	ds_read_b128 v[198:201], v169 offset:1024
	ds_read_b128 v[202:205], v169 offset:2048
	ds_read_b128 v[208:211], v169 offset:3072
	global_load_lds_dwordx4 v[140:141], off
	v_lshl_add_u64 v[212:213], s[6:7], 0, v[144:145]
	s_add_i32 m0, s86, 0x2000
	s_nop 0
	global_load_lds_dwordx4 v[212:213], off
	s_barrier
	s_waitcnt lgkmcnt(0)
	v_mfma_f32_16x16x32_bf16 v[116:119], v[194:197], v[158:161], v[116:119]
	v_mfma_f32_16x16x32_bf16 v[104:107], v[202:205], v[158:161], v[104:107]
	v_mfma_f32_16x16x32_bf16 v[96:99], v[194:197], v[170:173], v[96:99]
	v_mfma_f32_16x16x32_bf16 v[88:91], v[202:205], v[170:173], v[88:91]
	v_mfma_f32_16x16x32_bf16 v[80:83], v[194:197], v[178:181], v[80:83]
	v_mfma_f32_16x16x32_bf16 v[72:75], v[202:205], v[178:181], v[72:75]
	v_mfma_f32_16x16x32_bf16 v[68:71], v[194:197], v[186:189], v[68:71]
	v_mfma_f32_16x16x32_bf16 v[64:67], v[202:205], v[186:189], v[64:67]
	v_mfma_f32_16x16x32_bf16 v[116:119], v[198:201], v[162:165], v[116:119]
	v_mfma_f32_16x16x32_bf16 v[104:107], v[208:211], v[162:165], v[104:107]
	v_mfma_f32_16x16x32_bf16 v[96:99], v[198:201], v[174:177], v[96:99]
	v_mfma_f32_16x16x32_bf16 v[88:91], v[208:211], v[174:177], v[88:91]
	v_mfma_f32_16x16x32_bf16 v[80:83], v[198:201], v[182:185], v[80:83]
	v_mfma_f32_16x16x32_bf16 v[72:75], v[208:211], v[182:185], v[72:75]
	v_mfma_f32_16x16x32_bf16 v[68:71], v[198:201], v[190:193], v[68:71]
	v_mfma_f32_16x16x32_bf16 v[64:67], v[208:211], v[190:193], v[64:67]
	s_mov_b32 m0, s74
	v_lshl_add_u64 v[214:215], s[62:63], 0, v[142:143]
	s_barrier
	ds_read_b128 v[158:161], v168 offset:16384
	ds_read_b128 v[162:165], v168 offset:17408
	ds_read_b128 v[170:173], v168 offset:18432
	ds_read_b128 v[174:177], v168 offset:19456
	ds_read_b128 v[178:181], v168 offset:20480
	ds_read_b128 v[182:185], v168 offset:21504
	ds_read_b128 v[186:189], v168 offset:22528
	ds_read_b128 v[190:193], v168 offset:23552
	global_load_lds_dwordx4 v[214:215], off
	v_lshl_add_u64 v[216:217], s[62:63], 0, v[144:145]
	s_mov_b32 m0, s75
	s_nop 0
	global_load_lds_dwordx4 v[216:217], off
	s_barrier
	s_waitcnt lgkmcnt(0)
	v_mfma_f32_16x16x32_bf16 v[60:63], v[128:131], v[158:161], v[60:63]
	v_mfma_f32_16x16x32_bf16 v[56:59], v[136:139], v[158:161], v[56:59]
	v_mfma_f32_16x16x32_bf16 v[52:55], v[128:131], v[170:173], v[52:55]
	v_mfma_f32_16x16x32_bf16 v[44:47], v[136:139], v[170:173], v[44:47]
	v_mfma_f32_16x16x32_bf16 v[36:39], v[128:131], v[178:181], v[36:39]
	v_mfma_f32_16x16x32_bf16 v[28:31], v[136:139], v[178:181], v[28:31]
	v_mfma_f32_16x16x32_bf16 v[20:23], v[128:131], v[186:189], v[20:23]
	v_mfma_f32_16x16x32_bf16 v[12:15], v[136:139], v[186:189], v[12:15]
	v_mfma_f32_16x16x32_bf16 v[60:63], v[132:135], v[162:165], v[60:63]
	v_mfma_f32_16x16x32_bf16 v[56:59], v[154:157], v[162:165], v[56:59]
	v_mfma_f32_16x16x32_bf16 v[52:55], v[132:135], v[174:177], v[52:55]
	v_mfma_f32_16x16x32_bf16 v[44:47], v[154:157], v[174:177], v[44:47]
	v_mfma_f32_16x16x32_bf16 v[36:39], v[132:135], v[182:185], v[36:39]
	v_mfma_f32_16x16x32_bf16 v[28:31], v[154:157], v[182:185], v[28:31]
	v_mfma_f32_16x16x32_bf16 v[20:23], v[132:135], v[190:193], v[20:23]
	v_mfma_f32_16x16x32_bf16 v[12:15], v[154:157], v[190:193], v[12:15]
	s_barrier
; #define WAIT_V(n) asm volatile("s_waitcnt vmcnt(" #n ")" ::: "memory")
; #define WAIT_L(n) asm volatile("s_waitcnt lgkmcnt(" #n ")" ::: "memory")
; #define BAR __builtin_amdgcn_s_barrier()
; #define SCHED __builtin_amdgcn_sched_barrier(0)
; template <class Get, class Epi>
; DI void gemm_stream(LAS unsigned char* lds, const int K, const int ld, Get get, Epi epi) {
;     ...
;         for (int t = 0; t < nt; t += 2) {
;             const bool last = (t == nt - 2);
;             const char* a1 = cA + (size_t)(t + 1) * kstep;
;             const char* a2 = last ? nA : cA + (size_t)(t + 2) * kstep;
;             const char* b2 = last ? nB : cB + (size_t)(t + 2) * kstep;
;             const char* a3 = a2 + kstep;
;             const char* b3 = b2 + kstep;
;             LDB(B0, 0, 0); SCHED; LDA(At, 0, 0); STAGE(SAo(1, 1), a1 + hstep);
;             WAIT_L(8); BAR; WAIT_L(0); MMA(0, 0, At, B0); BAR; SCHED;
;             LDB(B1, 0, 1); STAGE(SBo(0, 0), b2);
;             BAR; WAIT_L(0); MMA(0, 1, At, B1); BAR;
;             LDA(At, 0, 1); STAGE(SAo(0, 0), a2);
;             BAR; WAIT_L(0); MMA(1, 0, At, B0); BAR; SCHED;
;             STAGE(SBo(0, 1), b2 + hstep);
;             WAIT_V(6); BAR; MMA(1, 1, At, B1); BAR;
;             LDB(B0, 1, 0); SCHED; LDA(At, 1, 0); STAGE(SAo(0, 1), a2 + hstep);
;             WAIT_L(8); BAR; WAIT_L(0); MMA(0, 0, At, B0); BAR; SCHED;
;             LDB(B1, 1, 1); STAGE(SBo(1, 0), b3);
;             BAR; WAIT_L(0); MMA(0, 1, At, B1); BAR;
;             LDA(At, 1, 1); STAGE(SAo(1, 0), a3);
;             BAR; WAIT_L(0); MMA(1, 0, At, B0); BAR; SCHED;
;             STAGE(SBo(1, 1), b3 + hstep);
;             WAIT_V(6); BAR; MMA(1, 1, At, B1); BAR;
;         }
	s_add_u32 s86, s6, 0x80000
	s_addc_u32 s87, s7, 0
	s_add_i32 s88, s96, s35
	v_lshl_add_u64 v[128:129], s[86:87], 0, v[142:143]
	s_mov_b32 m0, s88
	s_nop 0
	global_load_lds_dwordx4 v[128:129], off
	v_lshl_add_u64 v[128:129], s[86:87], 0, v[144:145]
	s_add_i32 m0, s88, 0x2000
	s_nop 0
	global_load_lds_dwordx4 v[128:129], off
	s_waitcnt vmcnt(6)
	s_barrier
	v_mfma_f32_16x16x32_bf16 v[48:51], v[194:197], v[158:161], v[48:51]
	v_mfma_f32_16x16x32_bf16 v[40:43], v[202:205], v[158:161], v[40:43]
	v_mfma_f32_16x16x32_bf16 v[32:35], v[194:197], v[170:173], v[32:35]
	v_mfma_f32_16x16x32_bf16 v[24:27], v[202:205], v[170:173], v[24:27]
	v_mfma_f32_16x16x32_bf16 v[16:19], v[194:197], v[178:181], v[16:19]
	v_mfma_f32_16x16x32_bf16 v[8:11], v[202:205], v[178:181], v[8:11]
	v_mfma_f32_16x16x32_bf16 v[4:7], v[194:197], v[186:189], v[4:7]
	v_mfma_f32_16x16x32_bf16 v[0:3], v[202:205], v[186:189], v[0:3]
	v_mfma_f32_16x16x32_bf16 v[48:51], v[198:201], v[162:165], v[48:51]
	v_mfma_f32_16x16x32_bf16 v[40:43], v[208:211], v[162:165], v[40:43]
	v_mfma_f32_16x16x32_bf16 v[32:35], v[198:201], v[174:177], v[32:35]
	v_mfma_f32_16x16x32_bf16 v[24:27], v[208:211], v[174:177], v[24:27]
	v_mfma_f32_16x16x32_bf16 v[16:19], v[198:201], v[182:185], v[16:19]
	v_mfma_f32_16x16x32_bf16 v[8:11], v[208:211], v[182:185], v[8:11]
	v_mfma_f32_16x16x32_bf16 v[4:7], v[198:201], v[190:193], v[4:7]
	v_mfma_f32_16x16x32_bf16 v[0:3], v[208:211], v[190:193], v[0:3]
	s_add_i32 s86, 16, 0x18000
	v_add_u32_e32 v146, s86, v166
	s_barrier
	ds_read_b128 v[128:131], v146
	ds_read_b128 v[132:135], v146 offset:1024
	ds_read_b128 v[136:139], v146 offset:2048
	ds_read_b128 v[154:157], v146 offset:3072
	s_add_u32 s62, s62, 0x80000
	s_addc_u32 s63, s63, 0
	s_mov_b32 m0, s76
	v_lshl_add_u64 v[194:195], s[62:63], 0, v[142:143]
	ds_read_b128 v[158:161], v168 offset:32768
	ds_read_b128 v[162:165], v168 offset:33792
	ds_read_b128 v[170:173], v168 offset:34816
	ds_read_b128 v[174:177], v168 offset:35840
	ds_read_b128 v[178:181], v168 offset:36864
	ds_read_b128 v[182:185], v168 offset:37888
	ds_read_b128 v[186:189], v168 offset:38912
	ds_read_b128 v[190:193], v168 offset:39936
	global_load_lds_dwordx4 v[194:195], off
	v_lshl_add_u64 v[194:195], s[62:63], 0, v[144:145]
	s_mov_b32 m0, s77
	s_nop 0
	global_load_lds_dwordx4 v[194:195], off
	s_waitcnt lgkmcnt(8)
	s_barrier
	s_waitcnt lgkmcnt(0)
	v_mfma_f32_16x16x32_bf16 v[124:127], v[128:131], v[158:161], v[124:127]
	v_mfma_f32_16x16x32_bf16 v[120:123], v[136:139], v[158:161], v[120:123]
	v_mfma_f32_16x16x32_bf16 v[112:115], v[128:131], v[170:173], v[112:115]
	v_mfma_f32_16x16x32_bf16 v[108:111], v[136:139], v[170:173], v[108:111]
	v_mfma_f32_16x16x32_bf16 v[100:103], v[128:131], v[178:181], v[100:103]
	v_mfma_f32_16x16x32_bf16 v[92:95], v[136:139], v[178:181], v[92:95]
	v_mfma_f32_16x16x32_bf16 v[84:87], v[128:131], v[186:189], v[84:87]
	v_mfma_f32_16x16x32_bf16 v[76:79], v[136:139], v[186:189], v[76:79]
	v_mfma_f32_16x16x32_bf16 v[124:127], v[132:135], v[162:165], v[124:127]
	v_mfma_f32_16x16x32_bf16 v[120:123], v[154:157], v[162:165], v[120:123]
	v_mfma_f32_16x16x32_bf16 v[112:115], v[132:135], v[174:177], v[112:115]
	v_mfma_f32_16x16x32_bf16 v[108:111], v[154:157], v[174:177], v[108:111]
	v_mfma_f32_16x16x32_bf16 v[100:103], v[132:135], v[182:185], v[100:103]
	v_mfma_f32_16x16x32_bf16 v[92:95], v[154:157], v[182:185], v[92:95]
	v_mfma_f32_16x16x32_bf16 v[84:87], v[132:135], v[190:193], v[84:87]
	v_mfma_f32_16x16x32_bf16 v[76:79], v[154:157], v[190:193], v[76:79]
	s_barrier
	s_add_i32 s62, 16, 0x1c000
	s_add_i32 s63, s86, s35
	v_add_u32_e32 v146, s62, v166
	v_lshl_add_u64 v[140:141], v[140:141], 0, s[0:1]
	s_mov_b32 m0, s63
	ds_read_b128 v[194:197], v146
	ds_read_b128 v[198:201], v146 offset:1024
	ds_read_b128 v[202:205], v146 offset:2048
	ds_read_b128 v[208:211], v146 offset:3072
	global_load_lds_dwordx4 v[140:141], off
	v_lshl_add_u64 v[140:141], v[212:213], 0, s[0:1]
	s_add_i32 m0, s63, 0x2000
	s_nop 0
	global_load_lds_dwordx4 v[140:141], off
	s_barrier
	s_waitcnt lgkmcnt(0)
	v_mfma_f32_16x16x32_bf16 v[116:119], v[194:197], v[158:161], v[116:119]
	v_mfma_f32_16x16x32_bf16 v[104:107], v[202:205], v[158:161], v[104:107]
	v_mfma_f32_16x16x32_bf16 v[96:99], v[194:197], v[170:173], v[96:99]
	v_mfma_f32_16x16x32_bf16 v[88:91], v[202:205], v[170:173], v[88:91]
	v_mfma_f32_16x16x32_bf16 v[80:83], v[194:197], v[178:181], v[80:83]
	v_mfma_f32_16x16x32_bf16 v[72:75], v[202:205], v[178:181], v[72:75]
	v_mfma_f32_16x16x32_bf16 v[68:71], v[194:197], v[186:189], v[68:71]
	v_mfma_f32_16x16x32_bf16 v[64:67], v[202:205], v[186:189], v[64:67]
	v_mfma_f32_16x16x32_bf16 v[116:119], v[198:201], v[162:165], v[116:119]
	v_mfma_f32_16x16x32_bf16 v[104:107], v[208:211], v[162:165], v[104:107]
	v_mfma_f32_16x16x32_bf16 v[96:99], v[198:201], v[174:177], v[96:99]
	v_mfma_f32_16x16x32_bf16 v[88:91], v[208:211], v[174:177], v[88:91]
	v_mfma_f32_16x16x32_bf16 v[80:83], v[198:201], v[182:185], v[80:83]
	v_mfma_f32_16x16x32_bf16 v[72:75], v[208:211], v[182:185], v[72:75]
	v_mfma_f32_16x16x32_bf16 v[68:71], v[198:201], v[190:193], v[68:71]
	v_mfma_f32_16x16x32_bf16 v[64:67], v[208:211], v[190:193], v[64:67]
	s_mov_b32 m0, s80
	v_lshl_add_u64 v[140:141], v[214:215], 0, s[0:1]
	s_barrier
; #define WAIT_V(n) asm volatile("s_waitcnt vmcnt(" #n ")" ::: "memory")
; #define WAIT_L(n) asm volatile("s_waitcnt lgkmcnt(" #n ")" ::: "memory")
; #define BAR __builtin_amdgcn_s_barrier()
; #define SCHED __builtin_amdgcn_sched_barrier(0)
; template <class Get, class Epi>
; DI void gemm_stream(LAS unsigned char* lds, const int K, const int ld, Get get, Epi epi) {
;     ...
;             WAIT_L(8); BAR; WAIT_L(0); MMA(0, 0, At, B0); BAR; SCHED;
;             LDB(B1, 1, 1); STAGE(SBo(1, 0), b3);
;             BAR; WAIT_L(0); MMA(0, 1, At, B1); BAR;
;             LDA(At, 1, 1); STAGE(SAo(1, 0), a3);
;             BAR; WAIT_L(0); MMA(1, 0, At, B0); BAR; SCHED;
;             STAGE(SBo(1, 1), b3 + hstep);
;             WAIT_V(6); BAR; MMA(1, 1, At, B1); BAR;
;         }
; template <int R>
; DI void epi_rope(const Acc& acc, const P& p, int brow, bf16_t* __restrict__ dst, int ld, int coff, int bstride, const float* rs, int nblk_valid) {
;     EPI_IDX
;     const float* __restrict__ cosT = (const float*)(p.ws + (R == 128 ? O_COSA : O_COSB));
;     const float* __restrict__ sinT = (const float*)(p.ws + (R == 128 ? O_SINA : O_SINB));
;     const int b = brow / PB, p0 = brow - b * PB;
;     const bool ctx = p0 < CTXL;
; #pragma unroll
;     for (int ai = 0; ai < 2; ++ai)
; #pragma unroll
;         for (int m = 0; m < 4; ++m) {
;             const int lr = ai * 128 + wr * 64 + m * 16 + fr;
;             const float s = rs ? rs[lr] : 1.f;
;             const int sq = p0 + lr - CTXL;
; #pragma unroll
;             for (int bj = 0; bj < 2; ++bj) {
;                 const int blk = R == 128 ? bj : bj * 2 + (wc >> 1);
;                 const int d0 = (R == 128 ? wc * 16 : (wc & 1) * 16) + fq * 4;
;                 if (blk < nblk_valid) {
;                     f32x4 cv = {1.f, 1.f, 1.f, 1.f}, sv = {0.f, 0.f, 0.f, 0.f};
;                     if (!ctx) { cv = *(const f32x4*)(cosT + (size_t)sq * (R / 2) + d0); sv = *(const f32x4*)(sinT + (size_t)sq * (R / 2) + d0); }
	ds_read_b128 v[158:161], v168 offset:49152
	ds_read_b128 v[162:165], v168 offset:50176
	ds_read_b128 v[170:173], v168 offset:51200
	ds_read_b128 v[174:177], v168 offset:52224
	ds_read_b128 v[178:181], v168 offset:53248
	ds_read_b128 v[182:185], v168 offset:54272
	ds_read_b128 v[186:189], v168 offset:55296
	ds_read_b128 v[190:193], v168 offset:56320
	global_load_lds_dwordx4 v[140:141], off
	v_lshl_add_u64 v[140:141], v[216:217], 0, s[0:1]
	s_mov_b32 m0, s81
	s_nop 0
	global_load_lds_dwordx4 v[140:141], off
	s_barrier
	s_waitcnt lgkmcnt(0)
	v_mfma_f32_16x16x32_bf16 v[60:63], v[128:131], v[158:161], v[60:63]
	v_mfma_f32_16x16x32_bf16 v[56:59], v[136:139], v[158:161], v[56:59]
	v_mfma_f32_16x16x32_bf16 v[52:55], v[128:131], v[170:173], v[52:55]
	v_mfma_f32_16x16x32_bf16 v[44:47], v[136:139], v[170:173], v[44:47]
	v_mfma_f32_16x16x32_bf16 v[36:39], v[128:131], v[178:181], v[36:39]
	v_mfma_f32_16x16x32_bf16 v[28:31], v[136:139], v[178:181], v[28:31]
	v_mfma_f32_16x16x32_bf16 v[20:23], v[128:131], v[186:189], v[20:23]
	v_mfma_f32_16x16x32_bf16 v[12:15], v[136:139], v[186:189], v[12:15]
	v_mfma_f32_16x16x32_bf16 v[60:63], v[132:135], v[162:165], v[60:63]
	v_mfma_f32_16x16x32_bf16 v[56:59], v[154:157], v[162:165], v[56:59]
	v_mfma_f32_16x16x32_bf16 v[52:55], v[132:135], v[174:177], v[52:55]
	v_mfma_f32_16x16x32_bf16 v[44:47], v[154:157], v[174:177], v[44:47]
	v_mfma_f32_16x16x32_bf16 v[36:39], v[132:135], v[182:185], v[36:39]
	v_mfma_f32_16x16x32_bf16 v[28:31], v[154:157], v[182:185], v[28:31]
	v_mfma_f32_16x16x32_bf16 v[20:23], v[132:135], v[190:193], v[20:23]
	v_mfma_f32_16x16x32_bf16 v[12:15], v[154:157], v[190:193], v[12:15]
	s_barrier
	s_add_u32 s6, s6, 0x80080
	s_addc_u32 s7, s7, 0
	s_add_i32 s62, s62, s35
	v_lshl_add_u64 v[128:129], s[6:7], 0, v[142:143]
	s_mov_b32 m0, s62
	s_nop 0
	global_load_lds_dwordx4 v[128:129], off
	v_lshl_add_u64 v[128:129], s[6:7], 0, v[144:145]
	s_add_i32 m0, s62, 0x2000
	s_nop 0
	global_load_lds_dwordx4 v[128:129], off
	s_waitcnt vmcnt(6)
	s_barrier
	v_mfma_f32_16x16x32_bf16 v[48:51], v[194:197], v[158:161], v[48:51]
	v_mfma_f32_16x16x32_bf16 v[40:43], v[202:205], v[158:161], v[40:43]
	v_mfma_f32_16x16x32_bf16 v[32:35], v[194:197], v[170:173], v[32:35]
	v_mfma_f32_16x16x32_bf16 v[24:27], v[202:205], v[170:173], v[24:27]
	v_mfma_f32_16x16x32_bf16 v[16:19], v[194:197], v[178:181], v[16:19]
	v_mfma_f32_16x16x32_bf16 v[8:11], v[202:205], v[178:181], v[8:11]
	v_mfma_f32_16x16x32_bf16 v[4:7], v[194:197], v[186:189], v[4:7]
	v_mfma_f32_16x16x32_bf16 v[0:3], v[202:205], v[186:189], v[0:3]
	v_mfma_f32_16x16x32_bf16 v[48:51], v[198:201], v[162:165], v[48:51]
	v_mfma_f32_16x16x32_bf16 v[40:43], v[208:211], v[162:165], v[40:43]
	v_mfma_f32_16x16x32_bf16 v[32:35], v[198:201], v[174:177], v[32:35]
	v_mfma_f32_16x16x32_bf16 v[24:27], v[208:211], v[174:177], v[24:27]
	v_mfma_f32_16x16x32_bf16 v[16:19], v[198:201], v[182:185], v[16:19]
	v_mfma_f32_16x16x32_bf16 v[8:11], v[208:211], v[182:185], v[8:11]
	v_mfma_f32_16x16x32_bf16 v[4:7], v[198:201], v[190:193], v[4:7]
	v_mfma_f32_16x16x32_bf16 v[0:3], v[208:211], v[190:193], v[0:3]
	s_add_i32 vcc_lo, vcc_lo, 2
	s_add_u32 s4, s4, 0x100
	s_addc_u32 s5, s5, 0
	s_add_u32 s29, s29, 0x100
	s_addc_u32 s55, s55, 0
	s_cmp_gt_u32 vcc_lo, 29
	s_barrier
	s_cbranch_scc0 .LBB0_726
	s_lshl_b32 s29, s21, 8
	s_cmp_lg_u32 s28, 5
	s_mov_b64 s[4:5], -1
	s_cbranch_scc0 .LBB0_849
	s_cmp_gt_i32 s28, 3
	s_cbranch_scc0 .LBB0_814
	s_cmp_lg_u32 s28, 4
	s_cbranch_scc0 .LBB0_779
	s_cmp_gt_u32 s28, 7
	s_cbranch_scc0 .LBB0_776
	s_cmp_lg_u32 s28, 8
	s_cbranch_scc0 .LBB0_773
	s_mul_hi_i32 s4, s29, 0x78787879
	s_lshr_b32 s5, s4, 31
	s_ashr_i32 s4, s4, 11
	v_mov_b32_e32 v128, v206
	s_add_i32 s4, s4, s5
	s_mulk_i32 s4, 0x1100
	v_and_b32_e32 v129, 15, v128
	v_ashrrev_i32_e32 v130, 2, v128
	s_sub_i32 s55, s29, s4
	v_and_or_b32 v154, v130, s97, v129
	v_lshrrev_b32_e32 v129, 2, v128
	s_cmpk_gt_i32 s55, 0xff
	v_and_b32_e32 v129, 28, v129
	s_cselect_b64 s[4:5], -1, 0
	v_lshlrev_b32_e32 v146, 2, v129
	v_and_b32_e32 v128, 0x80, v128
	v_lshl_add_u64 v[138:139], s[14:15], 0, v[146:147]
	v_lshl_add_u64 v[140:141], s[12:13], 0, v[146:147]
	v_lshlrev_b32_e32 v146, 1, v129
	v_cmp_eq_u32_e64 s[6:7], 0, v128
	v_cndmask_b32_e64 v128, 0, 1, s[4:5]
	s_addk_i32 s55, 0xff00
	v_lshl_add_u64 v[136:137], s[10:11], 0, v[146:147]
	v_cmp_ne_u32_e64 s[4:5], 1, v128
	s_and_saveexec_b64 s[62:63], s[6:7]
	s_cbranch_execz .LBB0_737
	s_and_b64 vcc, exec, s[4:5]
	s_cbranch_vccnz .LBB0_735
	v_add_u32_e32 v128, s55, v154
	v_ashrrev_i32_e32 v129, 31, v128
	v_lshlrev_b64 v[128:129], 7, v[128:129]
	v_lshl_add_u64 v[132:133], v[138:139], 0, v[128:129]
	v_lshl_add_u64 v[128:129], v[140:141], 0, v[128:129]
	global_load_dwordx4 v[128:131], v[128:129], off
	s_nop 0
	global_load_dwordx4 v[132:135], v[132:133], off
	s_branch .LBB0_736

; #define WAIT_V(n) asm volatile("s_waitcnt vmcnt(" #n ")" ::: "memory")
; #define WAIT_L(n) asm volatile("s_waitcnt lgkmcnt(" #n ")" ::: "memory")
; #define BAR __builtin_amdgcn_s_barrier()
; #define SCHED __builtin_amdgcn_sched_barrier(0)
; DI void gemm_tile(const bf16_t* __restrict__ A, const bf16_t* __restrict__ Bt, const int K, const int brow, const int bcol, LAS unsigned char* lds, Acc& acc) {
;     ...
;     for (int t = 0; t < nt - 2; t += 2) {
;         const char* a1 = cA + (size_t)(t + 1) * kstep;
;         const char* a2 = cA + (size_t)(t + 2) * kstep; const char* b2 = cB + (size_t)(t + 2) * kstep;
;         const char* a3 = a2 + kstep; const char* b3 = b2 + kstep;
;         LDB(B0, 0, 0); SCHED; LDA(At, 0, 0); STAGE(SAo(1, 1), a1 + hstep);
;         WAIT_L(8); BAR; WAIT_L(0); MMA(0, 0, At, B0); BAR; SCHED;
;         LDB(B1, 0, 1); STAGE(SBo(0, 0), b2);
;         BAR; WAIT_L(0); MMA(0, 1, At, B1); BAR;
;         LDA(At, 0, 1); STAGE(SAo(0, 0), a2);
;         BAR; WAIT_L(0); MMA(1, 0, At, B0); BAR; SCHED;
;         STAGE(SBo(0, 1), b2 + hstep);
;         WAIT_V(6); BAR; MMA(1, 1, At, B1); BAR;
;         LDB(B0, 1, 0); SCHED; LDA(At, 1, 0); STAGE(SAo(0, 1), a2 + hstep);
;         WAIT_L(8); BAR; WAIT_L(0); MMA(0, 0, At, B0); BAR; SCHED;
;         LDB(B1, 1, 1); STAGE(SBo(1, 0), b3);
;         BAR; WAIT_L(0); MMA(0, 1, At, B1); BAR;
;         LDA(At, 1, 1); STAGE(SAo(1, 0), a3);
;         BAR; WAIT_L(0); MMA(1, 0, At, B0); BAR; SCHED;
;         STAGE(SBo(1, 1), b3 + hstep);
;         WAIT_V(6); BAR; MMA(1, 1, At, B1); BAR;
;     }
.LBB0_930:
	s_add_i32 s6, 16, 0x10000
	v_add_u32_e32 v154, s6, v149
	ds_read_b128 v[150:153], v154
	ds_read_b128 v[160:163], v154 offset:1024
	ds_read_b128 v[164:167], v154 offset:2048
	ds_read_b128 v[168:171], v154 offset:3072
	s_add_i32 s62, s62, 2
	v_lshl_add_u64 v[154:155], v[134:135], 0, s[60:61]
	s_add_i32 s81, s86, 0xc000
	v_lshl_add_u64 v[204:205], v[154:155], 0, s[36:37]
	s_mov_b32 m0, s81
	ds_read_b128 v[172:175], v148
	ds_read_b128 v[176:179], v148 offset:1024
	ds_read_b128 v[180:183], v148 offset:2048
	ds_read_b128 v[184:187], v148 offset:3072
	ds_read_b128 v[188:191], v148 offset:4096
	ds_read_b128 v[192:195], v148 offset:5120
	ds_read_b128 v[196:199], v148 offset:6144
	ds_read_b128 v[200:203], v148 offset:7168
	global_load_lds_dwordx4 v[204:205], off
	v_lshl_add_u64 v[204:205], v[136:137], 0, s[60:61]
	s_add_i32 s63, s86, 0xe000
	v_lshl_add_u64 v[208:209], v[204:205], 0, s[36:37]
	s_mov_b32 m0, s63
	s_nop 0
	global_load_lds_dwordx4 v[208:209], off
	s_waitcnt lgkmcnt(8)
	s_barrier
	s_waitcnt lgkmcnt(0)
	v_mfma_f32_16x16x32_bf16 v[124:127], v[150:153], v[172:175], v[124:127]
	v_mfma_f32_16x16x32_bf16 v[120:123], v[164:167], v[172:175], v[120:123]
	v_mfma_f32_16x16x32_bf16 v[116:119], v[150:153], v[180:183], v[116:119]
	v_mfma_f32_16x16x32_bf16 v[112:115], v[164:167], v[180:183], v[112:115]
	v_mfma_f32_16x16x32_bf16 v[108:111], v[150:153], v[188:191], v[108:111]
	v_mfma_f32_16x16x32_bf16 v[104:107], v[164:167], v[188:191], v[104:107]
	v_mfma_f32_16x16x32_bf16 v[100:103], v[150:153], v[196:199], v[100:103]
	v_mfma_f32_16x16x32_bf16 v[96:99], v[164:167], v[196:199], v[96:99]
	v_mfma_f32_16x16x32_bf16 v[124:127], v[160:163], v[176:179], v[124:127]
	v_mfma_f32_16x16x32_bf16 v[120:123], v[168:171], v[176:179], v[120:123]
	v_mfma_f32_16x16x32_bf16 v[116:119], v[160:163], v[184:187], v[116:119]
	v_mfma_f32_16x16x32_bf16 v[112:115], v[168:171], v[184:187], v[112:115]
	v_mfma_f32_16x16x32_bf16 v[108:111], v[160:163], v[192:195], v[108:111]
	v_mfma_f32_16x16x32_bf16 v[104:107], v[168:171], v[192:195], v[104:107]
	v_mfma_f32_16x16x32_bf16 v[100:103], v[160:163], v[200:203], v[100:103]
	v_mfma_f32_16x16x32_bf16 v[96:99], v[168:171], v[200:203], v[96:99]
	s_barrier
	s_add_i32 s7, 16, 0x14000
	v_lshl_add_u64 v[224:225], v[138:139], 0, s[60:61]
	s_add_i32 s6, s6, s18
	v_add_u32_e32 v159, s7, v149
	v_lshl_add_u64 v[226:227], v[224:225], 0, s[38:39]
	s_mov_b32 m0, s6
	ds_read_b128 v[208:211], v159
	ds_read_b128 v[212:215], v159 offset:1024
	ds_read_b128 v[216:219], v159 offset:2048
	ds_read_b128 v[220:223], v159 offset:3072
	global_load_lds_dwordx4 v[226:227], off
	v_lshl_add_u64 v[226:227], v[140:141], 0, s[60:61]
	v_lshl_add_u64 v[228:229], v[226:227], 0, s[38:39]
	s_add_i32 m0, s6, 0x2000
	s_nop 0
	global_load_lds_dwordx4 v[228:229], off
	s_barrier
	s_waitcnt lgkmcnt(0)
	v_mfma_f32_16x16x32_bf16 v[92:95], v[208:211], v[172:175], v[92:95]
	v_mfma_f32_16x16x32_bf16 v[88:91], v[216:219], v[172:175], v[88:91]
	v_mfma_f32_16x16x32_bf16 v[84:87], v[208:211], v[180:183], v[84:87]
	v_mfma_f32_16x16x32_bf16 v[80:83], v[216:219], v[180:183], v[80:83]
	v_mfma_f32_16x16x32_bf16 v[76:79], v[208:211], v[188:191], v[76:79]
	v_mfma_f32_16x16x32_bf16 v[72:75], v[216:219], v[188:191], v[72:75]
	v_mfma_f32_16x16x32_bf16 v[68:71], v[208:211], v[196:199], v[68:71]
	v_mfma_f32_16x16x32_bf16 v[64:67], v[216:219], v[196:199], v[64:67]
	v_mfma_f32_16x16x32_bf16 v[92:95], v[212:215], v[176:179], v[92:95]
	v_mfma_f32_16x16x32_bf16 v[88:91], v[220:223], v[176:179], v[88:91]
	v_mfma_f32_16x16x32_bf16 v[84:87], v[212:215], v[184:187], v[84:87]
	v_mfma_f32_16x16x32_bf16 v[80:83], v[220:223], v[184:187], v[80:83]
	v_mfma_f32_16x16x32_bf16 v[76:79], v[212:215], v[192:195], v[76:79]
	v_mfma_f32_16x16x32_bf16 v[72:75], v[220:223], v[192:195], v[72:75]
	v_mfma_f32_16x16x32_bf16 v[68:71], v[212:215], v[200:203], v[68:71]
	v_mfma_f32_16x16x32_bf16 v[64:67], v[220:223], v[200:203], v[64:67]
	v_lshl_add_u64 v[228:229], v[130:131], 0, s[60:61]
	s_mov_b32 m0, s86
	v_lshl_add_u64 v[230:231], v[228:229], 0, s[38:39]
	s_barrier
	ds_read_b128 v[172:175], v148 offset:16384
	ds_read_b128 v[176:179], v148 offset:17408
	ds_read_b128 v[180:183], v148 offset:18432
	ds_read_b128 v[184:187], v148 offset:19456
	ds_read_b128 v[188:191], v148 offset:20480
	ds_read_b128 v[192:195], v148 offset:21504
	ds_read_b128 v[196:199], v148 offset:22528
	ds_read_b128 v[200:203], v148 offset:23552
	global_load_lds_dwordx4 v[230:231], off
	v_lshl_add_u64 v[230:231], v[132:133], 0, s[60:61]
	v_lshl_add_u64 v[232:233], v[230:231], 0, s[38:39]
	s_mov_b32 m0, s82
	s_nop 0
	global_load_lds_dwordx4 v[232:233], off
	s_barrier
	s_waitcnt lgkmcnt(0)
	v_mfma_f32_16x16x32_bf16 v[60:63], v[150:153], v[172:175], v[60:63]
	v_mfma_f32_16x16x32_bf16 v[56:59], v[164:167], v[172:175], v[56:59]
	v_mfma_f32_16x16x32_bf16 v[52:55], v[150:153], v[180:183], v[52:55]
	v_mfma_f32_16x16x32_bf16 v[48:51], v[164:167], v[180:183], v[48:51]
	v_mfma_f32_16x16x32_bf16 v[44:47], v[150:153], v[188:191], v[44:47]
	v_mfma_f32_16x16x32_bf16 v[40:43], v[164:167], v[188:191], v[40:43]
	v_mfma_f32_16x16x32_bf16 v[36:39], v[150:153], v[196:199], v[36:39]
	v_mfma_f32_16x16x32_bf16 v[32:35], v[164:167], v[196:199], v[32:35]
	v_mfma_f32_16x16x32_bf16 v[60:63], v[160:163], v[176:179], v[60:63]
	v_mfma_f32_16x16x32_bf16 v[56:59], v[168:171], v[176:179], v[56:59]
	v_mfma_f32_16x16x32_bf16 v[52:55], v[160:163], v[184:187], v[52:55]
	v_mfma_f32_16x16x32_bf16 v[48:51], v[168:171], v[184:187], v[48:51]
	v_mfma_f32_16x16x32_bf16 v[44:47], v[160:163], v[192:195], v[44:47]
	v_mfma_f32_16x16x32_bf16 v[40:43], v[168:171], v[192:195], v[40:43]
	v_mfma_f32_16x16x32_bf16 v[36:39], v[160:163], v[200:203], v[36:39]
	v_mfma_f32_16x16x32_bf16 v[32:35], v[168:171], v[200:203], v[32:35]
	s_barrier
; #define WAIT_V(n) asm volatile("s_waitcnt vmcnt(" #n ")" ::: "memory")
; #define WAIT_L(n) asm volatile("s_waitcnt lgkmcnt(" #n ")" ::: "memory")
; #define BAR __builtin_amdgcn_s_barrier()
; #define SCHED __builtin_amdgcn_sched_barrier(0)
; DI void gemm_tile(const bf16_t* __restrict__ A, const bf16_t* __restrict__ Bt, const int K, const int brow, const int bcol, LAS unsigned char* lds, Acc& acc) {
;     ...
;     for (int t = 0; t < nt - 2; t += 2) {
;         const char* a1 = cA + (size_t)(t + 1) * kstep;
;         const char* a2 = cA + (size_t)(t + 2) * kstep; const char* b2 = cB + (size_t)(t + 2) * kstep;
;         const char* a3 = a2 + kstep; const char* b3 = b2 + kstep;
;         LDB(B0, 0, 0); SCHED; LDA(At, 0, 0); STAGE(SAo(1, 1), a1 + hstep);
;         WAIT_L(8); BAR; WAIT_L(0); MMA(0, 0, At, B0); BAR; SCHED;
;         LDB(B1, 0, 1); STAGE(SBo(0, 0), b2);
;         BAR; WAIT_L(0); MMA(0, 1, At, B1); BAR;
;         LDA(At, 0, 1); STAGE(SAo(0, 0), a2);
;         BAR; WAIT_L(0); MMA(1, 0, At, B0); BAR; SCHED;
;         STAGE(SBo(0, 1), b2 + hstep);
;         WAIT_V(6); BAR; MMA(1, 1, At, B1); BAR;
;         LDB(B0, 1, 0); SCHED; LDA(At, 1, 0); STAGE(SAo(0, 1), a2 + hstep);
;         WAIT_L(8); BAR; WAIT_L(0); MMA(0, 0, At, B0); BAR; SCHED;
;         LDB(B1, 1, 1); STAGE(SBo(1, 0), b3);
;         BAR; WAIT_L(0); MMA(0, 1, At, B1); BAR;
;         LDA(At, 1, 1); STAGE(SAo(1, 0), a3);
;         BAR; WAIT_L(0); MMA(1, 0, At, B0); BAR; SCHED;
;         STAGE(SBo(1, 1), b3 + hstep);
;         WAIT_V(6); BAR; MMA(1, 1, At, B1); BAR;
;     }
	v_lshl_add_u64 v[232:233], v[144:145], 0, s[60:61]
	s_add_i32 s6, s7, s18
	v_lshl_add_u64 v[150:151], v[232:233], 0, s[38:39]
	s_mov_b32 m0, s6
	v_lshl_add_u64 v[234:235], v[146:147], 0, s[60:61]
	global_load_lds_dwordx4 v[150:151], off
	v_lshl_add_u64 v[150:151], v[234:235], 0, s[38:39]
	s_add_i32 m0, s6, 0x2000
	s_nop 0
	global_load_lds_dwordx4 v[150:151], off
	s_waitcnt vmcnt(6)
	s_barrier
	v_mfma_f32_16x16x32_bf16 v[28:31], v[208:211], v[172:175], v[28:31]
	v_mfma_f32_16x16x32_bf16 v[24:27], v[216:219], v[172:175], v[24:27]
	v_mfma_f32_16x16x32_bf16 v[20:23], v[208:211], v[180:183], v[20:23]
	v_mfma_f32_16x16x32_bf16 v[16:19], v[216:219], v[180:183], v[16:19]
	v_mfma_f32_16x16x32_bf16 v[12:15], v[208:211], v[188:191], v[12:15]
	v_mfma_f32_16x16x32_bf16 v[8:11], v[216:219], v[188:191], v[8:11]
	v_mfma_f32_16x16x32_bf16 v[4:7], v[208:211], v[196:199], v[4:7]
	v_mfma_f32_16x16x32_bf16 v[0:3], v[216:219], v[196:199], v[0:3]
	v_mfma_f32_16x16x32_bf16 v[28:31], v[212:215], v[176:179], v[28:31]
	v_mfma_f32_16x16x32_bf16 v[24:27], v[220:223], v[176:179], v[24:27]
	v_mfma_f32_16x16x32_bf16 v[20:23], v[212:215], v[184:187], v[20:23]
	v_mfma_f32_16x16x32_bf16 v[16:19], v[220:223], v[184:187], v[16:19]
	v_mfma_f32_16x16x32_bf16 v[12:15], v[212:215], v[192:195], v[12:15]
	v_mfma_f32_16x16x32_bf16 v[8:11], v[220:223], v[192:195], v[8:11]
	v_mfma_f32_16x16x32_bf16 v[4:7], v[212:215], v[200:203], v[4:7]
	v_mfma_f32_16x16x32_bf16 v[0:3], v[220:223], v[200:203], v[0:3]
	s_add_i32 s6, 16, 0x18000
	v_add_u32_e32 v159, s6, v149
	s_barrier
	ds_read_b128 v[150:153], v159
	ds_read_b128 v[160:163], v159 offset:1024
	ds_read_b128 v[164:167], v159 offset:2048
	ds_read_b128 v[168:171], v159 offset:3072
	s_mov_b32 m0, s83
	v_lshl_add_u64 v[154:155], v[154:155], 0, s[38:39]
	ds_read_b128 v[172:175], v148 offset:32768
	ds_read_b128 v[176:179], v148 offset:33792
	ds_read_b128 v[180:183], v148 offset:34816
	ds_read_b128 v[184:187], v148 offset:35840
	ds_read_b128 v[188:191], v148 offset:36864
	ds_read_b128 v[192:195], v148 offset:37888
	ds_read_b128 v[196:199], v148 offset:38912
	ds_read_b128 v[200:203], v148 offset:39936
	global_load_lds_dwordx4 v[154:155], off
	v_lshl_add_u64 v[154:155], v[204:205], 0, s[38:39]
	s_mov_b32 m0, s85
	s_nop 0
	global_load_lds_dwordx4 v[154:155], off
	s_waitcnt lgkmcnt(8)
	s_barrier
	s_waitcnt lgkmcnt(0)
	v_mfma_f32_16x16x32_bf16 v[124:127], v[150:153], v[172:175], v[124:127]
	v_mfma_f32_16x16x32_bf16 v[120:123], v[164:167], v[172:175], v[120:123]
	v_mfma_f32_16x16x32_bf16 v[116:119], v[150:153], v[180:183], v[116:119]
	v_mfma_f32_16x16x32_bf16 v[112:115], v[164:167], v[180:183], v[112:115]
	v_mfma_f32_16x16x32_bf16 v[108:111], v[150:153], v[188:191], v[108:111]
	v_mfma_f32_16x16x32_bf16 v[104:107], v[164:167], v[188:191], v[104:107]
	v_mfma_f32_16x16x32_bf16 v[100:103], v[150:153], v[196:199], v[100:103]
	v_mfma_f32_16x16x32_bf16 v[96:99], v[164:167], v[196:199], v[96:99]
	v_mfma_f32_16x16x32_bf16 v[124:127], v[160:163], v[176:179], v[124:127]
	v_mfma_f32_16x16x32_bf16 v[120:123], v[168:171], v[176:179], v[120:123]
	v_mfma_f32_16x16x32_bf16 v[116:119], v[160:163], v[184:187], v[116:119]
	v_mfma_f32_16x16x32_bf16 v[112:115], v[168:171], v[184:187], v[112:115]
	v_mfma_f32_16x16x32_bf16 v[108:111], v[160:163], v[192:195], v[108:111]
	v_mfma_f32_16x16x32_bf16 v[104:107], v[168:171], v[192:195], v[104:107]
	v_mfma_f32_16x16x32_bf16 v[100:103], v[160:163], v[200:203], v[100:103]
	v_mfma_f32_16x16x32_bf16 v[96:99], v[168:171], v[200:203], v[96:99]
	s_barrier
	s_add_i32 s7, 16, 0x1c000
	v_add_u32_e32 v154, s7, v149
	s_add_i32 s6, s6, s18
	ds_read_b128 v[208:211], v154
	ds_read_b128 v[212:215], v154 offset:1024
	ds_read_b128 v[216:219], v154 offset:2048
	ds_read_b128 v[220:223], v154 offset:3072
	v_lshl_add_u64 v[154:155], v[224:225], 0, s[40:41]
	s_mov_b32 m0, s6
	s_nop 0
	global_load_lds_dwordx4 v[154:155], off
	v_lshl_add_u64 v[154:155], v[226:227], 0, s[40:41]
	s_add_i32 m0, s6, 0x2000
	s_nop 0
	global_load_lds_dwordx4 v[154:155], off
	s_barrier
	s_waitcnt lgkmcnt(0)
	v_mfma_f32_16x16x32_bf16 v[92:95], v[208:211], v[172:175], v[92:95]
	v_mfma_f32_16x16x32_bf16 v[88:91], v[216:219], v[172:175], v[88:91]
	v_mfma_f32_16x16x32_bf16 v[84:87], v[208:211], v[180:183], v[84:87]
	v_mfma_f32_16x16x32_bf16 v[80:83], v[216:219], v[180:183], v[80:83]
	v_mfma_f32_16x16x32_bf16 v[76:79], v[208:211], v[188:191], v[76:79]
	v_mfma_f32_16x16x32_bf16 v[72:75], v[216:219], v[188:191], v[72:75]
	v_mfma_f32_16x16x32_bf16 v[68:71], v[208:211], v[196:199], v[68:71]
	v_mfma_f32_16x16x32_bf16 v[64:67], v[216:219], v[196:199], v[64:67]
	v_mfma_f32_16x16x32_bf16 v[92:95], v[212:215], v[176:179], v[92:95]
	v_mfma_f32_16x16x32_bf16 v[88:91], v[220:223], v[176:179], v[88:91]
	v_mfma_f32_16x16x32_bf16 v[84:87], v[212:215], v[184:187], v[84:87]
	v_mfma_f32_16x16x32_bf16 v[80:83], v[220:223], v[184:187], v[80:83]
	v_mfma_f32_16x16x32_bf16 v[76:79], v[212:215], v[192:195], v[76:79]
	v_mfma_f32_16x16x32_bf16 v[72:75], v[220:223], v[192:195], v[72:75]
	v_mfma_f32_16x16x32_bf16 v[68:71], v[212:215], v[200:203], v[68:71]
	v_mfma_f32_16x16x32_bf16 v[64:67], v[220:223], v[200:203], v[64:67]
	s_mov_b32 m0, s97
	v_lshl_add_u64 v[154:155], v[228:229], 0, s[40:41]
	s_barrier
	ds_read_b128 v[172:175], v148 offset:49152
	ds_read_b128 v[176:179], v148 offset:50176
	ds_read_b128 v[180:183], v148 offset:51200
	ds_read_b128 v[184:187], v148 offset:52224
	ds_read_b128 v[188:191], v148 offset:53248
	ds_read_b128 v[192:195], v148 offset:54272
	ds_read_b128 v[196:199], v148 offset:55296
	ds_read_b128 v[200:203], v148 offset:56320
	global_load_lds_dwordx4 v[154:155], off
	v_lshl_add_u64 v[154:155], v[230:231], 0, s[40:41]
	s_mov_b32 m0, vcc_lo
	s_nop 0
	global_load_lds_dwordx4 v[154:155], off
	s_barrier
; #define WAIT_V(n) asm volatile("s_waitcnt vmcnt(" #n ")" ::: "memory")
; #define WAIT_L(n) asm volatile("s_waitcnt lgkmcnt(" #n ")" ::: "memory")
; #define BAR __builtin_amdgcn_s_barrier()
; #define SCHED __builtin_amdgcn_sched_barrier(0)
; DI void gemm_tile(const bf16_t* __restrict__ A, const bf16_t* __restrict__ Bt, const int K, const int brow, const int bcol, LAS unsigned char* lds, Acc& acc) {
;     ...
;         BAR; WAIT_L(0); MMA(1, 0, At, B0); BAR; SCHED;
;         STAGE(SBo(1, 1), b3 + hstep);
;         WAIT_V(6); BAR; MMA(1, 1, At, B1); BAR;
;     }
;     { LDB(B0, 0, 0); LDA(At, 0, 0); STAGE(SAo(1, 1), cA + (size_t)(nt - 1) * kstep + hstep);
;       BAR; WAIT_L(0); MMA(0, 0, At, B0); BAR;
;       LDB(B1, 0, 1); BAR; WAIT_L(0); MMA(0, 1, At, B1); BAR;
;       LDA(At, 0, 1); WAIT_V(4); BAR; WAIT_L(0); MMA(1, 0, At, B0); MMA(1, 1, At, B1); BAR; }
	s_waitcnt lgkmcnt(0)
	v_mfma_f32_16x16x32_bf16 v[60:63], v[150:153], v[172:175], v[60:63]
	v_mfma_f32_16x16x32_bf16 v[56:59], v[164:167], v[172:175], v[56:59]
	v_mfma_f32_16x16x32_bf16 v[52:55], v[150:153], v[180:183], v[52:55]
	v_mfma_f32_16x16x32_bf16 v[48:51], v[164:167], v[180:183], v[48:51]
	v_mfma_f32_16x16x32_bf16 v[44:47], v[150:153], v[188:191], v[44:47]
	v_mfma_f32_16x16x32_bf16 v[40:43], v[164:167], v[188:191], v[40:43]
	v_mfma_f32_16x16x32_bf16 v[36:39], v[150:153], v[196:199], v[36:39]
	v_mfma_f32_16x16x32_bf16 v[32:35], v[164:167], v[196:199], v[32:35]
	v_mfma_f32_16x16x32_bf16 v[60:63], v[160:163], v[176:179], v[60:63]
	v_mfma_f32_16x16x32_bf16 v[56:59], v[168:171], v[176:179], v[56:59]
	v_mfma_f32_16x16x32_bf16 v[52:55], v[160:163], v[184:187], v[52:55]
	v_mfma_f32_16x16x32_bf16 v[48:51], v[168:171], v[184:187], v[48:51]
	v_mfma_f32_16x16x32_bf16 v[44:47], v[160:163], v[192:195], v[44:47]
	v_mfma_f32_16x16x32_bf16 v[40:43], v[168:171], v[192:195], v[40:43]
	v_mfma_f32_16x16x32_bf16 v[36:39], v[160:163], v[200:203], v[36:39]
	v_mfma_f32_16x16x32_bf16 v[32:35], v[168:171], v[200:203], v[32:35]
	s_barrier
	s_add_i32 s6, s7, s18
	v_lshl_add_u64 v[150:151], v[232:233], 0, s[40:41]
	s_mov_b32 m0, s6
	s_nop 0
	global_load_lds_dwordx4 v[150:151], off
	v_lshl_add_u64 v[150:151], v[234:235], 0, s[40:41]
	s_add_i32 m0, s6, 0x2000
	s_nop 0
	global_load_lds_dwordx4 v[150:151], off
	s_waitcnt vmcnt(6)
	s_barrier
	v_mfma_f32_16x16x32_bf16 v[28:31], v[208:211], v[172:175], v[28:31]
	v_mfma_f32_16x16x32_bf16 v[24:27], v[216:219], v[172:175], v[24:27]
	v_mfma_f32_16x16x32_bf16 v[20:23], v[208:211], v[180:183], v[20:23]
	v_mfma_f32_16x16x32_bf16 v[16:19], v[216:219], v[180:183], v[16:19]
	v_mfma_f32_16x16x32_bf16 v[12:15], v[208:211], v[188:191], v[12:15]
	v_mfma_f32_16x16x32_bf16 v[8:11], v[216:219], v[188:191], v[8:11]
	v_mfma_f32_16x16x32_bf16 v[4:7], v[208:211], v[196:199], v[4:7]
	v_mfma_f32_16x16x32_bf16 v[0:3], v[216:219], v[196:199], v[0:3]
	v_mfma_f32_16x16x32_bf16 v[28:31], v[212:215], v[176:179], v[28:31]
	v_mfma_f32_16x16x32_bf16 v[24:27], v[220:223], v[176:179], v[24:27]
	v_mfma_f32_16x16x32_bf16 v[20:23], v[212:215], v[184:187], v[20:23]
	v_mfma_f32_16x16x32_bf16 v[16:19], v[220:223], v[184:187], v[16:19]
	v_mfma_f32_16x16x32_bf16 v[12:15], v[212:215], v[192:195], v[12:15]
	v_mfma_f32_16x16x32_bf16 v[8:11], v[220:223], v[192:195], v[8:11]
	v_mfma_f32_16x16x32_bf16 v[4:7], v[212:215], v[200:203], v[4:7]
	v_mfma_f32_16x16x32_bf16 v[0:3], v[220:223], v[200:203], v[0:3]
	s_add_u32 s60, s60, 0x100
	s_addc_u32 s61, s61, 0
	s_cmp_ge_u32 s62, vcc_hi
	s_barrier
	s_cbranch_scc0 .LBB0_930
	s_add_i32 s18, s96, -1
	s_lshl_b64 s[6:7], s[18:19], 7
	s_add_u32 s4, s4, s6
	s_addc_u32 s5, s5, s7
	s_add_u32 s4, s4, s55
	v_add_u32_e32 v149, 16, v149
	s_addc_u32 s5, s5, 0
	s_mov_b32 m0, s81
	v_add_u32_e32 v144, 0x10000, v149
	v_lshl_add_u64 v[154:155], s[4:5], 0, v[142:143]
	ds_read_b128 v[130:133], v144
	ds_read_b128 v[134:137], v144 offset:1024
	ds_read_b128 v[138:141], v144 offset:2048
	ds_read_b128 v[144:147], v144 offset:3072
	ds_read_b128 v[150:153], v148
	ds_read_b128 v[160:163], v148 offset:1024
	ds_read_b128 v[164:167], v148 offset:2048
	ds_read_b128 v[168:171], v148 offset:3072
	ds_read_b128 v[172:175], v148 offset:4096
	ds_read_b128 v[176:179], v148 offset:5120
	ds_read_b128 v[180:183], v148 offset:6144
	ds_read_b128 v[184:187], v148 offset:7168
	global_load_lds_dwordx4 v[154:155], off
	v_lshl_add_u64 v[128:129], s[4:5], 0, v[128:129]
	s_mov_b32 m0, s63
	s_nop 0
	global_load_lds_dwordx4 v[128:129], off
	s_barrier
	s_waitcnt lgkmcnt(0)
	v_mfma_f32_16x16x32_bf16 v[124:127], v[130:133], v[150:153], v[124:127]
	v_mfma_f32_16x16x32_bf16 v[120:123], v[138:141], v[150:153], v[120:123]
	v_mfma_f32_16x16x32_bf16 v[116:119], v[130:133], v[164:167], v[116:119]
	v_mfma_f32_16x16x32_bf16 v[112:115], v[138:141], v[164:167], v[112:115]
	v_mfma_f32_16x16x32_bf16 v[100:103], v[130:133], v[180:183], v[100:103]
	v_mfma_f32_16x16x32_bf16 v[96:99], v[138:141], v[180:183], v[96:99]
	v_mfma_f32_16x16x32_bf16 v[124:127], v[134:137], v[160:163], v[124:127]
	v_mfma_f32_16x16x32_bf16 v[120:123], v[144:147], v[160:163], v[120:123]
	v_mfma_f32_16x16x32_bf16 v[116:119], v[134:137], v[168:171], v[116:119]
	v_mfma_f32_16x16x32_bf16 v[112:115], v[144:147], v[168:171], v[112:115]
	v_mfma_f32_16x16x32_bf16 v[108:111], v[130:133], v[172:175], v[108:111]
	v_mfma_f32_16x16x32_bf16 v[104:107], v[138:141], v[172:175], v[104:107]
	v_mfma_f32_16x16x32_bf16 v[100:103], v[134:137], v[184:187], v[100:103]
	v_mfma_f32_16x16x32_bf16 v[96:99], v[144:147], v[184:187], v[96:99]
	v_mfma_f32_16x16x32_bf16 v[188:191], v[134:137], v[176:179], v[108:111]
	v_mfma_f32_16x16x32_bf16 v[192:195], v[144:147], v[176:179], v[104:107]
	v_add_u32_e32 v128, 0x14000, v149
	s_barrier
	s_nop 0
	ds_read_b128 v[104:107], v128
	ds_read_b128 v[108:111], v128 offset:1024
	ds_read_b128 v[196:199], v128 offset:2048
	ds_read_b128 v[200:203], v128 offset:3072
	s_barrier
	s_waitcnt lgkmcnt(0)
	v_mfma_f32_16x16x32_bf16 v[84:87], v[104:107], v[164:167], v[84:87]
	v_mfma_f32_16x16x32_bf16 v[80:83], v[196:199], v[164:167], v[80:83]
	v_mfma_f32_16x16x32_bf16 v[68:71], v[104:107], v[180:183], v[68:71]
	v_mfma_f32_16x16x32_bf16 v[64:67], v[196:199], v[180:183], v[64:67]
	v_mfma_f32_16x16x32_bf16 v[92:95], v[104:107], v[150:153], v[92:95]
	v_mfma_f32_16x16x32_bf16 v[88:91], v[196:199], v[150:153], v[88:91]
	v_mfma_f32_16x16x32_bf16 v[84:87], v[108:111], v[168:171], v[84:87]
	v_mfma_f32_16x16x32_bf16 v[80:83], v[200:203], v[168:171], v[80:83]
	v_mfma_f32_16x16x32_bf16 v[76:79], v[104:107], v[172:175], v[76:79]
	v_mfma_f32_16x16x32_bf16 v[72:75], v[196:199], v[172:175], v[72:75]
	v_mfma_f32_16x16x32_bf16 v[68:71], v[108:111], v[184:187], v[68:71]
	v_mfma_f32_16x16x32_bf16 v[64:67], v[200:203], v[184:187], v[64:67]
	v_mfma_f32_16x16x32_bf16 v[208:211], v[108:111], v[160:163], v[92:95]
	v_mfma_f32_16x16x32_bf16 v[150:153], v[200:203], v[160:163], v[88:91]
	v_mfma_f32_16x16x32_bf16 v[160:163], v[108:111], v[176:179], v[76:79]
	v_mfma_f32_16x16x32_bf16 v[164:167], v[200:203], v[176:179], v[72:75]
	s_barrier
; #define WAIT_V(n) asm volatile("s_waitcnt vmcnt(" #n ")" ::: "memory")
; #define WAIT_L(n) asm volatile("s_waitcnt lgkmcnt(" #n ")" ::: "memory")
; #define BAR __builtin_amdgcn_s_barrier()
; DI void gemm_tile(const bf16_t* __restrict__ A, const bf16_t* __restrict__ Bt, const int K, const int brow, const int bcol, LAS unsigned char* lds, Acc& acc) {
;     ...
;     { LDB(B0, 0, 0); LDA(At, 0, 0); STAGE(SAo(1, 1), cA + (size_t)(nt - 1) * kstep + hstep);
;       BAR; WAIT_L(0); MMA(0, 0, At, B0); BAR;
;       LDB(B1, 0, 1); BAR; WAIT_L(0); MMA(0, 1, At, B1); BAR;
;       LDA(At, 0, 1); WAIT_V(4); BAR; WAIT_L(0); MMA(1, 0, At, B0); MMA(1, 1, At, B1); BAR; }
;     { LDB(B0, 1, 0); LDA(At, 1, 0); WAIT_V(2); BAR; WAIT_L(0); MMA(0, 0, At, B0); BAR;
;       LDB(B1, 1, 1); WAIT_V(0); BAR; WAIT_L(0); MMA(0, 1, At, B1); BAR;
;       LDA(At, 1, 1); BAR; WAIT_L(0); MMA(1, 0, At, B0); MMA(1, 1, At, B1); BAR; }
	s_nop 0
	ds_read_b128 v[72:75], v148 offset:16384
	ds_read_b128 v[76:79], v148 offset:17408
	ds_read_b128 v[88:91], v148 offset:18432
	ds_read_b128 v[92:95], v148 offset:19456
	ds_read_b128 v[168:171], v148 offset:20480
	ds_read_b128 v[172:175], v148 offset:21504
	ds_read_b128 v[176:179], v148 offset:22528
	ds_read_b128 v[180:183], v148 offset:23552
	s_waitcnt vmcnt(4)
	s_barrier
	s_waitcnt lgkmcnt(0)
	v_mfma_f32_16x16x32_bf16 v[60:63], v[130:133], v[72:75], v[60:63]
	v_mfma_f32_16x16x32_bf16 v[56:59], v[138:141], v[72:75], v[56:59]
	v_mfma_f32_16x16x32_bf16 v[52:55], v[130:133], v[88:91], v[52:55]
	v_mfma_f32_16x16x32_bf16 v[48:51], v[138:141], v[88:91], v[48:51]
	v_mfma_f32_16x16x32_bf16 v[36:39], v[130:133], v[176:179], v[36:39]
	v_mfma_f32_16x16x32_bf16 v[32:35], v[138:141], v[176:179], v[32:35]
	v_mfma_f32_16x16x32_bf16 v[60:63], v[134:137], v[76:79], v[60:63]
	v_mfma_f32_16x16x32_bf16 v[56:59], v[144:147], v[76:79], v[56:59]
	v_mfma_f32_16x16x32_bf16 v[52:55], v[134:137], v[92:95], v[52:55]
	v_mfma_f32_16x16x32_bf16 v[48:51], v[144:147], v[92:95], v[48:51]
	v_mfma_f32_16x16x32_bf16 v[44:47], v[130:133], v[168:171], v[44:47]
	v_mfma_f32_16x16x32_bf16 v[40:43], v[138:141], v[168:171], v[40:43]
	v_mfma_f32_16x16x32_bf16 v[36:39], v[134:137], v[180:183], v[36:39]
	v_mfma_f32_16x16x32_bf16 v[32:35], v[144:147], v[180:183], v[32:35]
	v_mfma_f32_16x16x32_bf16 v[184:187], v[134:137], v[172:175], v[44:47]
	v_mfma_f32_16x16x32_bf16 v[212:215], v[144:147], v[172:175], v[40:43]
	v_mfma_f32_16x16x32_bf16 v[20:23], v[104:107], v[88:91], v[20:23]
	v_mfma_f32_16x16x32_bf16 v[16:19], v[196:199], v[88:91], v[16:19]
	v_mfma_f32_16x16x32_bf16 v[4:7], v[104:107], v[176:179], v[4:7]
	v_mfma_f32_16x16x32_bf16 v[0:3], v[196:199], v[176:179], v[0:3]
	v_mfma_f32_16x16x32_bf16 v[28:31], v[104:107], v[72:75], v[28:31]
	v_mfma_f32_16x16x32_bf16 v[24:27], v[196:199], v[72:75], v[24:27]
	v_mfma_f32_16x16x32_bf16 v[20:23], v[108:111], v[92:95], v[20:23]
	v_mfma_f32_16x16x32_bf16 v[16:19], v[200:203], v[92:95], v[16:19]
	v_mfma_f32_16x16x32_bf16 v[12:15], v[104:107], v[168:171], v[12:15]
	v_mfma_f32_16x16x32_bf16 v[8:11], v[196:199], v[168:171], v[8:11]
	v_mfma_f32_16x16x32_bf16 v[4:7], v[108:111], v[180:183], v[4:7]
	v_mfma_f32_16x16x32_bf16 v[0:3], v[200:203], v[180:183], v[0:3]
	v_mfma_f32_16x16x32_bf16 v[128:131], v[108:111], v[76:79], v[28:31]
	v_mfma_f32_16x16x32_bf16 v[132:135], v[200:203], v[76:79], v[24:27]
	v_mfma_f32_16x16x32_bf16 v[136:139], v[108:111], v[172:175], v[12:15]
	v_mfma_f32_16x16x32_bf16 v[144:147], v[200:203], v[172:175], v[8:11]
	v_add_u32_e32 v24, 0x18000, v149
	s_barrier
	ds_read_b128 v[8:11], v24
	ds_read_b128 v[12:15], v24 offset:1024
	ds_read_b128 v[168:171], v24 offset:2048
	ds_read_b128 v[172:175], v24 offset:3072
	ds_read_b128 v[24:27], v148 offset:32768
	ds_read_b128 v[28:31], v148 offset:33792
	ds_read_b128 v[40:43], v148 offset:34816
	ds_read_b128 v[44:47], v148 offset:35840
	ds_read_b128 v[176:179], v148 offset:36864
	ds_read_b128 v[180:183], v148 offset:37888
	ds_read_b128 v[196:199], v148 offset:38912
	ds_read_b128 v[200:203], v148 offset:39936
	s_waitcnt vmcnt(2)
	s_barrier
	s_waitcnt lgkmcnt(0)
	v_mfma_f32_16x16x32_bf16 v[72:75], v[8:11], v[24:27], v[124:127]
	v_mfma_f32_16x16x32_bf16 v[124:127], v[12:15], v[28:31], v[72:75]
	v_mfma_f32_16x16x32_bf16 v[72:75], v[168:171], v[24:27], v[120:123]
	v_mfma_f32_16x16x32_bf16 v[120:123], v[172:175], v[28:31], v[72:75]
	v_mfma_f32_16x16x32_bf16 v[72:75], v[8:11], v[40:43], v[116:119]
	v_mfma_f32_16x16x32_bf16 v[108:111], v[12:15], v[44:47], v[72:75]
	v_mfma_f32_16x16x32_bf16 v[72:75], v[168:171], v[40:43], v[112:115]
	v_mfma_f32_16x16x32_bf16 v[104:107], v[172:175], v[44:47], v[72:75]
	v_mfma_f32_16x16x32_bf16 v[72:75], v[8:11], v[176:179], v[188:191]
	v_mfma_f32_16x16x32_bf16 v[92:95], v[12:15], v[180:183], v[72:75]
	v_mfma_f32_16x16x32_bf16 v[72:75], v[168:171], v[176:179], v[192:195]
	v_mfma_f32_16x16x32_bf16 v[88:91], v[172:175], v[180:183], v[72:75]
	v_mfma_f32_16x16x32_bf16 v[72:75], v[8:11], v[196:199], v[100:103]
	v_mfma_f32_16x16x32_bf16 v[76:79], v[12:15], v[200:203], v[72:75]
	v_mfma_f32_16x16x32_bf16 v[72:75], v[168:171], v[196:199], v[96:99]
	v_mfma_f32_16x16x32_bf16 v[72:75], v[172:175], v[200:203], v[72:75]
	s_nop 0
	v_add_u32_e32 v96, 0x1c000, v149
	s_barrier
; #define WAIT_V(n) asm volatile("s_waitcnt vmcnt(" #n ")" ::: "memory")
; #define WAIT_L(n) asm volatile("s_waitcnt lgkmcnt(" #n ")" ::: "memory")
; #define BAR __builtin_amdgcn_s_barrier()
; DI void gemm_tile(const bf16_t* __restrict__ A, const bf16_t* __restrict__ Bt, const int K, const int brow, const int bcol, LAS unsigned char* lds, Acc& acc) {
;     ...
;     { LDB(B0, 1, 0); LDA(At, 1, 0); WAIT_V(2); BAR; WAIT_L(0); MMA(0, 0, At, B0); BAR;
;       LDB(B1, 1, 1); WAIT_V(0); BAR; WAIT_L(0); MMA(0, 1, At, B1); BAR;
;       LDA(At, 1, 1); BAR; WAIT_L(0); MMA(1, 0, At, B0); MMA(1, 1, At, B1); BAR; }
;     if (wr == 0) BAR;
	ds_read_b128 v[188:191], v96
	ds_read_b128 v[192:195], v96 offset:1024
	ds_read_b128 v[216:219], v96 offset:2048
	ds_read_b128 v[220:223], v96 offset:3072
	s_waitcnt vmcnt(0)
	s_barrier
	s_waitcnt lgkmcnt(0)
	v_mfma_f32_16x16x32_bf16 v[96:99], v[188:191], v[24:27], v[208:211]
	v_mfma_f32_16x16x32_bf16 v[24:27], v[216:219], v[24:27], v[150:153]
	v_mfma_f32_16x16x32_bf16 v[112:115], v[220:223], v[28:31], v[24:27]
	v_mfma_f32_16x16x32_bf16 v[24:27], v[188:191], v[40:43], v[84:87]
	v_mfma_f32_16x16x32_bf16 v[100:103], v[192:195], v[44:47], v[24:27]
	v_mfma_f32_16x16x32_bf16 v[24:27], v[216:219], v[40:43], v[80:83]
	v_mfma_f32_16x16x32_bf16 v[116:119], v[192:195], v[28:31], v[96:99]
	v_mfma_f32_16x16x32_bf16 v[96:99], v[220:223], v[44:47], v[24:27]
	v_mfma_f32_16x16x32_bf16 v[24:27], v[188:191], v[176:179], v[160:163]
	v_mfma_f32_16x16x32_bf16 v[84:87], v[192:195], v[180:183], v[24:27]
	v_mfma_f32_16x16x32_bf16 v[24:27], v[216:219], v[176:179], v[164:167]
	v_mfma_f32_16x16x32_bf16 v[80:83], v[220:223], v[180:183], v[24:27]
	v_mfma_f32_16x16x32_bf16 v[24:27], v[188:191], v[196:199], v[68:71]
	v_mfma_f32_16x16x32_bf16 v[68:71], v[192:195], v[200:203], v[24:27]
	v_mfma_f32_16x16x32_bf16 v[24:27], v[216:219], v[196:199], v[64:67]
	v_mfma_f32_16x16x32_bf16 v[64:67], v[220:223], v[200:203], v[24:27]
	s_barrier
	ds_read_b128 v[150:153], v148 offset:49152
	ds_read_b128 v[160:163], v148 offset:50176
	ds_read_b128 v[164:167], v148 offset:51200
	ds_read_b128 v[176:179], v148 offset:52224
	ds_read_b128 v[180:183], v148 offset:53248
	ds_read_b128 v[196:199], v148 offset:54272
	ds_read_b128 v[200:203], v148 offset:55296
	ds_read_b128 v[208:211], v148 offset:56320
	s_barrier
	s_waitcnt lgkmcnt(0)
	v_mfma_f32_16x16x32_bf16 v[24:27], v[8:11], v[150:153], v[60:63]
	v_mfma_f32_16x16x32_bf16 v[60:63], v[12:15], v[160:163], v[24:27]
	v_mfma_f32_16x16x32_bf16 v[24:27], v[168:171], v[150:153], v[56:59]
	v_mfma_f32_16x16x32_bf16 v[56:59], v[172:175], v[160:163], v[24:27]
	v_mfma_f32_16x16x32_bf16 v[24:27], v[8:11], v[164:167], v[52:55]
	v_mfma_f32_16x16x32_bf16 v[44:47], v[12:15], v[176:179], v[24:27]
	v_mfma_f32_16x16x32_bf16 v[24:27], v[168:171], v[164:167], v[48:51]
	v_mfma_f32_16x16x32_bf16 v[40:43], v[172:175], v[176:179], v[24:27]
	v_mfma_f32_16x16x32_bf16 v[24:27], v[8:11], v[180:183], v[184:187]
	v_mfma_f32_16x16x32_bf16 v[8:11], v[8:11], v[200:203], v[36:39]
	v_mfma_f32_16x16x32_bf16 v[28:31], v[12:15], v[196:199], v[24:27]
	v_mfma_f32_16x16x32_bf16 v[24:27], v[168:171], v[180:183], v[212:215]
	v_mfma_f32_16x16x32_bf16 v[12:15], v[12:15], v[208:211], v[8:11]
	v_mfma_f32_16x16x32_bf16 v[8:11], v[168:171], v[200:203], v[32:35]
	v_mfma_f32_16x16x32_bf16 v[24:27], v[172:175], v[196:199], v[24:27]
	v_mfma_f32_16x16x32_bf16 v[8:11], v[172:175], v[208:211], v[8:11]
	v_mfma_f32_16x16x32_bf16 v[32:35], v[188:191], v[150:153], v[128:131]
	v_mfma_f32_16x16x32_bf16 v[52:55], v[192:195], v[160:163], v[32:35]
	v_mfma_f32_16x16x32_bf16 v[32:35], v[216:219], v[150:153], v[132:135]
	v_mfma_f32_16x16x32_bf16 v[16:19], v[216:219], v[164:167], v[16:19]
	v_mfma_f32_16x16x32_bf16 v[48:51], v[220:223], v[160:163], v[32:35]
	v_mfma_f32_16x16x32_bf16 v[20:23], v[188:191], v[164:167], v[20:23]
	v_mfma_f32_16x16x32_bf16 v[32:35], v[220:223], v[176:179], v[16:19]
	v_mfma_f32_16x16x32_bf16 v[16:19], v[188:191], v[180:183], v[136:139]
	v_mfma_f32_16x16x32_bf16 v[36:39], v[192:195], v[176:179], v[20:23]
	v_mfma_f32_16x16x32_bf16 v[20:23], v[192:195], v[196:199], v[16:19]
	v_mfma_f32_16x16x32_bf16 v[16:19], v[216:219], v[180:183], v[144:147]
	v_mfma_f32_16x16x32_bf16 v[4:7], v[188:191], v[200:203], v[4:7]
	v_mfma_f32_16x16x32_bf16 v[0:3], v[216:219], v[200:203], v[0:3]
	v_mfma_f32_16x16x32_bf16 v[16:19], v[220:223], v[196:199], v[16:19]
	v_mfma_f32_16x16x32_bf16 v[4:7], v[192:195], v[208:211], v[4:7]
	v_mfma_f32_16x16x32_bf16 v[0:3], v[220:223], v[208:211], v[0:3]
	s_cmpk_lt_u32 s29, 0x100
	s_mov_b32 s89, s23
	s_mov_b32 s90, s35
	s_mov_b32 s91, s8
	s_barrier
	s_cbranch_scc0 .LBB0_934
	s_barrier
	s_and_b64 vcc, exec, s[2:3]
	s_mov_b64 s[2:3], -1
	s_cbranch_vccz .LBB0_935

; #define WAIT_V(n) asm volatile("s_waitcnt vmcnt(" #n ")" ::: "memory")
; #define WAIT_L(n) asm volatile("s_waitcnt lgkmcnt(" #n ")" ::: "memory")
; #define BAR __builtin_amdgcn_s_barrier()
; #define SCHED __builtin_amdgcn_sched_barrier(0)
; template <class Get, class Epi>
; DI void gemm_stream(LAS unsigned char* lds, const int K, const int ld, Get get, Epi epi) {
;     ...
;         for (int t = 0; t < nt; t += 2) {
;             const bool last = (t == nt - 2);
;             const char* a1 = cA + (size_t)(t + 1) * kstep;
;             const char* a2 = last ? nA : cA + (size_t)(t + 2) * kstep;
;             const char* b2 = last ? nB : cB + (size_t)(t + 2) * kstep;
;             const char* a3 = a2 + kstep;
;             const char* b3 = b2 + kstep;
;             LDB(B0, 0, 0); SCHED; LDA(At, 0, 0); STAGE(SAo(1, 1), a1 + hstep);
;             WAIT_L(8); BAR; WAIT_L(0); MMA(0, 0, At, B0); BAR; SCHED;
;             LDB(B1, 0, 1); STAGE(SBo(0, 0), b2);
;             BAR; WAIT_L(0); MMA(0, 1, At, B1); BAR;
;             LDA(At, 0, 1); STAGE(SAo(0, 0), a2);
;             BAR; WAIT_L(0); MMA(1, 0, At, B0); BAR; SCHED;
;             STAGE(SBo(0, 1), b2 + hstep);
;             WAIT_V(6); BAR; MMA(1, 1, At, B1); BAR;
;             LDB(B0, 1, 0); SCHED; LDA(At, 1, 0); STAGE(SAo(0, 1), a2 + hstep);
;             WAIT_L(8); BAR; WAIT_L(0); MMA(0, 0, At, B0); BAR; SCHED;
;             LDB(B1, 1, 1); STAGE(SBo(1, 0), b3);
;             BAR; WAIT_L(0); MMA(0, 1, At, B1); BAR;
;             LDA(At, 1, 1); STAGE(SAo(1, 0), a3);
;             BAR; WAIT_L(0); MMA(1, 0, At, B0); BAR; SCHED;
;             STAGE(SBo(1, 1), b3 + hstep);
;             WAIT_V(6); BAR; MMA(1, 1, At, B1); BAR;
;         }
.LBB0_1238:
	ds_read_b128 v[128:131], v198
	ds_read_b128 v[132:135], v198 offset:1024
	ds_read_b128 v[136:139], v198 offset:2048
	ds_read_b128 v[140:143], v198 offset:3072
	s_add_u32 s8, s6, 0x100
	s_addc_u32 s9, s7, 0
	s_cmp_eq_u32 s18, 28
	s_cselect_b32 s13, s39, s9
	s_cselect_b32 s12, s38, s8
	s_cselect_b32 s11, s41, s17
	s_cselect_b32 s10, s40, s16
	s_mov_b32 m0, s74
	v_lshl_add_u64 v[186:187], s[6:7], 0, v[168:169]
	ds_read_b128 v[144:147], v199
	ds_read_b128 v[148:151], v199 offset:1024
	ds_read_b128 v[152:155], v199 offset:2048
	ds_read_b128 v[156:159], v199 offset:3072
	ds_read_b128 v[160:163], v199 offset:4096
	ds_read_b128 v[174:177], v199 offset:5120
	ds_read_b128 v[178:181], v199 offset:6144
	ds_read_b128 v[182:185], v199 offset:7168
	global_load_lds_dwordx4 v[186:187], off
	v_lshl_add_u64 v[186:187], s[6:7], 0, v[170:171]
	s_mov_b32 m0, s75
	s_nop 0
	global_load_lds_dwordx4 v[186:187], off
	s_waitcnt lgkmcnt(8)
	s_barrier
	s_waitcnt lgkmcnt(0)
	v_mfma_f32_16x16x32_bf16 v[124:127], v[128:131], v[144:147], v[124:127]
	v_mfma_f32_16x16x32_bf16 v[92:95], v[136:139], v[144:147], v[92:95]
	v_mfma_f32_16x16x32_bf16 v[120:123], v[128:131], v[152:155], v[120:123]
	v_mfma_f32_16x16x32_bf16 v[88:91], v[136:139], v[152:155], v[88:91]
	v_mfma_f32_16x16x32_bf16 v[116:119], v[128:131], v[160:163], v[116:119]
	v_mfma_f32_16x16x32_bf16 v[84:87], v[136:139], v[160:163], v[84:87]
	v_mfma_f32_16x16x32_bf16 v[112:115], v[128:131], v[178:181], v[112:115]
	v_mfma_f32_16x16x32_bf16 v[80:83], v[136:139], v[178:181], v[80:83]
	v_mfma_f32_16x16x32_bf16 v[124:127], v[132:135], v[148:151], v[124:127]
	v_mfma_f32_16x16x32_bf16 v[92:95], v[140:143], v[148:151], v[92:95]
	v_mfma_f32_16x16x32_bf16 v[120:123], v[132:135], v[156:159], v[120:123]
	v_mfma_f32_16x16x32_bf16 v[88:91], v[140:143], v[156:159], v[88:91]
	v_mfma_f32_16x16x32_bf16 v[116:119], v[132:135], v[174:177], v[116:119]
	v_mfma_f32_16x16x32_bf16 v[84:87], v[140:143], v[174:177], v[84:87]
	v_mfma_f32_16x16x32_bf16 v[112:115], v[132:135], v[182:185], v[112:115]
	v_mfma_f32_16x16x32_bf16 v[80:83], v[140:143], v[182:185], v[80:83]
	s_barrier
	s_mov_b32 m0, s80
	v_lshl_add_u64 v[204:205], s[10:11], 0, v[164:165]
	ds_read_b128 v[186:189], v200
	ds_read_b128 v[190:193], v200 offset:1024
	ds_read_b128 v[194:197], v200 offset:2048
	ds_read_b128 v[208:211], v200 offset:3072
	global_load_lds_dwordx4 v[204:205], off
	v_lshl_add_u64 v[212:213], s[10:11], 0, v[166:167]
	s_mov_b32 m0, s81
	s_nop 0
	global_load_lds_dwordx4 v[212:213], off
	s_barrier
	s_waitcnt lgkmcnt(0)
	v_mfma_f32_16x16x32_bf16 v[60:63], v[186:189], v[144:147], v[60:63]
	v_mfma_f32_16x16x32_bf16 v[28:31], v[194:197], v[144:147], v[28:31]
	v_mfma_f32_16x16x32_bf16 v[56:59], v[186:189], v[152:155], v[56:59]
	v_mfma_f32_16x16x32_bf16 v[24:27], v[194:197], v[152:155], v[24:27]
	v_mfma_f32_16x16x32_bf16 v[52:55], v[186:189], v[160:163], v[52:55]
	v_mfma_f32_16x16x32_bf16 v[20:23], v[194:197], v[160:163], v[20:23]
	v_mfma_f32_16x16x32_bf16 v[48:51], v[186:189], v[178:181], v[48:51]
	v_mfma_f32_16x16x32_bf16 v[16:19], v[194:197], v[178:181], v[16:19]
	v_mfma_f32_16x16x32_bf16 v[60:63], v[190:193], v[148:151], v[60:63]
	v_mfma_f32_16x16x32_bf16 v[28:31], v[208:211], v[148:151], v[28:31]
	v_mfma_f32_16x16x32_bf16 v[56:59], v[190:193], v[156:159], v[56:59]
	v_mfma_f32_16x16x32_bf16 v[24:27], v[208:211], v[156:159], v[24:27]
	v_mfma_f32_16x16x32_bf16 v[52:55], v[190:193], v[174:177], v[52:55]
	v_mfma_f32_16x16x32_bf16 v[20:23], v[208:211], v[174:177], v[20:23]
	v_mfma_f32_16x16x32_bf16 v[48:51], v[190:193], v[182:185], v[48:51]
	v_mfma_f32_16x16x32_bf16 v[16:19], v[208:211], v[182:185], v[16:19]
	s_mov_b32 m0, s21
	v_lshl_add_u64 v[214:215], s[12:13], 0, v[164:165]
	s_barrier
	ds_read_b128 v[144:147], v199 offset:16384
	ds_read_b128 v[148:151], v199 offset:17408
	ds_read_b128 v[152:155], v199 offset:18432
	ds_read_b128 v[156:159], v199 offset:19456
	ds_read_b128 v[160:163], v199 offset:20480
	ds_read_b128 v[174:177], v199 offset:21504
	ds_read_b128 v[178:181], v199 offset:22528
	ds_read_b128 v[182:185], v199 offset:23552
	global_load_lds_dwordx4 v[214:215], off
	v_lshl_add_u64 v[216:217], s[12:13], 0, v[166:167]
	s_mov_b32 m0, s58
	s_nop 0
	global_load_lds_dwordx4 v[216:217], off
	s_barrier
	s_waitcnt lgkmcnt(0)
	v_mfma_f32_16x16x32_bf16 v[108:111], v[128:131], v[144:147], v[108:111]
	v_mfma_f32_16x16x32_bf16 v[76:79], v[136:139], v[144:147], v[76:79]
	v_mfma_f32_16x16x32_bf16 v[104:107], v[128:131], v[152:155], v[104:107]
	v_mfma_f32_16x16x32_bf16 v[72:75], v[136:139], v[152:155], v[72:75]
	v_mfma_f32_16x16x32_bf16 v[100:103], v[128:131], v[160:163], v[100:103]
	v_mfma_f32_16x16x32_bf16 v[68:71], v[136:139], v[160:163], v[68:71]
	v_mfma_f32_16x16x32_bf16 v[96:99], v[128:131], v[178:181], v[96:99]
	v_mfma_f32_16x16x32_bf16 v[64:67], v[136:139], v[178:181], v[64:67]
	v_mfma_f32_16x16x32_bf16 v[108:111], v[132:135], v[148:151], v[108:111]
	v_mfma_f32_16x16x32_bf16 v[76:79], v[140:143], v[148:151], v[76:79]
	v_mfma_f32_16x16x32_bf16 v[104:107], v[132:135], v[156:159], v[104:107]
	v_mfma_f32_16x16x32_bf16 v[72:75], v[140:143], v[156:159], v[72:75]
	v_mfma_f32_16x16x32_bf16 v[100:103], v[132:135], v[174:177], v[100:103]
	v_mfma_f32_16x16x32_bf16 v[68:71], v[140:143], v[174:177], v[68:71]
	v_mfma_f32_16x16x32_bf16 v[96:99], v[132:135], v[182:185], v[96:99]
	v_mfma_f32_16x16x32_bf16 v[64:67], v[140:143], v[182:185], v[64:67]
	s_barrier
	s_add_u32 s6, s10, 0x80000
	s_addc_u32 s7, s11, 0
	s_mov_b32 m0, s82
	v_lshl_add_u64 v[128:129], s[6:7], 0, v[164:165]
	global_load_lds_dwordx4 v[128:129], off
	v_lshl_add_u64 v[128:129], s[6:7], 0, v[166:167]
	s_mov_b32 m0, s83
	s_nop 0
	global_load_lds_dwordx4 v[128:129], off
	s_waitcnt vmcnt(6)
	s_barrier
; #define WAIT_V(n) asm volatile("s_waitcnt vmcnt(" #n ")" ::: "memory")
; #define WAIT_L(n) asm volatile("s_waitcnt lgkmcnt(" #n ")" ::: "memory")
; #define BAR __builtin_amdgcn_s_barrier()
; #define SCHED __builtin_amdgcn_sched_barrier(0)
; template <class Get, class Epi>
; DI void gemm_stream(LAS unsigned char* lds, const int K, const int ld, Get get, Epi epi) {
;     ...
;         for (int t = 0; t < nt; t += 2) {
;             const bool last = (t == nt - 2);
;             const char* a1 = cA + (size_t)(t + 1) * kstep;
;             const char* a2 = last ? nA : cA + (size_t)(t + 2) * kstep;
;             const char* b2 = last ? nB : cB + (size_t)(t + 2) * kstep;
;             const char* a3 = a2 + kstep;
;             const char* b3 = b2 + kstep;
;             LDB(B0, 0, 0); SCHED; LDA(At, 0, 0); STAGE(SAo(1, 1), a1 + hstep);
;             WAIT_L(8); BAR; WAIT_L(0); MMA(0, 0, At, B0); BAR; SCHED;
;             LDB(B1, 0, 1); STAGE(SBo(0, 0), b2);
;             BAR; WAIT_L(0); MMA(0, 1, At, B1); BAR;
;             LDA(At, 0, 1); STAGE(SAo(0, 0), a2);
;             BAR; WAIT_L(0); MMA(1, 0, At, B0); BAR; SCHED;
;             STAGE(SBo(0, 1), b2 + hstep);
;             WAIT_V(6); BAR; MMA(1, 1, At, B1); BAR;
;             LDB(B0, 1, 0); SCHED; LDA(At, 1, 0); STAGE(SAo(0, 1), a2 + hstep);
;             WAIT_L(8); BAR; WAIT_L(0); MMA(0, 0, At, B0); BAR; SCHED;
;             LDB(B1, 1, 1); STAGE(SBo(1, 0), b3);
;             BAR; WAIT_L(0); MMA(0, 1, At, B1); BAR;
;             LDA(At, 1, 1); STAGE(SAo(1, 0), a3);
;             BAR; WAIT_L(0); MMA(1, 0, At, B0); BAR; SCHED;
;             STAGE(SBo(1, 1), b3 + hstep);
;             WAIT_V(6); BAR; MMA(1, 1, At, B1); BAR;
;         }
	v_mfma_f32_16x16x32_bf16 v[44:47], v[186:189], v[144:147], v[44:47]
	v_mfma_f32_16x16x32_bf16 v[12:15], v[194:197], v[144:147], v[12:15]
	v_mfma_f32_16x16x32_bf16 v[40:43], v[186:189], v[152:155], v[40:43]
	v_mfma_f32_16x16x32_bf16 v[8:11], v[194:197], v[152:155], v[8:11]
	v_mfma_f32_16x16x32_bf16 v[36:39], v[186:189], v[160:163], v[36:39]
	v_mfma_f32_16x16x32_bf16 v[4:7], v[194:197], v[160:163], v[4:7]
	v_mfma_f32_16x16x32_bf16 v[32:35], v[186:189], v[178:181], v[32:35]
	v_mfma_f32_16x16x32_bf16 v[0:3], v[194:197], v[178:181], v[0:3]
	v_mfma_f32_16x16x32_bf16 v[44:47], v[190:193], v[148:151], v[44:47]
	v_mfma_f32_16x16x32_bf16 v[12:15], v[208:211], v[148:151], v[12:15]
	v_mfma_f32_16x16x32_bf16 v[40:43], v[190:193], v[156:159], v[40:43]
	v_mfma_f32_16x16x32_bf16 v[8:11], v[208:211], v[156:159], v[8:11]
	v_mfma_f32_16x16x32_bf16 v[36:39], v[190:193], v[174:177], v[36:39]
	v_mfma_f32_16x16x32_bf16 v[4:7], v[208:211], v[174:177], v[4:7]
	v_mfma_f32_16x16x32_bf16 v[32:35], v[190:193], v[182:185], v[32:35]
	v_mfma_f32_16x16x32_bf16 v[0:3], v[208:211], v[182:185], v[0:3]
	s_barrier
	ds_read_b128 v[128:131], v201
	ds_read_b128 v[132:135], v201 offset:1024
	ds_read_b128 v[136:139], v201 offset:2048
	ds_read_b128 v[140:143], v201 offset:3072
	s_add_u32 s6, s12, 0x80000
	s_addc_u32 s7, s13, 0
	s_mov_b32 m0, s59
	v_lshl_add_u64 v[186:187], s[6:7], 0, v[164:165]
	ds_read_b128 v[144:147], v199 offset:32768
	ds_read_b128 v[148:151], v199 offset:33792
	ds_read_b128 v[152:155], v199 offset:34816
	ds_read_b128 v[156:159], v199 offset:35840
	ds_read_b128 v[160:163], v199 offset:36864
	ds_read_b128 v[174:177], v199 offset:37888
	ds_read_b128 v[178:181], v199 offset:38912
	ds_read_b128 v[182:185], v199 offset:39936
	global_load_lds_dwordx4 v[186:187], off
	v_lshl_add_u64 v[186:187], s[6:7], 0, v[166:167]
	s_mov_b32 m0, s60
	s_nop 0
	global_load_lds_dwordx4 v[186:187], off
	s_waitcnt lgkmcnt(8)
	s_barrier
	s_waitcnt lgkmcnt(0)
	v_mfma_f32_16x16x32_bf16 v[124:127], v[128:131], v[144:147], v[124:127]
	v_mfma_f32_16x16x32_bf16 v[92:95], v[136:139], v[144:147], v[92:95]
	v_mfma_f32_16x16x32_bf16 v[120:123], v[128:131], v[152:155], v[120:123]
	v_mfma_f32_16x16x32_bf16 v[88:91], v[136:139], v[152:155], v[88:91]
	v_mfma_f32_16x16x32_bf16 v[116:119], v[128:131], v[160:163], v[116:119]
	v_mfma_f32_16x16x32_bf16 v[84:87], v[136:139], v[160:163], v[84:87]
	v_mfma_f32_16x16x32_bf16 v[112:115], v[128:131], v[178:181], v[112:115]
	v_mfma_f32_16x16x32_bf16 v[80:83], v[136:139], v[178:181], v[80:83]
	v_mfma_f32_16x16x32_bf16 v[124:127], v[132:135], v[148:151], v[124:127]
	v_mfma_f32_16x16x32_bf16 v[92:95], v[140:143], v[148:151], v[92:95]
	v_mfma_f32_16x16x32_bf16 v[120:123], v[132:135], v[156:159], v[120:123]
	v_mfma_f32_16x16x32_bf16 v[88:91], v[140:143], v[156:159], v[88:91]
	v_mfma_f32_16x16x32_bf16 v[116:119], v[132:135], v[174:177], v[116:119]
	v_mfma_f32_16x16x32_bf16 v[84:87], v[140:143], v[174:177], v[84:87]
	v_mfma_f32_16x16x32_bf16 v[112:115], v[132:135], v[182:185], v[112:115]
	v_mfma_f32_16x16x32_bf16 v[80:83], v[140:143], v[182:185], v[80:83]
	s_barrier
	s_mov_b32 m0, s85
	v_lshl_add_u64 v[204:205], v[204:205], 0, s[0:1]
	ds_read_b128 v[186:189], v202
	ds_read_b128 v[190:193], v202 offset:1024
	ds_read_b128 v[194:197], v202 offset:2048
	ds_read_b128 v[208:211], v202 offset:3072
	global_load_lds_dwordx4 v[204:205], off
	v_lshl_add_u64 v[204:205], v[212:213], 0, s[0:1]
	s_mov_b32 m0, s96
	s_nop 0
	global_load_lds_dwordx4 v[204:205], off
	s_barrier
	s_waitcnt lgkmcnt(0)
	v_mfma_f32_16x16x32_bf16 v[60:63], v[186:189], v[144:147], v[60:63]
	v_mfma_f32_16x16x32_bf16 v[28:31], v[194:197], v[144:147], v[28:31]
	v_mfma_f32_16x16x32_bf16 v[56:59], v[186:189], v[152:155], v[56:59]
	v_mfma_f32_16x16x32_bf16 v[24:27], v[194:197], v[152:155], v[24:27]
	v_mfma_f32_16x16x32_bf16 v[52:55], v[186:189], v[160:163], v[52:55]
	v_mfma_f32_16x16x32_bf16 v[20:23], v[194:197], v[160:163], v[20:23]
	v_mfma_f32_16x16x32_bf16 v[48:51], v[186:189], v[178:181], v[48:51]
	v_mfma_f32_16x16x32_bf16 v[16:19], v[194:197], v[178:181], v[16:19]
	v_mfma_f32_16x16x32_bf16 v[60:63], v[190:193], v[148:151], v[60:63]
	v_mfma_f32_16x16x32_bf16 v[28:31], v[208:211], v[148:151], v[28:31]
	v_mfma_f32_16x16x32_bf16 v[56:59], v[190:193], v[156:159], v[56:59]
	v_mfma_f32_16x16x32_bf16 v[24:27], v[208:211], v[156:159], v[24:27]
	v_mfma_f32_16x16x32_bf16 v[52:55], v[190:193], v[174:177], v[52:55]
	v_mfma_f32_16x16x32_bf16 v[20:23], v[208:211], v[174:177], v[20:23]
	v_mfma_f32_16x16x32_bf16 v[48:51], v[190:193], v[182:185], v[48:51]
	v_mfma_f32_16x16x32_bf16 v[16:19], v[208:211], v[182:185], v[16:19]
	s_mov_b32 m0, s61
	v_lshl_add_u64 v[204:205], v[214:215], 0, s[0:1]
	s_barrier
	ds_read_b128 v[144:147], v199 offset:49152
	ds_read_b128 v[148:151], v199 offset:50176
	ds_read_b128 v[152:155], v199 offset:51200
	ds_read_b128 v[156:159], v199 offset:52224
	ds_read_b128 v[160:163], v199 offset:53248
	ds_read_b128 v[174:177], v199 offset:54272
	ds_read_b128 v[178:181], v199 offset:55296
	ds_read_b128 v[182:185], v199 offset:56320
	global_load_lds_dwordx4 v[204:205], off
	v_lshl_add_u64 v[204:205], v[216:217], 0, s[0:1]
	s_mov_b32 m0, s62
	s_nop 0
	global_load_lds_dwordx4 v[204:205], off
	s_barrier
; #define WAIT_V(n) asm volatile("s_waitcnt vmcnt(" #n ")" ::: "memory")
; #define WAIT_L(n) asm volatile("s_waitcnt lgkmcnt(" #n ")" ::: "memory")
; #define BAR __builtin_amdgcn_s_barrier()
; #define SCHED __builtin_amdgcn_sched_barrier(0)
; template <class Get, class Epi>
; DI void gemm_stream(LAS unsigned char* lds, const int K, const int ld, Get get, Epi epi) {
;     ...
;             BAR; WAIT_L(0); MMA(1, 0, At, B0); BAR; SCHED;
;             STAGE(SBo(1, 1), b3 + hstep);
;             WAIT_V(6); BAR; MMA(1, 1, At, B1); BAR;
;         }
; DI void epi_resid(const Acc& acc, const P& p, int brow, int bcol, int layer, int gch, bool from_input) {
;     EPI_IDX
;     const float* gate = modv(p, layer, brow, gch);
; #pragma unroll
;     for (int bj = 0; bj < 2; ++bj)
; #pragma unroll
;         for (int n = 0; n < 2; ++n) {
;             const int c0 = bcol + bj * 128 + wc * 32 + n * 16 + fq * 4;
;             const f32x4 g = *(const f32x4*)(gate + c0);
;             f32x4 xv[2][4];
; #pragma unroll
;             for (int ai = 0; ai < 2; ++ai)
; #pragma unroll
;                 for (int m = 0; m < 4; ++m) {
;                     const int r = brow + ai * 128 + wr * 64 + m * 16 + fr;
;                     const float* sp = (from_input ? inrow(p, r) : xrow(p, r)) + c0;
;                     xv[ai][m] = *(const f32x4*)sp;
	s_waitcnt lgkmcnt(0)
	v_mfma_f32_16x16x32_bf16 v[108:111], v[128:131], v[144:147], v[108:111]
	v_mfma_f32_16x16x32_bf16 v[76:79], v[136:139], v[144:147], v[76:79]
	v_mfma_f32_16x16x32_bf16 v[104:107], v[128:131], v[152:155], v[104:107]
	v_mfma_f32_16x16x32_bf16 v[72:75], v[136:139], v[152:155], v[72:75]
	v_mfma_f32_16x16x32_bf16 v[100:103], v[128:131], v[160:163], v[100:103]
	v_mfma_f32_16x16x32_bf16 v[68:71], v[136:139], v[160:163], v[68:71]
	v_mfma_f32_16x16x32_bf16 v[96:99], v[128:131], v[178:181], v[96:99]
	v_mfma_f32_16x16x32_bf16 v[64:67], v[136:139], v[178:181], v[64:67]
	v_mfma_f32_16x16x32_bf16 v[108:111], v[132:135], v[148:151], v[108:111]
	v_mfma_f32_16x16x32_bf16 v[76:79], v[140:143], v[148:151], v[76:79]
	v_mfma_f32_16x16x32_bf16 v[104:107], v[132:135], v[156:159], v[104:107]
	v_mfma_f32_16x16x32_bf16 v[72:75], v[140:143], v[156:159], v[72:75]
	v_mfma_f32_16x16x32_bf16 v[100:103], v[132:135], v[174:177], v[100:103]
	v_mfma_f32_16x16x32_bf16 v[68:71], v[140:143], v[174:177], v[68:71]
	v_mfma_f32_16x16x32_bf16 v[96:99], v[132:135], v[182:185], v[96:99]
	v_mfma_f32_16x16x32_bf16 v[64:67], v[140:143], v[182:185], v[64:67]
	s_barrier
	s_add_u32 s6, s10, 0x80080
	s_addc_u32 s7, s11, 0
	s_mov_b32 m0, s97
	v_lshl_add_u64 v[128:129], s[6:7], 0, v[164:165]
	global_load_lds_dwordx4 v[128:129], off
	v_lshl_add_u64 v[128:129], s[6:7], 0, v[166:167]
	s_add_i32 m0, s97, 0x2000
	s_nop 0
	global_load_lds_dwordx4 v[128:129], off
	s_waitcnt vmcnt(6)
	s_barrier
	v_mfma_f32_16x16x32_bf16 v[44:47], v[186:189], v[144:147], v[44:47]
	v_mfma_f32_16x16x32_bf16 v[12:15], v[194:197], v[144:147], v[12:15]
	v_mfma_f32_16x16x32_bf16 v[40:43], v[186:189], v[152:155], v[40:43]
	v_mfma_f32_16x16x32_bf16 v[8:11], v[194:197], v[152:155], v[8:11]
	v_mfma_f32_16x16x32_bf16 v[36:39], v[186:189], v[160:163], v[36:39]
	v_mfma_f32_16x16x32_bf16 v[4:7], v[194:197], v[160:163], v[4:7]
	v_mfma_f32_16x16x32_bf16 v[32:35], v[186:189], v[178:181], v[32:35]
	v_mfma_f32_16x16x32_bf16 v[0:3], v[194:197], v[178:181], v[0:3]
	v_mfma_f32_16x16x32_bf16 v[44:47], v[190:193], v[148:151], v[44:47]
	v_mfma_f32_16x16x32_bf16 v[12:15], v[208:211], v[148:151], v[12:15]
	v_mfma_f32_16x16x32_bf16 v[40:43], v[190:193], v[156:159], v[40:43]
	v_mfma_f32_16x16x32_bf16 v[8:11], v[208:211], v[156:159], v[8:11]
	v_mfma_f32_16x16x32_bf16 v[36:39], v[190:193], v[174:177], v[36:39]
	v_mfma_f32_16x16x32_bf16 v[4:7], v[208:211], v[174:177], v[4:7]
	v_mfma_f32_16x16x32_bf16 v[32:35], v[190:193], v[182:185], v[32:35]
	v_mfma_f32_16x16x32_bf16 v[0:3], v[208:211], v[182:185], v[0:3]
	s_add_i32 s18, s18, 2
	s_add_u32 s16, s16, 0x100
	s_addc_u32 s17, s17, 0
	s_cmp_gt_u32 s18, 29
	s_mov_b64 s[6:7], s[8:9]
	s_barrier
	s_cbranch_scc0 .LBB0_1238
	s_lshr_b32 s6, s15, 4
	s_lshl_b32 s7, s15, 8
	s_mulk_i32 s6, 0x1100
	s_and_b32 s7, s7, 0xf00
	s_add_i32 s6, s6, s7
	s_add_i32 s8, s6, 0x100
	s_mul_hi_i32 s6, s8, 0x78787879
	s_lshr_b32 s7, s6, 31
	s_ashr_i32 s6, s6, 11
	s_add_i32 s6, s6, s7
	s_mul_i32 s7, s6, 0xffffef00
	s_mul_i32 s6, s6, 6
	s_lshl_b32 s9, s14, 8
	s_add_i32 s7, s7, s8
	s_add_i32 s6, s6, 2
	s_cmpk_gt_i32 s7, 0xff
	v_mov_b32_e32 v132, v206
	s_cselect_b32 s6, s6, 26
	s_ashr_i32 s7, s6, 31
	v_lshrrev_b32_e32 v128, 1, v132
	v_lshrrev_b32_e32 v129, 2, v132
	s_lshl_b64 s[6:7], s[6:7], 13
	v_and_b32_e32 v128, 0x60, v128
	v_and_b32_e32 v129, 12, v129
	s_add_u32 s6, s26, s6
	v_or3_b32 v174, v128, s9, v129
	s_addc_u32 s7, s27, s7
	v_ashrrev_i32_e32 v175, 31, v174
	v_lshl_add_u64 v[192:193], v[174:175], 2, s[6:7]
	global_load_dwordx4 v[128:131], v[192:193], off
	v_ashrrev_i32_e32 v133, 2, v132
	v_and_b32_e32 v133, 0xffffffc0, v133
	v_and_or_b32 v132, v132, 15, s8
	v_add_u32_e32 v176, v132, v133
	v_mul_hi_i32 v132, v176, s76
	v_lshrrev_b32_e32 v133, 31, v132
	v_ashrrev_i32_e32 v132, 11, v132
	v_add_u32_e32 v203, v132, v133
	v_mad_i32_i24 v204, v203, s77, v176
	v_lshlrev_b32_e32 v211, 12, v203
	v_cmp_lt_i32_e64 s[18:19], s78, v204
	v_mov_b64_e32 v[132:133], s[56:57]
	v_add3_u32 v190, v211, v204, s79
	s_and_saveexec_b64 s[6:7], s[18:19]
	s_xor_b64 s[6:7], exec, s[6:7]
	v_add3_u32 v134, v211, v204, s79
	v_mov_b64_e32 v[132:133], s[52:53]
	s_or_saveexec_b64 s[6:7], s[6:7]
	v_lshl_add_u32 v191, v203, 8, v204
	s_xor_b64 exec, exec, s[6:7]
	v_lshl_add_u32 v134, v203, 8, v204
	s_or_b64 exec, exec, s[6:7]
	v_ashrrev_i32_e32 v135, 31, v134
	v_lshlrev_b64 v[134:135], 13, v[134:135]
	v_lshl_add_u64 v[132:133], v[132:133], 0, v[134:135]
	v_lshl_add_u64 v[132:133], v[174:175], 2, v[132:133]
	global_load_dwordx4 v[160:163], v[132:133], off
	v_or_b32_e32 v132, 16, v176
	v_mul_hi_i32 v133, v132, s76
	v_lshrrev_b32_e32 v134, 31, v133
	v_ashrrev_i32_e32 v133, 11, v133
	v_add_u32_e32 v205, v133, v134
	v_mad_i32_i24 v208, v205, s77, v132
	v_lshlrev_b32_e32 v216, 12, v205
	v_cmp_lt_i32_e64 s[16:17], s78, v208
	v_mov_b64_e32 v[132:133], s[56:57]
	v_add3_u32 v188, v216, v208, s79
	s_and_saveexec_b64 s[6:7], s[16:17]
	s_xor_b64 s[6:7], exec, s[6:7]
	v_add3_u32 v134, v216, v208, s79
	v_mov_b64_e32 v[132:133], s[52:53]
	s_or_saveexec_b64 s[6:7], s[6:7]
	v_lshl_add_u32 v189, v205, 8, v208
	s_xor_b64 exec, exec, s[6:7]
	v_lshl_add_u32 v134, v205, 8, v208
	s_or_b64 exec, exec, s[6:7]
	v_ashrrev_i32_e32 v135, 31, v134
	v_lshlrev_b64 v[134:135], 13, v[134:135]
	v_lshl_add_u64 v[132:133], v[132:133], 0, v[134:135]
	v_lshl_add_u64 v[132:133], v[174:175], 2, v[132:133]
	global_load_dwordx4 v[156:159], v[132:133], off
	v_or_b32_e32 v132, 32, v176
	v_mul_hi_i32 v133, v132, s76
	v_lshrrev_b32_e32 v134, 31, v133
	v_ashrrev_i32_e32 v133, 11, v133
	v_add_u32_e32 v209, v133, v134
	v_mad_i32_i24 v210, v209, s77, v132
	v_lshlrev_b32_e32 v219, 12, v209
; DI void epi_resid(const Acc& acc, const P& p, int brow, int bcol, int layer, int gch, bool from_input) {
;     ...
;             for (int ai = 0; ai < 2; ++ai)
; #pragma unroll
;                 for (int m = 0; m < 4; ++m) {
;                     const int r = brow + ai * 128 + wr * 64 + m * 16 + fr;
;                     const float* sp = (from_input ? inrow(p, r) : xrow(p, r)) + c0;
;                     xv[ai][m] = *(const f32x4*)sp;
;                 }
	v_cmp_lt_i32_e64 s[14:15], s78, v210
	v_mov_b64_e32 v[132:133], s[56:57]
	v_add3_u32 v186, v219, v210, s79
	s_and_saveexec_b64 s[6:7], s[14:15]
	s_xor_b64 s[6:7], exec, s[6:7]
	v_add3_u32 v134, v219, v210, s79
	v_mov_b64_e32 v[132:133], s[52:53]
	s_or_saveexec_b64 s[6:7], s[6:7]
	v_lshl_add_u32 v187, v209, 8, v210
	s_xor_b64 exec, exec, s[6:7]
	v_lshl_add_u32 v134, v209, 8, v210
	s_or_b64 exec, exec, s[6:7]
	v_ashrrev_i32_e32 v135, 31, v134
	v_lshlrev_b64 v[134:135], 13, v[134:135]
	v_lshl_add_u64 v[132:133], v[132:133], 0, v[134:135]
	v_lshl_add_u64 v[132:133], v[174:175], 2, v[132:133]
	global_load_dwordx4 v[152:155], v[132:133], off
	v_or_b32_e32 v132, 48, v176
	v_mul_hi_i32 v133, v132, s76
	v_lshrrev_b32_e32 v134, 31, v133
	v_ashrrev_i32_e32 v133, 11, v133
	v_add_u32_e32 v212, v133, v134
	v_mad_i32_i24 v213, v212, s77, v132
	v_lshlrev_b32_e32 v222, 12, v212
	v_cmp_lt_i32_e64 s[12:13], s78, v213
	v_mov_b64_e32 v[132:133], s[56:57]
	v_add3_u32 v184, v222, v213, s79
	s_and_saveexec_b64 s[6:7], s[12:13]
	s_xor_b64 s[6:7], exec, s[6:7]
	v_add3_u32 v134, v222, v213, s79
	v_mov_b64_e32 v[132:133], s[52:53]
	s_or_saveexec_b64 s[6:7], s[6:7]
	v_lshl_add_u32 v185, v212, 8, v213
	s_xor_b64 exec, exec, s[6:7]
	v_lshl_add_u32 v134, v212, 8, v213
	s_or_b64 exec, exec, s[6:7]
	v_ashrrev_i32_e32 v135, 31, v134
	v_lshlrev_b64 v[134:135], 13, v[134:135]
	v_lshl_add_u64 v[132:133], v[132:133], 0, v[134:135]
	v_lshl_add_u64 v[132:133], v[174:175], 2, v[132:133]
	global_load_dwordx4 v[148:151], v[132:133], off
	v_add_u32_e32 v132, 0x80, v176
	v_mul_hi_i32 v133, v132, s76
	v_lshrrev_b32_e32 v134, 31, v133
	v_ashrrev_i32_e32 v133, 11, v133
	v_add_u32_e32 v214, v133, v134
	v_mad_i32_i24 v215, v214, s77, v132
	v_lshlrev_b32_e32 v225, 12, v214
	v_cmp_lt_i32_e64 s[10:11], s78, v215
	v_mov_b64_e32 v[132:133], s[56:57]
	v_add3_u32 v182, v225, v215, s79
	s_and_saveexec_b64 s[6:7], s[10:11]
	s_xor_b64 s[6:7], exec, s[6:7]
	v_add3_u32 v134, v225, v215, s79
	v_mov_b64_e32 v[132:133], s[52:53]
	s_or_saveexec_b64 s[6:7], s[6:7]
	v_lshl_add_u32 v183, v214, 8, v215
	s_xor_b64 exec, exec, s[6:7]
	v_lshl_add_u32 v134, v214, 8, v215
	s_or_b64 exec, exec, s[6:7]
	v_ashrrev_i32_e32 v135, 31, v134
	v_lshlrev_b64 v[134:135], 13, v[134:135]
	v_lshl_add_u64 v[132:133], v[132:133], 0, v[134:135]
	v_lshl_add_u64 v[132:133], v[174:175], 2, v[132:133]
	global_load_dwordx4 v[144:147], v[132:133], off
	v_add_u32_e32 v132, 0x90, v176
	v_mul_hi_i32 v133, v132, s76
	v_lshrrev_b32_e32 v134, 31, v133
	v_ashrrev_i32_e32 v133, 11, v133
	v_add_u32_e32 v217, v133, v134
	v_mad_i32_i24 v218, v217, s77, v132
	v_lshlrev_b32_e32 v226, 12, v217
	v_cmp_lt_i32_e64 s[8:9], s78, v218
	v_mov_b64_e32 v[132:133], s[56:57]
	v_add3_u32 v180, v226, v218, s79
	s_and_saveexec_b64 s[6:7], s[8:9]
	s_xor_b64 s[6:7], exec, s[6:7]
	v_add3_u32 v134, v226, v218, s79
	v_mov_b64_e32 v[132:133], s[52:53]
	s_or_saveexec_b64 s[6:7], s[6:7]
	v_lshl_add_u32 v181, v217, 8, v218
	s_xor_b64 exec, exec, s[6:7]
	v_lshl_add_u32 v134, v217, 8, v218
	s_or_b64 exec, exec, s[6:7]
	v_ashrrev_i32_e32 v135, 31, v134
	v_lshlrev_b64 v[134:135], 13, v[134:135]
	v_lshl_add_u64 v[132:133], v[132:133], 0, v[134:135]
	v_lshl_add_u64 v[132:133], v[174:175], 2, v[132:133]
	global_load_dwordx4 v[140:143], v[132:133], off
	v_add_u32_e32 v132, 0xa0, v176
	v_mul_hi_i32 v133, v132, s76
	v_lshrrev_b32_e32 v134, 31, v133
	v_ashrrev_i32_e32 v133, 11, v133
	v_add_u32_e32 v220, v133, v134
	v_mad_i32_i24 v221, v220, s77, v132
	v_lshlrev_b32_e32 v227, 12, v220
	v_cmp_lt_i32_e64 s[6:7], s78, v221
	v_mov_b64_e32 v[132:133], s[56:57]
	v_add3_u32 v178, v227, v221, s79
	s_and_saveexec_b64 s[28:29], s[6:7]
	s_xor_b64 s[54:55], exec, s[28:29]
	v_add3_u32 v134, v227, v221, s79
	v_mov_b64_e32 v[132:133], s[52:53]
	s_or_saveexec_b64 s[54:55], s[54:55]
	v_lshl_add_u32 v179, v220, 8, v221
	s_xor_b64 exec, exec, s[54:55]
	v_lshl_add_u32 v134, v220, 8, v221
	s_or_b64 exec, exec, s[54:55]
	v_ashrrev_i32_e32 v135, 31, v134
	v_lshlrev_b64 v[134:135], 13, v[134:135]
	v_lshl_add_u64 v[132:133], v[132:133], 0, v[134:135]
	v_lshl_add_u64 v[132:133], v[174:175], 2, v[132:133]
	global_load_dwordx4 v[136:139], v[132:133], off
	v_add_u32_e32 v132, 0xb0, v176
	v_mul_hi_i32 v133, v132, s76
	v_lshrrev_b32_e32 v134, 31, v133
	v_ashrrev_i32_e32 v133, 11, v133
	v_add_u32_e32 v223, v133, v134
	v_mad_i32_i24 v224, v223, s77, v132
	v_lshlrev_b32_e32 v228, 12, v223
	v_cmp_lt_i32_e32 vcc, s78, v224
	v_mov_b64_e32 v[132:133], s[56:57]
	v_add3_u32 v176, v228, v224, s79
	s_and_saveexec_b64 s[28:29], vcc
	s_xor_b64 s[54:55], exec, s[28:29]
	v_add3_u32 v134, v228, v224, s79
	v_mov_b64_e32 v[132:133], s[52:53]
	s_or_saveexec_b64 s[54:55], s[54:55]
	v_lshl_add_u32 v177, v223, 8, v224
	s_xor_b64 exec, exec, s[54:55]
	v_lshl_add_u32 v134, v223, 8, v224
	s_or_b64 exec, exec, s[54:55]
	v_ashrrev_i32_e32 v135, 31, v134
	v_lshlrev_b64 v[134:135], 13, v[134:135]
	v_lshl_add_u64 v[132:133], v[132:133], 0, v[134:135]
	v_lshl_add_u64 v[132:133], v[174:175], 2, v[132:133]
	global_load_dwordx4 v[132:135], v[132:133], off
	s_and_saveexec_b64 s[28:29], s[18:19]
	s_xor_b64 s[54:55], exec, s[28:29]
	v_add3_u32 v194, v211, v204, s79
	s_or_saveexec_b64 s[54:55], s[54:55]
	v_mov_b64_e32 v[196:197], s[24:25]
	s_xor_b64 exec, exec, s[54:55]
	v_lshl_add_u32 v194, v203, 8, v204
	v_mov_b64_e32 v[196:197], s[36:37]
	s_or_b64 exec, exec, s[54:55]
	v_ashrrev_i32_e32 v195, 31, v194
	s_waitcnt vmcnt(0)
; DI void epi_resid(const Acc& acc, const P& p, int brow, int bcol, int layer, int gch, bool from_input) {
;     ...
;             const f32x4 g = *(const f32x4*)(gate + c0);
;             f32x4 xv[2][4];
; #pragma unroll
;             for (int ai = 0; ai < 2; ++ai)
; #pragma unroll
;                 for (int m = 0; m < 4; ++m) {
;                     const int r = brow + ai * 128 + wr * 64 + m * 16 + fr;
;                     const float* sp = (from_input ? inrow(p, r) : xrow(p, r)) + c0;
;                     xv[ai][m] = *(const f32x4*)sp;
;                 }
;             __builtin_amdgcn_sched_barrier(0);
; #pragma unroll
;             for (int ai = 0; ai < 2; ++ai)
; #pragma unroll
;                 for (int m = 0; m < 4; ++m) {
;                     const int r = brow + ai * 128 + wr * 64 + m * 16 + fr;
;                     *(f32x4*)(xrow(p, r) + c0) = xv[ai][m] + g * acc[ai][bj][m][n];
;                 }
;             __builtin_amdgcn_sched_barrier(0);
	v_pk_fma_f32 v[124:125], v[124:125], v[128:129], v[160:161]
	v_lshlrev_b64 v[160:161], 13, v[194:195]
	v_lshl_add_u64 v[160:161], v[196:197], 0, v[160:161]
	v_pk_fma_f32 v[126:127], v[126:127], v[130:131], v[162:163]
	v_lshl_add_u64 v[160:161], v[174:175], 2, v[160:161]
	global_store_dwordx4 v[160:161], v[124:127], off
	s_and_saveexec_b64 s[28:29], s[16:17]
	s_xor_b64 s[54:55], exec, s[28:29]
	v_add3_u32 v124, v216, v208, s79
	s_or_saveexec_b64 s[54:55], s[54:55]
	v_mov_b64_e32 v[126:127], s[24:25]
	s_xor_b64 exec, exec, s[54:55]
	v_lshl_add_u32 v124, v205, 8, v208
	v_mov_b64_e32 v[126:127], s[36:37]
	s_or_b64 exec, exec, s[54:55]
	v_ashrrev_i32_e32 v125, 31, v124
	v_lshlrev_b64 v[124:125], 13, v[124:125]
	v_lshl_add_u64 v[124:125], v[126:127], 0, v[124:125]
	v_pk_fma_f32 v[122:123], v[122:123], v[130:131], v[158:159]
	v_pk_fma_f32 v[120:121], v[120:121], v[128:129], v[156:157]
	v_lshl_add_u64 v[124:125], v[174:175], 2, v[124:125]
	global_store_dwordx4 v[124:125], v[120:123], off
	s_and_saveexec_b64 s[28:29], s[14:15]
	s_xor_b64 s[54:55], exec, s[28:29]
	v_add3_u32 v120, v219, v210, s79
	s_or_saveexec_b64 s[54:55], s[54:55]
	v_mov_b64_e32 v[122:123], s[24:25]
	s_xor_b64 exec, exec, s[54:55]
	v_lshl_add_u32 v120, v209, 8, v210
	v_mov_b64_e32 v[122:123], s[36:37]
	s_or_b64 exec, exec, s[54:55]
	v_ashrrev_i32_e32 v121, 31, v120
	v_lshlrev_b64 v[120:121], 13, v[120:121]
	v_lshl_add_u64 v[120:121], v[122:123], 0, v[120:121]
	v_pk_fma_f32 v[118:119], v[118:119], v[130:131], v[154:155]
	v_pk_fma_f32 v[116:117], v[116:117], v[128:129], v[152:153]
	v_lshl_add_u64 v[120:121], v[174:175], 2, v[120:121]
	global_store_dwordx4 v[120:121], v[116:119], off
	s_and_saveexec_b64 s[28:29], s[12:13]
	s_xor_b64 s[54:55], exec, s[28:29]
	v_add3_u32 v116, v222, v213, s79
	s_or_saveexec_b64 s[54:55], s[54:55]
	v_mov_b64_e32 v[118:119], s[24:25]
	s_xor_b64 exec, exec, s[54:55]
	v_lshl_add_u32 v116, v212, 8, v213
	v_mov_b64_e32 v[118:119], s[36:37]
	s_or_b64 exec, exec, s[54:55]
	v_ashrrev_i32_e32 v117, 31, v116
	v_lshlrev_b64 v[116:117], 13, v[116:117]
	v_lshl_add_u64 v[116:117], v[118:119], 0, v[116:117]
	v_pk_fma_f32 v[114:115], v[114:115], v[130:131], v[150:151]
	v_pk_fma_f32 v[112:113], v[112:113], v[128:129], v[148:149]
	v_lshl_add_u64 v[116:117], v[174:175], 2, v[116:117]
	global_store_dwordx4 v[116:117], v[112:115], off
	s_and_saveexec_b64 s[28:29], s[10:11]
	s_xor_b64 s[54:55], exec, s[28:29]
	v_add3_u32 v112, v225, v215, s79
	s_or_saveexec_b64 s[54:55], s[54:55]
	v_mov_b64_e32 v[114:115], s[24:25]
	s_xor_b64 exec, exec, s[54:55]
	v_lshl_add_u32 v112, v214, 8, v215
	v_mov_b64_e32 v[114:115], s[36:37]
	s_or_b64 exec, exec, s[54:55]
	v_ashrrev_i32_e32 v113, 31, v112
	v_lshlrev_b64 v[112:113], 13, v[112:113]
	v_lshl_add_u64 v[112:113], v[114:115], 0, v[112:113]
	v_pk_fma_f32 v[110:111], v[110:111], v[130:131], v[146:147]
	v_pk_fma_f32 v[108:109], v[108:109], v[128:129], v[144:145]
	v_lshl_add_u64 v[112:113], v[174:175], 2, v[112:113]
	global_store_dwordx4 v[112:113], v[108:111], off
	s_and_saveexec_b64 s[28:29], s[8:9]
	s_xor_b64 s[54:55], exec, s[28:29]
	v_add3_u32 v108, v226, v218, s79
	s_or_saveexec_b64 s[54:55], s[54:55]
	v_mov_b64_e32 v[110:111], s[24:25]
	s_xor_b64 exec, exec, s[54:55]
	v_lshl_add_u32 v108, v217, 8, v218
	v_mov_b64_e32 v[110:111], s[36:37]
	s_or_b64 exec, exec, s[54:55]
	v_ashrrev_i32_e32 v109, 31, v108
	v_lshlrev_b64 v[108:109], 13, v[108:109]
	v_lshl_add_u64 v[108:109], v[110:111], 0, v[108:109]
	v_pk_fma_f32 v[106:107], v[106:107], v[130:131], v[142:143]
	v_pk_fma_f32 v[104:105], v[104:105], v[128:129], v[140:141]
	v_lshl_add_u64 v[108:109], v[174:175], 2, v[108:109]
	global_store_dwordx4 v[108:109], v[104:107], off
	s_and_saveexec_b64 s[28:29], s[6:7]
	s_xor_b64 s[54:55], exec, s[28:29]
	v_add3_u32 v104, v227, v221, s79
	s_or_saveexec_b64 s[54:55], s[54:55]
	v_mov_b64_e32 v[106:107], s[24:25]
	s_xor_b64 exec, exec, s[54:55]
	v_lshl_add_u32 v104, v220, 8, v221
	v_mov_b64_e32 v[106:107], s[36:37]
	s_or_b64 exec, exec, s[54:55]
	v_ashrrev_i32_e32 v105, 31, v104
	v_lshlrev_b64 v[104:105], 13, v[104:105]
	v_lshl_add_u64 v[104:105], v[106:107], 0, v[104:105]
	v_pk_fma_f32 v[102:103], v[102:103], v[130:131], v[138:139]
	v_pk_fma_f32 v[100:101], v[100:101], v[128:129], v[136:137]
	v_lshl_add_u64 v[104:105], v[174:175], 2, v[104:105]
	global_store_dwordx4 v[104:105], v[100:103], off
	s_and_saveexec_b64 s[28:29], vcc
	s_xor_b64 s[54:55], exec, s[28:29]
	v_add3_u32 v100, v228, v224, s79
	s_or_saveexec_b64 s[54:55], s[54:55]
	v_mov_b64_e32 v[102:103], s[24:25]
	s_xor_b64 exec, exec, s[54:55]
	v_lshl_add_u32 v100, v223, 8, v224
	v_mov_b64_e32 v[102:103], s[36:37]
	s_or_b64 exec, exec, s[54:55]
	v_ashrrev_i32_e32 v101, 31, v100
	v_lshlrev_b64 v[100:101], 13, v[100:101]
	v_lshl_add_u64 v[100:101], v[102:103], 0, v[100:101]
	v_pk_fma_f32 v[98:99], v[98:99], v[130:131], v[134:135]
	v_pk_fma_f32 v[96:97], v[96:97], v[128:129], v[132:133]
	v_lshl_add_u64 v[100:101], v[174:175], 2, v[100:101]
	global_store_dwordx4 v[100:101], v[96:99], off
	global_load_dwordx4 v[96:99], v[192:193], off offset:64
	v_mov_b64_e32 v[100:101], s[56:57]
	s_and_saveexec_b64 s[28:29], s[18:19]
	s_xor_b64 s[54:55], exec, s[28:29]
	v_add3_u32 v102, v211, v204, s79
	v_mov_b64_e32 v[100:101], s[52:53]
	s_andn2_saveexec_b64 s[54:55], s[54:55]
	v_lshl_add_u32 v102, v203, 8, v204
	s_or_b64 exec, exec, s[54:55]
	v_ashrrev_i32_e32 v103, 31, v102
	v_lshlrev_b64 v[102:103], 13, v[102:103]
	v_lshl_add_u64 v[100:101], v[100:101], 0, v[102:103]
	v_lshl_add_u64 v[100:101], v[174:175], 2, v[100:101]
	global_load_dwordx4 v[128:131], v[100:101], off offset:64
	v_mov_b64_e32 v[100:101], s[56:57]
; DI void epi_resid(const Acc& acc, const P& p, int brow, int bcol, int layer, int gch, bool from_input) {
;     ...
;             const f32x4 g = *(const f32x4*)(gate + c0);
;             f32x4 xv[2][4];
; #pragma unroll
;             for (int ai = 0; ai < 2; ++ai)
; #pragma unroll
;                 for (int m = 0; m < 4; ++m) {
;                     const int r = brow + ai * 128 + wr * 64 + m * 16 + fr;
;                     const float* sp = (from_input ? inrow(p, r) : xrow(p, r)) + c0;
;                     xv[ai][m] = *(const f32x4*)sp;
;                 }
;             __builtin_amdgcn_sched_barrier(0);
; #pragma unroll
;             for (int ai = 0; ai < 2; ++ai)
; #pragma unroll
;                 for (int m = 0; m < 4; ++m) {
;                     const int r = brow + ai * 128 + wr * 64 + m * 16 + fr;
;                     *(f32x4*)(xrow(p, r) + c0) = xv[ai][m] + g * acc[ai][bj][m][n];
;                 }
;             __builtin_amdgcn_sched_barrier(0);
	s_and_saveexec_b64 s[28:29], s[16:17]
	s_xor_b64 s[54:55], exec, s[28:29]
	v_add3_u32 v102, v216, v208, s79
	v_mov_b64_e32 v[100:101], s[52:53]
	s_andn2_saveexec_b64 s[54:55], s[54:55]
	v_lshl_add_u32 v102, v205, 8, v208
	s_or_b64 exec, exec, s[54:55]
	v_ashrrev_i32_e32 v103, 31, v102
	v_lshlrev_b64 v[102:103], 13, v[102:103]
	v_lshl_add_u64 v[100:101], v[100:101], 0, v[102:103]
	v_lshl_add_u64 v[100:101], v[174:175], 2, v[100:101]
	global_load_dwordx4 v[124:127], v[100:101], off offset:64
	v_mov_b64_e32 v[100:101], s[56:57]
	s_and_saveexec_b64 s[28:29], s[14:15]
	s_xor_b64 s[54:55], exec, s[28:29]
	v_add3_u32 v102, v219, v210, s79
	v_mov_b64_e32 v[100:101], s[52:53]
	s_andn2_saveexec_b64 s[54:55], s[54:55]
	v_lshl_add_u32 v102, v209, 8, v210
	s_or_b64 exec, exec, s[54:55]
	v_ashrrev_i32_e32 v103, 31, v102
	v_lshlrev_b64 v[102:103], 13, v[102:103]
	v_lshl_add_u64 v[100:101], v[100:101], 0, v[102:103]
	v_lshl_add_u64 v[100:101], v[174:175], 2, v[100:101]
	global_load_dwordx4 v[120:123], v[100:101], off offset:64
	v_mov_b64_e32 v[100:101], s[56:57]
	s_and_saveexec_b64 s[28:29], s[12:13]
	s_xor_b64 s[54:55], exec, s[28:29]
	v_add3_u32 v102, v222, v213, s79
	v_mov_b64_e32 v[100:101], s[52:53]
	s_andn2_saveexec_b64 s[54:55], s[54:55]
	v_lshl_add_u32 v102, v212, 8, v213
	s_or_b64 exec, exec, s[54:55]
	v_ashrrev_i32_e32 v103, 31, v102
	v_lshlrev_b64 v[102:103], 13, v[102:103]
	v_lshl_add_u64 v[100:101], v[100:101], 0, v[102:103]
	v_lshl_add_u64 v[100:101], v[174:175], 2, v[100:101]
	global_load_dwordx4 v[116:119], v[100:101], off offset:64
	v_mov_b64_e32 v[100:101], s[56:57]
	s_and_saveexec_b64 s[28:29], s[10:11]
	s_xor_b64 s[54:55], exec, s[28:29]
	v_add3_u32 v102, v225, v215, s79
	v_mov_b64_e32 v[100:101], s[52:53]
	s_andn2_saveexec_b64 s[54:55], s[54:55]
	v_lshl_add_u32 v102, v214, 8, v215
	s_or_b64 exec, exec, s[54:55]
	v_ashrrev_i32_e32 v103, 31, v102
	v_lshlrev_b64 v[102:103], 13, v[102:103]
	v_lshl_add_u64 v[100:101], v[100:101], 0, v[102:103]
	v_lshl_add_u64 v[100:101], v[174:175], 2, v[100:101]
	global_load_dwordx4 v[112:115], v[100:101], off offset:64
	v_mov_b64_e32 v[100:101], s[56:57]
	s_and_saveexec_b64 s[28:29], s[8:9]
	s_xor_b64 s[54:55], exec, s[28:29]
	v_add3_u32 v102, v226, v218, s79
	v_mov_b64_e32 v[100:101], s[52:53]
	s_andn2_saveexec_b64 s[54:55], s[54:55]
	v_lshl_add_u32 v102, v217, 8, v218
	s_or_b64 exec, exec, s[54:55]
	v_ashrrev_i32_e32 v103, 31, v102
	v_lshlrev_b64 v[102:103], 13, v[102:103]
	v_lshl_add_u64 v[100:101], v[100:101], 0, v[102:103]
	v_lshl_add_u64 v[100:101], v[174:175], 2, v[100:101]
	global_load_dwordx4 v[108:111], v[100:101], off offset:64
	v_mov_b64_e32 v[100:101], s[56:57]
	s_and_saveexec_b64 s[28:29], s[6:7]
	s_xor_b64 s[54:55], exec, s[28:29]
	v_add3_u32 v102, v227, v221, s79
	v_mov_b64_e32 v[100:101], s[52:53]
	s_andn2_saveexec_b64 s[54:55], s[54:55]
	v_lshl_add_u32 v102, v220, 8, v221
	s_or_b64 exec, exec, s[54:55]
	v_ashrrev_i32_e32 v103, 31, v102
	v_lshlrev_b64 v[102:103], 13, v[102:103]
	v_lshl_add_u64 v[100:101], v[100:101], 0, v[102:103]
	v_lshl_add_u64 v[100:101], v[174:175], 2, v[100:101]
	global_load_dwordx4 v[104:107], v[100:101], off offset:64
	v_mov_b64_e32 v[100:101], s[56:57]
	s_and_saveexec_b64 s[28:29], vcc
	s_xor_b64 s[54:55], exec, s[28:29]
	v_add3_u32 v102, v228, v224, s79
	v_mov_b64_e32 v[100:101], s[52:53]
	s_andn2_saveexec_b64 s[54:55], s[54:55]
	v_lshl_add_u32 v102, v223, 8, v224
	s_or_b64 exec, exec, s[54:55]
	v_ashrrev_i32_e32 v103, 31, v102
	v_lshlrev_b64 v[102:103], 13, v[102:103]
	v_lshl_add_u64 v[100:101], v[100:101], 0, v[102:103]
	v_lshl_add_u64 v[100:101], v[174:175], 2, v[100:101]
	global_load_dwordx4 v[100:103], v[100:101], off offset:64
	s_and_saveexec_b64 s[28:29], s[18:19]
	s_xor_b64 s[54:55], exec, s[28:29]
	v_add3_u32 v132, v211, v204, s79
	s_or_saveexec_b64 s[54:55], s[54:55]
	v_mov_b64_e32 v[134:135], s[24:25]
	s_xor_b64 exec, exec, s[54:55]
	v_lshl_add_u32 v132, v203, 8, v204
	v_mov_b64_e32 v[134:135], s[36:37]
	s_or_b64 exec, exec, s[54:55]
	v_ashrrev_i32_e32 v133, 31, v132
	s_waitcnt vmcnt(0)
	v_pk_fma_f32 v[92:93], v[92:93], v[96:97], v[128:129]
	v_lshlrev_b64 v[128:129], 13, v[132:133]
	v_lshl_add_u64 v[128:129], v[134:135], 0, v[128:129]
	v_pk_fma_f32 v[94:95], v[94:95], v[98:99], v[130:131]
	v_lshl_add_u64 v[128:129], v[174:175], 2, v[128:129]
	global_store_dwordx4 v[128:129], v[92:95], off offset:64
	s_and_saveexec_b64 s[28:29], s[16:17]
	s_xor_b64 s[54:55], exec, s[28:29]
	v_add3_u32 v92, v216, v208, s79
	s_or_saveexec_b64 s[54:55], s[54:55]
	v_mov_b64_e32 v[94:95], s[24:25]
	s_xor_b64 exec, exec, s[54:55]
	v_lshl_add_u32 v92, v205, 8, v208
	v_mov_b64_e32 v[94:95], s[36:37]
	s_or_b64 exec, exec, s[54:55]
	v_ashrrev_i32_e32 v93, 31, v92
	v_lshlrev_b64 v[92:93], 13, v[92:93]
	v_lshl_add_u64 v[92:93], v[94:95], 0, v[92:93]
	v_pk_fma_f32 v[90:91], v[90:91], v[98:99], v[126:127]
	v_pk_fma_f32 v[88:89], v[88:89], v[96:97], v[124:125]
	v_lshl_add_u64 v[92:93], v[174:175], 2, v[92:93]
	global_store_dwordx4 v[92:93], v[88:91], off offset:64
	s_and_saveexec_b64 s[28:29], s[14:15]
	s_xor_b64 s[54:55], exec, s[28:29]
	v_add3_u32 v88, v219, v210, s79
	s_or_saveexec_b64 s[54:55], s[54:55]
	v_mov_b64_e32 v[90:91], s[24:25]
	s_xor_b64 exec, exec, s[54:55]
	v_lshl_add_u32 v88, v209, 8, v210
	v_mov_b64_e32 v[90:91], s[36:37]
	s_or_b64 exec, exec, s[54:55]
	v_ashrrev_i32_e32 v89, 31, v88
	v_lshlrev_b64 v[88:89], 13, v[88:89]
	v_lshl_add_u64 v[88:89], v[90:91], 0, v[88:89]
	v_pk_fma_f32 v[86:87], v[86:87], v[98:99], v[122:123]
	v_pk_fma_f32 v[84:85], v[84:85], v[96:97], v[120:121]
	v_lshl_add_u64 v[88:89], v[174:175], 2, v[88:89]
	global_store_dwordx4 v[88:89], v[84:87], off offset:64
; DI void epi_resid(const Acc& acc, const P& p, int brow, int bcol, int layer, int gch, bool from_input) {
;     ...
;             const f32x4 g = *(const f32x4*)(gate + c0);
;             f32x4 xv[2][4];
; #pragma unroll
;             for (int ai = 0; ai < 2; ++ai)
; #pragma unroll
;                 for (int m = 0; m < 4; ++m) {
;                     const int r = brow + ai * 128 + wr * 64 + m * 16 + fr;
;                     const float* sp = (from_input ? inrow(p, r) : xrow(p, r)) + c0;
;                     xv[ai][m] = *(const f32x4*)sp;
;                 }
;             __builtin_amdgcn_sched_barrier(0);
; #pragma unroll
;             for (int ai = 0; ai < 2; ++ai)
; #pragma unroll
;                 for (int m = 0; m < 4; ++m) {
;                     const int r = brow + ai * 128 + wr * 64 + m * 16 + fr;
;                     *(f32x4*)(xrow(p, r) + c0) = xv[ai][m] + g * acc[ai][bj][m][n];
;                 }
;             __builtin_amdgcn_sched_barrier(0);
	s_and_saveexec_b64 s[28:29], s[12:13]
	s_xor_b64 s[54:55], exec, s[28:29]
	v_add3_u32 v84, v222, v213, s79
	s_or_saveexec_b64 s[54:55], s[54:55]
	v_mov_b64_e32 v[86:87], s[24:25]
	s_xor_b64 exec, exec, s[54:55]
	v_lshl_add_u32 v84, v212, 8, v213
	v_mov_b64_e32 v[86:87], s[36:37]
	s_or_b64 exec, exec, s[54:55]
	v_ashrrev_i32_e32 v85, 31, v84
	v_lshlrev_b64 v[84:85], 13, v[84:85]
	v_lshl_add_u64 v[84:85], v[86:87], 0, v[84:85]
	v_pk_fma_f32 v[82:83], v[82:83], v[98:99], v[118:119]
	v_pk_fma_f32 v[80:81], v[80:81], v[96:97], v[116:117]
	v_lshl_add_u64 v[84:85], v[174:175], 2, v[84:85]
	global_store_dwordx4 v[84:85], v[80:83], off offset:64
	s_and_saveexec_b64 s[28:29], s[10:11]
	s_xor_b64 s[54:55], exec, s[28:29]
	v_add3_u32 v80, v225, v215, s79
	s_or_saveexec_b64 s[54:55], s[54:55]
	v_mov_b64_e32 v[82:83], s[24:25]
	s_xor_b64 exec, exec, s[54:55]
	v_lshl_add_u32 v80, v214, 8, v215
	v_mov_b64_e32 v[82:83], s[36:37]
	s_or_b64 exec, exec, s[54:55]
	v_ashrrev_i32_e32 v81, 31, v80
	v_lshlrev_b64 v[80:81], 13, v[80:81]
	v_lshl_add_u64 v[80:81], v[82:83], 0, v[80:81]
	v_pk_fma_f32 v[78:79], v[78:79], v[98:99], v[114:115]
	v_pk_fma_f32 v[76:77], v[76:77], v[96:97], v[112:113]
	v_lshl_add_u64 v[80:81], v[174:175], 2, v[80:81]
	global_store_dwordx4 v[80:81], v[76:79], off offset:64
	s_and_saveexec_b64 s[28:29], s[8:9]
	s_xor_b64 s[54:55], exec, s[28:29]
	v_add3_u32 v76, v226, v218, s79
	s_or_saveexec_b64 s[54:55], s[54:55]
	v_mov_b64_e32 v[78:79], s[24:25]
	s_xor_b64 exec, exec, s[54:55]
	v_lshl_add_u32 v76, v217, 8, v218
	v_mov_b64_e32 v[78:79], s[36:37]
	s_or_b64 exec, exec, s[54:55]
	v_ashrrev_i32_e32 v77, 31, v76
	v_lshlrev_b64 v[76:77], 13, v[76:77]
	v_lshl_add_u64 v[76:77], v[78:79], 0, v[76:77]
	v_pk_fma_f32 v[74:75], v[74:75], v[98:99], v[110:111]
	v_pk_fma_f32 v[72:73], v[72:73], v[96:97], v[108:109]
	v_lshl_add_u64 v[76:77], v[174:175], 2, v[76:77]
	global_store_dwordx4 v[76:77], v[72:75], off offset:64
	s_and_saveexec_b64 s[28:29], s[6:7]
	s_xor_b64 s[54:55], exec, s[28:29]
	v_add3_u32 v72, v227, v221, s79
	s_or_saveexec_b64 s[54:55], s[54:55]
	v_mov_b64_e32 v[74:75], s[24:25]
	s_xor_b64 exec, exec, s[54:55]
	v_lshl_add_u32 v72, v220, 8, v221
	v_mov_b64_e32 v[74:75], s[36:37]
	s_or_b64 exec, exec, s[54:55]
	v_ashrrev_i32_e32 v73, 31, v72
	v_lshlrev_b64 v[72:73], 13, v[72:73]
	v_lshl_add_u64 v[72:73], v[74:75], 0, v[72:73]
	v_pk_fma_f32 v[70:71], v[70:71], v[98:99], v[106:107]
	v_pk_fma_f32 v[68:69], v[68:69], v[96:97], v[104:105]
	v_lshl_add_u64 v[72:73], v[174:175], 2, v[72:73]
	global_store_dwordx4 v[72:73], v[68:71], off offset:64
	s_and_saveexec_b64 s[28:29], vcc
	s_xor_b64 s[54:55], exec, s[28:29]
	v_add3_u32 v68, v228, v224, s79
	s_or_saveexec_b64 s[54:55], s[54:55]
	v_mov_b64_e32 v[70:71], s[24:25]
	s_xor_b64 exec, exec, s[54:55]
	v_lshl_add_u32 v68, v223, 8, v224
	v_mov_b64_e32 v[70:71], s[36:37]
	s_or_b64 exec, exec, s[54:55]
	v_ashrrev_i32_e32 v69, 31, v68
	v_lshlrev_b64 v[68:69], 13, v[68:69]
	v_lshl_add_u64 v[68:69], v[70:71], 0, v[68:69]
	v_pk_fma_f32 v[66:67], v[66:67], v[98:99], v[102:103]
	v_pk_fma_f32 v[64:65], v[64:65], v[96:97], v[100:101]
	v_lshl_add_u64 v[68:69], v[174:175], 2, v[68:69]
	global_store_dwordx4 v[68:69], v[64:67], off offset:64
	global_load_dwordx4 v[64:67], v[192:193], off offset:512
	v_mov_b64_e32 v[68:69], s[56:57]
	s_and_saveexec_b64 s[28:29], s[18:19]
	s_xor_b64 s[54:55], exec, s[28:29]
	v_add3_u32 v70, v211, v204, s79
	v_mov_b64_e32 v[68:69], s[52:53]
	s_andn2_saveexec_b64 s[54:55], s[54:55]
	v_lshl_add_u32 v70, v203, 8, v204
	s_or_b64 exec, exec, s[54:55]
	v_ashrrev_i32_e32 v71, 31, v70
	v_lshlrev_b64 v[70:71], 13, v[70:71]
	v_lshl_add_u64 v[68:69], v[68:69], 0, v[70:71]
	v_lshl_add_u64 v[68:69], v[174:175], 2, v[68:69]
	global_load_dwordx4 v[96:99], v[68:69], off offset:512
	v_mov_b64_e32 v[68:69], s[56:57]
	s_and_saveexec_b64 s[28:29], s[16:17]
	s_xor_b64 s[54:55], exec, s[28:29]
	v_add3_u32 v70, v216, v208, s79
	v_mov_b64_e32 v[68:69], s[52:53]
	s_andn2_saveexec_b64 s[54:55], s[54:55]
	v_lshl_add_u32 v70, v205, 8, v208
	s_or_b64 exec, exec, s[54:55]
	v_ashrrev_i32_e32 v71, 31, v70
	v_lshlrev_b64 v[70:71], 13, v[70:71]
	v_lshl_add_u64 v[68:69], v[68:69], 0, v[70:71]
	v_lshl_add_u64 v[68:69], v[174:175], 2, v[68:69]
	global_load_dwordx4 v[92:95], v[68:69], off offset:512
	v_mov_b64_e32 v[68:69], s[56:57]
	s_and_saveexec_b64 s[28:29], s[14:15]
	s_xor_b64 s[54:55], exec, s[28:29]
	v_add3_u32 v70, v219, v210, s79
	v_mov_b64_e32 v[68:69], s[52:53]
	s_andn2_saveexec_b64 s[54:55], s[54:55]
	v_lshl_add_u32 v70, v209, 8, v210
	s_or_b64 exec, exec, s[54:55]
	v_ashrrev_i32_e32 v71, 31, v70
	v_lshlrev_b64 v[70:71], 13, v[70:71]
	v_lshl_add_u64 v[68:69], v[68:69], 0, v[70:71]
	v_lshl_add_u64 v[68:69], v[174:175], 2, v[68:69]
	global_load_dwordx4 v[88:91], v[68:69], off offset:512
	v_mov_b64_e32 v[68:69], s[56:57]
	s_and_saveexec_b64 s[28:29], s[12:13]
	s_xor_b64 s[54:55], exec, s[28:29]
	v_add3_u32 v70, v222, v213, s79
	v_mov_b64_e32 v[68:69], s[52:53]
	s_andn2_saveexec_b64 s[54:55], s[54:55]
	v_lshl_add_u32 v70, v212, 8, v213
	s_or_b64 exec, exec, s[54:55]
	v_ashrrev_i32_e32 v71, 31, v70
	v_lshlrev_b64 v[70:71], 13, v[70:71]
	v_lshl_add_u64 v[68:69], v[68:69], 0, v[70:71]
	v_lshl_add_u64 v[68:69], v[174:175], 2, v[68:69]
	global_load_dwordx4 v[84:87], v[68:69], off offset:512
	v_mov_b64_e32 v[68:69], s[56:57]
	s_and_saveexec_b64 s[28:29], s[10:11]
	s_xor_b64 s[54:55], exec, s[28:29]
	v_add3_u32 v70, v225, v215, s79
	v_mov_b64_e32 v[68:69], s[52:53]
	s_andn2_saveexec_b64 s[54:55], s[54:55]
	v_lshl_add_u32 v70, v214, 8, v215
	s_or_b64 exec, exec, s[54:55]
	v_ashrrev_i32_e32 v71, 31, v70
; DI void epi_resid(const Acc& acc, const P& p, int brow, int bcol, int layer, int gch, bool from_input) {
;     ...
;             const f32x4 g = *(const f32x4*)(gate + c0);
;             f32x4 xv[2][4];
; #pragma unroll
;             for (int ai = 0; ai < 2; ++ai)
; #pragma unroll
;                 for (int m = 0; m < 4; ++m) {
;                     const int r = brow + ai * 128 + wr * 64 + m * 16 + fr;
;                     const float* sp = (from_input ? inrow(p, r) : xrow(p, r)) + c0;
;                     xv[ai][m] = *(const f32x4*)sp;
;                 }
;             __builtin_amdgcn_sched_barrier(0);
; #pragma unroll
;             for (int ai = 0; ai < 2; ++ai)
; #pragma unroll
;                 for (int m = 0; m < 4; ++m) {
;                     const int r = brow + ai * 128 + wr * 64 + m * 16 + fr;
;                     *(f32x4*)(xrow(p, r) + c0) = xv[ai][m] + g * acc[ai][bj][m][n];
;                 }
;             __builtin_amdgcn_sched_barrier(0);
	v_lshlrev_b64 v[70:71], 13, v[70:71]
	v_lshl_add_u64 v[68:69], v[68:69], 0, v[70:71]
	v_lshl_add_u64 v[68:69], v[174:175], 2, v[68:69]
	global_load_dwordx4 v[80:83], v[68:69], off offset:512
	v_mov_b64_e32 v[68:69], s[56:57]
	s_and_saveexec_b64 s[28:29], s[8:9]
	s_xor_b64 s[54:55], exec, s[28:29]
	v_add3_u32 v70, v226, v218, s79
	v_mov_b64_e32 v[68:69], s[52:53]
	s_andn2_saveexec_b64 s[54:55], s[54:55]
	v_lshl_add_u32 v70, v217, 8, v218
	s_or_b64 exec, exec, s[54:55]
	v_ashrrev_i32_e32 v71, 31, v70
	v_lshlrev_b64 v[70:71], 13, v[70:71]
	v_lshl_add_u64 v[68:69], v[68:69], 0, v[70:71]
	v_lshl_add_u64 v[68:69], v[174:175], 2, v[68:69]
	global_load_dwordx4 v[76:79], v[68:69], off offset:512
	v_mov_b64_e32 v[68:69], s[56:57]
	s_and_saveexec_b64 s[28:29], s[6:7]
	s_xor_b64 s[54:55], exec, s[28:29]
	v_add3_u32 v70, v227, v221, s79
	v_mov_b64_e32 v[68:69], s[52:53]
	s_andn2_saveexec_b64 s[54:55], s[54:55]
	v_lshl_add_u32 v70, v220, 8, v221
	s_or_b64 exec, exec, s[54:55]
	v_ashrrev_i32_e32 v71, 31, v70
	v_lshlrev_b64 v[70:71], 13, v[70:71]
	v_lshl_add_u64 v[68:69], v[68:69], 0, v[70:71]
	v_lshl_add_u64 v[68:69], v[174:175], 2, v[68:69]
	global_load_dwordx4 v[72:75], v[68:69], off offset:512
	v_mov_b64_e32 v[68:69], s[56:57]
	s_and_saveexec_b64 s[28:29], vcc
	s_xor_b64 s[54:55], exec, s[28:29]
	v_add3_u32 v70, v228, v224, s79
	v_mov_b64_e32 v[68:69], s[52:53]
	s_andn2_saveexec_b64 s[54:55], s[54:55]
	v_lshl_add_u32 v70, v223, 8, v224
	s_or_b64 exec, exec, s[54:55]
	v_ashrrev_i32_e32 v71, 31, v70
	v_lshlrev_b64 v[70:71], 13, v[70:71]
	v_lshl_add_u64 v[68:69], v[68:69], 0, v[70:71]
	v_lshl_add_u64 v[68:69], v[174:175], 2, v[68:69]
	global_load_dwordx4 v[68:71], v[68:69], off offset:512
	s_and_saveexec_b64 s[28:29], s[18:19]
	s_xor_b64 s[54:55], exec, s[28:29]
	v_add3_u32 v100, v211, v204, s79
	s_or_saveexec_b64 s[54:55], s[54:55]
	v_mov_b64_e32 v[102:103], s[24:25]
	s_xor_b64 exec, exec, s[54:55]
	v_lshl_add_u32 v100, v203, 8, v204
	v_mov_b64_e32 v[102:103], s[36:37]
	s_or_b64 exec, exec, s[54:55]
	v_ashrrev_i32_e32 v101, 31, v100
	s_waitcnt vmcnt(0)
	v_pk_fma_f32 v[60:61], v[60:61], v[64:65], v[96:97]
	v_lshlrev_b64 v[96:97], 13, v[100:101]
	v_lshl_add_u64 v[96:97], v[102:103], 0, v[96:97]
	v_pk_fma_f32 v[62:63], v[62:63], v[66:67], v[98:99]
	v_lshl_add_u64 v[96:97], v[174:175], 2, v[96:97]
	global_store_dwordx4 v[96:97], v[60:63], off offset:512
	s_and_saveexec_b64 s[28:29], s[16:17]
	s_xor_b64 s[54:55], exec, s[28:29]
	v_add3_u32 v60, v216, v208, s79
	s_or_saveexec_b64 s[54:55], s[54:55]
	v_mov_b64_e32 v[62:63], s[24:25]
	s_xor_b64 exec, exec, s[54:55]
	v_lshl_add_u32 v60, v205, 8, v208
	v_mov_b64_e32 v[62:63], s[36:37]
	s_or_b64 exec, exec, s[54:55]
	v_ashrrev_i32_e32 v61, 31, v60
	v_lshlrev_b64 v[60:61], 13, v[60:61]
	v_lshl_add_u64 v[60:61], v[62:63], 0, v[60:61]
	v_pk_fma_f32 v[58:59], v[58:59], v[66:67], v[94:95]
	v_pk_fma_f32 v[56:57], v[56:57], v[64:65], v[92:93]
	v_lshl_add_u64 v[60:61], v[174:175], 2, v[60:61]
	global_store_dwordx4 v[60:61], v[56:59], off offset:512
	s_and_saveexec_b64 s[28:29], s[14:15]
	s_xor_b64 s[54:55], exec, s[28:29]
	v_add3_u32 v56, v219, v210, s79
	s_or_saveexec_b64 s[54:55], s[54:55]
	v_mov_b64_e32 v[58:59], s[24:25]
	s_xor_b64 exec, exec, s[54:55]
	v_lshl_add_u32 v56, v209, 8, v210
	v_mov_b64_e32 v[58:59], s[36:37]
	s_or_b64 exec, exec, s[54:55]
	v_ashrrev_i32_e32 v57, 31, v56
	v_lshlrev_b64 v[56:57], 13, v[56:57]
	v_lshl_add_u64 v[56:57], v[58:59], 0, v[56:57]
	v_pk_fma_f32 v[54:55], v[54:55], v[66:67], v[90:91]
	v_pk_fma_f32 v[52:53], v[52:53], v[64:65], v[88:89]
	v_lshl_add_u64 v[56:57], v[174:175], 2, v[56:57]
	global_store_dwordx4 v[56:57], v[52:55], off offset:512
	s_and_saveexec_b64 s[28:29], s[12:13]
	s_xor_b64 s[54:55], exec, s[28:29]
	v_add3_u32 v52, v222, v213, s79
	s_or_saveexec_b64 s[54:55], s[54:55]
	v_mov_b64_e32 v[54:55], s[24:25]
	s_xor_b64 exec, exec, s[54:55]
	v_lshl_add_u32 v52, v212, 8, v213
	v_mov_b64_e32 v[54:55], s[36:37]
	s_or_b64 exec, exec, s[54:55]
	v_ashrrev_i32_e32 v53, 31, v52
	v_lshlrev_b64 v[52:53], 13, v[52:53]
	v_lshl_add_u64 v[52:53], v[54:55], 0, v[52:53]
	v_pk_fma_f32 v[50:51], v[50:51], v[66:67], v[86:87]
	v_pk_fma_f32 v[48:49], v[48:49], v[64:65], v[84:85]
	v_lshl_add_u64 v[52:53], v[174:175], 2, v[52:53]
	global_store_dwordx4 v[52:53], v[48:51], off offset:512
	s_and_saveexec_b64 s[28:29], s[10:11]
	s_xor_b64 s[54:55], exec, s[28:29]
	v_add3_u32 v48, v225, v215, s79
	s_or_saveexec_b64 s[54:55], s[54:55]
	v_mov_b64_e32 v[50:51], s[24:25]
	s_xor_b64 exec, exec, s[54:55]
	v_lshl_add_u32 v48, v214, 8, v215
	v_mov_b64_e32 v[50:51], s[36:37]
	s_or_b64 exec, exec, s[54:55]
	v_ashrrev_i32_e32 v49, 31, v48
	v_lshlrev_b64 v[48:49], 13, v[48:49]
	v_lshl_add_u64 v[48:49], v[50:51], 0, v[48:49]
	v_pk_fma_f32 v[46:47], v[46:47], v[66:67], v[82:83]
	v_pk_fma_f32 v[44:45], v[44:45], v[64:65], v[80:81]
	v_lshl_add_u64 v[48:49], v[174:175], 2, v[48:49]
	global_store_dwordx4 v[48:49], v[44:47], off offset:512
	s_and_saveexec_b64 s[28:29], s[8:9]
	s_xor_b64 s[54:55], exec, s[28:29]
	v_add3_u32 v44, v226, v218, s79
	s_or_saveexec_b64 s[54:55], s[54:55]
	v_mov_b64_e32 v[46:47], s[24:25]
	s_xor_b64 exec, exec, s[54:55]
	v_lshl_add_u32 v44, v217, 8, v218
	v_mov_b64_e32 v[46:47], s[36:37]
	s_or_b64 exec, exec, s[54:55]
	v_ashrrev_i32_e32 v45, 31, v44
	v_lshlrev_b64 v[44:45], 13, v[44:45]
	v_lshl_add_u64 v[44:45], v[46:47], 0, v[44:45]
	v_pk_fma_f32 v[42:43], v[42:43], v[66:67], v[78:79]
	v_pk_fma_f32 v[40:41], v[40:41], v[64:65], v[76:77]
	v_lshl_add_u64 v[44:45], v[174:175], 2, v[44:45]
	global_store_dwordx4 v[44:45], v[40:43], off offset:512
	s_and_saveexec_b64 s[28:29], s[6:7]
; DI void epi_resid(const Acc& acc, const P& p, int brow, int bcol, int layer, int gch, bool from_input) {
;     ...
;             const f32x4 g = *(const f32x4*)(gate + c0);
;             f32x4 xv[2][4];
; #pragma unroll
;             for (int ai = 0; ai < 2; ++ai)
; #pragma unroll
;                 for (int m = 0; m < 4; ++m) {
;                     const int r = brow + ai * 128 + wr * 64 + m * 16 + fr;
;                     const float* sp = (from_input ? inrow(p, r) : xrow(p, r)) + c0;
;                     xv[ai][m] = *(const f32x4*)sp;
;                 }
;             __builtin_amdgcn_sched_barrier(0);
; #pragma unroll
;             for (int ai = 0; ai < 2; ++ai)
; #pragma unroll
;                 for (int m = 0; m < 4; ++m) {
;                     const int r = brow + ai * 128 + wr * 64 + m * 16 + fr;
;                     *(f32x4*)(xrow(p, r) + c0) = xv[ai][m] + g * acc[ai][bj][m][n];
;                 }
;             __builtin_amdgcn_sched_barrier(0);
	s_xor_b64 s[54:55], exec, s[28:29]
	v_add3_u32 v40, v227, v221, s79
	s_or_saveexec_b64 s[54:55], s[54:55]
	v_mov_b64_e32 v[42:43], s[24:25]
	s_xor_b64 exec, exec, s[54:55]
	v_lshl_add_u32 v40, v220, 8, v221
	v_mov_b64_e32 v[42:43], s[36:37]
	s_or_b64 exec, exec, s[54:55]
	v_ashrrev_i32_e32 v41, 31, v40
	v_lshlrev_b64 v[40:41], 13, v[40:41]
	v_lshl_add_u64 v[40:41], v[42:43], 0, v[40:41]
	v_pk_fma_f32 v[38:39], v[38:39], v[66:67], v[74:75]
	v_pk_fma_f32 v[36:37], v[36:37], v[64:65], v[72:73]
	v_lshl_add_u64 v[40:41], v[174:175], 2, v[40:41]
	global_store_dwordx4 v[40:41], v[36:39], off offset:512
	s_and_saveexec_b64 s[28:29], vcc
	s_xor_b64 s[54:55], exec, s[28:29]
	v_add3_u32 v36, v228, v224, s79
	s_or_saveexec_b64 s[54:55], s[54:55]
	v_mov_b64_e32 v[38:39], s[24:25]
	s_xor_b64 exec, exec, s[54:55]
	v_lshl_add_u32 v36, v223, 8, v224
	v_mov_b64_e32 v[38:39], s[36:37]
	s_or_b64 exec, exec, s[54:55]
	v_ashrrev_i32_e32 v37, 31, v36
	v_lshlrev_b64 v[36:37], 13, v[36:37]
	v_lshl_add_u64 v[36:37], v[38:39], 0, v[36:37]
	v_pk_fma_f32 v[34:35], v[34:35], v[66:67], v[70:71]
	v_pk_fma_f32 v[32:33], v[32:33], v[64:65], v[68:69]
	v_lshl_add_u64 v[36:37], v[174:175], 2, v[36:37]
	global_store_dwordx4 v[36:37], v[32:35], off offset:512
	global_load_dwordx4 v[32:35], v[192:193], off offset:576
	v_mov_b64_e32 v[36:37], s[56:57]
	s_and_saveexec_b64 s[28:29], s[18:19]
	s_xor_b64 s[54:55], exec, s[28:29]
	v_add3_u32 v38, v211, v204, s79
	v_mov_b64_e32 v[36:37], s[52:53]
	s_andn2_saveexec_b64 s[54:55], s[54:55]
	v_lshl_add_u32 v38, v203, 8, v204
	s_or_b64 exec, exec, s[54:55]
	v_ashrrev_i32_e32 v39, 31, v38
	v_lshlrev_b64 v[38:39], 13, v[38:39]
	v_lshl_add_u64 v[36:37], v[36:37], 0, v[38:39]
	v_lshl_add_u64 v[36:37], v[174:175], 2, v[36:37]
	global_load_dwordx4 v[64:67], v[36:37], off offset:576
	v_mov_b64_e32 v[36:37], s[56:57]
	s_and_saveexec_b64 s[28:29], s[16:17]
	s_xor_b64 s[54:55], exec, s[28:29]
	v_add3_u32 v38, v216, v208, s79
	v_mov_b64_e32 v[36:37], s[52:53]
	s_andn2_saveexec_b64 s[54:55], s[54:55]
	v_lshl_add_u32 v38, v205, 8, v208
	s_or_b64 exec, exec, s[54:55]
	v_ashrrev_i32_e32 v39, 31, v38
	v_lshlrev_b64 v[38:39], 13, v[38:39]
	v_lshl_add_u64 v[36:37], v[36:37], 0, v[38:39]
	v_lshl_add_u64 v[36:37], v[174:175], 2, v[36:37]
	global_load_dwordx4 v[60:63], v[36:37], off offset:576
	v_mov_b64_e32 v[36:37], s[56:57]
	s_and_saveexec_b64 s[28:29], s[14:15]
	s_xor_b64 s[54:55], exec, s[28:29]
	v_add3_u32 v38, v219, v210, s79
	v_mov_b64_e32 v[36:37], s[52:53]
	s_andn2_saveexec_b64 s[54:55], s[54:55]
	v_lshl_add_u32 v38, v209, 8, v210
	s_or_b64 exec, exec, s[54:55]
	v_ashrrev_i32_e32 v39, 31, v38
	v_lshlrev_b64 v[38:39], 13, v[38:39]
	v_lshl_add_u64 v[36:37], v[36:37], 0, v[38:39]
	v_lshl_add_u64 v[36:37], v[174:175], 2, v[36:37]
	global_load_dwordx4 v[56:59], v[36:37], off offset:576
	v_mov_b64_e32 v[36:37], s[56:57]
	s_and_saveexec_b64 s[28:29], s[12:13]
	s_xor_b64 s[54:55], exec, s[28:29]
	v_add3_u32 v38, v222, v213, s79
	v_mov_b64_e32 v[36:37], s[52:53]
	s_andn2_saveexec_b64 s[54:55], s[54:55]
	v_lshl_add_u32 v38, v212, 8, v213
	s_or_b64 exec, exec, s[54:55]
	v_ashrrev_i32_e32 v39, 31, v38
	v_lshlrev_b64 v[38:39], 13, v[38:39]
	v_lshl_add_u64 v[36:37], v[36:37], 0, v[38:39]
	v_lshl_add_u64 v[36:37], v[174:175], 2, v[36:37]
	global_load_dwordx4 v[52:55], v[36:37], off offset:576
	v_mov_b64_e32 v[36:37], s[56:57]
	s_and_saveexec_b64 s[28:29], s[10:11]
	s_xor_b64 s[54:55], exec, s[28:29]
	v_add3_u32 v38, v225, v215, s79
	v_mov_b64_e32 v[36:37], s[52:53]
	s_andn2_saveexec_b64 s[54:55], s[54:55]
	v_lshl_add_u32 v38, v214, 8, v215
	s_or_b64 exec, exec, s[54:55]
	v_ashrrev_i32_e32 v39, 31, v38
	v_lshlrev_b64 v[38:39], 13, v[38:39]
	v_lshl_add_u64 v[36:37], v[36:37], 0, v[38:39]
	v_lshl_add_u64 v[36:37], v[174:175], 2, v[36:37]
	global_load_dwordx4 v[48:51], v[36:37], off offset:576
	v_mov_b64_e32 v[36:37], s[56:57]
	s_and_saveexec_b64 s[28:29], s[8:9]
	s_xor_b64 s[54:55], exec, s[28:29]
	v_add3_u32 v38, v226, v218, s79
	v_mov_b64_e32 v[36:37], s[52:53]
	s_andn2_saveexec_b64 s[54:55], s[54:55]
	v_lshl_add_u32 v38, v217, 8, v218
	s_or_b64 exec, exec, s[54:55]
	v_ashrrev_i32_e32 v39, 31, v38
	v_lshlrev_b64 v[38:39], 13, v[38:39]
	v_lshl_add_u64 v[36:37], v[36:37], 0, v[38:39]
	v_lshl_add_u64 v[36:37], v[174:175], 2, v[36:37]
	global_load_dwordx4 v[44:47], v[36:37], off offset:576
	v_mov_b64_e32 v[36:37], s[56:57]
	s_and_saveexec_b64 s[28:29], s[6:7]
	s_xor_b64 s[54:55], exec, s[28:29]
	v_add3_u32 v38, v227, v221, s79
	v_mov_b64_e32 v[36:37], s[52:53]
	s_andn2_saveexec_b64 s[54:55], s[54:55]
	v_lshl_add_u32 v38, v220, 8, v221
	s_or_b64 exec, exec, s[54:55]
	v_ashrrev_i32_e32 v39, 31, v38
	v_lshlrev_b64 v[38:39], 13, v[38:39]
	v_lshl_add_u64 v[36:37], v[36:37], 0, v[38:39]
	v_lshl_add_u64 v[36:37], v[174:175], 2, v[36:37]
	global_load_dwordx4 v[40:43], v[36:37], off offset:576
	v_mov_b64_e32 v[36:37], s[56:57]
	s_and_saveexec_b64 s[28:29], vcc
	s_xor_b64 s[54:55], exec, s[28:29]
	v_add3_u32 v38, v228, v224, s79
	v_mov_b64_e32 v[36:37], s[52:53]
	s_andn2_saveexec_b64 s[54:55], s[54:55]
	v_lshl_add_u32 v38, v223, 8, v224
	s_or_b64 exec, exec, s[54:55]
	v_ashrrev_i32_e32 v39, 31, v38
	v_lshlrev_b64 v[38:39], 13, v[38:39]
	v_lshl_add_u64 v[36:37], v[36:37], 0, v[38:39]
	v_lshl_add_u64 v[36:37], v[174:175], 2, v[36:37]
	global_load_dwordx4 v[36:39], v[36:37], off offset:576
	s_and_saveexec_b64 s[28:29], s[18:19]
	s_xor_b64 s[18:19], exec, s[28:29]
	s_or_saveexec_b64 s[18:19], s[18:19]
	v_mov_b64_e32 v[68:69], s[24:25]
	s_xor_b64 exec, exec, s[18:19]
	v_mov_b64_e32 v[68:69], s[36:37]
	v_mov_b32_e32 v190, v191
	s_or_b64 exec, exec, s[18:19]
	v_ashrrev_i32_e32 v191, 31, v190
	s_waitcnt vmcnt(0)
; DI void epi_resid(const Acc& acc, const P& p, int brow, int bcol, int layer, int gch, bool from_input) {
;     ...
;             for (int ai = 0; ai < 2; ++ai)
; #pragma unroll
;                 for (int m = 0; m < 4; ++m) {
;                     const int r = brow + ai * 128 + wr * 64 + m * 16 + fr;
;                     *(f32x4*)(xrow(p, r) + c0) = xv[ai][m] + g * acc[ai][bj][m][n];
;                 }
;             __builtin_amdgcn_sched_barrier(0);
	v_pk_fma_f32 v[28:29], v[28:29], v[32:33], v[64:65]
	v_lshlrev_b64 v[64:65], 13, v[190:191]
	v_lshl_add_u64 v[64:65], v[68:69], 0, v[64:65]
	v_pk_fma_f32 v[30:31], v[30:31], v[34:35], v[66:67]
	v_lshl_add_u64 v[64:65], v[174:175], 2, v[64:65]
	global_store_dwordx4 v[64:65], v[28:31], off offset:576
	s_and_saveexec_b64 s[18:19], s[16:17]
	s_xor_b64 s[16:17], exec, s[18:19]
	s_or_saveexec_b64 s[16:17], s[16:17]
	v_mov_b64_e32 v[28:29], s[24:25]
	s_xor_b64 exec, exec, s[16:17]
	v_mov_b64_e32 v[28:29], s[36:37]
	v_mov_b32_e32 v188, v189
	s_or_b64 exec, exec, s[16:17]
	v_ashrrev_i32_e32 v189, 31, v188
	v_lshlrev_b64 v[30:31], 13, v[188:189]
	v_lshl_add_u64 v[28:29], v[28:29], 0, v[30:31]
	v_pk_fma_f32 v[26:27], v[26:27], v[34:35], v[62:63]
	v_pk_fma_f32 v[24:25], v[24:25], v[32:33], v[60:61]
	v_lshl_add_u64 v[28:29], v[174:175], 2, v[28:29]
	global_store_dwordx4 v[28:29], v[24:27], off offset:576
	s_and_saveexec_b64 s[16:17], s[14:15]
	s_xor_b64 s[14:15], exec, s[16:17]
	s_or_saveexec_b64 s[14:15], s[14:15]
	v_mov_b64_e32 v[24:25], s[24:25]
	s_xor_b64 exec, exec, s[14:15]
	v_mov_b64_e32 v[24:25], s[36:37]
	v_mov_b32_e32 v186, v187
	s_or_b64 exec, exec, s[14:15]
	v_ashrrev_i32_e32 v187, 31, v186
	v_lshlrev_b64 v[26:27], 13, v[186:187]
	v_lshl_add_u64 v[24:25], v[24:25], 0, v[26:27]
	v_pk_fma_f32 v[22:23], v[22:23], v[34:35], v[58:59]
	v_pk_fma_f32 v[20:21], v[20:21], v[32:33], v[56:57]
	v_lshl_add_u64 v[24:25], v[174:175], 2, v[24:25]
	global_store_dwordx4 v[24:25], v[20:23], off offset:576
	s_and_saveexec_b64 s[14:15], s[12:13]
	s_xor_b64 s[12:13], exec, s[14:15]
	s_or_saveexec_b64 s[12:13], s[12:13]
	v_mov_b64_e32 v[20:21], s[24:25]
	s_xor_b64 exec, exec, s[12:13]
	v_mov_b64_e32 v[20:21], s[36:37]
	v_mov_b32_e32 v184, v185
	s_or_b64 exec, exec, s[12:13]
	v_ashrrev_i32_e32 v185, 31, v184
	v_lshlrev_b64 v[22:23], 13, v[184:185]
	v_lshl_add_u64 v[20:21], v[20:21], 0, v[22:23]
	v_pk_fma_f32 v[18:19], v[18:19], v[34:35], v[54:55]
	v_pk_fma_f32 v[16:17], v[16:17], v[32:33], v[52:53]
	v_lshl_add_u64 v[20:21], v[174:175], 2, v[20:21]
	global_store_dwordx4 v[20:21], v[16:19], off offset:576
	s_and_saveexec_b64 s[12:13], s[10:11]
	s_xor_b64 s[10:11], exec, s[12:13]
	s_or_saveexec_b64 s[10:11], s[10:11]
	v_mov_b64_e32 v[16:17], s[24:25]
	s_xor_b64 exec, exec, s[10:11]
	v_mov_b64_e32 v[16:17], s[36:37]
	v_mov_b32_e32 v182, v183
	s_or_b64 exec, exec, s[10:11]
	v_ashrrev_i32_e32 v183, 31, v182
	v_lshlrev_b64 v[18:19], 13, v[182:183]
	v_lshl_add_u64 v[16:17], v[16:17], 0, v[18:19]
	v_pk_fma_f32 v[14:15], v[14:15], v[34:35], v[50:51]
	v_pk_fma_f32 v[12:13], v[12:13], v[32:33], v[48:49]
	v_lshl_add_u64 v[16:17], v[174:175], 2, v[16:17]
	global_store_dwordx4 v[16:17], v[12:15], off offset:576
	s_and_saveexec_b64 s[10:11], s[8:9]
	s_xor_b64 s[8:9], exec, s[10:11]
	s_or_saveexec_b64 s[8:9], s[8:9]
	v_mov_b64_e32 v[12:13], s[24:25]
	s_xor_b64 exec, exec, s[8:9]
	v_mov_b64_e32 v[12:13], s[36:37]
	v_mov_b32_e32 v180, v181
	s_or_b64 exec, exec, s[8:9]
	v_ashrrev_i32_e32 v181, 31, v180
	v_lshlrev_b64 v[14:15], 13, v[180:181]
	v_lshl_add_u64 v[12:13], v[12:13], 0, v[14:15]
	v_pk_fma_f32 v[10:11], v[10:11], v[34:35], v[46:47]
	v_pk_fma_f32 v[8:9], v[8:9], v[32:33], v[44:45]
	v_lshl_add_u64 v[12:13], v[174:175], 2, v[12:13]
	global_store_dwordx4 v[12:13], v[8:11], off offset:576
	s_and_saveexec_b64 s[8:9], s[6:7]
	s_xor_b64 s[6:7], exec, s[8:9]
	s_or_saveexec_b64 s[6:7], s[6:7]
	v_mov_b64_e32 v[8:9], s[24:25]
	s_xor_b64 exec, exec, s[6:7]
	v_mov_b64_e32 v[8:9], s[36:37]
	v_mov_b32_e32 v178, v179
	s_or_b64 exec, exec, s[6:7]
	v_ashrrev_i32_e32 v179, 31, v178
	v_lshlrev_b64 v[10:11], 13, v[178:179]
	v_lshl_add_u64 v[8:9], v[8:9], 0, v[10:11]
	v_pk_fma_f32 v[6:7], v[6:7], v[34:35], v[42:43]
	v_pk_fma_f32 v[4:5], v[4:5], v[32:33], v[40:41]
	v_lshl_add_u64 v[8:9], v[174:175], 2, v[8:9]
	global_store_dwordx4 v[8:9], v[4:7], off offset:576
	s_and_saveexec_b64 s[6:7], vcc
	s_xor_b64 s[6:7], exec, s[6:7]
	s_or_saveexec_b64 s[6:7], s[6:7]
	v_mov_b64_e32 v[4:5], s[24:25]
	s_xor_b64 exec, exec, s[6:7]
	s_cbranch_execz .LBB0_1234
	v_mov_b64_e32 v[4:5], s[36:37]
	v_mov_b32_e32 v176, v177
	s_branch .LBB0_1234

; #define WAIT_L(n) asm volatile("s_waitcnt lgkmcnt(" #n ")" ::: "memory")
; #define BAR __builtin_amdgcn_s_barrier()
; #define SCHED __builtin_amdgcn_sched_barrier(0)
; template <class Get, class Epi>
; DI void gemm_stream(LAS unsigned char* lds, const int K, const int ld, Get get, Epi epi) {
;     ...
;             const bool last = (t == nt - 2);
;             const char* a1 = cA + (size_t)(t + 1) * kstep;
;             const char* a2 = last ? nA : cA + (size_t)(t + 2) * kstep;
;             const char* b2 = last ? nB : cB + (size_t)(t + 2) * kstep;
;             const char* a3 = a2 + kstep;
;             const char* b3 = b2 + kstep;
;             LDB(B0, 0, 0); SCHED; LDA(At, 0, 0); STAGE(SAo(1, 1), a1 + hstep);
;             WAIT_L(8); BAR; WAIT_L(0); MMA(0, 0, At, B0); BAR; SCHED;
;             LDB(B1, 0, 1); STAGE(SBo(0, 0), b2);
;             BAR; WAIT_L(0); MMA(0, 1, At, B1); BAR;
;             LDA(At, 0, 1); STAGE(SAo(0, 0), a2);
;             BAR; WAIT_L(0); MMA(1, 0, At, B0); BAR; SCHED;
.LBB0_1505:
	s_add_u32 s38, s8, s0
	s_addc_u32 s39, s9, 0
	s_add_u32 s40, s38, 0x100
	s_addc_u32 s41, s39, 0
	s_and_b64 s[36:37], s[18:19], exec
	s_cselect_b32 s41, s13, s41
	s_cselect_b32 s40, s12, s40
	s_add_u32 s0, s10, s0
	s_addc_u32 s36, s11, 0
	s_add_u32 s0, s0, 0x100
	s_addc_u32 s36, s36, 0
	s_and_b64 s[18:19], s[18:19], exec
	s_cselect_b32 s53, s15, s36
	s_cselect_b32 s52, s14, s0
	s_add_u32 s54, s38, 0x80080
	s_addc_u32 s55, s39, 0
	s_add_i32 s87, s63, 0x2000
	s_add_u32 s38, s52, 0x80000
	s_addc_u32 s39, s53, 0
	s_add_i32 s86, s60, s3
	s_add_i32 s85, s86, 0x2000
	s_add_i32 s83, 16, 0x18000
	ds_read_b128 v[140:143], v137
	ds_read_b128 v[144:147], v137 offset:1024
	ds_read_b128 v[148:151], v137 offset:2048
	ds_read_b128 v[152:155], v137 offset:3072
	s_add_u32 s36, s40, 0x80000
	s_addc_u32 s37, s41, 0
	s_add_i32 s82, s83, s3
	s_add_i32 s81, 16, 0x1c000
	s_add_i32 s80, s82, 0x2000
	s_add_u32 s18, s52, 0x80080
	s_addc_u32 s19, s53, 0
	s_add_i32 s79, s81, s3
	s_add_i32 s0, s79, 0x2000
	s_mov_b32 m0, s61
	v_lshl_add_u64 v[188:189], s[54:55], 0, v[130:131]
	ds_read_b128 v[156:159], v138
	ds_read_b128 v[160:163], v138 offset:1024
	ds_read_b128 v[164:167], v138 offset:2048
	ds_read_b128 v[168:171], v138 offset:3072
	ds_read_b128 v[172:175], v138 offset:4096
	ds_read_b128 v[176:179], v138 offset:5120
	ds_read_b128 v[180:183], v138 offset:6144
	ds_read_b128 v[184:187], v138 offset:7168
	global_load_lds_dwordx4 v[188:189], off
	v_lshl_add_u64 v[188:189], s[54:55], 0, v[128:129]
	s_mov_b32 m0, s62
	s_nop 0
	global_load_lds_dwordx4 v[188:189], off
	s_waitcnt lgkmcnt(8)
	s_barrier
	s_waitcnt lgkmcnt(0)
	v_mfma_f32_16x16x32_bf16 v[124:127], v[140:143], v[156:159], v[124:127]
	v_mfma_f32_16x16x32_bf16 v[120:123], v[148:151], v[156:159], v[120:123]
	v_mfma_f32_16x16x32_bf16 v[116:119], v[140:143], v[164:167], v[116:119]
	v_mfma_f32_16x16x32_bf16 v[112:115], v[148:151], v[164:167], v[112:115]
	v_mfma_f32_16x16x32_bf16 v[104:107], v[140:143], v[172:175], v[104:107]
	v_mfma_f32_16x16x32_bf16 v[96:99], v[148:151], v[172:175], v[96:99]
	v_mfma_f32_16x16x32_bf16 v[88:91], v[140:143], v[180:183], v[88:91]
	v_mfma_f32_16x16x32_bf16 v[80:83], v[148:151], v[180:183], v[80:83]
	v_mfma_f32_16x16x32_bf16 v[124:127], v[144:147], v[160:163], v[124:127]
	v_mfma_f32_16x16x32_bf16 v[120:123], v[152:155], v[160:163], v[120:123]
	v_mfma_f32_16x16x32_bf16 v[116:119], v[144:147], v[168:171], v[116:119]
	v_mfma_f32_16x16x32_bf16 v[112:115], v[152:155], v[168:171], v[112:115]
	v_mfma_f32_16x16x32_bf16 v[104:107], v[144:147], v[176:179], v[104:107]
	v_mfma_f32_16x16x32_bf16 v[96:99], v[152:155], v[176:179], v[96:99]
	v_mfma_f32_16x16x32_bf16 v[88:91], v[144:147], v[184:187], v[88:91]
	v_mfma_f32_16x16x32_bf16 v[80:83], v[152:155], v[184:187], v[80:83]
	s_barrier
	s_mov_b32 m0, s63
	v_lshl_add_u64 v[204:205], s[52:53], 0, v[130:131]
	ds_read_b128 v[188:191], v139
	ds_read_b128 v[192:195], v139 offset:1024
	ds_read_b128 v[196:199], v139 offset:2048
	ds_read_b128 v[200:203], v139 offset:3072
	global_load_lds_dwordx4 v[204:205], off
	v_lshl_add_u64 v[208:209], s[52:53], 0, v[128:129]
	s_mov_b32 m0, s87
	s_nop 0
	global_load_lds_dwordx4 v[208:209], off
	s_barrier
	s_waitcnt lgkmcnt(0)
	v_mfma_f32_16x16x32_bf16 v[108:111], v[188:191], v[156:159], v[108:111]
	v_mfma_f32_16x16x32_bf16 v[100:103], v[196:199], v[156:159], v[100:103]
	v_mfma_f32_16x16x32_bf16 v[92:95], v[188:191], v[164:167], v[92:95]
	v_mfma_f32_16x16x32_bf16 v[84:87], v[196:199], v[164:167], v[84:87]
	v_mfma_f32_16x16x32_bf16 v[76:79], v[188:191], v[172:175], v[76:79]
	v_mfma_f32_16x16x32_bf16 v[72:75], v[196:199], v[172:175], v[72:75]
	v_mfma_f32_16x16x32_bf16 v[68:71], v[188:191], v[180:183], v[68:71]
	v_mfma_f32_16x16x32_bf16 v[64:67], v[196:199], v[180:183], v[64:67]
	v_mfma_f32_16x16x32_bf16 v[108:111], v[192:195], v[160:163], v[108:111]
	v_mfma_f32_16x16x32_bf16 v[100:103], v[200:203], v[160:163], v[100:103]
	v_mfma_f32_16x16x32_bf16 v[92:95], v[192:195], v[168:171], v[92:95]
	v_mfma_f32_16x16x32_bf16 v[84:87], v[200:203], v[168:171], v[84:87]
	v_mfma_f32_16x16x32_bf16 v[76:79], v[192:195], v[176:179], v[76:79]
	v_mfma_f32_16x16x32_bf16 v[72:75], v[200:203], v[176:179], v[72:75]
	v_mfma_f32_16x16x32_bf16 v[68:71], v[192:195], v[184:187], v[68:71]
	v_mfma_f32_16x16x32_bf16 v[64:67], v[200:203], v[184:187], v[64:67]
	s_mov_b32 m0, s20
	v_lshl_add_u64 v[210:211], s[40:41], 0, v[130:131]
	s_barrier
	ds_read_b128 v[156:159], v138 offset:16384
	ds_read_b128 v[160:163], v138 offset:17408
	ds_read_b128 v[164:167], v138 offset:18432
	ds_read_b128 v[168:171], v138 offset:19456
	ds_read_b128 v[172:175], v138 offset:20480
	ds_read_b128 v[176:179], v138 offset:21504
	ds_read_b128 v[180:183], v138 offset:22528
	ds_read_b128 v[184:187], v138 offset:23552
	global_load_lds_dwordx4 v[210:211], off
	v_lshl_add_u64 v[212:213], s[40:41], 0, v[128:129]
	s_mov_b32 m0, s21
	s_nop 0
	global_load_lds_dwordx4 v[212:213], off
	s_barrier
	s_waitcnt lgkmcnt(0)
	v_mfma_f32_16x16x32_bf16 v[60:63], v[140:143], v[156:159], v[60:63]
	v_mfma_f32_16x16x32_bf16 v[56:59], v[148:151], v[156:159], v[56:59]
	v_mfma_f32_16x16x32_bf16 v[52:55], v[140:143], v[164:167], v[52:55]
	v_mfma_f32_16x16x32_bf16 v[48:51], v[148:151], v[164:167], v[48:51]
	v_mfma_f32_16x16x32_bf16 v[40:43], v[140:143], v[172:175], v[40:43]
	v_mfma_f32_16x16x32_bf16 v[32:35], v[148:151], v[172:175], v[32:35]
	v_mfma_f32_16x16x32_bf16 v[24:27], v[140:143], v[180:183], v[24:27]
	v_mfma_f32_16x16x32_bf16 v[16:19], v[148:151], v[180:183], v[16:19]
	v_mfma_f32_16x16x32_bf16 v[60:63], v[144:147], v[160:163], v[60:63]
	v_mfma_f32_16x16x32_bf16 v[56:59], v[152:155], v[160:163], v[56:59]
	v_mfma_f32_16x16x32_bf16 v[52:55], v[144:147], v[168:171], v[52:55]
	v_mfma_f32_16x16x32_bf16 v[48:51], v[152:155], v[168:171], v[48:51]
	v_mfma_f32_16x16x32_bf16 v[40:43], v[144:147], v[176:179], v[40:43]
	v_mfma_f32_16x16x32_bf16 v[32:35], v[152:155], v[176:179], v[32:35]
	v_mfma_f32_16x16x32_bf16 v[24:27], v[144:147], v[184:187], v[24:27]
	v_mfma_f32_16x16x32_bf16 v[16:19], v[152:155], v[184:187], v[16:19]
	s_barrier
; #define WAIT_V(n) asm volatile("s_waitcnt vmcnt(" #n ")" ::: "memory")
; #define WAIT_L(n) asm volatile("s_waitcnt lgkmcnt(" #n ")" ::: "memory")
; #define BAR __builtin_amdgcn_s_barrier()
; #define SCHED __builtin_amdgcn_sched_barrier(0)
; template <class Get, class Epi>
; DI void gemm_stream(LAS unsigned char* lds, const int K, const int ld, Get get, Epi epi) {
;     ...
;             STAGE(SBo(0, 1), b2 + hstep);
;             WAIT_V(6); BAR; MMA(1, 1, At, B1); BAR;
;             LDB(B0, 1, 0); SCHED; LDA(At, 1, 0); STAGE(SAo(0, 1), a2 + hstep);
;             WAIT_L(8); BAR; WAIT_L(0); MMA(0, 0, At, B0); BAR; SCHED;
;             LDB(B1, 1, 1); STAGE(SBo(1, 0), b3);
;             BAR; WAIT_L(0); MMA(0, 1, At, B1); BAR;
;             LDA(At, 1, 1); STAGE(SAo(1, 0), a3);
;             BAR; WAIT_L(0); MMA(1, 0, At, B0); BAR; SCHED;
	s_mov_b32 m0, s86
	v_lshl_add_u64 v[140:141], s[38:39], 0, v[130:131]
	global_load_lds_dwordx4 v[140:141], off
	v_lshl_add_u64 v[140:141], s[38:39], 0, v[128:129]
	s_mov_b32 m0, s85
	s_nop 0
	global_load_lds_dwordx4 v[140:141], off
	s_waitcnt vmcnt(6)
	s_barrier
	v_mfma_f32_16x16x32_bf16 v[44:47], v[188:191], v[156:159], v[44:47]
	v_mfma_f32_16x16x32_bf16 v[36:39], v[196:199], v[156:159], v[36:39]
	v_mfma_f32_16x16x32_bf16 v[28:31], v[188:191], v[164:167], v[28:31]
	v_mfma_f32_16x16x32_bf16 v[20:23], v[196:199], v[164:167], v[20:23]
	v_mfma_f32_16x16x32_bf16 v[12:15], v[188:191], v[172:175], v[12:15]
	v_mfma_f32_16x16x32_bf16 v[8:11], v[196:199], v[172:175], v[8:11]
	v_mfma_f32_16x16x32_bf16 v[4:7], v[188:191], v[180:183], v[4:7]
	v_mfma_f32_16x16x32_bf16 v[0:3], v[196:199], v[180:183], v[0:3]
	v_mfma_f32_16x16x32_bf16 v[44:47], v[192:195], v[160:163], v[44:47]
	v_mfma_f32_16x16x32_bf16 v[36:39], v[200:203], v[160:163], v[36:39]
	v_mfma_f32_16x16x32_bf16 v[28:31], v[192:195], v[168:171], v[28:31]
	v_mfma_f32_16x16x32_bf16 v[20:23], v[200:203], v[168:171], v[20:23]
	v_mfma_f32_16x16x32_bf16 v[12:15], v[192:195], v[176:179], v[12:15]
	v_mfma_f32_16x16x32_bf16 v[8:11], v[200:203], v[176:179], v[8:11]
	v_mfma_f32_16x16x32_bf16 v[4:7], v[192:195], v[184:187], v[4:7]
	v_mfma_f32_16x16x32_bf16 v[0:3], v[200:203], v[184:187], v[0:3]
	v_add_u32_e32 v132, s83, v136
	s_barrier
	ds_read_b128 v[140:143], v132
	ds_read_b128 v[144:147], v132 offset:1024
	ds_read_b128 v[148:151], v132 offset:2048
	ds_read_b128 v[152:155], v132 offset:3072
	s_mov_b32 m0, s28
	v_lshl_add_u64 v[188:189], s[36:37], 0, v[130:131]
	ds_read_b128 v[156:159], v138 offset:32768
	ds_read_b128 v[160:163], v138 offset:33792
	ds_read_b128 v[164:167], v138 offset:34816
	ds_read_b128 v[168:171], v138 offset:35840
	ds_read_b128 v[172:175], v138 offset:36864
	ds_read_b128 v[176:179], v138 offset:37888
	ds_read_b128 v[180:183], v138 offset:38912
	ds_read_b128 v[184:187], v138 offset:39936
	global_load_lds_dwordx4 v[188:189], off
	v_lshl_add_u64 v[188:189], s[36:37], 0, v[128:129]
	s_mov_b32 m0, s29
	s_nop 0
	global_load_lds_dwordx4 v[188:189], off
	s_waitcnt lgkmcnt(8)
	s_barrier
	s_waitcnt lgkmcnt(0)
	v_mfma_f32_16x16x32_bf16 v[124:127], v[140:143], v[156:159], v[124:127]
	v_mfma_f32_16x16x32_bf16 v[120:123], v[148:151], v[156:159], v[120:123]
	v_mfma_f32_16x16x32_bf16 v[116:119], v[140:143], v[164:167], v[116:119]
	v_mfma_f32_16x16x32_bf16 v[112:115], v[148:151], v[164:167], v[112:115]
	v_mfma_f32_16x16x32_bf16 v[104:107], v[140:143], v[172:175], v[104:107]
	v_mfma_f32_16x16x32_bf16 v[96:99], v[148:151], v[172:175], v[96:99]
	v_mfma_f32_16x16x32_bf16 v[88:91], v[140:143], v[180:183], v[88:91]
	v_mfma_f32_16x16x32_bf16 v[80:83], v[148:151], v[180:183], v[80:83]
	v_mfma_f32_16x16x32_bf16 v[124:127], v[144:147], v[160:163], v[124:127]
	v_mfma_f32_16x16x32_bf16 v[120:123], v[152:155], v[160:163], v[120:123]
	v_mfma_f32_16x16x32_bf16 v[116:119], v[144:147], v[168:171], v[116:119]
	v_mfma_f32_16x16x32_bf16 v[112:115], v[152:155], v[168:171], v[112:115]
	v_mfma_f32_16x16x32_bf16 v[104:107], v[144:147], v[176:179], v[104:107]
	v_mfma_f32_16x16x32_bf16 v[96:99], v[152:155], v[176:179], v[96:99]
	v_mfma_f32_16x16x32_bf16 v[88:91], v[144:147], v[184:187], v[88:91]
	v_mfma_f32_16x16x32_bf16 v[80:83], v[152:155], v[184:187], v[80:83]
	s_barrier
	s_mov_b32 m0, s82
	v_add_u32_e32 v132, s81, v136
	v_lshl_add_u64 v[204:205], v[204:205], 0, s[6:7]
	ds_read_b128 v[188:191], v132
	ds_read_b128 v[192:195], v132 offset:1024
	ds_read_b128 v[196:199], v132 offset:2048
	ds_read_b128 v[200:203], v132 offset:3072
	global_load_lds_dwordx4 v[204:205], off
	v_lshl_add_u64 v[204:205], v[208:209], 0, s[6:7]
	s_mov_b32 m0, s80
	s_nop 0
	global_load_lds_dwordx4 v[204:205], off
	s_barrier
	s_waitcnt lgkmcnt(0)
	v_mfma_f32_16x16x32_bf16 v[108:111], v[188:191], v[156:159], v[108:111]
	v_mfma_f32_16x16x32_bf16 v[100:103], v[196:199], v[156:159], v[100:103]
	v_mfma_f32_16x16x32_bf16 v[92:95], v[188:191], v[164:167], v[92:95]
	v_mfma_f32_16x16x32_bf16 v[84:87], v[196:199], v[164:167], v[84:87]
	v_mfma_f32_16x16x32_bf16 v[76:79], v[188:191], v[172:175], v[76:79]
	v_mfma_f32_16x16x32_bf16 v[72:75], v[196:199], v[172:175], v[72:75]
	v_mfma_f32_16x16x32_bf16 v[68:71], v[188:191], v[180:183], v[68:71]
	v_mfma_f32_16x16x32_bf16 v[64:67], v[196:199], v[180:183], v[64:67]
	v_mfma_f32_16x16x32_bf16 v[108:111], v[192:195], v[160:163], v[108:111]
	v_mfma_f32_16x16x32_bf16 v[100:103], v[200:203], v[160:163], v[100:103]
	v_mfma_f32_16x16x32_bf16 v[92:95], v[192:195], v[168:171], v[92:95]
	v_mfma_f32_16x16x32_bf16 v[84:87], v[200:203], v[168:171], v[84:87]
	v_mfma_f32_16x16x32_bf16 v[76:79], v[192:195], v[176:179], v[76:79]
	v_mfma_f32_16x16x32_bf16 v[72:75], v[200:203], v[176:179], v[72:75]
	v_mfma_f32_16x16x32_bf16 v[68:71], v[192:195], v[184:187], v[68:71]
	v_mfma_f32_16x16x32_bf16 v[64:67], v[200:203], v[184:187], v[64:67]
	s_mov_b32 m0, s56
	v_lshl_add_u64 v[204:205], v[210:211], 0, s[6:7]
	s_barrier
	ds_read_b128 v[156:159], v138 offset:49152
	ds_read_b128 v[160:163], v138 offset:50176
	ds_read_b128 v[164:167], v138 offset:51200
	ds_read_b128 v[168:171], v138 offset:52224
	ds_read_b128 v[172:175], v138 offset:53248
	ds_read_b128 v[176:179], v138 offset:54272
	ds_read_b128 v[180:183], v138 offset:55296
	ds_read_b128 v[184:187], v138 offset:56320
	global_load_lds_dwordx4 v[204:205], off
	v_lshl_add_u64 v[204:205], v[212:213], 0, s[6:7]
	s_mov_b32 m0, s57
	s_nop 0
	global_load_lds_dwordx4 v[204:205], off
	s_barrier
; #define WAIT_V(n) asm volatile("s_waitcnt vmcnt(" #n ")" ::: "memory")
; #define WAIT_L(n) asm volatile("s_waitcnt lgkmcnt(" #n ")" ::: "memory")
; #define BAR __builtin_amdgcn_s_barrier()
; #define SCHED __builtin_amdgcn_sched_barrier(0)
; #define EPI_DONE do { } while (0)
; template <class Get, class Epi>
; DI void gemm_stream(LAS unsigned char* lds, const int K, const int ld, Get get, Epi epi) {
;     ...
;             BAR; WAIT_L(0); MMA(1, 0, At, B0); BAR; SCHED;
;             STAGE(SBo(1, 1), b3 + hstep);
;             WAIT_V(6); BAR; MMA(1, 1, At, B1); BAR;
;         }
;         epi(acc, cur);
;         if (!has_next) break;
;         ZERO_ACC;
;         cur = nxt; cA = nA; cB = nB; ++ui;
;     }
;     WAIT_V(0);
;     if (wr == 0) BAR;
; DI void epi_part(const Acc& acc, const P& p, int brow, int bcol, int sl) {
;     EPI_IDX
;     const int b = brow / PB;
;     float* part = (float*)(p.ws + O_PART) + ((size_t)sl * (NBATCH * CTXL) + b * CTXL) * DM;
; #pragma unroll
;     for (int ai = 0; ai < 2; ++ai)
; #pragma unroll
;         for (int m = 0; m < 4; ++m) {
;             float* rp = part + (size_t)(ai * 128 + wr * 64 + m * 16 + fr) * DM + bcol + wc * 32 + fq * 4;
; #pragma unroll
;             for (int bj = 0; bj < 2; ++bj)
; #pragma unroll
;                 for (int n = 0; n < 2; ++n) *(f32x4*)(rp + bj * 128 + n * 16) = acc[ai][bj][m][n];
;         }
;     EPI_DONE;
; }
	s_waitcnt lgkmcnt(0)
	v_mfma_f32_16x16x32_bf16 v[60:63], v[140:143], v[156:159], v[60:63]
	v_mfma_f32_16x16x32_bf16 v[56:59], v[148:151], v[156:159], v[56:59]
	v_mfma_f32_16x16x32_bf16 v[52:55], v[140:143], v[164:167], v[52:55]
	v_mfma_f32_16x16x32_bf16 v[48:51], v[148:151], v[164:167], v[48:51]
	v_mfma_f32_16x16x32_bf16 v[40:43], v[140:143], v[172:175], v[40:43]
	v_mfma_f32_16x16x32_bf16 v[32:35], v[148:151], v[172:175], v[32:35]
	v_mfma_f32_16x16x32_bf16 v[24:27], v[140:143], v[180:183], v[24:27]
	v_mfma_f32_16x16x32_bf16 v[16:19], v[148:151], v[180:183], v[16:19]
	v_mfma_f32_16x16x32_bf16 v[60:63], v[144:147], v[160:163], v[60:63]
	v_mfma_f32_16x16x32_bf16 v[56:59], v[152:155], v[160:163], v[56:59]
	v_mfma_f32_16x16x32_bf16 v[52:55], v[144:147], v[168:171], v[52:55]
	v_mfma_f32_16x16x32_bf16 v[48:51], v[152:155], v[168:171], v[48:51]
	v_mfma_f32_16x16x32_bf16 v[40:43], v[144:147], v[176:179], v[40:43]
	v_mfma_f32_16x16x32_bf16 v[32:35], v[152:155], v[176:179], v[32:35]
	v_mfma_f32_16x16x32_bf16 v[24:27], v[144:147], v[184:187], v[24:27]
	v_mfma_f32_16x16x32_bf16 v[16:19], v[152:155], v[184:187], v[16:19]
	s_barrier
	s_mov_b32 m0, s79
	v_lshl_add_u64 v[140:141], s[18:19], 0, v[130:131]
	global_load_lds_dwordx4 v[140:141], off
	v_lshl_add_u64 v[140:141], s[18:19], 0, v[128:129]
	s_mov_b32 m0, s0
	s_nop 0
	global_load_lds_dwordx4 v[140:141], off
	s_waitcnt vmcnt(6)
	s_barrier
	v_mfma_f32_16x16x32_bf16 v[44:47], v[188:191], v[156:159], v[44:47]
	v_mfma_f32_16x16x32_bf16 v[36:39], v[196:199], v[156:159], v[36:39]
	v_mfma_f32_16x16x32_bf16 v[28:31], v[188:191], v[164:167], v[28:31]
	v_mfma_f32_16x16x32_bf16 v[20:23], v[196:199], v[164:167], v[20:23]
	v_mfma_f32_16x16x32_bf16 v[12:15], v[188:191], v[172:175], v[12:15]
	v_mfma_f32_16x16x32_bf16 v[8:11], v[196:199], v[172:175], v[8:11]
	v_mfma_f32_16x16x32_bf16 v[4:7], v[188:191], v[180:183], v[4:7]
	v_mfma_f32_16x16x32_bf16 v[0:3], v[196:199], v[180:183], v[0:3]
	v_mfma_f32_16x16x32_bf16 v[44:47], v[192:195], v[160:163], v[44:47]
	v_mfma_f32_16x16x32_bf16 v[36:39], v[200:203], v[160:163], v[36:39]
	v_mfma_f32_16x16x32_bf16 v[28:31], v[192:195], v[168:171], v[28:31]
	v_mfma_f32_16x16x32_bf16 v[20:23], v[200:203], v[168:171], v[20:23]
	v_mfma_f32_16x16x32_bf16 v[12:15], v[192:195], v[176:179], v[12:15]
	v_mfma_f32_16x16x32_bf16 v[8:11], v[200:203], v[176:179], v[8:11]
	v_mfma_f32_16x16x32_bf16 v[4:7], v[192:195], v[184:187], v[4:7]
	v_mfma_f32_16x16x32_bf16 v[0:3], v[200:203], v[184:187], v[0:3]
	s_movk_i32 s0, 0x100
	s_andn2_b64 vcc, exec, s[16:17]
	s_mov_b64 s[18:19], -1
	s_mov_b64 s[16:17], 0
	s_barrier
	s_cbranch_vccz .LBB0_1505
	s_mul_hi_i32 s0, s78, 0x78787879
	s_lshr_b32 s9, s0, 31
	s_lshr_b32 s0, s0, 3
	s_ashr_i32 s8, s77, 4
	s_add_i32 s0, s0, s9
	s_ashr_i32 s9, s8, 31
	s_lshl_b32 s10, s0, 8
	s_ashr_i32 s11, s10, 31
	s_lshl_b64 s[8:9], s[8:9], 23
	s_add_u32 s0, s58, s8
	v_mov_b32_e32 v141, v206
	s_addc_u32 s16, s59, s9
	s_lshl_b64 s[8:9], s[10:11], 13
	s_add_u32 s0, s0, s8
	v_and_b32_e32 v132, 15, v141
	v_ashrrev_i32_e32 v140, 2, v141
	s_movk_i32 s8, 0xffc0
	s_addc_u32 s9, s16, s9
	v_and_or_b32 v140, v140, s8, v132
	s_lshl_b32 s8, s77, 10
	s_and_b32 s8, s8, 0x3c00
	s_add_u32 s8, s0, s8
	v_lshlrev_b32_e32 v132, 1, v141
	s_addc_u32 s9, s9, 0
	v_and_b32_e32 v132, 0x180, v132
	v_lshl_add_u64 v[142:143], s[8:9], 0, v[132:133]
	v_and_b32_e32 v132, 48, v141
	v_ashrrev_i32_e32 v141, 31, v140
	v_lshl_add_u64 v[142:143], v[142:143], 0, v[132:133]
	v_lshlrev_b64 v[144:145], 13, v[140:141]
	v_lshl_add_u64 v[144:145], v[142:143], 0, v[144:145]
	global_store_dwordx4 v[144:145], v[124:127], off
	global_store_dwordx4 v[144:145], v[120:123], off offset:64
	global_store_dwordx4 v[144:145], v[108:111], off offset:512
	global_store_dwordx4 v[144:145], v[100:103], off offset:576
	s_mov_b32 s0, 0x100000
	s_mov_b64 s[8:9], 0x100000
	v_or_b32_e32 v100, 16, v140
	v_ashrrev_i32_e32 v101, 31, v100
	v_lshlrev_b64 v[100:101], 13, v[100:101]
	v_lshl_add_u64 v[100:101], v[142:143], 0, v[100:101]
	global_store_dwordx4 v[100:101], v[116:119], off
	global_store_dwordx4 v[100:101], v[112:115], off offset:64
	global_store_dwordx4 v[100:101], v[92:95], off offset:512
	global_store_dwordx4 v[100:101], v[84:87], off offset:576
	s_mov_b32 s77, s76
	s_mov_b32 s78, s74
	v_or_b32_e32 v84, 32, v140
	v_ashrrev_i32_e32 v85, 31, v84
	v_lshlrev_b64 v[84:85], 13, v[84:85]
	v_lshl_add_u64 v[84:85], v[142:143], 0, v[84:85]
	global_store_dwordx4 v[84:85], v[104:107], off
	global_store_dwordx4 v[84:85], v[96:99], off offset:64
	global_store_dwordx4 v[84:85], v[76:79], off offset:512
	global_store_dwordx4 v[84:85], v[72:75], off offset:576
	s_mov_b64 s[10:11], s[14:15]
	s_nop 0
	v_or_b32_e32 v72, 48, v140
	v_ashrrev_i32_e32 v73, 31, v72
	v_lshlrev_b64 v[72:73], 13, v[72:73]
	v_lshl_add_u64 v[72:73], v[142:143], 0, v[72:73]
	global_store_dwordx4 v[72:73], v[88:91], off
	global_store_dwordx4 v[72:73], v[80:83], off offset:64
	global_store_dwordx4 v[72:73], v[68:71], off offset:512
	global_store_dwordx4 v[72:73], v[64:67], off offset:576
	s_nop 1
	v_add_co_u32_e32 v66, vcc, s0, v144
	s_mov_b32 s0, 0x120000
	s_nop 0
	v_addc_co_u32_e32 v67, vcc, 0, v145, vcc
	v_lshl_add_u64 v[64:65], v[144:145], 0, s[8:9]
	global_store_dwordx4 v[66:67], v[60:63], off
	global_store_dwordx4 v[64:65], v[56:59], off offset:64
	global_store_dwordx4 v[64:65], v[44:47], off offset:512
	global_store_dwordx4 v[64:65], v[36:39], off offset:576
	s_mov_b64 s[8:9], 0x120000
	s_nop 0
	v_add_co_u32_e32 v38, vcc, s0, v144
	s_mov_b32 s0, 0x140000
	s_nop 0
	v_addc_co_u32_e32 v39, vcc, 0, v145, vcc
	v_lshl_add_u64 v[36:37], v[144:145], 0, s[8:9]
	global_store_dwordx4 v[38:39], v[52:55], off
	global_store_dwordx4 v[36:37], v[48:51], off offset:64
	global_store_dwordx4 v[36:37], v[28:31], off offset:512
	global_store_dwordx4 v[36:37], v[20:23], off offset:576
	s_mov_b64 s[8:9], 0x140000
	s_nop 0
	v_add_co_u32_e32 v22, vcc, s0, v144
	v_lshl_add_u64 v[20:21], v[144:145], 0, s[8:9]
	s_nop 0
	v_addc_co_u32_e32 v23, vcc, 0, v145, vcc
	global_store_dwordx4 v[22:23], v[40:43], off
	global_store_dwordx4 v[20:21], v[32:35], off offset:64
	global_store_dwordx4 v[20:21], v[12:15], off offset:512
	global_store_dwordx4 v[20:21], v[8:11], off offset:576
	s_mov_b64 s[8:9], 0x160000
	s_nop 0
	v_add_co_u32_e32 v10, vcc, 0x160000, v144
	v_lshl_add_u64 v[8:9], v[144:145], 0, s[8:9]
	s_nop 0
	v_addc_co_u32_e32 v11, vcc, 0, v145, vcc
	s_and_b64 vcc, exec, s[4:5]
	s_mov_b64 s[8:9], s[12:13]
	global_store_dwordx4 v[10:11], v[24:27], off
	global_store_dwordx4 v[8:9], v[16:19], off offset:64
	global_store_dwordx4 v[8:9], v[4:7], off offset:512
	global_store_dwordx4 v[8:9], v[0:3], off offset:576
	s_cbranch_vccz .LBB0_1502
	s_waitcnt vmcnt(0)
	s_cmpk_gt_u32 s2, 0xff
	v_readlane_b32 s76, v254, 10
	s_cbranch_scc1 .LBB0_1509
	s_barrier

; #define WAIT_V(n) asm volatile("s_waitcnt vmcnt(" #n ")" ::: "memory")
; #define WAIT_L(n) asm volatile("s_waitcnt lgkmcnt(" #n ")" ::: "memory")
; #define BAR __builtin_amdgcn_s_barrier()
; #define SCHED __builtin_amdgcn_sched_barrier(0)
; template <class Get, class Epi>
; DI void gemm_stream(LAS unsigned char* lds, const int K, const int ld, Get get, Epi epi) {
;     ...
;             LDB(B0, 0, 0); SCHED; LDA(At, 0, 0); STAGE(SAo(1, 1), a1 + hstep);
;             WAIT_L(8); BAR; WAIT_L(0); MMA(0, 0, At, B0); BAR; SCHED;
;             LDB(B1, 0, 1); STAGE(SBo(0, 0), b2);
;             BAR; WAIT_L(0); MMA(0, 1, At, B1); BAR;
;             LDA(At, 0, 1); STAGE(SAo(0, 0), a2);
;             BAR; WAIT_L(0); MMA(1, 0, At, B0); BAR; SCHED;
;             STAGE(SBo(0, 1), b2 + hstep);
;             WAIT_V(6); BAR; MMA(1, 1, At, B1); BAR;
;             LDB(B0, 1, 0); SCHED; LDA(At, 1, 0); STAGE(SAo(0, 1), a2 + hstep);
;             WAIT_L(8); BAR; WAIT_L(0); MMA(0, 0, At, B0); BAR; SCHED;
.LBB0_1630:
	ds_read_b128 v[148:151], v142
	ds_read_b128 v[152:155], v142 offset:1024
	ds_read_b128 v[156:159], v142 offset:2048
	ds_read_b128 v[160:163], v142 offset:3072
	s_add_u32 s12, s10, 0xfff80080
	s_addc_u32 s13, s11, -1
	s_cmp_eq_u32 s59, 28
	s_cselect_b32 s15, s7, s13
	s_cselect_b32 s14, s6, s12
	s_cselect_b32 s13, s9, s58
	s_cselect_b32 s12, s8, s57
	s_mov_b32 m0, s28
	v_lshl_add_u64 v[140:141], s[10:11], 0, v[134:135]
	ds_read_b128 v[164:167], v143
	ds_read_b128 v[168:171], v143 offset:1024
	ds_read_b128 v[172:175], v143 offset:2048
	ds_read_b128 v[176:179], v143 offset:3072
	ds_read_b128 v[180:183], v143 offset:4096
	ds_read_b128 v[184:187], v143 offset:5120
	ds_read_b128 v[188:191], v143 offset:6144
	ds_read_b128 v[192:195], v143 offset:7168
	global_load_lds_dwordx4 v[140:141], off
	v_lshl_add_u64 v[140:141], s[10:11], 0, v[136:137]
	s_mov_b32 m0, s29
	s_nop 0
	global_load_lds_dwordx4 v[140:141], off
	s_waitcnt lgkmcnt(8)
	s_barrier
	s_waitcnt lgkmcnt(0)
	v_mfma_f32_16x16x32_bf16 v[124:127], v[148:151], v[164:167], v[124:127]
	v_mfma_f32_16x16x32_bf16 v[116:119], v[156:159], v[164:167], v[116:119]
	v_mfma_f32_16x16x32_bf16 v[108:111], v[148:151], v[172:175], v[108:111]
	v_mfma_f32_16x16x32_bf16 v[100:103], v[156:159], v[172:175], v[100:103]
	v_mfma_f32_16x16x32_bf16 v[92:95], v[148:151], v[180:183], v[92:95]
	v_mfma_f32_16x16x32_bf16 v[84:87], v[156:159], v[180:183], v[84:87]
	v_mfma_f32_16x16x32_bf16 v[76:79], v[148:151], v[188:191], v[76:79]
	v_mfma_f32_16x16x32_bf16 v[68:71], v[156:159], v[188:191], v[68:71]
	v_mfma_f32_16x16x32_bf16 v[124:127], v[152:155], v[168:171], v[124:127]
	v_mfma_f32_16x16x32_bf16 v[116:119], v[160:163], v[168:171], v[116:119]
	v_mfma_f32_16x16x32_bf16 v[108:111], v[152:155], v[176:179], v[108:111]
	v_mfma_f32_16x16x32_bf16 v[100:103], v[160:163], v[176:179], v[100:103]
	v_mfma_f32_16x16x32_bf16 v[92:95], v[152:155], v[184:187], v[92:95]
	v_mfma_f32_16x16x32_bf16 v[84:87], v[160:163], v[184:187], v[84:87]
	v_mfma_f32_16x16x32_bf16 v[76:79], v[152:155], v[192:195], v[76:79]
	v_mfma_f32_16x16x32_bf16 v[68:71], v[160:163], v[192:195], v[68:71]
	s_barrier
	s_mov_b32 m0, s35
	v_lshl_add_u64 v[140:141], s[12:13], 0, v[130:131]
	ds_read_b128 v[196:199], v144
	ds_read_b128 v[200:203], v144 offset:1024
	ds_read_b128 v[208:211], v144 offset:2048
	ds_read_b128 v[212:215], v144 offset:3072
	global_load_lds_dwordx4 v[140:141], off
	v_lshl_add_u64 v[204:205], s[12:13], 0, v[128:129]
	s_mov_b32 m0, s36
	s_nop 0
	global_load_lds_dwordx4 v[204:205], off
	s_barrier
	s_waitcnt lgkmcnt(0)
	v_mfma_f32_16x16x32_bf16 v[120:123], v[196:199], v[164:167], v[120:123]
	v_mfma_f32_16x16x32_bf16 v[112:115], v[208:211], v[164:167], v[112:115]
	v_mfma_f32_16x16x32_bf16 v[104:107], v[196:199], v[172:175], v[104:107]
	v_mfma_f32_16x16x32_bf16 v[96:99], v[208:211], v[172:175], v[96:99]
	v_mfma_f32_16x16x32_bf16 v[88:91], v[196:199], v[180:183], v[88:91]
	v_mfma_f32_16x16x32_bf16 v[80:83], v[208:211], v[180:183], v[80:83]
	v_mfma_f32_16x16x32_bf16 v[72:75], v[196:199], v[188:191], v[72:75]
	v_mfma_f32_16x16x32_bf16 v[64:67], v[208:211], v[188:191], v[64:67]
	v_mfma_f32_16x16x32_bf16 v[120:123], v[200:203], v[168:171], v[120:123]
	v_mfma_f32_16x16x32_bf16 v[112:115], v[212:215], v[168:171], v[112:115]
	v_mfma_f32_16x16x32_bf16 v[104:107], v[200:203], v[176:179], v[104:107]
	v_mfma_f32_16x16x32_bf16 v[96:99], v[212:215], v[176:179], v[96:99]
	v_mfma_f32_16x16x32_bf16 v[88:91], v[200:203], v[184:187], v[88:91]
	v_mfma_f32_16x16x32_bf16 v[80:83], v[212:215], v[184:187], v[80:83]
	v_mfma_f32_16x16x32_bf16 v[72:75], v[200:203], v[192:195], v[72:75]
	v_mfma_f32_16x16x32_bf16 v[64:67], v[212:215], v[192:195], v[64:67]
	s_mov_b32 m0, s3
	v_lshl_add_u64 v[216:217], s[14:15], 0, v[130:131]
	s_barrier
	ds_read_b128 v[164:167], v143 offset:16384
	ds_read_b128 v[168:171], v143 offset:17408
	ds_read_b128 v[172:175], v143 offset:18432
	ds_read_b128 v[176:179], v143 offset:19456
	ds_read_b128 v[180:183], v143 offset:20480
	ds_read_b128 v[184:187], v143 offset:21504
	ds_read_b128 v[188:191], v143 offset:22528
	ds_read_b128 v[192:195], v143 offset:23552
	global_load_lds_dwordx4 v[216:217], off
	v_lshl_add_u64 v[218:219], s[14:15], 0, v[128:129]
	s_mov_b32 m0, s16
	s_nop 0
	global_load_lds_dwordx4 v[218:219], off
	s_barrier
	s_waitcnt lgkmcnt(0)
	v_mfma_f32_16x16x32_bf16 v[60:63], v[148:151], v[164:167], v[60:63]
	v_mfma_f32_16x16x32_bf16 v[52:55], v[156:159], v[164:167], v[52:55]
	v_mfma_f32_16x16x32_bf16 v[44:47], v[148:151], v[172:175], v[44:47]
	v_mfma_f32_16x16x32_bf16 v[36:39], v[156:159], v[172:175], v[36:39]
	v_mfma_f32_16x16x32_bf16 v[28:31], v[148:151], v[180:183], v[28:31]
	v_mfma_f32_16x16x32_bf16 v[20:23], v[156:159], v[180:183], v[20:23]
	v_mfma_f32_16x16x32_bf16 v[12:15], v[148:151], v[188:191], v[12:15]
	v_mfma_f32_16x16x32_bf16 v[4:7], v[156:159], v[188:191], v[4:7]
	v_mfma_f32_16x16x32_bf16 v[60:63], v[152:155], v[168:171], v[60:63]
	v_mfma_f32_16x16x32_bf16 v[52:55], v[160:163], v[168:171], v[52:55]
	v_mfma_f32_16x16x32_bf16 v[44:47], v[152:155], v[176:179], v[44:47]
	v_mfma_f32_16x16x32_bf16 v[36:39], v[160:163], v[176:179], v[36:39]
	v_mfma_f32_16x16x32_bf16 v[28:31], v[152:155], v[184:187], v[28:31]
	v_mfma_f32_16x16x32_bf16 v[20:23], v[160:163], v[184:187], v[20:23]
	v_mfma_f32_16x16x32_bf16 v[12:15], v[152:155], v[192:195], v[12:15]
	v_mfma_f32_16x16x32_bf16 v[4:7], v[160:163], v[192:195], v[4:7]
	s_barrier
	s_add_u32 s60, s12, 0x80000
	s_addc_u32 s61, s13, 0
	s_mov_b32 m0, s37
	v_lshl_add_u64 v[148:149], s[60:61], 0, v[130:131]
	global_load_lds_dwordx4 v[148:149], off
	v_lshl_add_u64 v[148:149], s[60:61], 0, v[128:129]
	s_mov_b32 m0, s38
	s_nop 0
	global_load_lds_dwordx4 v[148:149], off
	s_waitcnt vmcnt(6)
	s_barrier
; #define WAIT_V(n) asm volatile("s_waitcnt vmcnt(" #n ")" ::: "memory")
; #define WAIT_L(n) asm volatile("s_waitcnt lgkmcnt(" #n ")" ::: "memory")
; #define BAR __builtin_amdgcn_s_barrier()
; #define SCHED __builtin_amdgcn_sched_barrier(0)
; template <class Get, class Epi>
; DI void gemm_stream(LAS unsigned char* lds, const int K, const int ld, Get get, Epi epi) {
;     ...
;             STAGE(SBo(0, 1), b2 + hstep);
;             WAIT_V(6); BAR; MMA(1, 1, At, B1); BAR;
;             LDB(B0, 1, 0); SCHED; LDA(At, 1, 0); STAGE(SAo(0, 1), a2 + hstep);
;             WAIT_L(8); BAR; WAIT_L(0); MMA(0, 0, At, B0); BAR; SCHED;
;             LDB(B1, 1, 1); STAGE(SBo(1, 0), b3);
;             BAR; WAIT_L(0); MMA(0, 1, At, B1); BAR;
;             LDA(At, 1, 1); STAGE(SAo(1, 0), a3);
;             BAR; WAIT_L(0); MMA(1, 0, At, B0); BAR; SCHED;
	v_mfma_f32_16x16x32_bf16 v[56:59], v[196:199], v[164:167], v[56:59]
	v_mfma_f32_16x16x32_bf16 v[48:51], v[208:211], v[164:167], v[48:51]
	v_mfma_f32_16x16x32_bf16 v[40:43], v[196:199], v[172:175], v[40:43]
	v_mfma_f32_16x16x32_bf16 v[32:35], v[208:211], v[172:175], v[32:35]
	v_mfma_f32_16x16x32_bf16 v[24:27], v[196:199], v[180:183], v[24:27]
	v_mfma_f32_16x16x32_bf16 v[16:19], v[208:211], v[180:183], v[16:19]
	v_mfma_f32_16x16x32_bf16 v[8:11], v[196:199], v[188:191], v[8:11]
	v_mfma_f32_16x16x32_bf16 v[0:3], v[208:211], v[188:191], v[0:3]
	v_mfma_f32_16x16x32_bf16 v[56:59], v[200:203], v[168:171], v[56:59]
	v_mfma_f32_16x16x32_bf16 v[48:51], v[212:215], v[168:171], v[48:51]
	v_mfma_f32_16x16x32_bf16 v[40:43], v[200:203], v[176:179], v[40:43]
	v_mfma_f32_16x16x32_bf16 v[32:35], v[212:215], v[176:179], v[32:35]
	v_mfma_f32_16x16x32_bf16 v[24:27], v[200:203], v[184:187], v[24:27]
	v_mfma_f32_16x16x32_bf16 v[16:19], v[212:215], v[184:187], v[16:19]
	v_mfma_f32_16x16x32_bf16 v[8:11], v[200:203], v[192:195], v[8:11]
	v_mfma_f32_16x16x32_bf16 v[0:3], v[212:215], v[192:195], v[0:3]
	s_barrier
	ds_read_b128 v[148:151], v145
	ds_read_b128 v[152:155], v145 offset:1024
	ds_read_b128 v[156:159], v145 offset:2048
	ds_read_b128 v[160:163], v145 offset:3072
	s_add_u32 s14, s14, 0x80000
	s_addc_u32 s15, s15, 0
	s_mov_b32 m0, s17
	v_lshl_add_u64 v[196:197], s[14:15], 0, v[130:131]
	ds_read_b128 v[164:167], v143 offset:32768
	ds_read_b128 v[168:171], v143 offset:33792
	ds_read_b128 v[172:175], v143 offset:34816
	ds_read_b128 v[176:179], v143 offset:35840
	ds_read_b128 v[180:183], v143 offset:36864
	ds_read_b128 v[184:187], v143 offset:37888
	ds_read_b128 v[188:191], v143 offset:38912
	ds_read_b128 v[192:195], v143 offset:39936
	global_load_lds_dwordx4 v[196:197], off
	v_lshl_add_u64 v[196:197], s[14:15], 0, v[128:129]
	s_mov_b32 m0, s18
	s_nop 0
	global_load_lds_dwordx4 v[196:197], off
	s_waitcnt lgkmcnt(8)
	s_barrier
	s_waitcnt lgkmcnt(0)
	v_mfma_f32_16x16x32_bf16 v[124:127], v[148:151], v[164:167], v[124:127]
	v_mfma_f32_16x16x32_bf16 v[116:119], v[156:159], v[164:167], v[116:119]
	v_mfma_f32_16x16x32_bf16 v[108:111], v[148:151], v[172:175], v[108:111]
	v_mfma_f32_16x16x32_bf16 v[100:103], v[156:159], v[172:175], v[100:103]
	v_mfma_f32_16x16x32_bf16 v[92:95], v[148:151], v[180:183], v[92:95]
	v_mfma_f32_16x16x32_bf16 v[84:87], v[156:159], v[180:183], v[84:87]
	v_mfma_f32_16x16x32_bf16 v[76:79], v[148:151], v[188:191], v[76:79]
	v_mfma_f32_16x16x32_bf16 v[68:71], v[156:159], v[188:191], v[68:71]
	v_mfma_f32_16x16x32_bf16 v[124:127], v[152:155], v[168:171], v[124:127]
	v_mfma_f32_16x16x32_bf16 v[116:119], v[160:163], v[168:171], v[116:119]
	v_mfma_f32_16x16x32_bf16 v[108:111], v[152:155], v[176:179], v[108:111]
	v_mfma_f32_16x16x32_bf16 v[100:103], v[160:163], v[176:179], v[100:103]
	v_mfma_f32_16x16x32_bf16 v[92:95], v[152:155], v[184:187], v[92:95]
	v_mfma_f32_16x16x32_bf16 v[84:87], v[160:163], v[184:187], v[84:87]
	v_mfma_f32_16x16x32_bf16 v[76:79], v[152:155], v[192:195], v[76:79]
	v_mfma_f32_16x16x32_bf16 v[68:71], v[160:163], v[192:195], v[68:71]
	s_barrier
	s_mov_b32 m0, s39
	v_lshl_add_u64 v[140:141], v[140:141], 0, s[0:1]
	ds_read_b128 v[196:199], v146
	ds_read_b128 v[200:203], v146 offset:1024
	ds_read_b128 v[208:211], v146 offset:2048
	ds_read_b128 v[212:215], v146 offset:3072
	global_load_lds_dwordx4 v[140:141], off
	v_lshl_add_u64 v[140:141], v[204:205], 0, s[0:1]
	s_mov_b32 m0, s40
	s_nop 0
	global_load_lds_dwordx4 v[140:141], off
	s_barrier
	s_waitcnt lgkmcnt(0)
	v_mfma_f32_16x16x32_bf16 v[120:123], v[196:199], v[164:167], v[120:123]
	v_mfma_f32_16x16x32_bf16 v[112:115], v[208:211], v[164:167], v[112:115]
	v_mfma_f32_16x16x32_bf16 v[104:107], v[196:199], v[172:175], v[104:107]
	v_mfma_f32_16x16x32_bf16 v[96:99], v[208:211], v[172:175], v[96:99]
	v_mfma_f32_16x16x32_bf16 v[88:91], v[196:199], v[180:183], v[88:91]
	v_mfma_f32_16x16x32_bf16 v[80:83], v[208:211], v[180:183], v[80:83]
	v_mfma_f32_16x16x32_bf16 v[72:75], v[196:199], v[188:191], v[72:75]
	v_mfma_f32_16x16x32_bf16 v[64:67], v[208:211], v[188:191], v[64:67]
	v_mfma_f32_16x16x32_bf16 v[120:123], v[200:203], v[168:171], v[120:123]
	v_mfma_f32_16x16x32_bf16 v[112:115], v[212:215], v[168:171], v[112:115]
	v_mfma_f32_16x16x32_bf16 v[104:107], v[200:203], v[176:179], v[104:107]
	v_mfma_f32_16x16x32_bf16 v[96:99], v[212:215], v[176:179], v[96:99]
	v_mfma_f32_16x16x32_bf16 v[88:91], v[200:203], v[184:187], v[88:91]
	v_mfma_f32_16x16x32_bf16 v[80:83], v[212:215], v[184:187], v[80:83]
	v_mfma_f32_16x16x32_bf16 v[72:75], v[200:203], v[192:195], v[72:75]
	v_mfma_f32_16x16x32_bf16 v[64:67], v[212:215], v[192:195], v[64:67]
	s_mov_b32 m0, s20
	v_lshl_add_u64 v[140:141], v[216:217], 0, s[0:1]
	s_barrier
	ds_read_b128 v[164:167], v143 offset:49152
	ds_read_b128 v[168:171], v143 offset:50176
	ds_read_b128 v[172:175], v143 offset:51200
	ds_read_b128 v[176:179], v143 offset:52224
	ds_read_b128 v[180:183], v143 offset:53248
	ds_read_b128 v[184:187], v143 offset:54272
	ds_read_b128 v[188:191], v143 offset:55296
	ds_read_b128 v[192:195], v143 offset:56320
	global_load_lds_dwordx4 v[140:141], off
	v_lshl_add_u64 v[140:141], v[218:219], 0, s[0:1]
	s_mov_b32 m0, s21
	s_nop 0
	global_load_lds_dwordx4 v[140:141], off
	s_barrier
; #define WAIT_V(n) asm volatile("s_waitcnt vmcnt(" #n ")" ::: "memory")
; #define WAIT_L(n) asm volatile("s_waitcnt lgkmcnt(" #n ")" ::: "memory")
; #define BAR __builtin_amdgcn_s_barrier()
; #define SCHED __builtin_amdgcn_sched_barrier(0)
; DI float silu_f(float g) { return g * __builtin_amdgcn_rcpf(1.f + __builtin_amdgcn_exp2f(-LOG2E * g)); }
; template <class Get, class Epi>
; DI void gemm_stream(LAS unsigned char* lds, const int K, const int ld, Get get, Epi epi) {
;     ...
;             BAR; WAIT_L(0); MMA(1, 0, At, B0); BAR; SCHED;
;             STAGE(SBo(1, 1), b3 + hstep);
;             WAIT_V(6); BAR; MMA(1, 1, At, B1); BAR;
;         }
;         epi(acc, cur);
; DI void epi_swiglu(const Acc& acc, int brow, int pn, bf16_t* hid) {
;     ...
;     for (int ai = 0; ai < 2; ++ai)
; #pragma unroll
;         for (int m = 0; m < 4; ++m) {
;             const int r = brow + ai * 128 + wr * 64 + m * 16 + fr;
;             bf16_t* rp = hid + (size_t)r * FF + pn * 128 + wc * 32 + fq * 4;
; #pragma unroll
;             for (int n = 0; n < 2; ++n) {
;                 const f32x4 g = acc[ai][0][m][n], u = acc[ai][1][m][n];
;                 float o[4];
; #pragma unroll
;                 for (int j = 0; j < 4; ++j) o[j] = silu_f(g[j]) * u[j];
;                 st4(rp + n * 16, o[0], o[1], o[2], o[3]);
;             }
	s_waitcnt lgkmcnt(0)
	v_mfma_f32_16x16x32_bf16 v[60:63], v[148:151], v[164:167], v[60:63]
	v_mfma_f32_16x16x32_bf16 v[52:55], v[156:159], v[164:167], v[52:55]
	v_mfma_f32_16x16x32_bf16 v[44:47], v[148:151], v[172:175], v[44:47]
	v_mfma_f32_16x16x32_bf16 v[36:39], v[156:159], v[172:175], v[36:39]
	v_mfma_f32_16x16x32_bf16 v[28:31], v[148:151], v[180:183], v[28:31]
	v_mfma_f32_16x16x32_bf16 v[20:23], v[156:159], v[180:183], v[20:23]
	v_mfma_f32_16x16x32_bf16 v[12:15], v[148:151], v[188:191], v[12:15]
	v_mfma_f32_16x16x32_bf16 v[4:7], v[156:159], v[188:191], v[4:7]
	v_mfma_f32_16x16x32_bf16 v[60:63], v[152:155], v[168:171], v[60:63]
	v_mfma_f32_16x16x32_bf16 v[52:55], v[160:163], v[168:171], v[52:55]
	v_mfma_f32_16x16x32_bf16 v[44:47], v[152:155], v[176:179], v[44:47]
	v_mfma_f32_16x16x32_bf16 v[36:39], v[160:163], v[176:179], v[36:39]
	v_mfma_f32_16x16x32_bf16 v[28:31], v[152:155], v[184:187], v[28:31]
	v_mfma_f32_16x16x32_bf16 v[20:23], v[160:163], v[184:187], v[20:23]
	v_mfma_f32_16x16x32_bf16 v[12:15], v[152:155], v[192:195], v[12:15]
	v_mfma_f32_16x16x32_bf16 v[4:7], v[160:163], v[192:195], v[4:7]
	s_barrier
	s_add_u32 s12, s12, 0x80080
	s_addc_u32 s13, s13, 0
	s_mov_b32 m0, s41
	v_lshl_add_u64 v[140:141], s[12:13], 0, v[130:131]
	global_load_lds_dwordx4 v[140:141], off
	v_lshl_add_u64 v[140:141], s[12:13], 0, v[128:129]
	s_mov_b32 m0, s52
	s_nop 0
	global_load_lds_dwordx4 v[140:141], off
	s_waitcnt vmcnt(6)
	s_barrier
	v_mfma_f32_16x16x32_bf16 v[56:59], v[196:199], v[164:167], v[56:59]
	v_mfma_f32_16x16x32_bf16 v[48:51], v[208:211], v[164:167], v[48:51]
	v_mfma_f32_16x16x32_bf16 v[40:43], v[196:199], v[172:175], v[40:43]
	v_mfma_f32_16x16x32_bf16 v[32:35], v[208:211], v[172:175], v[32:35]
	v_mfma_f32_16x16x32_bf16 v[24:27], v[196:199], v[180:183], v[24:27]
	v_mfma_f32_16x16x32_bf16 v[16:19], v[208:211], v[180:183], v[16:19]
	v_mfma_f32_16x16x32_bf16 v[8:11], v[196:199], v[188:191], v[8:11]
	v_mfma_f32_16x16x32_bf16 v[0:3], v[208:211], v[188:191], v[0:3]
	v_mfma_f32_16x16x32_bf16 v[56:59], v[200:203], v[168:171], v[56:59]
	v_mfma_f32_16x16x32_bf16 v[48:51], v[212:215], v[168:171], v[48:51]
	v_mfma_f32_16x16x32_bf16 v[40:43], v[200:203], v[176:179], v[40:43]
	v_mfma_f32_16x16x32_bf16 v[32:35], v[212:215], v[176:179], v[32:35]
	v_mfma_f32_16x16x32_bf16 v[24:27], v[200:203], v[184:187], v[24:27]
	v_mfma_f32_16x16x32_bf16 v[16:19], v[212:215], v[184:187], v[16:19]
	v_mfma_f32_16x16x32_bf16 v[8:11], v[200:203], v[192:195], v[8:11]
	v_mfma_f32_16x16x32_bf16 v[0:3], v[212:215], v[192:195], v[0:3]
	s_add_i32 s59, s59, 2
	s_add_u32 s10, s10, 0x100
	s_addc_u32 s11, s11, 0
	s_add_u32 s57, s57, 0x100
	s_addc_u32 s58, s58, 0
	s_cmp_gt_u32 s59, 29
	s_barrier
	s_cbranch_scc0 .LBB0_1630
	s_lshl_b32 s10, s55, 8
	v_mov_b32_e32 v132, v206
	v_mul_f32_e32 v149, 0xbfb8aa3b, v125
	v_and_or_b32 v141, v132, 15, s10
	s_lshl_b32 s10, s56, 7
	s_ashr_i32 s11, s10, 31
	s_lshl_b64 s[10:11], s[10:11], 1
	v_ashrrev_i32_e32 v140, 2, v132
	s_add_u32 s10, s80, s10
	v_and_b32_e32 v140, 0xffffffc0, v140
	s_addc_u32 s11, s81, s11
	v_lshrrev_b32_e32 v148, 1, v132
	v_and_b32_e32 v132, 0xc0, v132
	v_add_u32_e32 v147, v141, v140
	v_lshl_add_u64 v[140:141], s[10:11], 0, v[132:133]
	v_and_b32_e32 v132, 24, v148
	v_mul_f32_e32 v148, 0xbfb8aa3b, v124
	v_exp_f32_e32 v148, v148
	v_exp_f32_e32 v149, v149
	v_lshl_add_u64 v[140:141], v[140:141], 0, v[132:133]
	v_mad_i64_i32 v[152:153], s[10:11], v147, s23, v[140:141]
	v_add_f32_e32 v132, 1.0, v148
	v_rcp_f32_e32 v148, v132
	v_add_f32_e32 v132, 1.0, v149
	v_mul_f32_e32 v149, 0xbfb8aa3b, v126
	v_exp_f32_e32 v150, v149
	v_mul_f32_e32 v149, 0xbfb8aa3b, v127
	v_exp_f32_e32 v151, v149
	v_rcp_f32_e32 v149, v132
	v_add_f32_e32 v132, 1.0, v150
	v_rcp_f32_e32 v150, v132
	v_add_f32_e32 v132, 1.0, v151
	v_rcp_f32_e32 v151, v132
	v_pk_mul_f32 v[124:125], v[124:125], v[148:149]
	s_and_b64 vcc, exec, s[4:5]
	v_pk_mul_f32 v[120:121], v[124:125], v[120:121]
	v_pk_mul_f32 v[124:125], v[126:127], v[150:151]
	v_cvt_pk_bf16_f32 v120, v120, v121
	v_mul_f32_e32 v121, 0xbfb8aa3b, v116
	v_pk_mul_f32 v[122:123], v[124:125], v[122:123]
	v_exp_f32_e32 v124, v121
	v_mul_f32_e32 v121, 0xbfb8aa3b, v117
	v_exp_f32_e32 v125, v121
	v_cvt_pk_bf16_f32 v121, v122, v123
	v_add_f32_e32 v122, 1.0, v124
	v_mul_f32_e32 v124, 0xbfb8aa3b, v118
	v_add_f32_e32 v123, 1.0, v125
	v_mul_f32_e32 v125, 0xbfb8aa3b, v119
	v_exp_f32_e32 v124, v124
	v_exp_f32_e32 v125, v125
	v_rcp_f32_e32 v122, v122
	v_rcp_f32_e32 v123, v123
	v_add_f32_e32 v124, 1.0, v124
	v_add_f32_e32 v125, 1.0, v125
	v_rcp_f32_e32 v124, v124
	v_rcp_f32_e32 v125, v125
	v_pk_mul_f32 v[116:117], v[116:117], v[122:123]
	s_mov_b32 s56, s53
	v_pk_mul_f32 v[112:113], v[116:117], v[112:113]
	v_pk_mul_f32 v[116:117], v[118:119], v[124:125]
	v_cvt_pk_bf16_f32 v112, v112, v113
	v_pk_mul_f32 v[114:115], v[116:117], v[114:115]
	v_or_b32_e32 v116, 16, v147
	v_cvt_pk_bf16_f32 v113, v114, v115
	global_store_dwordx2 v[152:153], v[112:113], off offset:32
	v_mul_f32_e32 v112, 0xbfb8aa3b, v108
	v_mul_f32_e32 v113, 0xbfb8aa3b, v109
	v_exp_f32_e32 v112, v112
	v_exp_f32_e32 v113, v113
	v_mul_f32_e32 v114, 0xbfb8aa3b, v110
	v_mul_f32_e32 v115, 0xbfb8aa3b, v111
	v_exp_f32_e32 v114, v114
	v_exp_f32_e32 v115, v115
	v_add_f32_e32 v112, 1.0, v112
	v_add_f32_e32 v113, 1.0, v113
	v_rcp_f32_e32 v112, v112
	v_rcp_f32_e32 v113, v113
	v_add_f32_e32 v114, 1.0, v114
	v_add_f32_e32 v115, 1.0, v115
	v_rcp_f32_e32 v114, v114
	v_rcp_f32_e32 v115, v115
	v_pk_mul_f32 v[108:109], v[108:109], v[112:113]
	v_mad_i64_i32 v[116:117], s[10:11], v116, s23, v[140:141]
	v_pk_mul_f32 v[104:105], v[108:109], v[104:105]
	v_pk_mul_f32 v[108:109], v[110:111], v[114:115]
; DI float silu_f(float g) { return g * __builtin_amdgcn_rcpf(1.f + __builtin_amdgcn_exp2f(-LOG2E * g)); }
; DI void epi_swiglu(const Acc& acc, int brow, int pn, bf16_t* hid) {
;     ...
;     for (int ai = 0; ai < 2; ++ai)
; #pragma unroll
;         for (int m = 0; m < 4; ++m) {
;             const int r = brow + ai * 128 + wr * 64 + m * 16 + fr;
;             bf16_t* rp = hid + (size_t)r * FF + pn * 128 + wc * 32 + fq * 4;
; #pragma unroll
;             for (int n = 0; n < 2; ++n) {
;                 const f32x4 g = acc[ai][0][m][n], u = acc[ai][1][m][n];
;                 float o[4];
; #pragma unroll
;                 for (int j = 0; j < 4; ++j) o[j] = silu_f(g[j]) * u[j];
;                 st4(rp + n * 16, o[0], o[1], o[2], o[3]);
;             }
	v_cvt_pk_bf16_f32 v104, v104, v105
	v_mul_f32_e32 v105, 0xbfb8aa3b, v100
	v_pk_mul_f32 v[106:107], v[108:109], v[106:107]
	v_exp_f32_e32 v108, v105
	v_mul_f32_e32 v105, 0xbfb8aa3b, v101
	v_exp_f32_e32 v109, v105
	v_cvt_pk_bf16_f32 v105, v106, v107
	v_add_f32_e32 v106, 1.0, v108
	v_mul_f32_e32 v108, 0xbfb8aa3b, v102
	v_add_f32_e32 v107, 1.0, v109
	v_mul_f32_e32 v109, 0xbfb8aa3b, v103
	v_exp_f32_e32 v108, v108
	v_exp_f32_e32 v109, v109
	v_rcp_f32_e32 v106, v106
	v_rcp_f32_e32 v107, v107
	v_add_f32_e32 v108, 1.0, v108
	v_add_f32_e32 v109, 1.0, v109
	v_rcp_f32_e32 v108, v108
	v_rcp_f32_e32 v109, v109
	v_pk_mul_f32 v[100:101], v[100:101], v[106:107]
	s_mov_b32 s55, s54
	v_pk_mul_f32 v[96:97], v[100:101], v[96:97]
	v_pk_mul_f32 v[100:101], v[102:103], v[108:109]
	v_cvt_pk_bf16_f32 v96, v96, v97
	v_pk_mul_f32 v[98:99], v[100:101], v[98:99]
	v_or_b32_e32 v100, 32, v147
	v_cvt_pk_bf16_f32 v97, v98, v99
	global_store_dwordx2 v[116:117], v[96:97], off offset:32
	v_mul_f32_e32 v96, 0xbfb8aa3b, v92
	v_mul_f32_e32 v97, 0xbfb8aa3b, v93
	v_exp_f32_e32 v96, v96
	v_exp_f32_e32 v97, v97
	v_mul_f32_e32 v98, 0xbfb8aa3b, v94
	v_mul_f32_e32 v99, 0xbfb8aa3b, v95
	v_exp_f32_e32 v98, v98
	v_exp_f32_e32 v99, v99
	v_add_f32_e32 v96, 1.0, v96
	v_add_f32_e32 v97, 1.0, v97
	v_rcp_f32_e32 v96, v96
	v_rcp_f32_e32 v97, v97
	v_add_f32_e32 v98, 1.0, v98
	v_add_f32_e32 v99, 1.0, v99
	v_rcp_f32_e32 v98, v98
	v_rcp_f32_e32 v99, v99
	v_pk_mul_f32 v[92:93], v[92:93], v[96:97]
	v_mad_i64_i32 v[100:101], s[10:11], v100, s23, v[140:141]
	v_pk_mul_f32 v[88:89], v[92:93], v[88:89]
	v_pk_mul_f32 v[92:93], v[94:95], v[98:99]
	v_cvt_pk_bf16_f32 v88, v88, v89
	v_mul_f32_e32 v89, 0xbfb8aa3b, v84
	v_pk_mul_f32 v[90:91], v[92:93], v[90:91]
	v_exp_f32_e32 v92, v89
	v_mul_f32_e32 v89, 0xbfb8aa3b, v85
	v_exp_f32_e32 v93, v89
	v_cvt_pk_bf16_f32 v89, v90, v91
	v_add_f32_e32 v90, 1.0, v92
	v_mul_f32_e32 v92, 0xbfb8aa3b, v86
	v_add_f32_e32 v91, 1.0, v93
	v_mul_f32_e32 v93, 0xbfb8aa3b, v87
	v_exp_f32_e32 v92, v92
	v_exp_f32_e32 v93, v93
	v_rcp_f32_e32 v90, v90
	v_rcp_f32_e32 v91, v91
	v_add_f32_e32 v92, 1.0, v92
	v_add_f32_e32 v93, 1.0, v93
	v_rcp_f32_e32 v92, v92
	v_rcp_f32_e32 v93, v93
	v_pk_mul_f32 v[84:85], v[84:85], v[90:91]
	s_mov_b64 s[12:13], s[8:9]
	v_pk_mul_f32 v[80:81], v[84:85], v[80:81]
	v_pk_mul_f32 v[84:85], v[86:87], v[92:93]
	v_cvt_pk_bf16_f32 v80, v80, v81
	v_pk_mul_f32 v[82:83], v[84:85], v[82:83]
	v_or_b32_e32 v84, 48, v147
	v_cvt_pk_bf16_f32 v81, v82, v83
	global_store_dwordx2 v[100:101], v[80:81], off offset:32
	v_mul_f32_e32 v80, 0xbfb8aa3b, v76
	v_mul_f32_e32 v81, 0xbfb8aa3b, v77
	v_exp_f32_e32 v80, v80
	v_exp_f32_e32 v81, v81
	v_mul_f32_e32 v82, 0xbfb8aa3b, v78
	v_mul_f32_e32 v83, 0xbfb8aa3b, v79
	v_exp_f32_e32 v82, v82
	v_exp_f32_e32 v83, v83
	v_add_f32_e32 v80, 1.0, v80
	v_add_f32_e32 v81, 1.0, v81
	v_rcp_f32_e32 v80, v80
	v_rcp_f32_e32 v81, v81
	v_add_f32_e32 v82, 1.0, v82
	v_add_f32_e32 v83, 1.0, v83
	v_rcp_f32_e32 v82, v82
	v_rcp_f32_e32 v83, v83
	v_pk_mul_f32 v[76:77], v[76:77], v[80:81]
	v_mad_i64_i32 v[84:85], s[10:11], v84, s23, v[140:141]
	v_pk_mul_f32 v[72:73], v[76:77], v[72:73]
	v_pk_mul_f32 v[76:77], v[78:79], v[82:83]
	v_cvt_pk_bf16_f32 v72, v72, v73
	v_mul_f32_e32 v73, 0xbfb8aa3b, v68
	v_pk_mul_f32 v[74:75], v[76:77], v[74:75]
	v_exp_f32_e32 v76, v73
	v_mul_f32_e32 v73, 0xbfb8aa3b, v69
	v_exp_f32_e32 v77, v73
	v_cvt_pk_bf16_f32 v73, v74, v75
	v_add_f32_e32 v74, 1.0, v76
	v_mul_f32_e32 v76, 0xbfb8aa3b, v70
	v_add_f32_e32 v75, 1.0, v77
	v_mul_f32_e32 v77, 0xbfb8aa3b, v71
	v_exp_f32_e32 v76, v76
	v_exp_f32_e32 v77, v77
	v_rcp_f32_e32 v74, v74
	v_rcp_f32_e32 v75, v75
	v_add_f32_e32 v76, 1.0, v76
	v_add_f32_e32 v77, 1.0, v77
	v_rcp_f32_e32 v76, v76
	v_rcp_f32_e32 v77, v77
	v_pk_mul_f32 v[68:69], v[68:69], v[74:75]
	global_store_dwordx2 v[152:153], v[120:121], off
	v_pk_mul_f32 v[64:65], v[68:69], v[64:65]
	v_pk_mul_f32 v[68:69], v[70:71], v[76:77]
	v_cvt_pk_bf16_f32 v64, v64, v65
	v_pk_mul_f32 v[66:67], v[68:69], v[66:67]
	v_add_u32_e32 v68, 0x80, v147
	v_cvt_pk_bf16_f32 v65, v66, v67
	global_store_dwordx2 v[84:85], v[64:65], off offset:32
	v_mul_f32_e32 v64, 0xbfb8aa3b, v60
	v_mul_f32_e32 v65, 0xbfb8aa3b, v61
	v_exp_f32_e32 v64, v64
	v_exp_f32_e32 v65, v65
	v_mul_f32_e32 v66, 0xbfb8aa3b, v62
	v_mul_f32_e32 v67, 0xbfb8aa3b, v63
	v_exp_f32_e32 v66, v66
	v_exp_f32_e32 v67, v67
	v_add_f32_e32 v64, 1.0, v64
	v_add_f32_e32 v65, 1.0, v65
	v_rcp_f32_e32 v64, v64
	v_rcp_f32_e32 v65, v65
	v_add_f32_e32 v66, 1.0, v66
	v_add_f32_e32 v67, 1.0, v67
	v_rcp_f32_e32 v66, v66
	v_rcp_f32_e32 v67, v67
	v_pk_mul_f32 v[60:61], v[60:61], v[64:65]
	v_mad_i64_i32 v[68:69], s[10:11], v68, s23, v[140:141]
	v_pk_mul_f32 v[56:57], v[60:61], v[56:57]
	v_pk_mul_f32 v[60:61], v[62:63], v[66:67]
	v_cvt_pk_bf16_f32 v56, v56, v57
	v_mul_f32_e32 v57, 0xbfb8aa3b, v52
	v_pk_mul_f32 v[58:59], v[60:61], v[58:59]
	v_exp_f32_e32 v60, v57
	v_mul_f32_e32 v57, 0xbfb8aa3b, v53
	v_exp_f32_e32 v61, v57
	v_cvt_pk_bf16_f32 v57, v58, v59
	v_add_f32_e32 v58, 1.0, v60
	v_mul_f32_e32 v60, 0xbfb8aa3b, v54
	v_add_f32_e32 v59, 1.0, v61
	v_mul_f32_e32 v61, 0xbfb8aa3b, v55
	v_exp_f32_e32 v60, v60
	v_exp_f32_e32 v61, v61
	v_rcp_f32_e32 v58, v58
	v_rcp_f32_e32 v59, v59
	v_add_f32_e32 v60, 1.0, v60
	v_add_f32_e32 v61, 1.0, v61
	v_rcp_f32_e32 v60, v60
	v_rcp_f32_e32 v61, v61
; DI float silu_f(float g) { return g * __builtin_amdgcn_rcpf(1.f + __builtin_amdgcn_exp2f(-LOG2E * g)); }
; DI void epi_swiglu(const Acc& acc, int brow, int pn, bf16_t* hid) {
;     ...
;     for (int ai = 0; ai < 2; ++ai)
; #pragma unroll
;         for (int m = 0; m < 4; ++m) {
;             const int r = brow + ai * 128 + wr * 64 + m * 16 + fr;
;             bf16_t* rp = hid + (size_t)r * FF + pn * 128 + wc * 32 + fq * 4;
; #pragma unroll
;             for (int n = 0; n < 2; ++n) {
;                 const f32x4 g = acc[ai][0][m][n], u = acc[ai][1][m][n];
;                 float o[4];
; #pragma unroll
;                 for (int j = 0; j < 4; ++j) o[j] = silu_f(g[j]) * u[j];
;                 st4(rp + n * 16, o[0], o[1], o[2], o[3]);
;             }
	v_pk_mul_f32 v[52:53], v[52:53], v[58:59]
	global_store_dwordx2 v[116:117], v[104:105], off
	v_pk_mul_f32 v[48:49], v[52:53], v[48:49]
	v_pk_mul_f32 v[52:53], v[54:55], v[60:61]
	v_cvt_pk_bf16_f32 v48, v48, v49
	v_pk_mul_f32 v[50:51], v[52:53], v[50:51]
	v_add_u32_e32 v52, 0x90, v147
	v_cvt_pk_bf16_f32 v49, v50, v51
	global_store_dwordx2 v[68:69], v[48:49], off offset:32
	v_mul_f32_e32 v48, 0xbfb8aa3b, v44
	v_mul_f32_e32 v49, 0xbfb8aa3b, v45
	v_exp_f32_e32 v48, v48
	v_exp_f32_e32 v49, v49
	v_mul_f32_e32 v50, 0xbfb8aa3b, v46
	v_mul_f32_e32 v51, 0xbfb8aa3b, v47
	v_exp_f32_e32 v50, v50
	v_exp_f32_e32 v51, v51
	v_add_f32_e32 v48, 1.0, v48
	v_add_f32_e32 v49, 1.0, v49
	v_rcp_f32_e32 v48, v48
	v_rcp_f32_e32 v49, v49
	v_add_f32_e32 v50, 1.0, v50
	v_add_f32_e32 v51, 1.0, v51
	v_rcp_f32_e32 v50, v50
	v_rcp_f32_e32 v51, v51
	v_pk_mul_f32 v[44:45], v[44:45], v[48:49]
	v_mad_i64_i32 v[52:53], s[10:11], v52, s23, v[140:141]
	v_pk_mul_f32 v[40:41], v[44:45], v[40:41]
	v_pk_mul_f32 v[44:45], v[46:47], v[50:51]
	v_cvt_pk_bf16_f32 v40, v40, v41
	v_mul_f32_e32 v41, 0xbfb8aa3b, v36
	v_pk_mul_f32 v[42:43], v[44:45], v[42:43]
	v_exp_f32_e32 v44, v41
	v_mul_f32_e32 v41, 0xbfb8aa3b, v37
	v_exp_f32_e32 v45, v41
	v_cvt_pk_bf16_f32 v41, v42, v43
	v_add_f32_e32 v42, 1.0, v44
	v_mul_f32_e32 v44, 0xbfb8aa3b, v38
	v_add_f32_e32 v43, 1.0, v45
	v_mul_f32_e32 v45, 0xbfb8aa3b, v39
	v_exp_f32_e32 v44, v44
	v_exp_f32_e32 v45, v45
	v_rcp_f32_e32 v42, v42
	v_rcp_f32_e32 v43, v43
	v_add_f32_e32 v44, 1.0, v44
	v_add_f32_e32 v45, 1.0, v45
	v_rcp_f32_e32 v44, v44
	v_rcp_f32_e32 v45, v45
	v_pk_mul_f32 v[36:37], v[36:37], v[42:43]
	global_store_dwordx2 v[100:101], v[88:89], off
	v_pk_mul_f32 v[32:33], v[36:37], v[32:33]
	v_pk_mul_f32 v[36:37], v[38:39], v[44:45]
	v_cvt_pk_bf16_f32 v32, v32, v33
	v_pk_mul_f32 v[34:35], v[36:37], v[34:35]
	v_add_u32_e32 v36, 0xa0, v147
	v_cvt_pk_bf16_f32 v33, v34, v35
	global_store_dwordx2 v[52:53], v[32:33], off offset:32
	v_mul_f32_e32 v32, 0xbfb8aa3b, v28
	v_mul_f32_e32 v33, 0xbfb8aa3b, v29
	v_exp_f32_e32 v32, v32
	v_exp_f32_e32 v33, v33
	v_mul_f32_e32 v34, 0xbfb8aa3b, v30
	v_mul_f32_e32 v35, 0xbfb8aa3b, v31
	v_exp_f32_e32 v34, v34
	v_exp_f32_e32 v35, v35
	v_add_f32_e32 v32, 1.0, v32
	v_add_f32_e32 v33, 1.0, v33
	v_rcp_f32_e32 v32, v32
	v_rcp_f32_e32 v33, v33
	v_add_f32_e32 v34, 1.0, v34
	v_add_f32_e32 v35, 1.0, v35
	v_rcp_f32_e32 v34, v34
	v_rcp_f32_e32 v35, v35
	v_pk_mul_f32 v[28:29], v[28:29], v[32:33]
	v_mad_i64_i32 v[36:37], s[10:11], v36, s23, v[140:141]
	v_pk_mul_f32 v[24:25], v[28:29], v[24:25]
	v_pk_mul_f32 v[28:29], v[30:31], v[34:35]
	v_cvt_pk_bf16_f32 v24, v24, v25
	v_mul_f32_e32 v25, 0xbfb8aa3b, v20
	v_pk_mul_f32 v[26:27], v[28:29], v[26:27]
	v_exp_f32_e32 v28, v25
	v_mul_f32_e32 v25, 0xbfb8aa3b, v21
	v_exp_f32_e32 v29, v25
	v_cvt_pk_bf16_f32 v25, v26, v27
	v_add_f32_e32 v26, 1.0, v28
	v_mul_f32_e32 v28, 0xbfb8aa3b, v22
	v_add_f32_e32 v27, 1.0, v29
	v_mul_f32_e32 v29, 0xbfb8aa3b, v23
	v_exp_f32_e32 v28, v28
	v_exp_f32_e32 v29, v29
	v_rcp_f32_e32 v26, v26
	v_rcp_f32_e32 v27, v27
	v_add_f32_e32 v28, 1.0, v28
	v_add_f32_e32 v29, 1.0, v29
	v_rcp_f32_e32 v28, v28
	v_rcp_f32_e32 v29, v29
	v_pk_mul_f32 v[20:21], v[20:21], v[26:27]
	global_store_dwordx2 v[84:85], v[72:73], off
	v_pk_mul_f32 v[16:17], v[20:21], v[16:17]
	v_pk_mul_f32 v[20:21], v[22:23], v[28:29]
	v_cvt_pk_bf16_f32 v16, v16, v17
	v_pk_mul_f32 v[18:19], v[20:21], v[18:19]
	v_add_u32_e32 v20, 0xb0, v147
	v_cvt_pk_bf16_f32 v17, v18, v19
	global_store_dwordx2 v[36:37], v[16:17], off offset:32
	v_mul_f32_e32 v16, 0xbfb8aa3b, v12
	v_mul_f32_e32 v17, 0xbfb8aa3b, v13
	v_exp_f32_e32 v16, v16
	v_exp_f32_e32 v17, v17
	v_mul_f32_e32 v18, 0xbfb8aa3b, v14
	v_mul_f32_e32 v19, 0xbfb8aa3b, v15
	v_exp_f32_e32 v18, v18
	v_exp_f32_e32 v19, v19
	v_add_f32_e32 v16, 1.0, v16
	v_add_f32_e32 v17, 1.0, v17
	v_rcp_f32_e32 v16, v16
	v_rcp_f32_e32 v17, v17
	v_add_f32_e32 v18, 1.0, v18
	v_add_f32_e32 v19, 1.0, v19
	v_rcp_f32_e32 v18, v18
	v_rcp_f32_e32 v19, v19
	v_pk_mul_f32 v[12:13], v[12:13], v[16:17]
	v_mad_i64_i32 v[20:21], s[10:11], v20, s23, v[140:141]
	v_pk_mul_f32 v[8:9], v[12:13], v[8:9]
	v_pk_mul_f32 v[12:13], v[14:15], v[18:19]
	v_cvt_pk_bf16_f32 v8, v8, v9
	v_mul_f32_e32 v9, 0xbfb8aa3b, v4
	v_pk_mul_f32 v[10:11], v[12:13], v[10:11]
	v_exp_f32_e32 v12, v9
	v_mul_f32_e32 v9, 0xbfb8aa3b, v5
	v_exp_f32_e32 v13, v9
	v_cvt_pk_bf16_f32 v9, v10, v11
	v_add_f32_e32 v10, 1.0, v12
	v_mul_f32_e32 v12, 0xbfb8aa3b, v6
	v_add_f32_e32 v11, 1.0, v13
	v_mul_f32_e32 v13, 0xbfb8aa3b, v7
	v_exp_f32_e32 v12, v12
	v_exp_f32_e32 v13, v13
	v_rcp_f32_e32 v10, v10
	v_rcp_f32_e32 v11, v11
	v_add_f32_e32 v12, 1.0, v12
	v_add_f32_e32 v13, 1.0, v13
	v_rcp_f32_e32 v12, v12
	v_rcp_f32_e32 v13, v13
	v_pk_mul_f32 v[4:5], v[4:5], v[10:11]
	s_mov_b64 s[10:11], s[6:7]
	v_pk_mul_f32 v[0:1], v[4:5], v[0:1]
	v_pk_mul_f32 v[4:5], v[6:7], v[12:13]
	v_cvt_pk_bf16_f32 v0, v0, v1
	v_pk_mul_f32 v[2:3], v[4:5], v[2:3]
	global_store_dwordx2 v[68:69], v[56:57], off
	v_cvt_pk_bf16_f32 v1, v2, v3
	global_store_dwordx2 v[52:53], v[40:41], off
	global_store_dwordx2 v[36:37], v[24:25], off
	global_store_dwordx2 v[20:21], v[8:9], off
	global_store_dwordx2 v[20:21], v[0:1], off offset:32
	s_cbranch_vccz .LBB0_1627
	s_waitcnt vmcnt(0)
	s_cmpk_gt_u32 s2, 0xff
	s_cbranch_scc1 .LBB0_1634
	s_barrier

; #define WAIT_V(n) asm volatile("s_waitcnt vmcnt(" #n ")" ::: "memory")
; #define WAIT_L(n) asm volatile("s_waitcnt lgkmcnt(" #n ")" ::: "memory")
; #define BAR __builtin_amdgcn_s_barrier()
; #define SCHED __builtin_amdgcn_sched_barrier(0)
; template <class Get, class Epi>
; DI void gemm_stream(LAS unsigned char* lds, const int K, const int ld, Get get, Epi epi) {
;     ...
;             LDB(B0, 0, 0); SCHED; LDA(At, 0, 0); STAGE(SAo(1, 1), a1 + hstep);
;             WAIT_L(8); BAR; WAIT_L(0); MMA(0, 0, At, B0); BAR; SCHED;
;             LDB(B1, 0, 1); STAGE(SBo(0, 0), b2);
;             BAR; WAIT_L(0); MMA(0, 1, At, B1); BAR;
;             LDA(At, 0, 1); STAGE(SAo(0, 0), a2);
;             BAR; WAIT_L(0); MMA(1, 0, At, B0); BAR; SCHED;
;             STAGE(SBo(0, 1), b2 + hstep);
;             WAIT_V(6); BAR; MMA(1, 1, At, B1); BAR;
;             LDB(B0, 1, 0); SCHED; LDA(At, 1, 0); STAGE(SAo(0, 1), a2 + hstep);
;             WAIT_L(8); BAR; WAIT_L(0); MMA(0, 0, At, B0); BAR; SCHED;
.LBB0_1697:
	ds_read_b128 v[128:131], v199
	ds_read_b128 v[132:135], v199 offset:1024
	ds_read_b128 v[136:139], v199 offset:2048
	ds_read_b128 v[140:143], v199 offset:3072
	s_add_u32 s8, s6, 0x100
	s_addc_u32 s9, s7, 0
	s_cmpk_eq_i32 s16, 0x54
	s_cselect_b32 s13, s39, s9
	s_cselect_b32 s12, s38, s8
	s_cselect_b32 s11, s41, s15
	s_cselect_b32 s10, s40, s14
	s_mov_b32 m0, s63
	v_lshl_add_u64 v[186:187], s[6:7], 0, v[168:169]
	ds_read_b128 v[144:147], v200
	ds_read_b128 v[148:151], v200 offset:1024
	ds_read_b128 v[152:155], v200 offset:2048
	ds_read_b128 v[156:159], v200 offset:3072
	ds_read_b128 v[160:163], v200 offset:4096
	ds_read_b128 v[174:177], v200 offset:5120
	ds_read_b128 v[178:181], v200 offset:6144
	ds_read_b128 v[182:185], v200 offset:7168
	global_load_lds_dwordx4 v[186:187], off
	v_lshl_add_u64 v[186:187], s[6:7], 0, v[170:171]
	s_mov_b32 m0, s74
	s_nop 0
	global_load_lds_dwordx4 v[186:187], off
	s_waitcnt lgkmcnt(8)
	s_barrier
	s_waitcnt lgkmcnt(0)
	v_mfma_f32_16x16x32_bf16 v[124:127], v[128:131], v[144:147], v[124:127]
	v_mfma_f32_16x16x32_bf16 v[92:95], v[136:139], v[144:147], v[92:95]
	v_mfma_f32_16x16x32_bf16 v[120:123], v[128:131], v[152:155], v[120:123]
	v_mfma_f32_16x16x32_bf16 v[88:91], v[136:139], v[152:155], v[88:91]
	v_mfma_f32_16x16x32_bf16 v[116:119], v[128:131], v[160:163], v[116:119]
	v_mfma_f32_16x16x32_bf16 v[84:87], v[136:139], v[160:163], v[84:87]
	v_mfma_f32_16x16x32_bf16 v[112:115], v[128:131], v[178:181], v[112:115]
	v_mfma_f32_16x16x32_bf16 v[80:83], v[136:139], v[178:181], v[80:83]
	v_mfma_f32_16x16x32_bf16 v[124:127], v[132:135], v[148:151], v[124:127]
	v_mfma_f32_16x16x32_bf16 v[92:95], v[140:143], v[148:151], v[92:95]
	v_mfma_f32_16x16x32_bf16 v[120:123], v[132:135], v[156:159], v[120:123]
	v_mfma_f32_16x16x32_bf16 v[88:91], v[140:143], v[156:159], v[88:91]
	v_mfma_f32_16x16x32_bf16 v[116:119], v[132:135], v[174:177], v[116:119]
	v_mfma_f32_16x16x32_bf16 v[84:87], v[140:143], v[174:177], v[84:87]
	v_mfma_f32_16x16x32_bf16 v[112:115], v[132:135], v[182:185], v[112:115]
	v_mfma_f32_16x16x32_bf16 v[80:83], v[140:143], v[182:185], v[80:83]
	s_barrier
	s_mov_b32 m0, s75
	v_lshl_add_u64 v[208:209], s[10:11], 0, v[164:165]
	ds_read_b128 v[186:189], v201
	ds_read_b128 v[190:193], v201 offset:1024
	ds_read_b128 v[194:197], v201 offset:2048
	ds_read_b128 v[202:205], v201 offset:3072
	global_load_lds_dwordx4 v[208:209], off
	v_lshl_add_u64 v[210:211], s[10:11], 0, v[166:167]
	s_mov_b32 m0, s76
	s_nop 0
	global_load_lds_dwordx4 v[210:211], off
	s_barrier
	s_waitcnt lgkmcnt(0)
	v_mfma_f32_16x16x32_bf16 v[60:63], v[186:189], v[144:147], v[60:63]
	v_mfma_f32_16x16x32_bf16 v[28:31], v[194:197], v[144:147], v[28:31]
	v_mfma_f32_16x16x32_bf16 v[56:59], v[186:189], v[152:155], v[56:59]
	v_mfma_f32_16x16x32_bf16 v[24:27], v[194:197], v[152:155], v[24:27]
	v_mfma_f32_16x16x32_bf16 v[52:55], v[186:189], v[160:163], v[52:55]
	v_mfma_f32_16x16x32_bf16 v[20:23], v[194:197], v[160:163], v[20:23]
	v_mfma_f32_16x16x32_bf16 v[48:51], v[186:189], v[178:181], v[48:51]
	v_mfma_f32_16x16x32_bf16 v[16:19], v[194:197], v[178:181], v[16:19]
	v_mfma_f32_16x16x32_bf16 v[60:63], v[190:193], v[148:151], v[60:63]
	v_mfma_f32_16x16x32_bf16 v[28:31], v[202:205], v[148:151], v[28:31]
	v_mfma_f32_16x16x32_bf16 v[56:59], v[190:193], v[156:159], v[56:59]
	v_mfma_f32_16x16x32_bf16 v[24:27], v[202:205], v[156:159], v[24:27]
	v_mfma_f32_16x16x32_bf16 v[52:55], v[190:193], v[174:177], v[52:55]
	v_mfma_f32_16x16x32_bf16 v[20:23], v[202:205], v[174:177], v[20:23]
	v_mfma_f32_16x16x32_bf16 v[48:51], v[190:193], v[182:185], v[48:51]
	v_mfma_f32_16x16x32_bf16 v[16:19], v[202:205], v[182:185], v[16:19]
	s_mov_b32 m0, s23
	v_lshl_add_u64 v[212:213], s[12:13], 0, v[164:165]
	s_barrier
	ds_read_b128 v[144:147], v200 offset:16384
	ds_read_b128 v[148:151], v200 offset:17408
	ds_read_b128 v[152:155], v200 offset:18432
	ds_read_b128 v[156:159], v200 offset:19456
	ds_read_b128 v[160:163], v200 offset:20480
	ds_read_b128 v[174:177], v200 offset:21504
	ds_read_b128 v[178:181], v200 offset:22528
	ds_read_b128 v[182:185], v200 offset:23552
	global_load_lds_dwordx4 v[212:213], off
	v_lshl_add_u64 v[214:215], s[12:13], 0, v[166:167]
	s_mov_b32 m0, s35
	s_nop 0
	global_load_lds_dwordx4 v[214:215], off
	s_barrier
	s_waitcnt lgkmcnt(0)
	v_mfma_f32_16x16x32_bf16 v[108:111], v[128:131], v[144:147], v[108:111]
	v_mfma_f32_16x16x32_bf16 v[76:79], v[136:139], v[144:147], v[76:79]
	v_mfma_f32_16x16x32_bf16 v[104:107], v[128:131], v[152:155], v[104:107]
	v_mfma_f32_16x16x32_bf16 v[72:75], v[136:139], v[152:155], v[72:75]
	v_mfma_f32_16x16x32_bf16 v[100:103], v[128:131], v[160:163], v[100:103]
	v_mfma_f32_16x16x32_bf16 v[68:71], v[136:139], v[160:163], v[68:71]
	v_mfma_f32_16x16x32_bf16 v[96:99], v[128:131], v[178:181], v[96:99]
	v_mfma_f32_16x16x32_bf16 v[64:67], v[136:139], v[178:181], v[64:67]
	v_mfma_f32_16x16x32_bf16 v[108:111], v[132:135], v[148:151], v[108:111]
	v_mfma_f32_16x16x32_bf16 v[76:79], v[140:143], v[148:151], v[76:79]
	v_mfma_f32_16x16x32_bf16 v[104:107], v[132:135], v[156:159], v[104:107]
	v_mfma_f32_16x16x32_bf16 v[72:75], v[140:143], v[156:159], v[72:75]
	v_mfma_f32_16x16x32_bf16 v[100:103], v[132:135], v[174:177], v[100:103]
	v_mfma_f32_16x16x32_bf16 v[68:71], v[140:143], v[174:177], v[68:71]
	v_mfma_f32_16x16x32_bf16 v[96:99], v[132:135], v[182:185], v[96:99]
	v_mfma_f32_16x16x32_bf16 v[64:67], v[140:143], v[182:185], v[64:67]
	s_barrier
	s_add_u32 s6, s10, 0x160000
	s_addc_u32 s7, s11, 0
	s_mov_b32 m0, s77
	v_lshl_add_u64 v[128:129], s[6:7], 0, v[164:165]
	global_load_lds_dwordx4 v[128:129], off
	v_lshl_add_u64 v[128:129], s[6:7], 0, v[166:167]
	s_mov_b32 m0, s78
	s_nop 0
	global_load_lds_dwordx4 v[128:129], off
	s_waitcnt vmcnt(6)
	s_barrier
; #define WAIT_V(n) asm volatile("s_waitcnt vmcnt(" #n ")" ::: "memory")
; #define WAIT_L(n) asm volatile("s_waitcnt lgkmcnt(" #n ")" ::: "memory")
; #define BAR __builtin_amdgcn_s_barrier()
; #define SCHED __builtin_amdgcn_sched_barrier(0)
; template <class Get, class Epi>
; DI void gemm_stream(LAS unsigned char* lds, const int K, const int ld, Get get, Epi epi) {
;     ...
;             STAGE(SBo(0, 1), b2 + hstep);
;             WAIT_V(6); BAR; MMA(1, 1, At, B1); BAR;
;             LDB(B0, 1, 0); SCHED; LDA(At, 1, 0); STAGE(SAo(0, 1), a2 + hstep);
;             WAIT_L(8); BAR; WAIT_L(0); MMA(0, 0, At, B0); BAR; SCHED;
;             LDB(B1, 1, 1); STAGE(SBo(1, 0), b3);
;             BAR; WAIT_L(0); MMA(0, 1, At, B1); BAR;
;             LDA(At, 1, 1); STAGE(SAo(1, 0), a3);
;             BAR; WAIT_L(0); MMA(1, 0, At, B0); BAR; SCHED;
	v_mfma_f32_16x16x32_bf16 v[44:47], v[186:189], v[144:147], v[44:47]
	v_mfma_f32_16x16x32_bf16 v[12:15], v[194:197], v[144:147], v[12:15]
	v_mfma_f32_16x16x32_bf16 v[40:43], v[186:189], v[152:155], v[40:43]
	v_mfma_f32_16x16x32_bf16 v[8:11], v[194:197], v[152:155], v[8:11]
	v_mfma_f32_16x16x32_bf16 v[36:39], v[186:189], v[160:163], v[36:39]
	v_mfma_f32_16x16x32_bf16 v[4:7], v[194:197], v[160:163], v[4:7]
	v_mfma_f32_16x16x32_bf16 v[32:35], v[186:189], v[178:181], v[32:35]
	v_mfma_f32_16x16x32_bf16 v[0:3], v[194:197], v[178:181], v[0:3]
	v_mfma_f32_16x16x32_bf16 v[44:47], v[190:193], v[148:151], v[44:47]
	v_mfma_f32_16x16x32_bf16 v[12:15], v[202:205], v[148:151], v[12:15]
	v_mfma_f32_16x16x32_bf16 v[40:43], v[190:193], v[156:159], v[40:43]
	v_mfma_f32_16x16x32_bf16 v[8:11], v[202:205], v[156:159], v[8:11]
	v_mfma_f32_16x16x32_bf16 v[36:39], v[190:193], v[174:177], v[36:39]
	v_mfma_f32_16x16x32_bf16 v[4:7], v[202:205], v[174:177], v[4:7]
	v_mfma_f32_16x16x32_bf16 v[32:35], v[190:193], v[182:185], v[32:35]
	v_mfma_f32_16x16x32_bf16 v[0:3], v[202:205], v[182:185], v[0:3]
	s_add_i32 s17, 16, 0x18000
	v_add_u32_e32 v140, s17, v198
	s_barrier
	ds_read_b128 v[128:131], v140
	ds_read_b128 v[132:135], v140 offset:1024
	ds_read_b128 v[136:139], v140 offset:2048
	ds_read_b128 v[140:143], v140 offset:3072
	s_add_u32 s6, s12, 0x160000
	s_addc_u32 s7, s13, 0
	s_mov_b32 m0, s54
	v_lshl_add_u64 v[186:187], s[6:7], 0, v[164:165]
	ds_read_b128 v[144:147], v200 offset:32768
	ds_read_b128 v[148:151], v200 offset:33792
	ds_read_b128 v[152:155], v200 offset:34816
	ds_read_b128 v[156:159], v200 offset:35840
	ds_read_b128 v[160:163], v200 offset:36864
	ds_read_b128 v[174:177], v200 offset:37888
	ds_read_b128 v[178:181], v200 offset:38912
	ds_read_b128 v[182:185], v200 offset:39936
	global_load_lds_dwordx4 v[186:187], off
	v_lshl_add_u64 v[186:187], s[6:7], 0, v[166:167]
	s_mov_b32 m0, s55
	s_nop 0
	global_load_lds_dwordx4 v[186:187], off
	s_waitcnt lgkmcnt(8)
	s_barrier
	s_waitcnt lgkmcnt(0)
	v_mfma_f32_16x16x32_bf16 v[124:127], v[128:131], v[144:147], v[124:127]
	v_mfma_f32_16x16x32_bf16 v[92:95], v[136:139], v[144:147], v[92:95]
	v_mfma_f32_16x16x32_bf16 v[120:123], v[128:131], v[152:155], v[120:123]
	v_mfma_f32_16x16x32_bf16 v[88:91], v[136:139], v[152:155], v[88:91]
	v_mfma_f32_16x16x32_bf16 v[116:119], v[128:131], v[160:163], v[116:119]
	v_mfma_f32_16x16x32_bf16 v[84:87], v[136:139], v[160:163], v[84:87]
	v_mfma_f32_16x16x32_bf16 v[112:115], v[128:131], v[178:181], v[112:115]
	v_mfma_f32_16x16x32_bf16 v[80:83], v[136:139], v[178:181], v[80:83]
	v_mfma_f32_16x16x32_bf16 v[124:127], v[132:135], v[148:151], v[124:127]
	v_mfma_f32_16x16x32_bf16 v[92:95], v[140:143], v[148:151], v[92:95]
	v_mfma_f32_16x16x32_bf16 v[120:123], v[132:135], v[156:159], v[120:123]
	v_mfma_f32_16x16x32_bf16 v[88:91], v[140:143], v[156:159], v[88:91]
	v_mfma_f32_16x16x32_bf16 v[116:119], v[132:135], v[174:177], v[116:119]
	v_mfma_f32_16x16x32_bf16 v[84:87], v[140:143], v[174:177], v[84:87]
	v_mfma_f32_16x16x32_bf16 v[112:115], v[132:135], v[182:185], v[112:115]
	v_mfma_f32_16x16x32_bf16 v[80:83], v[140:143], v[182:185], v[80:83]
	s_barrier
	s_add_i32 s12, 16, 0x1c000
	s_add_i32 s6, s17, s21
	v_add_u32_e32 v202, s12, v198
	v_lshl_add_u64 v[208:209], v[208:209], 0, s[0:1]
	s_mov_b32 m0, s6
	ds_read_b128 v[186:189], v202
	ds_read_b128 v[190:193], v202 offset:1024
	ds_read_b128 v[194:197], v202 offset:2048
	ds_read_b128 v[202:205], v202 offset:3072
	global_load_lds_dwordx4 v[208:209], off
	v_lshl_add_u64 v[208:209], v[210:211], 0, s[0:1]
	s_add_i32 m0, s6, 0x2000
	s_nop 0
	global_load_lds_dwordx4 v[208:209], off
	s_barrier
	s_waitcnt lgkmcnt(0)
	v_mfma_f32_16x16x32_bf16 v[60:63], v[186:189], v[144:147], v[60:63]
	v_mfma_f32_16x16x32_bf16 v[28:31], v[194:197], v[144:147], v[28:31]
	v_mfma_f32_16x16x32_bf16 v[56:59], v[186:189], v[152:155], v[56:59]
	v_mfma_f32_16x16x32_bf16 v[24:27], v[194:197], v[152:155], v[24:27]
	v_mfma_f32_16x16x32_bf16 v[52:55], v[186:189], v[160:163], v[52:55]
	v_mfma_f32_16x16x32_bf16 v[20:23], v[194:197], v[160:163], v[20:23]
	v_mfma_f32_16x16x32_bf16 v[48:51], v[186:189], v[178:181], v[48:51]
	v_mfma_f32_16x16x32_bf16 v[16:19], v[194:197], v[178:181], v[16:19]
	v_mfma_f32_16x16x32_bf16 v[60:63], v[190:193], v[148:151], v[60:63]
	v_mfma_f32_16x16x32_bf16 v[28:31], v[202:205], v[148:151], v[28:31]
	v_mfma_f32_16x16x32_bf16 v[56:59], v[190:193], v[156:159], v[56:59]
	v_mfma_f32_16x16x32_bf16 v[24:27], v[202:205], v[156:159], v[24:27]
	v_mfma_f32_16x16x32_bf16 v[52:55], v[190:193], v[174:177], v[52:55]
	v_mfma_f32_16x16x32_bf16 v[20:23], v[202:205], v[174:177], v[20:23]
	v_mfma_f32_16x16x32_bf16 v[48:51], v[190:193], v[182:185], v[48:51]
	v_mfma_f32_16x16x32_bf16 v[16:19], v[202:205], v[182:185], v[16:19]
	s_mov_b32 m0, s56
	v_lshl_add_u64 v[208:209], v[212:213], 0, s[0:1]
	s_barrier
	ds_read_b128 v[144:147], v200 offset:49152
	ds_read_b128 v[148:151], v200 offset:50176
	ds_read_b128 v[152:155], v200 offset:51200
	ds_read_b128 v[156:159], v200 offset:52224
	ds_read_b128 v[160:163], v200 offset:53248
	ds_read_b128 v[174:177], v200 offset:54272
	ds_read_b128 v[178:181], v200 offset:55296
	ds_read_b128 v[182:185], v200 offset:56320
	global_load_lds_dwordx4 v[208:209], off
	v_lshl_add_u64 v[208:209], v[214:215], 0, s[0:1]
	s_mov_b32 m0, s57
	s_nop 0
	global_load_lds_dwordx4 v[208:209], off
	s_barrier
; #define WAIT_V(n) asm volatile("s_waitcnt vmcnt(" #n ")" ::: "memory")
; #define WAIT_L(n) asm volatile("s_waitcnt lgkmcnt(" #n ")" ::: "memory")
; #define BAR __builtin_amdgcn_s_barrier()
; #define SCHED __builtin_amdgcn_sched_barrier(0)
; template <class Get, class Epi>
; DI void gemm_stream(LAS unsigned char* lds, const int K, const int ld, Get get, Epi epi) {
;     ...
;             BAR; WAIT_L(0); MMA(1, 0, At, B0); BAR; SCHED;
;             STAGE(SBo(1, 1), b3 + hstep);
;             WAIT_V(6); BAR; MMA(1, 1, At, B1); BAR;
;         }
;         epi(acc, cur);
; DI void epi_resid(const Acc& acc, const P& p, int brow, int bcol, int layer, int gch, bool from_input) {
;     EPI_IDX
;     const float* gate = modv(p, layer, brow, gch);
; #pragma unroll
;     for (int bj = 0; bj < 2; ++bj)
; #pragma unroll
;         for (int n = 0; n < 2; ++n) {
;             const int c0 = bcol + bj * 128 + wc * 32 + n * 16 + fq * 4;
;             const f32x4 g = *(const f32x4*)(gate + c0);
;             f32x4 xv[2][4];
; #pragma unroll
;             for (int ai = 0; ai < 2; ++ai)
; #pragma unroll
;                 for (int m = 0; m < 4; ++m) {
;                     const int r = brow + ai * 128 + wr * 64 + m * 16 + fr;
;                     const float* sp = (from_input ? inrow(p, r) : xrow(p, r)) + c0;
;                     xv[ai][m] = *(const f32x4*)sp;
;                 }
	s_waitcnt lgkmcnt(0)
	v_mfma_f32_16x16x32_bf16 v[108:111], v[128:131], v[144:147], v[108:111]
	v_mfma_f32_16x16x32_bf16 v[76:79], v[136:139], v[144:147], v[76:79]
	v_mfma_f32_16x16x32_bf16 v[104:107], v[128:131], v[152:155], v[104:107]
	v_mfma_f32_16x16x32_bf16 v[72:75], v[136:139], v[152:155], v[72:75]
	v_mfma_f32_16x16x32_bf16 v[100:103], v[128:131], v[160:163], v[100:103]
	v_mfma_f32_16x16x32_bf16 v[68:71], v[136:139], v[160:163], v[68:71]
	v_mfma_f32_16x16x32_bf16 v[96:99], v[128:131], v[178:181], v[96:99]
	v_mfma_f32_16x16x32_bf16 v[64:67], v[136:139], v[178:181], v[64:67]
	v_mfma_f32_16x16x32_bf16 v[108:111], v[132:135], v[148:151], v[108:111]
	v_mfma_f32_16x16x32_bf16 v[76:79], v[140:143], v[148:151], v[76:79]
	v_mfma_f32_16x16x32_bf16 v[104:107], v[132:135], v[156:159], v[104:107]
	v_mfma_f32_16x16x32_bf16 v[72:75], v[140:143], v[156:159], v[72:75]
	v_mfma_f32_16x16x32_bf16 v[100:103], v[132:135], v[174:177], v[100:103]
	v_mfma_f32_16x16x32_bf16 v[68:71], v[140:143], v[174:177], v[68:71]
	v_mfma_f32_16x16x32_bf16 v[96:99], v[132:135], v[182:185], v[96:99]
	v_mfma_f32_16x16x32_bf16 v[64:67], v[140:143], v[182:185], v[64:67]
	s_barrier
	s_add_u32 s6, s10, 0x160080
	s_addc_u32 s7, s11, 0
	s_add_i32 s10, s12, s21
	v_lshl_add_u64 v[128:129], s[6:7], 0, v[164:165]
	s_mov_b32 m0, s10
	s_nop 0
	global_load_lds_dwordx4 v[128:129], off
	v_lshl_add_u64 v[128:129], s[6:7], 0, v[166:167]
	s_add_i32 m0, s10, 0x2000
	s_nop 0
	global_load_lds_dwordx4 v[128:129], off
	s_waitcnt vmcnt(6)
	s_barrier
	v_mfma_f32_16x16x32_bf16 v[44:47], v[186:189], v[144:147], v[44:47]
	v_mfma_f32_16x16x32_bf16 v[12:15], v[194:197], v[144:147], v[12:15]
	v_mfma_f32_16x16x32_bf16 v[40:43], v[186:189], v[152:155], v[40:43]
	v_mfma_f32_16x16x32_bf16 v[8:11], v[194:197], v[152:155], v[8:11]
	v_mfma_f32_16x16x32_bf16 v[36:39], v[186:189], v[160:163], v[36:39]
	v_mfma_f32_16x16x32_bf16 v[4:7], v[194:197], v[160:163], v[4:7]
	v_mfma_f32_16x16x32_bf16 v[32:35], v[186:189], v[178:181], v[32:35]
	v_mfma_f32_16x16x32_bf16 v[0:3], v[194:197], v[178:181], v[0:3]
	v_mfma_f32_16x16x32_bf16 v[44:47], v[190:193], v[148:151], v[44:47]
	v_mfma_f32_16x16x32_bf16 v[12:15], v[202:205], v[148:151], v[12:15]
	v_mfma_f32_16x16x32_bf16 v[40:43], v[190:193], v[156:159], v[40:43]
	v_mfma_f32_16x16x32_bf16 v[8:11], v[202:205], v[156:159], v[8:11]
	v_mfma_f32_16x16x32_bf16 v[36:39], v[190:193], v[174:177], v[36:39]
	v_mfma_f32_16x16x32_bf16 v[4:7], v[202:205], v[174:177], v[4:7]
	v_mfma_f32_16x16x32_bf16 v[32:35], v[190:193], v[182:185], v[32:35]
	v_mfma_f32_16x16x32_bf16 v[0:3], v[202:205], v[182:185], v[0:3]
	s_add_i32 s16, s16, 2
	s_add_u32 s14, s14, 0x100
	s_addc_u32 s15, s15, 0
	s_cmpk_gt_u32 s16, 0x55
	s_mov_b64 s[6:7], s[8:9]
	s_barrier
	s_cbranch_scc0 .LBB0_1697
	s_lshr_b32 s6, s3, 4
	s_lshl_b32 s3, s3, 8
	s_mulk_i32 s6, 0x1100
	s_and_b32 s3, s3, 0xf00
	s_add_i32 s3, s6, s3
	s_add_i32 s6, s3, 0x100
	s_lshl_b32 s7, s2, 8
	s_mul_hi_i32 s2, s6, 0x78787879
	s_lshr_b32 s3, s2, 31
	s_ashr_i32 s2, s2, 11
	s_add_i32 s2, s2, s3
	s_mul_i32 s3, s2, 0xffffef00
	s_mul_i32 s2, s2, 6
	s_add_i32 s3, s3, s6
	s_add_i32 s2, s2, 5
	s_cmpk_gt_i32 s3, 0xff
	v_mov_b32_e32 v132, v206
	s_cselect_b32 s2, s2, 29
	s_ashr_i32 s3, s2, 31
	v_lshrrev_b32_e32 v128, 1, v132
	v_lshrrev_b32_e32 v129, 2, v132
	s_lshl_b64 s[2:3], s[2:3], 13
	v_and_b32_e32 v128, 0x60, v128
	v_and_b32_e32 v129, 12, v129
	s_add_u32 s2, s26, s2
	v_or3_b32 v174, v128, s7, v129
	s_addc_u32 s3, s27, s3
	v_ashrrev_i32_e32 v175, 31, v174
	v_lshl_add_u64 v[192:193], v[174:175], 2, s[2:3]
	global_load_dwordx4 v[128:131], v[192:193], off
	v_ashrrev_i32_e32 v133, 2, v132
	v_and_b32_e32 v133, 0xffffffc0, v133
	v_and_or_b32 v132, v132, 15, s6
	v_add_u32_e32 v176, v132, v133
	v_mul_hi_i32 v132, v176, s59
	v_lshrrev_b32_e32 v133, 31, v132
	v_ashrrev_i32_e32 v132, 11, v132
	v_add_u32_e32 v203, v132, v133
	v_mad_i32_i24 v202, v203, s60, v176
	v_lshlrev_b32_e32 v212, 12, v203
	v_cmp_lt_i32_e64 s[18:19], s61, v202
	v_add3_u32 v190, v212, v202, s62
	s_and_saveexec_b64 s[2:3], s[18:19]
	s_xor_b64 s[6:7], exec, s[2:3]
	v_add3_u32 v132, v212, v202, s62
	s_or_saveexec_b64 s[6:7], s[6:7]
	v_mov_b64_e32 v[134:135], s[24:25]
	v_lshl_add_u32 v191, v203, 8, v202
	s_xor_b64 exec, exec, s[6:7]
	v_lshl_add_u32 v132, v203, 8, v202
	v_mov_b64_e32 v[134:135], s[36:37]
	s_or_b64 exec, exec, s[6:7]
	v_ashrrev_i32_e32 v133, 31, v132
	v_lshlrev_b64 v[132:133], 13, v[132:133]
	v_lshl_add_u64 v[132:133], v[134:135], 0, v[132:133]
	v_lshl_add_u64 v[132:133], v[174:175], 2, v[132:133]
	global_load_dwordx4 v[160:163], v[132:133], off
	v_or_b32_e32 v132, 16, v176
	v_mul_hi_i32 v133, v132, s59
	v_lshrrev_b32_e32 v134, 31, v133
	v_ashrrev_i32_e32 v133, 11, v133
	v_add_u32_e32 v205, v133, v134
	v_mad_i32_i24 v204, v205, s60, v132
	v_lshlrev_b32_e32 v217, 12, v205
	v_cmp_lt_i32_e64 s[16:17], s61, v204
	v_add3_u32 v188, v217, v204, s62
	s_and_saveexec_b64 s[2:3], s[16:17]
	s_xor_b64 s[6:7], exec, s[2:3]
	v_add3_u32 v132, v217, v204, s62
	s_or_saveexec_b64 s[6:7], s[6:7]
	v_mov_b64_e32 v[134:135], s[24:25]
	v_lshl_add_u32 v189, v205, 8, v204
	s_xor_b64 exec, exec, s[6:7]
	v_lshl_add_u32 v132, v205, 8, v204
	v_mov_b64_e32 v[134:135], s[36:37]
	s_or_b64 exec, exec, s[6:7]
	v_ashrrev_i32_e32 v133, 31, v132
	v_lshlrev_b64 v[132:133], 13, v[132:133]
	v_lshl_add_u64 v[132:133], v[134:135], 0, v[132:133]
	v_lshl_add_u64 v[132:133], v[174:175], 2, v[132:133]
	global_load_dwordx4 v[156:159], v[132:133], off
	v_or_b32_e32 v132, 32, v176
	v_mul_hi_i32 v133, v132, s59
	v_lshrrev_b32_e32 v134, 31, v133
	v_ashrrev_i32_e32 v133, 11, v133
	v_add_u32_e32 v209, v133, v134
	v_mad_i32_i24 v208, v209, s60, v132
; DI void epi_resid(const Acc& acc, const P& p, int brow, int bcol, int layer, int gch, bool from_input) {
;     ...
;             const f32x4 g = *(const f32x4*)(gate + c0);
;             f32x4 xv[2][4];
; #pragma unroll
;             for (int ai = 0; ai < 2; ++ai)
; #pragma unroll
;                 for (int m = 0; m < 4; ++m) {
;                     const int r = brow + ai * 128 + wr * 64 + m * 16 + fr;
;                     const float* sp = (from_input ? inrow(p, r) : xrow(p, r)) + c0;
;                     xv[ai][m] = *(const f32x4*)sp;
;                 }
	v_lshlrev_b32_e32 v220, 12, v209
	v_cmp_lt_i32_e64 s[14:15], s61, v208
	v_add3_u32 v186, v220, v208, s62
	s_and_saveexec_b64 s[2:3], s[14:15]
	s_xor_b64 s[6:7], exec, s[2:3]
	v_add3_u32 v132, v220, v208, s62
	s_or_saveexec_b64 s[6:7], s[6:7]
	v_mov_b64_e32 v[134:135], s[24:25]
	v_lshl_add_u32 v187, v209, 8, v208
	s_xor_b64 exec, exec, s[6:7]
	v_lshl_add_u32 v132, v209, 8, v208
	v_mov_b64_e32 v[134:135], s[36:37]
	s_or_b64 exec, exec, s[6:7]
	v_ashrrev_i32_e32 v133, 31, v132
	v_lshlrev_b64 v[132:133], 13, v[132:133]
	v_lshl_add_u64 v[132:133], v[134:135], 0, v[132:133]
	v_lshl_add_u64 v[132:133], v[174:175], 2, v[132:133]
	global_load_dwordx4 v[152:155], v[132:133], off
	v_or_b32_e32 v132, 48, v176
	v_mul_hi_i32 v133, v132, s59
	v_lshrrev_b32_e32 v134, 31, v133
	v_ashrrev_i32_e32 v133, 11, v133
	v_add_u32_e32 v211, v133, v134
	v_mad_i32_i24 v210, v211, s60, v132
	v_lshlrev_b32_e32 v223, 12, v211
	v_cmp_lt_i32_e64 s[12:13], s61, v210
	v_add3_u32 v184, v223, v210, s62
	s_and_saveexec_b64 s[2:3], s[12:13]
	s_xor_b64 s[6:7], exec, s[2:3]
	v_add3_u32 v132, v223, v210, s62
	s_or_saveexec_b64 s[6:7], s[6:7]
	v_mov_b64_e32 v[134:135], s[24:25]
	v_lshl_add_u32 v185, v211, 8, v210
	s_xor_b64 exec, exec, s[6:7]
	v_lshl_add_u32 v132, v211, 8, v210
	v_mov_b64_e32 v[134:135], s[36:37]
	s_or_b64 exec, exec, s[6:7]
	v_ashrrev_i32_e32 v133, 31, v132
	v_lshlrev_b64 v[132:133], 13, v[132:133]
	v_lshl_add_u64 v[132:133], v[134:135], 0, v[132:133]
	v_lshl_add_u64 v[132:133], v[174:175], 2, v[132:133]
	global_load_dwordx4 v[148:151], v[132:133], off
	v_add_u32_e32 v132, 0x80, v176
	v_mul_hi_i32 v133, v132, s59
	v_lshrrev_b32_e32 v134, 31, v133
	v_ashrrev_i32_e32 v133, 11, v133
	v_add_u32_e32 v214, v133, v134
	v_mad_i32_i24 v213, v214, s60, v132
	v_lshlrev_b32_e32 v224, 12, v214
	v_cmp_lt_i32_e64 s[10:11], s61, v213
	v_add3_u32 v182, v224, v213, s62
	s_and_saveexec_b64 s[2:3], s[10:11]
	s_xor_b64 s[6:7], exec, s[2:3]
	v_add3_u32 v132, v224, v213, s62
	s_or_saveexec_b64 s[6:7], s[6:7]
	v_mov_b64_e32 v[134:135], s[24:25]
	v_lshl_add_u32 v183, v214, 8, v213
	s_xor_b64 exec, exec, s[6:7]
	v_lshl_add_u32 v132, v214, 8, v213
	v_mov_b64_e32 v[134:135], s[36:37]
	s_or_b64 exec, exec, s[6:7]
	v_ashrrev_i32_e32 v133, 31, v132
	v_lshlrev_b64 v[132:133], 13, v[132:133]
	v_lshl_add_u64 v[132:133], v[134:135], 0, v[132:133]
	v_lshl_add_u64 v[132:133], v[174:175], 2, v[132:133]
	global_load_dwordx4 v[144:147], v[132:133], off
	v_add_u32_e32 v132, 0x90, v176
	v_mul_hi_i32 v133, v132, s59
	v_lshrrev_b32_e32 v134, 31, v133
	v_ashrrev_i32_e32 v133, 11, v133
	v_add_u32_e32 v216, v133, v134
	v_mad_i32_i24 v215, v216, s60, v132
	v_lshlrev_b32_e32 v225, 12, v216
	v_cmp_lt_i32_e64 s[8:9], s61, v215
	v_add3_u32 v180, v225, v215, s62
	s_and_saveexec_b64 s[2:3], s[8:9]
	s_xor_b64 s[6:7], exec, s[2:3]
	v_add3_u32 v132, v225, v215, s62
	s_or_saveexec_b64 s[6:7], s[6:7]
	v_mov_b64_e32 v[134:135], s[24:25]
	v_lshl_add_u32 v181, v216, 8, v215
	s_xor_b64 exec, exec, s[6:7]
	v_lshl_add_u32 v132, v216, 8, v215
	v_mov_b64_e32 v[134:135], s[36:37]
	s_or_b64 exec, exec, s[6:7]
	v_ashrrev_i32_e32 v133, 31, v132
	v_lshlrev_b64 v[132:133], 13, v[132:133]
	v_lshl_add_u64 v[132:133], v[134:135], 0, v[132:133]
	v_lshl_add_u64 v[132:133], v[174:175], 2, v[132:133]
	global_load_dwordx4 v[140:143], v[132:133], off
	v_add_u32_e32 v132, 0xa0, v176
	v_mul_hi_i32 v133, v132, s59
	v_lshrrev_b32_e32 v134, 31, v133
	v_ashrrev_i32_e32 v133, 11, v133
	v_add_u32_e32 v219, v133, v134
	v_mad_i32_i24 v218, v219, s60, v132
	v_lshlrev_b32_e32 v226, 12, v219
	v_cmp_lt_i32_e64 s[6:7], s61, v218
	v_add3_u32 v178, v226, v218, s62
	s_and_saveexec_b64 s[2:3], s[6:7]
	s_xor_b64 s[52:53], exec, s[2:3]
	v_add3_u32 v132, v226, v218, s62
	s_or_saveexec_b64 s[52:53], s[52:53]
	v_mov_b64_e32 v[134:135], s[24:25]
	v_lshl_add_u32 v179, v219, 8, v218
	s_xor_b64 exec, exec, s[52:53]
	v_lshl_add_u32 v132, v219, 8, v218
	v_mov_b64_e32 v[134:135], s[36:37]
	s_or_b64 exec, exec, s[52:53]
	v_ashrrev_i32_e32 v133, 31, v132
	v_lshlrev_b64 v[132:133], 13, v[132:133]
	v_lshl_add_u64 v[132:133], v[134:135], 0, v[132:133]
	v_lshl_add_u64 v[132:133], v[174:175], 2, v[132:133]
	global_load_dwordx4 v[136:139], v[132:133], off
	v_add_u32_e32 v132, 0xb0, v176
	v_mul_hi_i32 v133, v132, s59
	v_lshrrev_b32_e32 v134, 31, v133
	v_ashrrev_i32_e32 v133, 11, v133
	v_add_u32_e32 v222, v133, v134
	v_mad_i32_i24 v221, v222, s60, v132
	v_lshlrev_b32_e32 v227, 12, v222
	v_cmp_lt_i32_e32 vcc, s61, v221
	v_add3_u32 v176, v227, v221, s62
	s_and_saveexec_b64 s[2:3], vcc
	s_xor_b64 s[52:53], exec, s[2:3]
	v_add3_u32 v132, v227, v221, s62
	s_or_saveexec_b64 s[52:53], s[52:53]
	v_mov_b64_e32 v[134:135], s[24:25]
	v_lshl_add_u32 v177, v222, 8, v221
	s_xor_b64 exec, exec, s[52:53]
	v_lshl_add_u32 v132, v222, 8, v221
	v_mov_b64_e32 v[134:135], s[36:37]
	s_or_b64 exec, exec, s[52:53]
	v_ashrrev_i32_e32 v133, 31, v132
	v_lshlrev_b64 v[132:133], 13, v[132:133]
	v_lshl_add_u64 v[132:133], v[134:135], 0, v[132:133]
	v_lshl_add_u64 v[132:133], v[174:175], 2, v[132:133]
	global_load_dwordx4 v[132:135], v[132:133], off
	s_and_saveexec_b64 s[2:3], s[18:19]
	s_xor_b64 s[52:53], exec, s[2:3]
	v_add3_u32 v194, v212, v202, s62
	s_or_saveexec_b64 s[52:53], s[52:53]
	v_mov_b64_e32 v[196:197], s[24:25]
	s_xor_b64 exec, exec, s[52:53]
	v_lshl_add_u32 v194, v203, 8, v202
	v_mov_b64_e32 v[196:197], s[36:37]
	s_or_b64 exec, exec, s[52:53]
	v_ashrrev_i32_e32 v195, 31, v194
	s_waitcnt vmcnt(0)
; DI void epi_resid(const Acc& acc, const P& p, int brow, int bcol, int layer, int gch, bool from_input) {
;     ...
;             const f32x4 g = *(const f32x4*)(gate + c0);
;             f32x4 xv[2][4];
; #pragma unroll
;             for (int ai = 0; ai < 2; ++ai)
; #pragma unroll
;                 for (int m = 0; m < 4; ++m) {
;                     const int r = brow + ai * 128 + wr * 64 + m * 16 + fr;
;                     const float* sp = (from_input ? inrow(p, r) : xrow(p, r)) + c0;
;                     xv[ai][m] = *(const f32x4*)sp;
;                 }
;             __builtin_amdgcn_sched_barrier(0);
; #pragma unroll
;             for (int ai = 0; ai < 2; ++ai)
; #pragma unroll
;                 for (int m = 0; m < 4; ++m) {
;                     const int r = brow + ai * 128 + wr * 64 + m * 16 + fr;
;                     *(f32x4*)(xrow(p, r) + c0) = xv[ai][m] + g * acc[ai][bj][m][n];
;                 }
;             __builtin_amdgcn_sched_barrier(0);
	v_pk_fma_f32 v[124:125], v[124:125], v[128:129], v[160:161]
	v_lshlrev_b64 v[160:161], 13, v[194:195]
	v_lshl_add_u64 v[160:161], v[196:197], 0, v[160:161]
	v_pk_fma_f32 v[126:127], v[126:127], v[130:131], v[162:163]
	v_lshl_add_u64 v[160:161], v[174:175], 2, v[160:161]
	global_store_dwordx4 v[160:161], v[124:127], off
	s_and_saveexec_b64 s[2:3], s[16:17]
	s_xor_b64 s[52:53], exec, s[2:3]
	v_add3_u32 v124, v217, v204, s62
	s_or_saveexec_b64 s[52:53], s[52:53]
	v_mov_b64_e32 v[126:127], s[24:25]
	s_xor_b64 exec, exec, s[52:53]
	v_lshl_add_u32 v124, v205, 8, v204
	v_mov_b64_e32 v[126:127], s[36:37]
	s_or_b64 exec, exec, s[52:53]
	v_ashrrev_i32_e32 v125, 31, v124
	v_lshlrev_b64 v[124:125], 13, v[124:125]
	v_lshl_add_u64 v[124:125], v[126:127], 0, v[124:125]
	v_pk_fma_f32 v[122:123], v[122:123], v[130:131], v[158:159]
	v_pk_fma_f32 v[120:121], v[120:121], v[128:129], v[156:157]
	v_lshl_add_u64 v[124:125], v[174:175], 2, v[124:125]
	global_store_dwordx4 v[124:125], v[120:123], off
	s_and_saveexec_b64 s[2:3], s[14:15]
	s_xor_b64 s[52:53], exec, s[2:3]
	v_add3_u32 v120, v220, v208, s62
	s_or_saveexec_b64 s[52:53], s[52:53]
	v_mov_b64_e32 v[122:123], s[24:25]
	s_xor_b64 exec, exec, s[52:53]
	v_lshl_add_u32 v120, v209, 8, v208
	v_mov_b64_e32 v[122:123], s[36:37]
	s_or_b64 exec, exec, s[52:53]
	v_ashrrev_i32_e32 v121, 31, v120
	v_lshlrev_b64 v[120:121], 13, v[120:121]
	v_lshl_add_u64 v[120:121], v[122:123], 0, v[120:121]
	v_pk_fma_f32 v[118:119], v[118:119], v[130:131], v[154:155]
	v_pk_fma_f32 v[116:117], v[116:117], v[128:129], v[152:153]
	v_lshl_add_u64 v[120:121], v[174:175], 2, v[120:121]
	global_store_dwordx4 v[120:121], v[116:119], off
	s_and_saveexec_b64 s[2:3], s[12:13]
	s_xor_b64 s[52:53], exec, s[2:3]
	v_add3_u32 v116, v223, v210, s62
	s_or_saveexec_b64 s[52:53], s[52:53]
	v_mov_b64_e32 v[118:119], s[24:25]
	s_xor_b64 exec, exec, s[52:53]
	v_lshl_add_u32 v116, v211, 8, v210
	v_mov_b64_e32 v[118:119], s[36:37]
	s_or_b64 exec, exec, s[52:53]
	v_ashrrev_i32_e32 v117, 31, v116
	v_lshlrev_b64 v[116:117], 13, v[116:117]
	v_lshl_add_u64 v[116:117], v[118:119], 0, v[116:117]
	v_pk_fma_f32 v[114:115], v[114:115], v[130:131], v[150:151]
	v_pk_fma_f32 v[112:113], v[112:113], v[128:129], v[148:149]
	v_lshl_add_u64 v[116:117], v[174:175], 2, v[116:117]
	global_store_dwordx4 v[116:117], v[112:115], off
	s_and_saveexec_b64 s[2:3], s[10:11]
	s_xor_b64 s[52:53], exec, s[2:3]
	v_add3_u32 v112, v224, v213, s62
	s_or_saveexec_b64 s[52:53], s[52:53]
	v_mov_b64_e32 v[114:115], s[24:25]
	s_xor_b64 exec, exec, s[52:53]
	v_lshl_add_u32 v112, v214, 8, v213
	v_mov_b64_e32 v[114:115], s[36:37]
	s_or_b64 exec, exec, s[52:53]
	v_ashrrev_i32_e32 v113, 31, v112
	v_lshlrev_b64 v[112:113], 13, v[112:113]
	v_lshl_add_u64 v[112:113], v[114:115], 0, v[112:113]
	v_pk_fma_f32 v[110:111], v[110:111], v[130:131], v[146:147]
	v_pk_fma_f32 v[108:109], v[108:109], v[128:129], v[144:145]
	v_lshl_add_u64 v[112:113], v[174:175], 2, v[112:113]
	global_store_dwordx4 v[112:113], v[108:111], off
	s_and_saveexec_b64 s[2:3], s[8:9]
	s_xor_b64 s[52:53], exec, s[2:3]
	v_add3_u32 v108, v225, v215, s62
	s_or_saveexec_b64 s[52:53], s[52:53]
	v_mov_b64_e32 v[110:111], s[24:25]
	s_xor_b64 exec, exec, s[52:53]
	v_lshl_add_u32 v108, v216, 8, v215
	v_mov_b64_e32 v[110:111], s[36:37]
	s_or_b64 exec, exec, s[52:53]
	v_ashrrev_i32_e32 v109, 31, v108
	v_lshlrev_b64 v[108:109], 13, v[108:109]
	v_lshl_add_u64 v[108:109], v[110:111], 0, v[108:109]
	v_pk_fma_f32 v[106:107], v[106:107], v[130:131], v[142:143]
	v_pk_fma_f32 v[104:105], v[104:105], v[128:129], v[140:141]
	v_lshl_add_u64 v[108:109], v[174:175], 2, v[108:109]
	global_store_dwordx4 v[108:109], v[104:107], off
	s_and_saveexec_b64 s[2:3], s[6:7]
	s_xor_b64 s[52:53], exec, s[2:3]
	v_add3_u32 v104, v226, v218, s62
	s_or_saveexec_b64 s[52:53], s[52:53]
	v_mov_b64_e32 v[106:107], s[24:25]
	s_xor_b64 exec, exec, s[52:53]
	v_lshl_add_u32 v104, v219, 8, v218
	v_mov_b64_e32 v[106:107], s[36:37]
	s_or_b64 exec, exec, s[52:53]
	v_ashrrev_i32_e32 v105, 31, v104
	v_lshlrev_b64 v[104:105], 13, v[104:105]
	v_lshl_add_u64 v[104:105], v[106:107], 0, v[104:105]
	v_pk_fma_f32 v[102:103], v[102:103], v[130:131], v[138:139]
	v_pk_fma_f32 v[100:101], v[100:101], v[128:129], v[136:137]
	v_lshl_add_u64 v[104:105], v[174:175], 2, v[104:105]
	global_store_dwordx4 v[104:105], v[100:103], off
	s_and_saveexec_b64 s[2:3], vcc
	s_xor_b64 s[52:53], exec, s[2:3]
	v_add3_u32 v100, v227, v221, s62
	s_or_saveexec_b64 s[52:53], s[52:53]
	v_mov_b64_e32 v[102:103], s[24:25]
	s_xor_b64 exec, exec, s[52:53]
	v_lshl_add_u32 v100, v222, 8, v221
	v_mov_b64_e32 v[102:103], s[36:37]
	s_or_b64 exec, exec, s[52:53]
	v_ashrrev_i32_e32 v101, 31, v100
	v_lshlrev_b64 v[100:101], 13, v[100:101]
	v_lshl_add_u64 v[100:101], v[102:103], 0, v[100:101]
	v_pk_fma_f32 v[98:99], v[98:99], v[130:131], v[134:135]
	v_pk_fma_f32 v[96:97], v[96:97], v[128:129], v[132:133]
	v_lshl_add_u64 v[100:101], v[174:175], 2, v[100:101]
	global_store_dwordx4 v[100:101], v[96:99], off
	global_load_dwordx4 v[96:99], v[192:193], off offset:64
	s_and_saveexec_b64 s[2:3], s[18:19]
	s_xor_b64 s[52:53], exec, s[2:3]
	v_add3_u32 v100, v212, v202, s62
	s_or_saveexec_b64 s[52:53], s[52:53]
	v_mov_b64_e32 v[102:103], s[24:25]
	s_xor_b64 exec, exec, s[52:53]
	v_lshl_add_u32 v100, v203, 8, v202
	v_mov_b64_e32 v[102:103], s[36:37]
	s_or_b64 exec, exec, s[52:53]
	v_ashrrev_i32_e32 v101, 31, v100
	v_lshlrev_b64 v[100:101], 13, v[100:101]
	v_lshl_add_u64 v[100:101], v[102:103], 0, v[100:101]
	v_lshl_add_u64 v[100:101], v[174:175], 2, v[100:101]
	global_load_dwordx4 v[128:131], v[100:101], off offset:64
	s_and_saveexec_b64 s[2:3], s[16:17]
; DI void epi_resid(const Acc& acc, const P& p, int brow, int bcol, int layer, int gch, bool from_input) {
;     ...
;             const f32x4 g = *(const f32x4*)(gate + c0);
;             f32x4 xv[2][4];
; #pragma unroll
;             for (int ai = 0; ai < 2; ++ai)
; #pragma unroll
;                 for (int m = 0; m < 4; ++m) {
;                     const int r = brow + ai * 128 + wr * 64 + m * 16 + fr;
;                     const float* sp = (from_input ? inrow(p, r) : xrow(p, r)) + c0;
;                     xv[ai][m] = *(const f32x4*)sp;
;                 }
;             __builtin_amdgcn_sched_barrier(0);
; #pragma unroll
;             for (int ai = 0; ai < 2; ++ai)
; #pragma unroll
;                 for (int m = 0; m < 4; ++m) {
;                     const int r = brow + ai * 128 + wr * 64 + m * 16 + fr;
;                     *(f32x4*)(xrow(p, r) + c0) = xv[ai][m] + g * acc[ai][bj][m][n];
;                 }
;             __builtin_amdgcn_sched_barrier(0);
	s_xor_b64 s[52:53], exec, s[2:3]
	v_add3_u32 v100, v217, v204, s62
	s_or_saveexec_b64 s[52:53], s[52:53]
	v_mov_b64_e32 v[102:103], s[24:25]
	s_xor_b64 exec, exec, s[52:53]
	v_lshl_add_u32 v100, v205, 8, v204
	v_mov_b64_e32 v[102:103], s[36:37]
	s_or_b64 exec, exec, s[52:53]
	v_ashrrev_i32_e32 v101, 31, v100
	v_lshlrev_b64 v[100:101], 13, v[100:101]
	v_lshl_add_u64 v[100:101], v[102:103], 0, v[100:101]
	v_lshl_add_u64 v[100:101], v[174:175], 2, v[100:101]
	global_load_dwordx4 v[124:127], v[100:101], off offset:64
	s_and_saveexec_b64 s[2:3], s[14:15]
	s_xor_b64 s[52:53], exec, s[2:3]
	v_add3_u32 v100, v220, v208, s62
	s_or_saveexec_b64 s[52:53], s[52:53]
	v_mov_b64_e32 v[102:103], s[24:25]
	s_xor_b64 exec, exec, s[52:53]
	v_lshl_add_u32 v100, v209, 8, v208
	v_mov_b64_e32 v[102:103], s[36:37]
	s_or_b64 exec, exec, s[52:53]
	v_ashrrev_i32_e32 v101, 31, v100
	v_lshlrev_b64 v[100:101], 13, v[100:101]
	v_lshl_add_u64 v[100:101], v[102:103], 0, v[100:101]
	v_lshl_add_u64 v[100:101], v[174:175], 2, v[100:101]
	global_load_dwordx4 v[120:123], v[100:101], off offset:64
	s_and_saveexec_b64 s[2:3], s[12:13]
	s_xor_b64 s[52:53], exec, s[2:3]
	v_add3_u32 v100, v223, v210, s62
	s_or_saveexec_b64 s[52:53], s[52:53]
	v_mov_b64_e32 v[102:103], s[24:25]
	s_xor_b64 exec, exec, s[52:53]
	v_lshl_add_u32 v100, v211, 8, v210
	v_mov_b64_e32 v[102:103], s[36:37]
	s_or_b64 exec, exec, s[52:53]
	v_ashrrev_i32_e32 v101, 31, v100
	v_lshlrev_b64 v[100:101], 13, v[100:101]
	v_lshl_add_u64 v[100:101], v[102:103], 0, v[100:101]
	v_lshl_add_u64 v[100:101], v[174:175], 2, v[100:101]
	global_load_dwordx4 v[116:119], v[100:101], off offset:64
	s_and_saveexec_b64 s[2:3], s[10:11]
	s_xor_b64 s[52:53], exec, s[2:3]
	v_add3_u32 v100, v224, v213, s62
	s_or_saveexec_b64 s[52:53], s[52:53]
	v_mov_b64_e32 v[102:103], s[24:25]
	s_xor_b64 exec, exec, s[52:53]
	v_lshl_add_u32 v100, v214, 8, v213
	v_mov_b64_e32 v[102:103], s[36:37]
	s_or_b64 exec, exec, s[52:53]
	v_ashrrev_i32_e32 v101, 31, v100
	v_lshlrev_b64 v[100:101], 13, v[100:101]
	v_lshl_add_u64 v[100:101], v[102:103], 0, v[100:101]
	v_lshl_add_u64 v[100:101], v[174:175], 2, v[100:101]
	global_load_dwordx4 v[112:115], v[100:101], off offset:64
	s_and_saveexec_b64 s[2:3], s[8:9]
	s_xor_b64 s[52:53], exec, s[2:3]
	v_add3_u32 v100, v225, v215, s62
	s_or_saveexec_b64 s[52:53], s[52:53]
	v_mov_b64_e32 v[102:103], s[24:25]
	s_xor_b64 exec, exec, s[52:53]
	v_lshl_add_u32 v100, v216, 8, v215
	v_mov_b64_e32 v[102:103], s[36:37]
	s_or_b64 exec, exec, s[52:53]
	v_ashrrev_i32_e32 v101, 31, v100
	v_lshlrev_b64 v[100:101], 13, v[100:101]
	v_lshl_add_u64 v[100:101], v[102:103], 0, v[100:101]
	v_lshl_add_u64 v[100:101], v[174:175], 2, v[100:101]
	global_load_dwordx4 v[108:111], v[100:101], off offset:64
	s_and_saveexec_b64 s[2:3], s[6:7]
	s_xor_b64 s[52:53], exec, s[2:3]
	v_add3_u32 v100, v226, v218, s62
	s_or_saveexec_b64 s[52:53], s[52:53]
	v_mov_b64_e32 v[102:103], s[24:25]
	s_xor_b64 exec, exec, s[52:53]
	v_lshl_add_u32 v100, v219, 8, v218
	v_mov_b64_e32 v[102:103], s[36:37]
	s_or_b64 exec, exec, s[52:53]
	v_ashrrev_i32_e32 v101, 31, v100
	v_lshlrev_b64 v[100:101], 13, v[100:101]
	v_lshl_add_u64 v[100:101], v[102:103], 0, v[100:101]
	v_lshl_add_u64 v[100:101], v[174:175], 2, v[100:101]
	global_load_dwordx4 v[104:107], v[100:101], off offset:64
	s_and_saveexec_b64 s[2:3], vcc
	s_xor_b64 s[52:53], exec, s[2:3]
	v_add3_u32 v100, v227, v221, s62
	s_or_saveexec_b64 s[52:53], s[52:53]
	v_mov_b64_e32 v[102:103], s[24:25]
	s_xor_b64 exec, exec, s[52:53]
	v_lshl_add_u32 v100, v222, 8, v221
	v_mov_b64_e32 v[102:103], s[36:37]
	s_or_b64 exec, exec, s[52:53]
	v_ashrrev_i32_e32 v101, 31, v100
	v_lshlrev_b64 v[100:101], 13, v[100:101]
	v_lshl_add_u64 v[100:101], v[102:103], 0, v[100:101]
	v_lshl_add_u64 v[100:101], v[174:175], 2, v[100:101]
	global_load_dwordx4 v[100:103], v[100:101], off offset:64
	s_and_saveexec_b64 s[2:3], s[18:19]
	s_xor_b64 s[52:53], exec, s[2:3]
	v_add3_u32 v132, v212, v202, s62
	s_or_saveexec_b64 s[52:53], s[52:53]
	v_mov_b64_e32 v[134:135], s[24:25]
	s_xor_b64 exec, exec, s[52:53]
	v_lshl_add_u32 v132, v203, 8, v202
	v_mov_b64_e32 v[134:135], s[36:37]
	s_or_b64 exec, exec, s[52:53]
	v_ashrrev_i32_e32 v133, 31, v132
	s_waitcnt vmcnt(0)
	v_pk_fma_f32 v[92:93], v[92:93], v[96:97], v[128:129]
	v_lshlrev_b64 v[128:129], 13, v[132:133]
	v_lshl_add_u64 v[128:129], v[134:135], 0, v[128:129]
	v_pk_fma_f32 v[94:95], v[94:95], v[98:99], v[130:131]
	v_lshl_add_u64 v[128:129], v[174:175], 2, v[128:129]
	global_store_dwordx4 v[128:129], v[92:95], off offset:64
	s_and_saveexec_b64 s[2:3], s[16:17]
	s_xor_b64 s[52:53], exec, s[2:3]
	v_add3_u32 v92, v217, v204, s62
	s_or_saveexec_b64 s[52:53], s[52:53]
	v_mov_b64_e32 v[94:95], s[24:25]
	s_xor_b64 exec, exec, s[52:53]
	v_lshl_add_u32 v92, v205, 8, v204
	v_mov_b64_e32 v[94:95], s[36:37]
	s_or_b64 exec, exec, s[52:53]
	v_ashrrev_i32_e32 v93, 31, v92
	v_lshlrev_b64 v[92:93], 13, v[92:93]
	v_lshl_add_u64 v[92:93], v[94:95], 0, v[92:93]
	v_pk_fma_f32 v[90:91], v[90:91], v[98:99], v[126:127]
	v_pk_fma_f32 v[88:89], v[88:89], v[96:97], v[124:125]
	v_lshl_add_u64 v[92:93], v[174:175], 2, v[92:93]
	global_store_dwordx4 v[92:93], v[88:91], off offset:64
	s_and_saveexec_b64 s[2:3], s[14:15]
	s_xor_b64 s[52:53], exec, s[2:3]
	v_add3_u32 v88, v220, v208, s62
	s_or_saveexec_b64 s[52:53], s[52:53]
	v_mov_b64_e32 v[90:91], s[24:25]
	s_xor_b64 exec, exec, s[52:53]
	v_lshl_add_u32 v88, v209, 8, v208
	v_mov_b64_e32 v[90:91], s[36:37]
	s_or_b64 exec, exec, s[52:53]
	v_ashrrev_i32_e32 v89, 31, v88
	v_lshlrev_b64 v[88:89], 13, v[88:89]
	v_lshl_add_u64 v[88:89], v[90:91], 0, v[88:89]
	v_pk_fma_f32 v[86:87], v[86:87], v[98:99], v[122:123]
; DI void epi_resid(const Acc& acc, const P& p, int brow, int bcol, int layer, int gch, bool from_input) {
;     ...
;             const f32x4 g = *(const f32x4*)(gate + c0);
;             f32x4 xv[2][4];
; #pragma unroll
;             for (int ai = 0; ai < 2; ++ai)
; #pragma unroll
;                 for (int m = 0; m < 4; ++m) {
;                     const int r = brow + ai * 128 + wr * 64 + m * 16 + fr;
;                     const float* sp = (from_input ? inrow(p, r) : xrow(p, r)) + c0;
;                     xv[ai][m] = *(const f32x4*)sp;
;                 }
;             __builtin_amdgcn_sched_barrier(0);
; #pragma unroll
;             for (int ai = 0; ai < 2; ++ai)
; #pragma unroll
;                 for (int m = 0; m < 4; ++m) {
;                     const int r = brow + ai * 128 + wr * 64 + m * 16 + fr;
;                     *(f32x4*)(xrow(p, r) + c0) = xv[ai][m] + g * acc[ai][bj][m][n];
;                 }
;             __builtin_amdgcn_sched_barrier(0);
	v_pk_fma_f32 v[84:85], v[84:85], v[96:97], v[120:121]
	v_lshl_add_u64 v[88:89], v[174:175], 2, v[88:89]
	global_store_dwordx4 v[88:89], v[84:87], off offset:64
	s_and_saveexec_b64 s[2:3], s[12:13]
	s_xor_b64 s[52:53], exec, s[2:3]
	v_add3_u32 v84, v223, v210, s62
	s_or_saveexec_b64 s[52:53], s[52:53]
	v_mov_b64_e32 v[86:87], s[24:25]
	s_xor_b64 exec, exec, s[52:53]
	v_lshl_add_u32 v84, v211, 8, v210
	v_mov_b64_e32 v[86:87], s[36:37]
	s_or_b64 exec, exec, s[52:53]
	v_ashrrev_i32_e32 v85, 31, v84
	v_lshlrev_b64 v[84:85], 13, v[84:85]
	v_lshl_add_u64 v[84:85], v[86:87], 0, v[84:85]
	v_pk_fma_f32 v[82:83], v[82:83], v[98:99], v[118:119]
	v_pk_fma_f32 v[80:81], v[80:81], v[96:97], v[116:117]
	v_lshl_add_u64 v[84:85], v[174:175], 2, v[84:85]
	global_store_dwordx4 v[84:85], v[80:83], off offset:64
	s_and_saveexec_b64 s[2:3], s[10:11]
	s_xor_b64 s[52:53], exec, s[2:3]
	v_add3_u32 v80, v224, v213, s62
	s_or_saveexec_b64 s[52:53], s[52:53]
	v_mov_b64_e32 v[82:83], s[24:25]
	s_xor_b64 exec, exec, s[52:53]
	v_lshl_add_u32 v80, v214, 8, v213
	v_mov_b64_e32 v[82:83], s[36:37]
	s_or_b64 exec, exec, s[52:53]
	v_ashrrev_i32_e32 v81, 31, v80
	v_lshlrev_b64 v[80:81], 13, v[80:81]
	v_lshl_add_u64 v[80:81], v[82:83], 0, v[80:81]
	v_pk_fma_f32 v[78:79], v[78:79], v[98:99], v[114:115]
	v_pk_fma_f32 v[76:77], v[76:77], v[96:97], v[112:113]
	v_lshl_add_u64 v[80:81], v[174:175], 2, v[80:81]
	global_store_dwordx4 v[80:81], v[76:79], off offset:64
	s_and_saveexec_b64 s[2:3], s[8:9]
	s_xor_b64 s[52:53], exec, s[2:3]
	v_add3_u32 v76, v225, v215, s62
	s_or_saveexec_b64 s[52:53], s[52:53]
	v_mov_b64_e32 v[78:79], s[24:25]
	s_xor_b64 exec, exec, s[52:53]
	v_lshl_add_u32 v76, v216, 8, v215
	v_mov_b64_e32 v[78:79], s[36:37]
	s_or_b64 exec, exec, s[52:53]
	v_ashrrev_i32_e32 v77, 31, v76
	v_lshlrev_b64 v[76:77], 13, v[76:77]
	v_lshl_add_u64 v[76:77], v[78:79], 0, v[76:77]
	v_pk_fma_f32 v[74:75], v[74:75], v[98:99], v[110:111]
	v_pk_fma_f32 v[72:73], v[72:73], v[96:97], v[108:109]
	v_lshl_add_u64 v[76:77], v[174:175], 2, v[76:77]
	global_store_dwordx4 v[76:77], v[72:75], off offset:64
	s_and_saveexec_b64 s[2:3], s[6:7]
	s_xor_b64 s[52:53], exec, s[2:3]
	v_add3_u32 v72, v226, v218, s62
	s_or_saveexec_b64 s[52:53], s[52:53]
	v_mov_b64_e32 v[74:75], s[24:25]
	s_xor_b64 exec, exec, s[52:53]
	v_lshl_add_u32 v72, v219, 8, v218
	v_mov_b64_e32 v[74:75], s[36:37]
	s_or_b64 exec, exec, s[52:53]
	v_ashrrev_i32_e32 v73, 31, v72
	v_lshlrev_b64 v[72:73], 13, v[72:73]
	v_lshl_add_u64 v[72:73], v[74:75], 0, v[72:73]
	v_pk_fma_f32 v[70:71], v[70:71], v[98:99], v[106:107]
	v_pk_fma_f32 v[68:69], v[68:69], v[96:97], v[104:105]
	v_lshl_add_u64 v[72:73], v[174:175], 2, v[72:73]
	global_store_dwordx4 v[72:73], v[68:71], off offset:64
	s_and_saveexec_b64 s[2:3], vcc
	s_xor_b64 s[52:53], exec, s[2:3]
	v_add3_u32 v68, v227, v221, s62
	s_or_saveexec_b64 s[52:53], s[52:53]
	v_mov_b64_e32 v[70:71], s[24:25]
	s_xor_b64 exec, exec, s[52:53]
	v_lshl_add_u32 v68, v222, 8, v221
	v_mov_b64_e32 v[70:71], s[36:37]
	s_or_b64 exec, exec, s[52:53]
	v_ashrrev_i32_e32 v69, 31, v68
	v_lshlrev_b64 v[68:69], 13, v[68:69]
	v_lshl_add_u64 v[68:69], v[70:71], 0, v[68:69]
	v_pk_fma_f32 v[66:67], v[66:67], v[98:99], v[102:103]
	v_pk_fma_f32 v[64:65], v[64:65], v[96:97], v[100:101]
	v_lshl_add_u64 v[68:69], v[174:175], 2, v[68:69]
	global_store_dwordx4 v[68:69], v[64:67], off offset:64
	global_load_dwordx4 v[64:67], v[192:193], off offset:512
	s_and_saveexec_b64 s[2:3], s[18:19]
	s_xor_b64 s[52:53], exec, s[2:3]
	v_add3_u32 v68, v212, v202, s62
	s_or_saveexec_b64 s[52:53], s[52:53]
	v_mov_b64_e32 v[70:71], s[24:25]
	s_xor_b64 exec, exec, s[52:53]
	v_lshl_add_u32 v68, v203, 8, v202
	v_mov_b64_e32 v[70:71], s[36:37]
	s_or_b64 exec, exec, s[52:53]
	v_ashrrev_i32_e32 v69, 31, v68
	v_lshlrev_b64 v[68:69], 13, v[68:69]
	v_lshl_add_u64 v[68:69], v[70:71], 0, v[68:69]
	v_lshl_add_u64 v[68:69], v[174:175], 2, v[68:69]
	global_load_dwordx4 v[96:99], v[68:69], off offset:512
	s_and_saveexec_b64 s[2:3], s[16:17]
	s_xor_b64 s[52:53], exec, s[2:3]
	v_add3_u32 v68, v217, v204, s62
	s_or_saveexec_b64 s[52:53], s[52:53]
	v_mov_b64_e32 v[70:71], s[24:25]
	s_xor_b64 exec, exec, s[52:53]
	v_lshl_add_u32 v68, v205, 8, v204
	v_mov_b64_e32 v[70:71], s[36:37]
	s_or_b64 exec, exec, s[52:53]
	v_ashrrev_i32_e32 v69, 31, v68
	v_lshlrev_b64 v[68:69], 13, v[68:69]
	v_lshl_add_u64 v[68:69], v[70:71], 0, v[68:69]
	v_lshl_add_u64 v[68:69], v[174:175], 2, v[68:69]
	global_load_dwordx4 v[92:95], v[68:69], off offset:512
	s_and_saveexec_b64 s[2:3], s[14:15]
	s_xor_b64 s[52:53], exec, s[2:3]
	v_add3_u32 v68, v220, v208, s62
	s_or_saveexec_b64 s[52:53], s[52:53]
	v_mov_b64_e32 v[70:71], s[24:25]
	s_xor_b64 exec, exec, s[52:53]
	v_lshl_add_u32 v68, v209, 8, v208
	v_mov_b64_e32 v[70:71], s[36:37]
	s_or_b64 exec, exec, s[52:53]
	v_ashrrev_i32_e32 v69, 31, v68
	v_lshlrev_b64 v[68:69], 13, v[68:69]
	v_lshl_add_u64 v[68:69], v[70:71], 0, v[68:69]
	v_lshl_add_u64 v[68:69], v[174:175], 2, v[68:69]
	global_load_dwordx4 v[88:91], v[68:69], off offset:512
	s_and_saveexec_b64 s[2:3], s[12:13]
	s_xor_b64 s[52:53], exec, s[2:3]
	v_add3_u32 v68, v223, v210, s62
	s_or_saveexec_b64 s[52:53], s[52:53]
	v_mov_b64_e32 v[70:71], s[24:25]
	s_xor_b64 exec, exec, s[52:53]
	v_lshl_add_u32 v68, v211, 8, v210
	v_mov_b64_e32 v[70:71], s[36:37]
	s_or_b64 exec, exec, s[52:53]
	v_ashrrev_i32_e32 v69, 31, v68
	v_lshlrev_b64 v[68:69], 13, v[68:69]
	v_lshl_add_u64 v[68:69], v[70:71], 0, v[68:69]
	v_lshl_add_u64 v[68:69], v[174:175], 2, v[68:69]
	global_load_dwordx4 v[84:87], v[68:69], off offset:512
	s_and_saveexec_b64 s[2:3], s[10:11]
	s_xor_b64 s[52:53], exec, s[2:3]
	v_add3_u32 v68, v224, v213, s62
; DI void epi_resid(const Acc& acc, const P& p, int brow, int bcol, int layer, int gch, bool from_input) {
;     ...
; #pragma unroll
;             for (int ai = 0; ai < 2; ++ai)
; #pragma unroll
;                 for (int m = 0; m < 4; ++m) {
;                     const int r = brow + ai * 128 + wr * 64 + m * 16 + fr;
;                     const float* sp = (from_input ? inrow(p, r) : xrow(p, r)) + c0;
;                     xv[ai][m] = *(const f32x4*)sp;
;                 }
;             __builtin_amdgcn_sched_barrier(0);
; #pragma unroll
;             for (int ai = 0; ai < 2; ++ai)
; #pragma unroll
;                 for (int m = 0; m < 4; ++m) {
;                     const int r = brow + ai * 128 + wr * 64 + m * 16 + fr;
;                     *(f32x4*)(xrow(p, r) + c0) = xv[ai][m] + g * acc[ai][bj][m][n];
	s_or_saveexec_b64 s[52:53], s[52:53]
	v_mov_b64_e32 v[70:71], s[24:25]
	s_xor_b64 exec, exec, s[52:53]
	v_lshl_add_u32 v68, v214, 8, v213
	v_mov_b64_e32 v[70:71], s[36:37]
	s_or_b64 exec, exec, s[52:53]
	v_ashrrev_i32_e32 v69, 31, v68
	v_lshlrev_b64 v[68:69], 13, v[68:69]
	v_lshl_add_u64 v[68:69], v[70:71], 0, v[68:69]
	v_lshl_add_u64 v[68:69], v[174:175], 2, v[68:69]
	global_load_dwordx4 v[80:83], v[68:69], off offset:512
	s_and_saveexec_b64 s[2:3], s[8:9]
	s_xor_b64 s[52:53], exec, s[2:3]
	v_add3_u32 v68, v225, v215, s62
	s_or_saveexec_b64 s[52:53], s[52:53]
	v_mov_b64_e32 v[70:71], s[24:25]
	s_xor_b64 exec, exec, s[52:53]
	v_lshl_add_u32 v68, v216, 8, v215
	v_mov_b64_e32 v[70:71], s[36:37]
	s_or_b64 exec, exec, s[52:53]
	v_ashrrev_i32_e32 v69, 31, v68
	v_lshlrev_b64 v[68:69], 13, v[68:69]
	v_lshl_add_u64 v[68:69], v[70:71], 0, v[68:69]
	v_lshl_add_u64 v[68:69], v[174:175], 2, v[68:69]
	global_load_dwordx4 v[76:79], v[68:69], off offset:512
	s_and_saveexec_b64 s[2:3], s[6:7]
	s_xor_b64 s[52:53], exec, s[2:3]
	v_add3_u32 v68, v226, v218, s62
	s_or_saveexec_b64 s[52:53], s[52:53]
	v_mov_b64_e32 v[70:71], s[24:25]
	s_xor_b64 exec, exec, s[52:53]
	v_lshl_add_u32 v68, v219, 8, v218
	v_mov_b64_e32 v[70:71], s[36:37]
	s_or_b64 exec, exec, s[52:53]
	v_ashrrev_i32_e32 v69, 31, v68
	v_lshlrev_b64 v[68:69], 13, v[68:69]
	v_lshl_add_u64 v[68:69], v[70:71], 0, v[68:69]
	v_lshl_add_u64 v[68:69], v[174:175], 2, v[68:69]
	global_load_dwordx4 v[72:75], v[68:69], off offset:512
	s_and_saveexec_b64 s[2:3], vcc
	s_xor_b64 s[52:53], exec, s[2:3]
	v_add3_u32 v68, v227, v221, s62
	s_or_saveexec_b64 s[52:53], s[52:53]
	v_mov_b64_e32 v[70:71], s[24:25]
	s_xor_b64 exec, exec, s[52:53]
	v_lshl_add_u32 v68, v222, 8, v221
	v_mov_b64_e32 v[70:71], s[36:37]
	s_or_b64 exec, exec, s[52:53]
	v_ashrrev_i32_e32 v69, 31, v68
	v_lshlrev_b64 v[68:69], 13, v[68:69]
	v_lshl_add_u64 v[68:69], v[70:71], 0, v[68:69]
	v_lshl_add_u64 v[68:69], v[174:175], 2, v[68:69]
	global_load_dwordx4 v[68:71], v[68:69], off offset:512
	s_and_saveexec_b64 s[2:3], s[18:19]
	s_xor_b64 s[52:53], exec, s[2:3]
	v_add3_u32 v100, v212, v202, s62
	s_or_saveexec_b64 s[52:53], s[52:53]
	v_mov_b64_e32 v[102:103], s[24:25]
	s_xor_b64 exec, exec, s[52:53]
	v_lshl_add_u32 v100, v203, 8, v202
	v_mov_b64_e32 v[102:103], s[36:37]
	s_or_b64 exec, exec, s[52:53]
	v_ashrrev_i32_e32 v101, 31, v100
	s_waitcnt vmcnt(0)
	v_pk_fma_f32 v[60:61], v[60:61], v[64:65], v[96:97]
	v_lshlrev_b64 v[96:97], 13, v[100:101]
	v_lshl_add_u64 v[96:97], v[102:103], 0, v[96:97]
	v_pk_fma_f32 v[62:63], v[62:63], v[66:67], v[98:99]
	v_lshl_add_u64 v[96:97], v[174:175], 2, v[96:97]
	global_store_dwordx4 v[96:97], v[60:63], off offset:512
	s_and_saveexec_b64 s[2:3], s[16:17]
	s_xor_b64 s[52:53], exec, s[2:3]
	v_add3_u32 v60, v217, v204, s62
	s_or_saveexec_b64 s[52:53], s[52:53]
	v_mov_b64_e32 v[62:63], s[24:25]
	s_xor_b64 exec, exec, s[52:53]
	v_lshl_add_u32 v60, v205, 8, v204
	v_mov_b64_e32 v[62:63], s[36:37]
	s_or_b64 exec, exec, s[52:53]
	v_ashrrev_i32_e32 v61, 31, v60
	v_lshlrev_b64 v[60:61], 13, v[60:61]
	v_lshl_add_u64 v[60:61], v[62:63], 0, v[60:61]
	v_pk_fma_f32 v[58:59], v[58:59], v[66:67], v[94:95]
	v_pk_fma_f32 v[56:57], v[56:57], v[64:65], v[92:93]
	v_lshl_add_u64 v[60:61], v[174:175], 2, v[60:61]
	global_store_dwordx4 v[60:61], v[56:59], off offset:512
	s_and_saveexec_b64 s[2:3], s[14:15]
	s_xor_b64 s[52:53], exec, s[2:3]
	v_add3_u32 v56, v220, v208, s62
	s_or_saveexec_b64 s[52:53], s[52:53]
	v_mov_b64_e32 v[58:59], s[24:25]
	s_xor_b64 exec, exec, s[52:53]
	v_lshl_add_u32 v56, v209, 8, v208
	v_mov_b64_e32 v[58:59], s[36:37]
	s_or_b64 exec, exec, s[52:53]
	v_ashrrev_i32_e32 v57, 31, v56
	v_lshlrev_b64 v[56:57], 13, v[56:57]
	v_lshl_add_u64 v[56:57], v[58:59], 0, v[56:57]
	v_pk_fma_f32 v[54:55], v[54:55], v[66:67], v[90:91]
	v_pk_fma_f32 v[52:53], v[52:53], v[64:65], v[88:89]
	v_lshl_add_u64 v[56:57], v[174:175], 2, v[56:57]
	global_store_dwordx4 v[56:57], v[52:55], off offset:512
	s_and_saveexec_b64 s[2:3], s[12:13]
	s_xor_b64 s[52:53], exec, s[2:3]
	v_add3_u32 v52, v223, v210, s62
	s_or_saveexec_b64 s[52:53], s[52:53]
	v_mov_b64_e32 v[54:55], s[24:25]
	s_xor_b64 exec, exec, s[52:53]
	v_lshl_add_u32 v52, v211, 8, v210
	v_mov_b64_e32 v[54:55], s[36:37]
	s_or_b64 exec, exec, s[52:53]
	v_ashrrev_i32_e32 v53, 31, v52
	v_lshlrev_b64 v[52:53], 13, v[52:53]
	v_lshl_add_u64 v[52:53], v[54:55], 0, v[52:53]
	v_pk_fma_f32 v[50:51], v[50:51], v[66:67], v[86:87]
	v_pk_fma_f32 v[48:49], v[48:49], v[64:65], v[84:85]
	v_lshl_add_u64 v[52:53], v[174:175], 2, v[52:53]
	global_store_dwordx4 v[52:53], v[48:51], off offset:512
	s_and_saveexec_b64 s[2:3], s[10:11]
	s_xor_b64 s[52:53], exec, s[2:3]
	v_add3_u32 v48, v224, v213, s62
	s_or_saveexec_b64 s[52:53], s[52:53]
	v_mov_b64_e32 v[50:51], s[24:25]
	s_xor_b64 exec, exec, s[52:53]
	v_lshl_add_u32 v48, v214, 8, v213
	v_mov_b64_e32 v[50:51], s[36:37]
	s_or_b64 exec, exec, s[52:53]
	v_ashrrev_i32_e32 v49, 31, v48
	v_lshlrev_b64 v[48:49], 13, v[48:49]
	v_lshl_add_u64 v[48:49], v[50:51], 0, v[48:49]
	v_pk_fma_f32 v[46:47], v[46:47], v[66:67], v[82:83]
	v_pk_fma_f32 v[44:45], v[44:45], v[64:65], v[80:81]
	v_lshl_add_u64 v[48:49], v[174:175], 2, v[48:49]
	global_store_dwordx4 v[48:49], v[44:47], off offset:512
	s_and_saveexec_b64 s[2:3], s[8:9]
	s_xor_b64 s[52:53], exec, s[2:3]
	v_add3_u32 v44, v225, v215, s62
	s_or_saveexec_b64 s[52:53], s[52:53]
	v_mov_b64_e32 v[46:47], s[24:25]
	s_xor_b64 exec, exec, s[52:53]
	v_lshl_add_u32 v44, v216, 8, v215
	v_mov_b64_e32 v[46:47], s[36:37]
	s_or_b64 exec, exec, s[52:53]
	v_ashrrev_i32_e32 v45, 31, v44
	v_lshlrev_b64 v[44:45], 13, v[44:45]
; DI void epi_resid(const Acc& acc, const P& p, int brow, int bcol, int layer, int gch, bool from_input) {
;     ...
;             const int c0 = bcol + bj * 128 + wc * 32 + n * 16 + fq * 4;
;             const f32x4 g = *(const f32x4*)(gate + c0);
;             f32x4 xv[2][4];
; #pragma unroll
;             for (int ai = 0; ai < 2; ++ai)
; #pragma unroll
;                 for (int m = 0; m < 4; ++m) {
;                     const int r = brow + ai * 128 + wr * 64 + m * 16 + fr;
;                     const float* sp = (from_input ? inrow(p, r) : xrow(p, r)) + c0;
;                     xv[ai][m] = *(const f32x4*)sp;
;                 }
;             __builtin_amdgcn_sched_barrier(0);
; #pragma unroll
;             for (int ai = 0; ai < 2; ++ai)
; #pragma unroll
;                 for (int m = 0; m < 4; ++m) {
;                     const int r = brow + ai * 128 + wr * 64 + m * 16 + fr;
;                     *(f32x4*)(xrow(p, r) + c0) = xv[ai][m] + g * acc[ai][bj][m][n];
	v_lshl_add_u64 v[44:45], v[46:47], 0, v[44:45]
	v_pk_fma_f32 v[42:43], v[42:43], v[66:67], v[78:79]
	v_pk_fma_f32 v[40:41], v[40:41], v[64:65], v[76:77]
	v_lshl_add_u64 v[44:45], v[174:175], 2, v[44:45]
	global_store_dwordx4 v[44:45], v[40:43], off offset:512
	s_and_saveexec_b64 s[2:3], s[6:7]
	s_xor_b64 s[52:53], exec, s[2:3]
	v_add3_u32 v40, v226, v218, s62
	s_or_saveexec_b64 s[52:53], s[52:53]
	v_mov_b64_e32 v[42:43], s[24:25]
	s_xor_b64 exec, exec, s[52:53]
	v_lshl_add_u32 v40, v219, 8, v218
	v_mov_b64_e32 v[42:43], s[36:37]
	s_or_b64 exec, exec, s[52:53]
	v_ashrrev_i32_e32 v41, 31, v40
	v_lshlrev_b64 v[40:41], 13, v[40:41]
	v_lshl_add_u64 v[40:41], v[42:43], 0, v[40:41]
	v_pk_fma_f32 v[38:39], v[38:39], v[66:67], v[74:75]
	v_pk_fma_f32 v[36:37], v[36:37], v[64:65], v[72:73]
	v_lshl_add_u64 v[40:41], v[174:175], 2, v[40:41]
	global_store_dwordx4 v[40:41], v[36:39], off offset:512
	s_and_saveexec_b64 s[2:3], vcc
	s_xor_b64 s[52:53], exec, s[2:3]
	v_add3_u32 v36, v227, v221, s62
	s_or_saveexec_b64 s[52:53], s[52:53]
	v_mov_b64_e32 v[38:39], s[24:25]
	s_xor_b64 exec, exec, s[52:53]
	v_lshl_add_u32 v36, v222, 8, v221
	v_mov_b64_e32 v[38:39], s[36:37]
	s_or_b64 exec, exec, s[52:53]
	v_ashrrev_i32_e32 v37, 31, v36
	v_lshlrev_b64 v[36:37], 13, v[36:37]
	v_lshl_add_u64 v[36:37], v[38:39], 0, v[36:37]
	v_pk_fma_f32 v[34:35], v[34:35], v[66:67], v[70:71]
	v_pk_fma_f32 v[32:33], v[32:33], v[64:65], v[68:69]
	v_lshl_add_u64 v[36:37], v[174:175], 2, v[36:37]
	global_store_dwordx4 v[36:37], v[32:35], off offset:512
	global_load_dwordx4 v[32:35], v[192:193], off offset:576
	s_and_saveexec_b64 s[2:3], s[18:19]
	s_xor_b64 s[52:53], exec, s[2:3]
	v_add3_u32 v36, v212, v202, s62
	s_or_saveexec_b64 s[52:53], s[52:53]
	v_mov_b64_e32 v[38:39], s[24:25]
	s_xor_b64 exec, exec, s[52:53]
	v_lshl_add_u32 v36, v203, 8, v202
	v_mov_b64_e32 v[38:39], s[36:37]
	s_or_b64 exec, exec, s[52:53]
	v_ashrrev_i32_e32 v37, 31, v36
	v_lshlrev_b64 v[36:37], 13, v[36:37]
	v_lshl_add_u64 v[36:37], v[38:39], 0, v[36:37]
	v_lshl_add_u64 v[36:37], v[174:175], 2, v[36:37]
	global_load_dwordx4 v[64:67], v[36:37], off offset:576
	s_and_saveexec_b64 s[2:3], s[16:17]
	s_xor_b64 s[52:53], exec, s[2:3]
	v_add3_u32 v36, v217, v204, s62
	s_or_saveexec_b64 s[52:53], s[52:53]
	v_mov_b64_e32 v[38:39], s[24:25]
	s_xor_b64 exec, exec, s[52:53]
	v_lshl_add_u32 v36, v205, 8, v204
	v_mov_b64_e32 v[38:39], s[36:37]
	s_or_b64 exec, exec, s[52:53]
	v_ashrrev_i32_e32 v37, 31, v36
	v_lshlrev_b64 v[36:37], 13, v[36:37]
	v_lshl_add_u64 v[36:37], v[38:39], 0, v[36:37]
	v_lshl_add_u64 v[36:37], v[174:175], 2, v[36:37]
	global_load_dwordx4 v[60:63], v[36:37], off offset:576
	s_and_saveexec_b64 s[2:3], s[14:15]
	s_xor_b64 s[52:53], exec, s[2:3]
	v_add3_u32 v36, v220, v208, s62
	s_or_saveexec_b64 s[52:53], s[52:53]
	v_mov_b64_e32 v[38:39], s[24:25]
	s_xor_b64 exec, exec, s[52:53]
	v_lshl_add_u32 v36, v209, 8, v208
	v_mov_b64_e32 v[38:39], s[36:37]
	s_or_b64 exec, exec, s[52:53]
	v_ashrrev_i32_e32 v37, 31, v36
	v_lshlrev_b64 v[36:37], 13, v[36:37]
	v_lshl_add_u64 v[36:37], v[38:39], 0, v[36:37]
	v_lshl_add_u64 v[36:37], v[174:175], 2, v[36:37]
	global_load_dwordx4 v[56:59], v[36:37], off offset:576
	s_and_saveexec_b64 s[2:3], s[12:13]
	s_xor_b64 s[52:53], exec, s[2:3]
	v_add3_u32 v36, v223, v210, s62
	s_or_saveexec_b64 s[52:53], s[52:53]
	v_mov_b64_e32 v[38:39], s[24:25]
	s_xor_b64 exec, exec, s[52:53]
	v_lshl_add_u32 v36, v211, 8, v210
	v_mov_b64_e32 v[38:39], s[36:37]
	s_or_b64 exec, exec, s[52:53]
	v_ashrrev_i32_e32 v37, 31, v36
	v_lshlrev_b64 v[36:37], 13, v[36:37]
	v_lshl_add_u64 v[36:37], v[38:39], 0, v[36:37]
	v_lshl_add_u64 v[36:37], v[174:175], 2, v[36:37]
	global_load_dwordx4 v[52:55], v[36:37], off offset:576
	s_and_saveexec_b64 s[2:3], s[10:11]
	s_xor_b64 s[52:53], exec, s[2:3]
	v_add3_u32 v36, v224, v213, s62
	s_or_saveexec_b64 s[52:53], s[52:53]
	v_mov_b64_e32 v[38:39], s[24:25]
	s_xor_b64 exec, exec, s[52:53]
	v_lshl_add_u32 v36, v214, 8, v213
	v_mov_b64_e32 v[38:39], s[36:37]
	s_or_b64 exec, exec, s[52:53]
	v_ashrrev_i32_e32 v37, 31, v36
	v_lshlrev_b64 v[36:37], 13, v[36:37]
	v_lshl_add_u64 v[36:37], v[38:39], 0, v[36:37]
	v_lshl_add_u64 v[36:37], v[174:175], 2, v[36:37]
	global_load_dwordx4 v[48:51], v[36:37], off offset:576
	s_and_saveexec_b64 s[2:3], s[8:9]
	s_xor_b64 s[52:53], exec, s[2:3]
	v_add3_u32 v36, v225, v215, s62
	s_or_saveexec_b64 s[52:53], s[52:53]
	v_mov_b64_e32 v[38:39], s[24:25]
	s_xor_b64 exec, exec, s[52:53]
	v_lshl_add_u32 v36, v216, 8, v215
	v_mov_b64_e32 v[38:39], s[36:37]
	s_or_b64 exec, exec, s[52:53]
	v_ashrrev_i32_e32 v37, 31, v36
	v_lshlrev_b64 v[36:37], 13, v[36:37]
	v_lshl_add_u64 v[36:37], v[38:39], 0, v[36:37]
	v_lshl_add_u64 v[36:37], v[174:175], 2, v[36:37]
	global_load_dwordx4 v[44:47], v[36:37], off offset:576
	s_and_saveexec_b64 s[2:3], s[6:7]
	s_xor_b64 s[52:53], exec, s[2:3]
	v_add3_u32 v36, v226, v218, s62
	s_or_saveexec_b64 s[52:53], s[52:53]
	v_mov_b64_e32 v[38:39], s[24:25]
	s_xor_b64 exec, exec, s[52:53]
	v_lshl_add_u32 v36, v219, 8, v218
	v_mov_b64_e32 v[38:39], s[36:37]
	s_or_b64 exec, exec, s[52:53]
	v_ashrrev_i32_e32 v37, 31, v36
	v_lshlrev_b64 v[36:37], 13, v[36:37]
	v_lshl_add_u64 v[36:37], v[38:39], 0, v[36:37]
	v_lshl_add_u64 v[36:37], v[174:175], 2, v[36:37]
	global_load_dwordx4 v[40:43], v[36:37], off offset:576
	s_and_saveexec_b64 s[2:3], vcc
	s_xor_b64 s[52:53], exec, s[2:3]
	v_add3_u32 v36, v227, v221, s62
	s_or_saveexec_b64 s[52:53], s[52:53]
	v_mov_b64_e32 v[38:39], s[24:25]
	s_xor_b64 exec, exec, s[52:53]
	v_lshl_add_u32 v36, v222, 8, v221
	v_mov_b64_e32 v[38:39], s[36:37]
	s_or_b64 exec, exec, s[52:53]
	v_ashrrev_i32_e32 v37, 31, v36
	v_lshlrev_b64 v[36:37], 13, v[36:37]
	v_lshl_add_u64 v[36:37], v[38:39], 0, v[36:37]
	v_lshl_add_u64 v[36:37], v[174:175], 2, v[36:37]
	global_load_dwordx4 v[36:39], v[36:37], off offset:576
	s_and_saveexec_b64 s[2:3], s[18:19]
	s_xor_b64 s[18:19], exec, s[2:3]
	s_or_saveexec_b64 s[18:19], s[18:19]
	v_mov_b64_e32 v[68:69], s[24:25]
	s_xor_b64 exec, exec, s[18:19]
	v_mov_b64_e32 v[68:69], s[36:37]
	v_mov_b32_e32 v190, v191
	s_or_b64 exec, exec, s[18:19]
	v_ashrrev_i32_e32 v191, 31, v190
	s_waitcnt vmcnt(0)
; DI void epi_resid(const Acc& acc, const P& p, int brow, int bcol, int layer, int gch, bool from_input) {
;     ...
;             for (int ai = 0; ai < 2; ++ai)
; #pragma unroll
;                 for (int m = 0; m < 4; ++m) {
;                     const int r = brow + ai * 128 + wr * 64 + m * 16 + fr;
;                     *(f32x4*)(xrow(p, r) + c0) = xv[ai][m] + g * acc[ai][bj][m][n];
	v_pk_fma_f32 v[28:29], v[28:29], v[32:33], v[64:65]
	v_lshlrev_b64 v[64:65], 13, v[190:191]
	v_lshl_add_u64 v[64:65], v[68:69], 0, v[64:65]
	v_pk_fma_f32 v[30:31], v[30:31], v[34:35], v[66:67]
	v_lshl_add_u64 v[64:65], v[174:175], 2, v[64:65]
	global_store_dwordx4 v[64:65], v[28:31], off offset:576
	s_and_saveexec_b64 s[2:3], s[16:17]
	s_xor_b64 s[16:17], exec, s[2:3]
	s_or_saveexec_b64 s[16:17], s[16:17]
	v_mov_b64_e32 v[28:29], s[24:25]
	s_xor_b64 exec, exec, s[16:17]
	v_mov_b64_e32 v[28:29], s[36:37]
	v_mov_b32_e32 v188, v189
	s_or_b64 exec, exec, s[16:17]
	v_ashrrev_i32_e32 v189, 31, v188
	v_lshlrev_b64 v[30:31], 13, v[188:189]
	v_lshl_add_u64 v[28:29], v[28:29], 0, v[30:31]
	v_pk_fma_f32 v[26:27], v[26:27], v[34:35], v[62:63]
	v_pk_fma_f32 v[24:25], v[24:25], v[32:33], v[60:61]
	v_lshl_add_u64 v[28:29], v[174:175], 2, v[28:29]
	global_store_dwordx4 v[28:29], v[24:27], off offset:576
	s_and_saveexec_b64 s[2:3], s[14:15]
	s_xor_b64 s[14:15], exec, s[2:3]
	s_or_saveexec_b64 s[14:15], s[14:15]
	v_mov_b64_e32 v[24:25], s[24:25]
	s_xor_b64 exec, exec, s[14:15]
	v_mov_b64_e32 v[24:25], s[36:37]
	v_mov_b32_e32 v186, v187
	s_or_b64 exec, exec, s[14:15]
	v_ashrrev_i32_e32 v187, 31, v186
	v_lshlrev_b64 v[26:27], 13, v[186:187]
	v_lshl_add_u64 v[24:25], v[24:25], 0, v[26:27]
	v_pk_fma_f32 v[22:23], v[22:23], v[34:35], v[58:59]
	v_pk_fma_f32 v[20:21], v[20:21], v[32:33], v[56:57]
	v_lshl_add_u64 v[24:25], v[174:175], 2, v[24:25]
	global_store_dwordx4 v[24:25], v[20:23], off offset:576
	s_and_saveexec_b64 s[2:3], s[12:13]
	s_xor_b64 s[12:13], exec, s[2:3]
	s_or_saveexec_b64 s[12:13], s[12:13]
	v_mov_b64_e32 v[20:21], s[24:25]
	s_xor_b64 exec, exec, s[12:13]
	v_mov_b64_e32 v[20:21], s[36:37]
	v_mov_b32_e32 v184, v185
	s_or_b64 exec, exec, s[12:13]
	v_ashrrev_i32_e32 v185, 31, v184
	v_lshlrev_b64 v[22:23], 13, v[184:185]
	v_lshl_add_u64 v[20:21], v[20:21], 0, v[22:23]
	v_pk_fma_f32 v[18:19], v[18:19], v[34:35], v[54:55]
	v_pk_fma_f32 v[16:17], v[16:17], v[32:33], v[52:53]
	v_lshl_add_u64 v[20:21], v[174:175], 2, v[20:21]
	global_store_dwordx4 v[20:21], v[16:19], off offset:576
	s_and_saveexec_b64 s[2:3], s[10:11]
	s_xor_b64 s[10:11], exec, s[2:3]
	s_or_saveexec_b64 s[10:11], s[10:11]
	v_mov_b64_e32 v[16:17], s[24:25]
	s_xor_b64 exec, exec, s[10:11]
	v_mov_b64_e32 v[16:17], s[36:37]
	v_mov_b32_e32 v182, v183
	s_or_b64 exec, exec, s[10:11]
	v_ashrrev_i32_e32 v183, 31, v182
	v_lshlrev_b64 v[18:19], 13, v[182:183]
	v_lshl_add_u64 v[16:17], v[16:17], 0, v[18:19]
	v_pk_fma_f32 v[14:15], v[14:15], v[34:35], v[50:51]
	v_pk_fma_f32 v[12:13], v[12:13], v[32:33], v[48:49]
	v_lshl_add_u64 v[16:17], v[174:175], 2, v[16:17]
	global_store_dwordx4 v[16:17], v[12:15], off offset:576
	s_and_saveexec_b64 s[2:3], s[8:9]
	s_xor_b64 s[8:9], exec, s[2:3]
	s_or_saveexec_b64 s[8:9], s[8:9]
	v_mov_b64_e32 v[12:13], s[24:25]
	s_xor_b64 exec, exec, s[8:9]
	v_mov_b64_e32 v[12:13], s[36:37]
	v_mov_b32_e32 v180, v181
	s_or_b64 exec, exec, s[8:9]
	v_ashrrev_i32_e32 v181, 31, v180
	v_lshlrev_b64 v[14:15], 13, v[180:181]
	v_lshl_add_u64 v[12:13], v[12:13], 0, v[14:15]
	v_pk_fma_f32 v[10:11], v[10:11], v[34:35], v[46:47]
	v_pk_fma_f32 v[8:9], v[8:9], v[32:33], v[44:45]
	v_lshl_add_u64 v[12:13], v[174:175], 2, v[12:13]
	global_store_dwordx4 v[12:13], v[8:11], off offset:576
	s_and_saveexec_b64 s[2:3], s[6:7]
	s_xor_b64 s[6:7], exec, s[2:3]
	s_or_saveexec_b64 s[6:7], s[6:7]
	v_mov_b64_e32 v[8:9], s[24:25]
	s_xor_b64 exec, exec, s[6:7]
	v_mov_b64_e32 v[8:9], s[36:37]
	v_mov_b32_e32 v178, v179
	s_or_b64 exec, exec, s[6:7]
	v_ashrrev_i32_e32 v179, 31, v178
	v_lshlrev_b64 v[10:11], 13, v[178:179]
	v_lshl_add_u64 v[8:9], v[8:9], 0, v[10:11]
	v_pk_fma_f32 v[6:7], v[6:7], v[34:35], v[42:43]
	v_pk_fma_f32 v[4:5], v[4:5], v[32:33], v[40:41]
	v_lshl_add_u64 v[8:9], v[174:175], 2, v[8:9]
	global_store_dwordx4 v[8:9], v[4:7], off offset:576
	s_and_saveexec_b64 s[2:3], vcc
	s_xor_b64 s[6:7], exec, s[2:3]
	s_or_saveexec_b64 s[6:7], s[6:7]
	v_mov_b64_e32 v[4:5], s[24:25]
	s_xor_b64 exec, exec, s[6:7]
	s_cbranch_execz .LBB0_1693
	v_mov_b64_e32 v[4:5], s[36:37]
	v_mov_b32_e32 v176, v177
	s_branch .LBB0_1693

; #define WAIT_V(n) asm volatile("s_waitcnt vmcnt(" #n ")" ::: "memory")
; #define WAIT_L(n) asm volatile("s_waitcnt lgkmcnt(" #n ")" ::: "memory")
; #define BAR __builtin_amdgcn_s_barrier()
; #define SCHED __builtin_amdgcn_sched_barrier(0)
; template <class Get, class Epi>
; DI void gemm_stream(LAS unsigned char* lds, const int K, const int ld, Get get, Epi epi) {
;     ...
;         for (int t = 0; t < nt; t += 2) {
;             const bool last = (t == nt - 2);
;             const char* a1 = cA + (size_t)(t + 1) * kstep;
;             const char* a2 = last ? nA : cA + (size_t)(t + 2) * kstep;
;             const char* b2 = last ? nB : cB + (size_t)(t + 2) * kstep;
;             const char* a3 = a2 + kstep;
;             const char* b3 = b2 + kstep;
;             LDB(B0, 0, 0); SCHED; LDA(At, 0, 0); STAGE(SAo(1, 1), a1 + hstep);
;             WAIT_L(8); BAR; WAIT_L(0); MMA(0, 0, At, B0); BAR; SCHED;
;             LDB(B1, 0, 1); STAGE(SBo(0, 0), b2);
;             BAR; WAIT_L(0); MMA(0, 1, At, B1); BAR;
;             LDA(At, 0, 1); STAGE(SAo(0, 0), a2);
;             BAR; WAIT_L(0); MMA(1, 0, At, B0); BAR; SCHED;
;             STAGE(SBo(0, 1), b2 + hstep);
;             WAIT_V(6); BAR; MMA(1, 1, At, B1); BAR;
;             LDB(B0, 1, 0); SCHED; LDA(At, 1, 0); STAGE(SAo(0, 1), a2 + hstep);
;             WAIT_L(8); BAR; WAIT_L(0); MMA(0, 0, At, B0); BAR; SCHED;
.LBB0_1964:
	ds_read_b128 v[144:147], v141
	ds_read_b128 v[148:151], v141 offset:1024
	ds_read_b128 v[152:155], v141 offset:2048
	ds_read_b128 v[156:159], v141 offset:3072
	s_add_u32 s38, s36, 0x100
	s_addc_u32 s39, s37, 0
	s_cmp_eq_u32 s77, 4
	s_cselect_b32 s53, s17, s39
	s_cselect_b32 s52, s16, s38
	s_cselect_b32 s41, s19, s76
	s_cselect_b32 s40, s18, s0
	v_lshl_add_u64 v[192:193], s[36:37], 0, v[134:135]
	s_add_i32 m0, s20, 0xc000
	ds_read_b128 v[160:163], v142
	ds_read_b128 v[164:167], v142 offset:1024
	ds_read_b128 v[168:171], v142 offset:2048
	ds_read_b128 v[172:175], v142 offset:3072
	ds_read_b128 v[176:179], v142 offset:4096
	ds_read_b128 v[180:183], v142 offset:5120
	ds_read_b128 v[184:187], v142 offset:6144
	ds_read_b128 v[188:191], v142 offset:7168
	global_load_lds_dwordx4 v[192:193], off
	v_lshl_add_u64 v[192:193], s[36:37], 0, v[136:137]
	s_add_i32 m0, s20, 0xe000
	s_nop 0
	global_load_lds_dwordx4 v[192:193], off
	s_waitcnt lgkmcnt(8)
	s_barrier
	s_waitcnt lgkmcnt(0)
	v_mfma_f32_16x16x32_bf16 v[124:127], v[144:147], v[160:163], v[124:127]
	v_mfma_f32_16x16x32_bf16 v[120:123], v[152:155], v[160:163], v[120:123]
	v_mfma_f32_16x16x32_bf16 v[116:119], v[144:147], v[168:171], v[116:119]
	v_mfma_f32_16x16x32_bf16 v[112:115], v[152:155], v[168:171], v[112:115]
	v_mfma_f32_16x16x32_bf16 v[104:107], v[144:147], v[176:179], v[104:107]
	v_mfma_f32_16x16x32_bf16 v[96:99], v[152:155], v[176:179], v[96:99]
	v_mfma_f32_16x16x32_bf16 v[88:91], v[144:147], v[184:187], v[88:91]
	v_mfma_f32_16x16x32_bf16 v[80:83], v[152:155], v[184:187], v[80:83]
	v_mfma_f32_16x16x32_bf16 v[124:127], v[148:151], v[164:167], v[124:127]
	v_mfma_f32_16x16x32_bf16 v[120:123], v[156:159], v[164:167], v[120:123]
	v_mfma_f32_16x16x32_bf16 v[116:119], v[148:151], v[172:175], v[116:119]
	v_mfma_f32_16x16x32_bf16 v[112:115], v[156:159], v[172:175], v[112:115]
	v_mfma_f32_16x16x32_bf16 v[104:107], v[148:151], v[180:183], v[104:107]
	v_mfma_f32_16x16x32_bf16 v[96:99], v[156:159], v[180:183], v[96:99]
	v_mfma_f32_16x16x32_bf16 v[88:91], v[148:151], v[188:191], v[88:91]
	v_mfma_f32_16x16x32_bf16 v[80:83], v[156:159], v[188:191], v[80:83]
	s_barrier
	s_add_i32 s36, s56, s3
	v_lshl_add_u64 v[204:205], s[40:41], 0, v[130:131]
	s_mov_b32 m0, s36
	ds_read_b128 v[192:195], v143
	ds_read_b128 v[196:199], v143 offset:1024
	ds_read_b128 v[200:203], v143 offset:2048
	ds_read_b128 v[208:211], v143 offset:3072
	global_load_lds_dwordx4 v[204:205], off
	v_lshl_add_u64 v[212:213], s[40:41], 0, v[128:129]
	s_add_i32 m0, s36, 0x2000
	s_nop 0
	global_load_lds_dwordx4 v[212:213], off
	s_barrier
	s_waitcnt lgkmcnt(0)
	v_mfma_f32_16x16x32_bf16 v[108:111], v[192:195], v[160:163], v[108:111]
	v_mfma_f32_16x16x32_bf16 v[100:103], v[200:203], v[160:163], v[100:103]
	v_mfma_f32_16x16x32_bf16 v[92:95], v[192:195], v[168:171], v[92:95]
	v_mfma_f32_16x16x32_bf16 v[84:87], v[200:203], v[168:171], v[84:87]
	v_mfma_f32_16x16x32_bf16 v[76:79], v[192:195], v[176:179], v[76:79]
	v_mfma_f32_16x16x32_bf16 v[72:75], v[200:203], v[176:179], v[72:75]
	v_mfma_f32_16x16x32_bf16 v[68:71], v[192:195], v[184:187], v[68:71]
	v_mfma_f32_16x16x32_bf16 v[64:67], v[200:203], v[184:187], v[64:67]
	v_mfma_f32_16x16x32_bf16 v[108:111], v[196:199], v[164:167], v[108:111]
	v_mfma_f32_16x16x32_bf16 v[100:103], v[208:211], v[164:167], v[100:103]
	v_mfma_f32_16x16x32_bf16 v[92:95], v[196:199], v[172:175], v[92:95]
	v_mfma_f32_16x16x32_bf16 v[84:87], v[208:211], v[172:175], v[84:87]
	v_mfma_f32_16x16x32_bf16 v[76:79], v[196:199], v[180:183], v[76:79]
	v_mfma_f32_16x16x32_bf16 v[72:75], v[208:211], v[180:183], v[72:75]
	v_mfma_f32_16x16x32_bf16 v[68:71], v[196:199], v[188:191], v[68:71]
	v_mfma_f32_16x16x32_bf16 v[64:67], v[208:211], v[188:191], v[64:67]
	s_mov_b32 m0, s20
	v_lshl_add_u64 v[214:215], s[52:53], 0, v[130:131]
	s_barrier
	ds_read_b128 v[160:163], v142 offset:16384
	ds_read_b128 v[164:167], v142 offset:17408
	ds_read_b128 v[168:171], v142 offset:18432
	ds_read_b128 v[172:175], v142 offset:19456
	ds_read_b128 v[176:179], v142 offset:20480
	ds_read_b128 v[180:183], v142 offset:21504
	ds_read_b128 v[184:187], v142 offset:22528
	ds_read_b128 v[188:191], v142 offset:23552
	global_load_lds_dwordx4 v[214:215], off
	v_lshl_add_u64 v[216:217], s[52:53], 0, v[128:129]
	s_mov_b32 m0, s21
	s_nop 0
	global_load_lds_dwordx4 v[216:217], off
	s_barrier
	s_waitcnt lgkmcnt(0)
	v_mfma_f32_16x16x32_bf16 v[60:63], v[144:147], v[160:163], v[60:63]
	v_mfma_f32_16x16x32_bf16 v[56:59], v[152:155], v[160:163], v[56:59]
	v_mfma_f32_16x16x32_bf16 v[52:55], v[144:147], v[168:171], v[52:55]
	v_mfma_f32_16x16x32_bf16 v[48:51], v[152:155], v[168:171], v[48:51]
	v_mfma_f32_16x16x32_bf16 v[40:43], v[144:147], v[176:179], v[40:43]
	v_mfma_f32_16x16x32_bf16 v[32:35], v[152:155], v[176:179], v[32:35]
	v_mfma_f32_16x16x32_bf16 v[24:27], v[144:147], v[184:187], v[24:27]
	v_mfma_f32_16x16x32_bf16 v[16:19], v[152:155], v[184:187], v[16:19]
	v_mfma_f32_16x16x32_bf16 v[60:63], v[148:151], v[164:167], v[60:63]
	v_mfma_f32_16x16x32_bf16 v[56:59], v[156:159], v[164:167], v[56:59]
	v_mfma_f32_16x16x32_bf16 v[52:55], v[148:151], v[172:175], v[52:55]
	v_mfma_f32_16x16x32_bf16 v[48:51], v[156:159], v[172:175], v[48:51]
	v_mfma_f32_16x16x32_bf16 v[40:43], v[148:151], v[180:183], v[40:43]
	v_mfma_f32_16x16x32_bf16 v[32:35], v[156:159], v[180:183], v[32:35]
	v_mfma_f32_16x16x32_bf16 v[24:27], v[148:151], v[188:191], v[24:27]
	v_mfma_f32_16x16x32_bf16 v[16:19], v[156:159], v[188:191], v[16:19]
	s_barrier
; #define WAIT_V(n) asm volatile("s_waitcnt vmcnt(" #n ")" ::: "memory")
; #define WAIT_L(n) asm volatile("s_waitcnt lgkmcnt(" #n ")" ::: "memory")
; #define BAR __builtin_amdgcn_s_barrier()
; #define SCHED __builtin_amdgcn_sched_barrier(0)
; template <class Get, class Epi>
; DI void gemm_stream(LAS unsigned char* lds, const int K, const int ld, Get get, Epi epi) {
;     ...
;             STAGE(SBo(0, 1), b2 + hstep);
;             WAIT_V(6); BAR; MMA(1, 1, At, B1); BAR;
;             LDB(B0, 1, 0); SCHED; LDA(At, 1, 0); STAGE(SAo(0, 1), a2 + hstep);
;             WAIT_L(8); BAR; WAIT_L(0); MMA(0, 0, At, B0); BAR; SCHED;
;             LDB(B1, 1, 1); STAGE(SBo(1, 0), b3);
;             BAR; WAIT_L(0); MMA(0, 1, At, B1); BAR;
;             LDA(At, 1, 1); STAGE(SAo(1, 0), a3);
;             BAR; WAIT_L(0); MMA(1, 0, At, B0); BAR; SCHED;
	s_add_u32 s36, s40, 0x160000
	s_addc_u32 s37, s41, 0
	s_add_i32 s78, s57, s3
	v_lshl_add_u64 v[144:145], s[36:37], 0, v[130:131]
	s_mov_b32 m0, s78
	s_nop 0
	global_load_lds_dwordx4 v[144:145], off
	v_lshl_add_u64 v[144:145], s[36:37], 0, v[128:129]
	s_add_i32 m0, s78, 0x2000
	s_nop 0
	global_load_lds_dwordx4 v[144:145], off
	s_waitcnt vmcnt(6)
	s_barrier
	v_mfma_f32_16x16x32_bf16 v[44:47], v[192:195], v[160:163], v[44:47]
	v_mfma_f32_16x16x32_bf16 v[36:39], v[200:203], v[160:163], v[36:39]
	v_mfma_f32_16x16x32_bf16 v[28:31], v[192:195], v[168:171], v[28:31]
	v_mfma_f32_16x16x32_bf16 v[20:23], v[200:203], v[168:171], v[20:23]
	v_mfma_f32_16x16x32_bf16 v[12:15], v[192:195], v[176:179], v[12:15]
	v_mfma_f32_16x16x32_bf16 v[8:11], v[200:203], v[176:179], v[8:11]
	v_mfma_f32_16x16x32_bf16 v[4:7], v[192:195], v[184:187], v[4:7]
	v_mfma_f32_16x16x32_bf16 v[0:3], v[200:203], v[184:187], v[0:3]
	v_mfma_f32_16x16x32_bf16 v[44:47], v[196:199], v[164:167], v[44:47]
	v_mfma_f32_16x16x32_bf16 v[36:39], v[208:211], v[164:167], v[36:39]
	v_mfma_f32_16x16x32_bf16 v[28:31], v[196:199], v[172:175], v[28:31]
	v_mfma_f32_16x16x32_bf16 v[20:23], v[208:211], v[172:175], v[20:23]
	v_mfma_f32_16x16x32_bf16 v[12:15], v[196:199], v[180:183], v[12:15]
	v_mfma_f32_16x16x32_bf16 v[8:11], v[208:211], v[180:183], v[8:11]
	v_mfma_f32_16x16x32_bf16 v[4:7], v[196:199], v[188:191], v[4:7]
	v_mfma_f32_16x16x32_bf16 v[0:3], v[208:211], v[188:191], v[0:3]
	s_add_i32 s78, 16, 0x18000
	v_add_u32_e32 v132, s78, v140
	s_barrier
	ds_read_b128 v[144:147], v132
	ds_read_b128 v[148:151], v132 offset:1024
	ds_read_b128 v[152:155], v132 offset:2048
	ds_read_b128 v[156:159], v132 offset:3072
	s_add_u32 s36, s52, 0x160000
	s_addc_u32 s37, s53, 0
	s_mov_b32 m0, s23
	v_lshl_add_u64 v[192:193], s[36:37], 0, v[130:131]
	ds_read_b128 v[160:163], v142 offset:32768
	ds_read_b128 v[164:167], v142 offset:33792
	ds_read_b128 v[168:171], v142 offset:34816
	ds_read_b128 v[172:175], v142 offset:35840
	ds_read_b128 v[176:179], v142 offset:36864
	ds_read_b128 v[180:183], v142 offset:37888
	ds_read_b128 v[184:187], v142 offset:38912
	ds_read_b128 v[188:191], v142 offset:39936
	global_load_lds_dwordx4 v[192:193], off
	v_lshl_add_u64 v[192:193], s[36:37], 0, v[128:129]
	s_mov_b32 m0, s28
	s_nop 0
	global_load_lds_dwordx4 v[192:193], off
	s_waitcnt lgkmcnt(8)
	s_barrier
	s_waitcnt lgkmcnt(0)
	v_mfma_f32_16x16x32_bf16 v[124:127], v[144:147], v[160:163], v[124:127]
	v_mfma_f32_16x16x32_bf16 v[120:123], v[152:155], v[160:163], v[120:123]
	v_mfma_f32_16x16x32_bf16 v[116:119], v[144:147], v[168:171], v[116:119]
	v_mfma_f32_16x16x32_bf16 v[112:115], v[152:155], v[168:171], v[112:115]
	v_mfma_f32_16x16x32_bf16 v[104:107], v[144:147], v[176:179], v[104:107]
	v_mfma_f32_16x16x32_bf16 v[96:99], v[152:155], v[176:179], v[96:99]
	v_mfma_f32_16x16x32_bf16 v[88:91], v[144:147], v[184:187], v[88:91]
	v_mfma_f32_16x16x32_bf16 v[80:83], v[152:155], v[184:187], v[80:83]
	v_mfma_f32_16x16x32_bf16 v[124:127], v[148:151], v[164:167], v[124:127]
	v_mfma_f32_16x16x32_bf16 v[120:123], v[156:159], v[164:167], v[120:123]
	v_mfma_f32_16x16x32_bf16 v[116:119], v[148:151], v[172:175], v[116:119]
	v_mfma_f32_16x16x32_bf16 v[112:115], v[156:159], v[172:175], v[112:115]
	v_mfma_f32_16x16x32_bf16 v[104:107], v[148:151], v[180:183], v[104:107]
	v_mfma_f32_16x16x32_bf16 v[96:99], v[156:159], v[180:183], v[96:99]
	v_mfma_f32_16x16x32_bf16 v[88:91], v[148:151], v[188:191], v[88:91]
	v_mfma_f32_16x16x32_bf16 v[80:83], v[156:159], v[188:191], v[80:83]
	s_barrier
	s_add_i32 s52, 16, 0x1c000
	s_add_i32 s36, s78, s3
	v_add_u32_e32 v132, s52, v140
	v_lshl_add_u64 v[204:205], v[204:205], 0, s[8:9]
	s_mov_b32 m0, s36
	ds_read_b128 v[192:195], v132
	ds_read_b128 v[196:199], v132 offset:1024
	ds_read_b128 v[200:203], v132 offset:2048
	ds_read_b128 v[208:211], v132 offset:3072
	global_load_lds_dwordx4 v[204:205], off
	v_lshl_add_u64 v[204:205], v[212:213], 0, s[8:9]
	s_add_i32 m0, s36, 0x2000
	s_nop 0
	global_load_lds_dwordx4 v[204:205], off
	s_barrier
	s_waitcnt lgkmcnt(0)
	v_mfma_f32_16x16x32_bf16 v[108:111], v[192:195], v[160:163], v[108:111]
	v_mfma_f32_16x16x32_bf16 v[100:103], v[200:203], v[160:163], v[100:103]
	v_mfma_f32_16x16x32_bf16 v[92:95], v[192:195], v[168:171], v[92:95]
	v_mfma_f32_16x16x32_bf16 v[84:87], v[200:203], v[168:171], v[84:87]
	v_mfma_f32_16x16x32_bf16 v[76:79], v[192:195], v[176:179], v[76:79]
	v_mfma_f32_16x16x32_bf16 v[72:75], v[200:203], v[176:179], v[72:75]
	v_mfma_f32_16x16x32_bf16 v[68:71], v[192:195], v[184:187], v[68:71]
	v_mfma_f32_16x16x32_bf16 v[64:67], v[200:203], v[184:187], v[64:67]
	v_mfma_f32_16x16x32_bf16 v[108:111], v[196:199], v[164:167], v[108:111]
	v_mfma_f32_16x16x32_bf16 v[100:103], v[208:211], v[164:167], v[100:103]
	v_mfma_f32_16x16x32_bf16 v[92:95], v[196:199], v[172:175], v[92:95]
	v_mfma_f32_16x16x32_bf16 v[84:87], v[208:211], v[172:175], v[84:87]
	v_mfma_f32_16x16x32_bf16 v[76:79], v[196:199], v[180:183], v[76:79]
	v_mfma_f32_16x16x32_bf16 v[72:75], v[208:211], v[180:183], v[72:75]
	v_mfma_f32_16x16x32_bf16 v[68:71], v[196:199], v[188:191], v[68:71]
	v_mfma_f32_16x16x32_bf16 v[64:67], v[208:211], v[188:191], v[64:67]
	s_mov_b32 m0, s29
	v_lshl_add_u64 v[204:205], v[214:215], 0, s[8:9]
	s_barrier
	ds_read_b128 v[160:163], v142 offset:49152
	ds_read_b128 v[164:167], v142 offset:50176
	ds_read_b128 v[168:171], v142 offset:51200
	ds_read_b128 v[172:175], v142 offset:52224
	ds_read_b128 v[176:179], v142 offset:53248
	ds_read_b128 v[180:183], v142 offset:54272
	ds_read_b128 v[184:187], v142 offset:55296
	ds_read_b128 v[188:191], v142 offset:56320
	global_load_lds_dwordx4 v[204:205], off
	v_lshl_add_u64 v[204:205], v[216:217], 0, s[8:9]
	s_mov_b32 m0, s35
	s_nop 0
	global_load_lds_dwordx4 v[204:205], off
	s_barrier
; #define WAIT_V(n) asm volatile("s_waitcnt vmcnt(" #n ")" ::: "memory")
; #define WAIT_L(n) asm volatile("s_waitcnt lgkmcnt(" #n ")" ::: "memory")
; #define BAR __builtin_amdgcn_s_barrier()
; #define SCHED __builtin_amdgcn_sched_barrier(0)
; template <class Get, class Epi>
; DI void gemm_stream(LAS unsigned char* lds, const int K, const int ld, Get get, Epi epi) {
;     ...
;             LDB(B0, 1, 0); SCHED; LDA(At, 1, 0); STAGE(SAo(0, 1), a2 + hstep);
;             WAIT_L(8); BAR; WAIT_L(0); MMA(0, 0, At, B0); BAR; SCHED;
;             LDB(B1, 1, 1); STAGE(SBo(1, 0), b3);
;             BAR; WAIT_L(0); MMA(0, 1, At, B1); BAR;
;             LDA(At, 1, 1); STAGE(SAo(1, 0), a3);
;             BAR; WAIT_L(0); MMA(1, 0, At, B0); BAR; SCHED;
;             STAGE(SBo(1, 1), b3 + hstep);
;             WAIT_V(6); BAR; MMA(1, 1, At, B1); BAR;
;         }
;         epi(acc, cur);
;         if (!has_next) break;
;         ZERO_ACC;
;         cur = nxt; cA = nA; cB = nB; ++ui;
;     }
;     WAIT_V(0);
;     if (wr == 0) BAR;
; DI void epi_part(const Acc& acc, const P& p, int brow, int bcol, int sl) {
;     EPI_IDX
;     const int b = brow / PB;
;     float* part = (float*)(p.ws + O_PART) + ((size_t)sl * (NBATCH * CTXL) + b * CTXL) * DM;
; #pragma unroll
;     for (int ai = 0; ai < 2; ++ai)
; #pragma unroll
;         for (int m = 0; m < 4; ++m) {
;             float* rp = part + (size_t)(ai * 128 + wr * 64 + m * 16 + fr) * DM + bcol + wc * 32 + fq * 4;
; #pragma unroll
;             for (int bj = 0; bj < 2; ++bj)
; #pragma unroll
;                 for (int n = 0; n < 2; ++n) *(f32x4*)(rp + bj * 128 + n * 16) = acc[ai][bj][m][n];
;         }
	s_waitcnt lgkmcnt(0)
	v_mfma_f32_16x16x32_bf16 v[60:63], v[144:147], v[160:163], v[60:63]
	v_mfma_f32_16x16x32_bf16 v[56:59], v[152:155], v[160:163], v[56:59]
	v_mfma_f32_16x16x32_bf16 v[52:55], v[144:147], v[168:171], v[52:55]
	v_mfma_f32_16x16x32_bf16 v[48:51], v[152:155], v[168:171], v[48:51]
	v_mfma_f32_16x16x32_bf16 v[40:43], v[144:147], v[176:179], v[40:43]
	v_mfma_f32_16x16x32_bf16 v[32:35], v[152:155], v[176:179], v[32:35]
	v_mfma_f32_16x16x32_bf16 v[24:27], v[144:147], v[184:187], v[24:27]
	v_mfma_f32_16x16x32_bf16 v[16:19], v[152:155], v[184:187], v[16:19]
	v_mfma_f32_16x16x32_bf16 v[60:63], v[148:151], v[164:167], v[60:63]
	v_mfma_f32_16x16x32_bf16 v[56:59], v[156:159], v[164:167], v[56:59]
	v_mfma_f32_16x16x32_bf16 v[52:55], v[148:151], v[172:175], v[52:55]
	v_mfma_f32_16x16x32_bf16 v[48:51], v[156:159], v[172:175], v[48:51]
	v_mfma_f32_16x16x32_bf16 v[40:43], v[148:151], v[180:183], v[40:43]
	v_mfma_f32_16x16x32_bf16 v[32:35], v[156:159], v[180:183], v[32:35]
	v_mfma_f32_16x16x32_bf16 v[24:27], v[148:151], v[188:191], v[24:27]
	v_mfma_f32_16x16x32_bf16 v[16:19], v[156:159], v[188:191], v[16:19]
	s_barrier
	s_add_u32 s36, s40, 0x160080
	s_addc_u32 s37, s41, 0
	s_add_i32 s40, s52, s3
	v_lshl_add_u64 v[144:145], s[36:37], 0, v[130:131]
	s_mov_b32 m0, s40
	s_nop 0
	global_load_lds_dwordx4 v[144:145], off
	v_lshl_add_u64 v[144:145], s[36:37], 0, v[128:129]
	s_add_i32 m0, s40, 0x2000
	s_nop 0
	global_load_lds_dwordx4 v[144:145], off
	s_waitcnt vmcnt(6)
	s_barrier
	v_mfma_f32_16x16x32_bf16 v[44:47], v[192:195], v[160:163], v[44:47]
	v_mfma_f32_16x16x32_bf16 v[36:39], v[200:203], v[160:163], v[36:39]
	v_mfma_f32_16x16x32_bf16 v[28:31], v[192:195], v[168:171], v[28:31]
	v_mfma_f32_16x16x32_bf16 v[20:23], v[200:203], v[168:171], v[20:23]
	v_mfma_f32_16x16x32_bf16 v[12:15], v[192:195], v[176:179], v[12:15]
	v_mfma_f32_16x16x32_bf16 v[8:11], v[200:203], v[176:179], v[8:11]
	v_mfma_f32_16x16x32_bf16 v[4:7], v[192:195], v[184:187], v[4:7]
	v_mfma_f32_16x16x32_bf16 v[0:3], v[200:203], v[184:187], v[0:3]
	v_mfma_f32_16x16x32_bf16 v[44:47], v[196:199], v[164:167], v[44:47]
	v_mfma_f32_16x16x32_bf16 v[36:39], v[208:211], v[164:167], v[36:39]
	v_mfma_f32_16x16x32_bf16 v[28:31], v[196:199], v[172:175], v[28:31]
	v_mfma_f32_16x16x32_bf16 v[20:23], v[208:211], v[172:175], v[20:23]
	v_mfma_f32_16x16x32_bf16 v[12:15], v[196:199], v[180:183], v[12:15]
	v_mfma_f32_16x16x32_bf16 v[8:11], v[208:211], v[180:183], v[8:11]
	v_mfma_f32_16x16x32_bf16 v[4:7], v[196:199], v[188:191], v[4:7]
	v_mfma_f32_16x16x32_bf16 v[0:3], v[208:211], v[188:191], v[0:3]
	s_add_i32 s77, s77, 2
	s_add_u32 s0, s0, 0x100
	s_addc_u32 s76, s76, 0
	s_cmp_gt_u32 s77, 5
	s_mov_b64 s[36:37], s[38:39]
	s_barrier
	s_cbranch_scc0 .LBB0_1964
	s_mul_hi_i32 s0, s75, 0x78787879
	s_lshr_b32 s37, s0, 31
	s_lshr_b32 s0, s0, 3
	s_ashr_i32 s36, s61, 4
	s_add_i32 s0, s0, s37
	s_ashr_i32 s37, s36, 31
	s_lshl_b32 s38, s0, 8
	s_ashr_i32 s39, s38, 31
	s_lshl_b64 s[36:37], s[36:37], 23
	s_add_u32 s0, s54, s36
	s_addc_u32 s40, s55, s37
	s_lshl_b64 s[36:37], s[38:39], 13
	s_add_u32 s0, s0, s36
	v_mov_b32_e32 v145, v206
	s_addc_u32 s37, s40, s37
	s_lshl_b32 s36, s61, 10
	s_and_b32 s36, s36, 0x3c00
	v_and_b32_e32 v132, 15, v145
	v_ashrrev_i32_e32 v144, 2, v145
	v_and_or_b32 v144, v144, s58, v132
	s_add_u32 s36, s0, s36
	v_lshlrev_b32_e32 v132, 1, v145
	s_addc_u32 s37, s37, 0
	v_and_b32_e32 v132, 0x180, v132
	v_lshl_add_u64 v[146:147], s[36:37], 0, v[132:133]
	v_and_b32_e32 v132, 48, v145
	v_ashrrev_i32_e32 v145, 31, v144
	v_lshl_add_u64 v[146:147], v[146:147], 0, v[132:133]
	v_lshlrev_b64 v[148:149], 13, v[144:145]
	v_lshl_add_u64 v[148:149], v[146:147], 0, v[148:149]
	global_store_dwordx4 v[148:149], v[124:127], off
	global_store_dwordx4 v[148:149], v[120:123], off offset:64
	global_store_dwordx4 v[148:149], v[108:111], off offset:512
	global_store_dwordx4 v[148:149], v[100:103], off offset:576
	s_mov_b32 s61, s74
	s_mov_b32 s75, s63
	v_or_b32_e32 v100, 16, v144
	v_ashrrev_i32_e32 v101, 31, v100
	v_lshlrev_b64 v[100:101], 13, v[100:101]
	v_lshl_add_u64 v[100:101], v[146:147], 0, v[100:101]
	global_store_dwordx4 v[100:101], v[116:119], off
	global_store_dwordx4 v[100:101], v[112:115], off offset:64
	global_store_dwordx4 v[100:101], v[92:95], off offset:512
	global_store_dwordx4 v[100:101], v[84:87], off offset:576
	s_mov_b64 s[38:39], s[18:19]
	s_mov_b64 s[36:37], s[16:17]
	v_or_b32_e32 v84, 32, v144
	v_ashrrev_i32_e32 v85, 31, v84
	v_lshlrev_b64 v[84:85], 13, v[84:85]
	v_lshl_add_u64 v[84:85], v[146:147], 0, v[84:85]
	global_store_dwordx4 v[84:85], v[104:107], off
	global_store_dwordx4 v[84:85], v[96:99], off offset:64
	global_store_dwordx4 v[84:85], v[76:79], off offset:512
	global_store_dwordx4 v[84:85], v[72:75], off offset:576
	s_nop 1
	v_or_b32_e32 v72, 48, v144
	v_ashrrev_i32_e32 v73, 31, v72
	v_lshlrev_b64 v[72:73], 13, v[72:73]
	v_lshl_add_u64 v[72:73], v[146:147], 0, v[72:73]
	global_store_dwordx4 v[72:73], v[88:91], off
	global_store_dwordx4 v[72:73], v[80:83], off offset:64
	global_store_dwordx4 v[72:73], v[68:71], off offset:512
	global_store_dwordx4 v[72:73], v[64:67], off offset:576
	s_nop 1
	v_add_co_u32_e32 v66, vcc, s59, v148
	v_lshl_add_u64 v[64:65], v[148:149], 0, s[10:11]
	s_nop 0
	v_addc_co_u32_e32 v67, vcc, 0, v149, vcc
	global_store_dwordx4 v[66:67], v[60:63], off
	global_store_dwordx4 v[64:65], v[56:59], off offset:64
	global_store_dwordx4 v[64:65], v[44:47], off offset:512
	global_store_dwordx4 v[64:65], v[36:39], off offset:576
	s_nop 1
	v_add_co_u32_e32 v38, vcc, s60, v148
	v_lshl_add_u64 v[36:37], v[148:149], 0, s[12:13]
	s_nop 0
	v_addc_co_u32_e32 v39, vcc, 0, v149, vcc
	global_store_dwordx4 v[38:39], v[52:55], off
	global_store_dwordx4 v[36:37], v[48:51], off offset:64
	global_store_dwordx4 v[36:37], v[28:31], off offset:512
	global_store_dwordx4 v[36:37], v[20:23], off offset:576
	s_nop 1
	v_add_co_u32_e32 v22, vcc, 0x140000, v148
	v_lshl_add_u64 v[20:21], v[148:149], 0, s[14:15]
	s_nop 0
	v_addc_co_u32_e32 v23, vcc, 0, v149, vcc
	global_store_dwordx4 v[22:23], v[40:43], off
	global_store_dwordx4 v[20:21], v[32:35], off offset:64
	global_store_dwordx4 v[20:21], v[12:15], off offset:512
	global_store_dwordx4 v[20:21], v[8:11], off offset:576
	s_nop 1
	v_add_co_u32_e32 v10, vcc, 0x160000, v148
	v_lshl_add_u64 v[8:9], v[148:149], 0, s[6:7]
	s_nop 0
	v_addc_co_u32_e32 v11, vcc, 0, v149, vcc
	s_and_b64 vcc, exec, s[4:5]
	global_store_dwordx4 v[10:11], v[24:27], off
	global_store_dwordx4 v[8:9], v[16:19], off offset:64
	global_store_dwordx4 v[8:9], v[4:7], off offset:512
	global_store_dwordx4 v[8:9], v[0:3], off offset:576
	s_cbranch_vccz .LBB0_1961
	s_waitcnt vmcnt(0)
	s_cmpk_gt_u32 s2, 0xff
	s_cbranch_scc1 .LBB0_1968
	s_barrier

; #define WAIT_V(n) asm volatile("s_waitcnt vmcnt(" #n ")" ::: "memory")
; #define WAIT_L(n) asm volatile("s_waitcnt lgkmcnt(" #n ")" ::: "memory")
; #define BAR __builtin_amdgcn_s_barrier()
; #define SCHED __builtin_amdgcn_sched_barrier(0)
; template <class Get, class Epi>
; DI void gemm_stream(LAS unsigned char* lds, const int K, const int ld, Get get, Epi epi) {
;     ...
;         for (int t = 0; t < nt; t += 2) {
;             const bool last = (t == nt - 2);
;             const char* a1 = cA + (size_t)(t + 1) * kstep;
;             const char* a2 = last ? nA : cA + (size_t)(t + 2) * kstep;
;             const char* b2 = last ? nB : cB + (size_t)(t + 2) * kstep;
;             const char* a3 = a2 + kstep;
;             const char* b3 = b2 + kstep;
;             LDB(B0, 0, 0); SCHED; LDA(At, 0, 0); STAGE(SAo(1, 1), a1 + hstep);
;             WAIT_L(8); BAR; WAIT_L(0); MMA(0, 0, At, B0); BAR; SCHED;
;             LDB(B1, 0, 1); STAGE(SBo(0, 0), b2);
;             BAR; WAIT_L(0); MMA(0, 1, At, B1); BAR;
;             LDA(At, 0, 1); STAGE(SAo(0, 0), a2);
;             BAR; WAIT_L(0); MMA(1, 0, At, B0); BAR; SCHED;
;             STAGE(SBo(0, 1), b2 + hstep);
;             WAIT_V(6); BAR; MMA(1, 1, At, B1); BAR;
;             LDB(B0, 1, 0); SCHED; LDA(At, 1, 0); STAGE(SAo(0, 1), a2 + hstep);
;             WAIT_L(8); BAR; WAIT_L(0); MMA(0, 0, At, B0); BAR; SCHED;
.LBB0_2102:
	ds_read_b128 v[128:131], v209
	ds_read_b128 v[132:135], v209 offset:1024
	ds_read_b128 v[136:139], v209 offset:2048
	ds_read_b128 v[156:159], v209 offset:3072
	s_add_u32 s28, s64, 0xfff80080
	s_addc_u32 s29, s65, -1
	s_cmp_eq_u32 s7, 28
	s_cselect_b32 s77, s59, s29
	s_cselect_b32 s76, s58, s28
	s_cselect_b32 s75, s61, s3
	s_cselect_b32 s74, s60, s2
	v_lshl_add_u64 v[140:141], s[64:65], 0, v[148:149]
	s_add_i32 m0, s23, 0xc000
	ds_read_b128 v[160:163], v210
	ds_read_b128 v[164:167], v210 offset:1024
	ds_read_b128 v[168:171], v210 offset:2048
	ds_read_b128 v[172:175], v210 offset:3072
	ds_read_b128 v[176:179], v210 offset:4096
	ds_read_b128 v[180:183], v210 offset:5120
	ds_read_b128 v[184:187], v210 offset:6144
	ds_read_b128 v[188:191], v210 offset:7168
	global_load_lds_dwordx4 v[140:141], off
	v_lshl_add_u64 v[140:141], s[64:65], 0, v[150:151]
	s_add_i32 m0, s23, 0xe000
	s_nop 0
	global_load_lds_dwordx4 v[140:141], off
	s_waitcnt lgkmcnt(8)
	s_barrier
	s_waitcnt lgkmcnt(0)
	v_mfma_f32_16x16x32_bf16 v[124:127], v[128:131], v[160:163], v[124:127]
	v_mfma_f32_16x16x32_bf16 v[116:119], v[136:139], v[160:163], v[116:119]
	v_mfma_f32_16x16x32_bf16 v[108:111], v[128:131], v[168:171], v[108:111]
	v_mfma_f32_16x16x32_bf16 v[100:103], v[136:139], v[168:171], v[100:103]
	v_mfma_f32_16x16x32_bf16 v[92:95], v[128:131], v[176:179], v[92:95]
	v_mfma_f32_16x16x32_bf16 v[84:87], v[136:139], v[176:179], v[84:87]
	v_mfma_f32_16x16x32_bf16 v[76:79], v[128:131], v[184:187], v[76:79]
	v_mfma_f32_16x16x32_bf16 v[68:71], v[136:139], v[184:187], v[68:71]
	v_mfma_f32_16x16x32_bf16 v[124:127], v[132:135], v[164:167], v[124:127]
	v_mfma_f32_16x16x32_bf16 v[116:119], v[156:159], v[164:167], v[116:119]
	v_mfma_f32_16x16x32_bf16 v[108:111], v[132:135], v[172:175], v[108:111]
	v_mfma_f32_16x16x32_bf16 v[100:103], v[156:159], v[172:175], v[100:103]
	v_mfma_f32_16x16x32_bf16 v[92:95], v[132:135], v[180:183], v[92:95]
	v_mfma_f32_16x16x32_bf16 v[84:87], v[156:159], v[180:183], v[84:87]
	v_mfma_f32_16x16x32_bf16 v[76:79], v[132:135], v[188:191], v[76:79]
	v_mfma_f32_16x16x32_bf16 v[68:71], v[156:159], v[188:191], v[68:71]
	s_barrier
	s_add_i32 s28, s90, s21
	v_lshl_add_u64 v[140:141], s[74:75], 0, v[142:143]
	s_mov_b32 m0, s28
	ds_read_b128 v[192:195], v211
	ds_read_b128 v[196:199], v211 offset:1024
	ds_read_b128 v[200:203], v211 offset:2048
	ds_read_b128 v[212:215], v211 offset:3072
	global_load_lds_dwordx4 v[140:141], off
	v_lshl_add_u64 v[204:205], s[74:75], 0, v[144:145]
	s_add_i32 m0, s28, 0x2000
	s_nop 0
	global_load_lds_dwordx4 v[204:205], off
	s_barrier
	s_waitcnt lgkmcnt(0)
	v_mfma_f32_16x16x32_bf16 v[120:123], v[192:195], v[160:163], v[120:123]
	v_mfma_f32_16x16x32_bf16 v[112:115], v[200:203], v[160:163], v[112:115]
	v_mfma_f32_16x16x32_bf16 v[104:107], v[192:195], v[168:171], v[104:107]
	v_mfma_f32_16x16x32_bf16 v[96:99], v[200:203], v[168:171], v[96:99]
	v_mfma_f32_16x16x32_bf16 v[88:91], v[192:195], v[176:179], v[88:91]
	v_mfma_f32_16x16x32_bf16 v[80:83], v[200:203], v[176:179], v[80:83]
	v_mfma_f32_16x16x32_bf16 v[72:75], v[192:195], v[184:187], v[72:75]
	v_mfma_f32_16x16x32_bf16 v[64:67], v[200:203], v[184:187], v[64:67]
	v_mfma_f32_16x16x32_bf16 v[120:123], v[196:199], v[164:167], v[120:123]
	v_mfma_f32_16x16x32_bf16 v[112:115], v[212:215], v[164:167], v[112:115]
	v_mfma_f32_16x16x32_bf16 v[104:107], v[196:199], v[172:175], v[104:107]
	v_mfma_f32_16x16x32_bf16 v[96:99], v[212:215], v[172:175], v[96:99]
	v_mfma_f32_16x16x32_bf16 v[88:91], v[196:199], v[180:183], v[88:91]
	v_mfma_f32_16x16x32_bf16 v[80:83], v[212:215], v[180:183], v[80:83]
	v_mfma_f32_16x16x32_bf16 v[72:75], v[196:199], v[188:191], v[72:75]
	v_mfma_f32_16x16x32_bf16 v[64:67], v[212:215], v[188:191], v[64:67]
	s_mov_b32 m0, s23
	v_lshl_add_u64 v[216:217], s[76:77], 0, v[142:143]
	s_barrier
	ds_read_b128 v[160:163], v210 offset:16384
	ds_read_b128 v[164:167], v210 offset:17408
	ds_read_b128 v[168:171], v210 offset:18432
	ds_read_b128 v[172:175], v210 offset:19456
	ds_read_b128 v[176:179], v210 offset:20480
	ds_read_b128 v[180:183], v210 offset:21504
	ds_read_b128 v[184:187], v210 offset:22528
	ds_read_b128 v[188:191], v210 offset:23552
	global_load_lds_dwordx4 v[216:217], off
	v_lshl_add_u64 v[218:219], s[76:77], 0, v[144:145]
	s_mov_b32 m0, s35
	s_nop 0
	global_load_lds_dwordx4 v[218:219], off
	s_barrier
	s_waitcnt lgkmcnt(0)
	v_mfma_f32_16x16x32_bf16 v[60:63], v[128:131], v[160:163], v[60:63]
	v_mfma_f32_16x16x32_bf16 v[52:55], v[136:139], v[160:163], v[52:55]
	v_mfma_f32_16x16x32_bf16 v[44:47], v[128:131], v[168:171], v[44:47]
	v_mfma_f32_16x16x32_bf16 v[36:39], v[136:139], v[168:171], v[36:39]
	v_mfma_f32_16x16x32_bf16 v[28:31], v[128:131], v[176:179], v[28:31]
	v_mfma_f32_16x16x32_bf16 v[20:23], v[136:139], v[176:179], v[20:23]
	v_mfma_f32_16x16x32_bf16 v[12:15], v[128:131], v[184:187], v[12:15]
	v_mfma_f32_16x16x32_bf16 v[4:7], v[136:139], v[184:187], v[4:7]
	v_mfma_f32_16x16x32_bf16 v[60:63], v[132:135], v[164:167], v[60:63]
	v_mfma_f32_16x16x32_bf16 v[52:55], v[156:159], v[164:167], v[52:55]
	v_mfma_f32_16x16x32_bf16 v[44:47], v[132:135], v[172:175], v[44:47]
	v_mfma_f32_16x16x32_bf16 v[36:39], v[156:159], v[172:175], v[36:39]
	v_mfma_f32_16x16x32_bf16 v[28:31], v[132:135], v[180:183], v[28:31]
	v_mfma_f32_16x16x32_bf16 v[20:23], v[156:159], v[180:183], v[20:23]
	v_mfma_f32_16x16x32_bf16 v[12:15], v[132:135], v[188:191], v[12:15]
	v_mfma_f32_16x16x32_bf16 v[4:7], v[156:159], v[188:191], v[4:7]
	s_barrier
; #define WAIT_V(n) asm volatile("s_waitcnt vmcnt(" #n ")" ::: "memory")
; #define WAIT_L(n) asm volatile("s_waitcnt lgkmcnt(" #n ")" ::: "memory")
; #define BAR __builtin_amdgcn_s_barrier()
; #define SCHED __builtin_amdgcn_sched_barrier(0)
; template <class Get, class Epi>
; DI void gemm_stream(LAS unsigned char* lds, const int K, const int ld, Get get, Epi epi) {
;     ...
;             STAGE(SBo(0, 1), b2 + hstep);
;             WAIT_V(6); BAR; MMA(1, 1, At, B1); BAR;
;             LDB(B0, 1, 0); SCHED; LDA(At, 1, 0); STAGE(SAo(0, 1), a2 + hstep);
;             WAIT_L(8); BAR; WAIT_L(0); MMA(0, 0, At, B0); BAR; SCHED;
;             LDB(B1, 1, 1); STAGE(SBo(1, 0), b3);
;             BAR; WAIT_L(0); MMA(0, 1, At, B1); BAR;
;             LDA(At, 1, 1); STAGE(SAo(1, 0), a3);
;             BAR; WAIT_L(0); MMA(1, 0, At, B0); BAR; SCHED;
	s_add_u32 s28, s74, 0x80000
	s_addc_u32 s29, s75, 0
	s_add_i32 s57, s91, s21
	v_lshl_add_u64 v[128:129], s[28:29], 0, v[142:143]
	s_mov_b32 m0, s57
	s_nop 0
	global_load_lds_dwordx4 v[128:129], off
	v_lshl_add_u64 v[128:129], s[28:29], 0, v[144:145]
	s_add_i32 m0, s57, 0x2000
	s_nop 0
	global_load_lds_dwordx4 v[128:129], off
	s_waitcnt vmcnt(6)
	s_barrier
	v_mfma_f32_16x16x32_bf16 v[56:59], v[192:195], v[160:163], v[56:59]
	v_mfma_f32_16x16x32_bf16 v[48:51], v[200:203], v[160:163], v[48:51]
	v_mfma_f32_16x16x32_bf16 v[40:43], v[192:195], v[168:171], v[40:43]
	v_mfma_f32_16x16x32_bf16 v[32:35], v[200:203], v[168:171], v[32:35]
	v_mfma_f32_16x16x32_bf16 v[24:27], v[192:195], v[176:179], v[24:27]
	v_mfma_f32_16x16x32_bf16 v[16:19], v[200:203], v[176:179], v[16:19]
	v_mfma_f32_16x16x32_bf16 v[8:11], v[192:195], v[184:187], v[8:11]
	v_mfma_f32_16x16x32_bf16 v[0:3], v[200:203], v[184:187], v[0:3]
	v_mfma_f32_16x16x32_bf16 v[56:59], v[196:199], v[164:167], v[56:59]
	v_mfma_f32_16x16x32_bf16 v[48:51], v[212:215], v[164:167], v[48:51]
	v_mfma_f32_16x16x32_bf16 v[40:43], v[196:199], v[172:175], v[40:43]
	v_mfma_f32_16x16x32_bf16 v[32:35], v[212:215], v[172:175], v[32:35]
	v_mfma_f32_16x16x32_bf16 v[24:27], v[196:199], v[180:183], v[24:27]
	v_mfma_f32_16x16x32_bf16 v[16:19], v[212:215], v[180:183], v[16:19]
	v_mfma_f32_16x16x32_bf16 v[8:11], v[196:199], v[188:191], v[8:11]
	v_mfma_f32_16x16x32_bf16 v[0:3], v[212:215], v[188:191], v[0:3]
	s_add_i32 s57, 16, 0x18000
	v_add_u32_e32 v146, s57, v208
	s_barrier
	ds_read_b128 v[128:131], v146
	ds_read_b128 v[132:135], v146 offset:1024
	ds_read_b128 v[136:139], v146 offset:2048
	ds_read_b128 v[156:159], v146 offset:3072
	s_add_u32 s28, s76, 0x80000
	s_addc_u32 s29, s77, 0
	s_mov_b32 m0, s55
	v_lshl_add_u64 v[192:193], s[28:29], 0, v[142:143]
	ds_read_b128 v[160:163], v210 offset:32768
	ds_read_b128 v[164:167], v210 offset:33792
	ds_read_b128 v[168:171], v210 offset:34816
	ds_read_b128 v[172:175], v210 offset:35840
	ds_read_b128 v[176:179], v210 offset:36864
	ds_read_b128 v[180:183], v210 offset:37888
	ds_read_b128 v[184:187], v210 offset:38912
	ds_read_b128 v[188:191], v210 offset:39936
	global_load_lds_dwordx4 v[192:193], off
	v_lshl_add_u64 v[192:193], s[28:29], 0, v[144:145]
	s_mov_b32 m0, s82
	s_nop 0
	global_load_lds_dwordx4 v[192:193], off
	s_waitcnt lgkmcnt(8)
	s_barrier
	s_waitcnt lgkmcnt(0)
	v_mfma_f32_16x16x32_bf16 v[124:127], v[128:131], v[160:163], v[124:127]
	v_mfma_f32_16x16x32_bf16 v[116:119], v[136:139], v[160:163], v[116:119]
	v_mfma_f32_16x16x32_bf16 v[108:111], v[128:131], v[168:171], v[108:111]
	v_mfma_f32_16x16x32_bf16 v[100:103], v[136:139], v[168:171], v[100:103]
	v_mfma_f32_16x16x32_bf16 v[92:95], v[128:131], v[176:179], v[92:95]
	v_mfma_f32_16x16x32_bf16 v[84:87], v[136:139], v[176:179], v[84:87]
	v_mfma_f32_16x16x32_bf16 v[76:79], v[128:131], v[184:187], v[76:79]
	v_mfma_f32_16x16x32_bf16 v[68:71], v[136:139], v[184:187], v[68:71]
	v_mfma_f32_16x16x32_bf16 v[124:127], v[132:135], v[164:167], v[124:127]
	v_mfma_f32_16x16x32_bf16 v[116:119], v[156:159], v[164:167], v[116:119]
	v_mfma_f32_16x16x32_bf16 v[108:111], v[132:135], v[172:175], v[108:111]
	v_mfma_f32_16x16x32_bf16 v[100:103], v[156:159], v[172:175], v[100:103]
	v_mfma_f32_16x16x32_bf16 v[92:95], v[132:135], v[180:183], v[92:95]
	v_mfma_f32_16x16x32_bf16 v[84:87], v[156:159], v[180:183], v[84:87]
	v_mfma_f32_16x16x32_bf16 v[76:79], v[132:135], v[188:191], v[76:79]
	v_mfma_f32_16x16x32_bf16 v[68:71], v[156:159], v[188:191], v[68:71]
	s_barrier
	s_add_i32 s63, 16, 0x1c000
	s_add_i32 s28, s57, s21
	v_add_u32_e32 v146, s63, v208
	v_lshl_add_u64 v[140:141], v[140:141], 0, s[0:1]
	s_mov_b32 m0, s28
	ds_read_b128 v[192:195], v146
	ds_read_b128 v[196:199], v146 offset:1024
	ds_read_b128 v[200:203], v146 offset:2048
	ds_read_b128 v[212:215], v146 offset:3072
	global_load_lds_dwordx4 v[140:141], off
	v_lshl_add_u64 v[140:141], v[204:205], 0, s[0:1]
	s_add_i32 m0, s28, 0x2000
	s_nop 0
	global_load_lds_dwordx4 v[140:141], off
	s_barrier
	s_waitcnt lgkmcnt(0)
	v_mfma_f32_16x16x32_bf16 v[120:123], v[192:195], v[160:163], v[120:123]
	v_mfma_f32_16x16x32_bf16 v[112:115], v[200:203], v[160:163], v[112:115]
	v_mfma_f32_16x16x32_bf16 v[104:107], v[192:195], v[168:171], v[104:107]
	v_mfma_f32_16x16x32_bf16 v[96:99], v[200:203], v[168:171], v[96:99]
	v_mfma_f32_16x16x32_bf16 v[88:91], v[192:195], v[176:179], v[88:91]
	v_mfma_f32_16x16x32_bf16 v[80:83], v[200:203], v[176:179], v[80:83]
	v_mfma_f32_16x16x32_bf16 v[72:75], v[192:195], v[184:187], v[72:75]
	v_mfma_f32_16x16x32_bf16 v[64:67], v[200:203], v[184:187], v[64:67]
	v_mfma_f32_16x16x32_bf16 v[120:123], v[196:199], v[164:167], v[120:123]
	v_mfma_f32_16x16x32_bf16 v[112:115], v[212:215], v[164:167], v[112:115]
	v_mfma_f32_16x16x32_bf16 v[104:107], v[196:199], v[172:175], v[104:107]
	v_mfma_f32_16x16x32_bf16 v[96:99], v[212:215], v[172:175], v[96:99]
	v_mfma_f32_16x16x32_bf16 v[88:91], v[196:199], v[180:183], v[88:91]
	v_mfma_f32_16x16x32_bf16 v[80:83], v[212:215], v[180:183], v[80:83]
	v_mfma_f32_16x16x32_bf16 v[72:75], v[196:199], v[188:191], v[72:75]
	v_mfma_f32_16x16x32_bf16 v[64:67], v[212:215], v[188:191], v[64:67]
	s_mov_b32 m0, s83
	v_lshl_add_u64 v[140:141], v[216:217], 0, s[0:1]
	s_barrier
	ds_read_b128 v[160:163], v210 offset:49152
	ds_read_b128 v[164:167], v210 offset:50176
	ds_read_b128 v[168:171], v210 offset:51200
	ds_read_b128 v[172:175], v210 offset:52224
	ds_read_b128 v[176:179], v210 offset:53248
	ds_read_b128 v[180:183], v210 offset:54272
	ds_read_b128 v[184:187], v210 offset:55296
	ds_read_b128 v[188:191], v210 offset:56320
	global_load_lds_dwordx4 v[140:141], off
	v_lshl_add_u64 v[140:141], v[218:219], 0, s[0:1]
	s_mov_b32 m0, s85
	s_nop 0
	global_load_lds_dwordx4 v[140:141], off
	s_barrier
; #define WAIT_V(n) asm volatile("s_waitcnt vmcnt(" #n ")" ::: "memory")
; #define WAIT_L(n) asm volatile("s_waitcnt lgkmcnt(" #n ")" ::: "memory")
; #define BAR __builtin_amdgcn_s_barrier()
; #define SCHED __builtin_amdgcn_sched_barrier(0)
; template <class Get, class Epi>
; DI void gemm_stream(LAS unsigned char* lds, const int K, const int ld, Get get, Epi epi) {
;     ...
;             LDB(B0, 1, 0); SCHED; LDA(At, 1, 0); STAGE(SAo(0, 1), a2 + hstep);
;             WAIT_L(8); BAR; WAIT_L(0); MMA(0, 0, At, B0); BAR; SCHED;
;             LDB(B1, 1, 1); STAGE(SBo(1, 0), b3);
;             BAR; WAIT_L(0); MMA(0, 1, At, B1); BAR;
;             LDA(At, 1, 1); STAGE(SAo(1, 0), a3);
;             BAR; WAIT_L(0); MMA(1, 0, At, B0); BAR; SCHED;
;             STAGE(SBo(1, 1), b3 + hstep);
;             WAIT_V(6); BAR; MMA(1, 1, At, B1); BAR;
;         }
; DI void epi_plain(const Acc& acc, int brow, bf16_t* dst, int ld, int coff, const float* rs) {
;     EPI_IDX
; #pragma unroll
;     for (int ai = 0; ai < 2; ++ai)
; #pragma unroll
;         for (int m = 0; m < 4; ++m) {
;             const int lr = ai * 128 + wr * 64 + m * 16 + fr;
;             const float s = rs ? rs[lr] : 1.f;
;             bf16_t* rp = dst + (size_t)(brow + lr) * ld + coff + wc * 32 + fq * 4;
; #pragma unroll
;             for (int bj = 0; bj < 2; ++bj)
; #pragma unroll
;                 for (int n = 0; n < 2; ++n) { const f32x4 v = acc[ai][bj][m][n]; st4(rp + bj * 128 + n * 16, v[0] * s, v[1] * s, v[2] * s, v[3] * s); }
; DI void phase_inproj1(const P& p, char* shm) {
;     ...
;     auto epi = [&](const Acc& acc, const Unit& u) {
;         const int brow = u.pm * 256, pn = u.pn;
;         const int b = u.pm / 17, pt = u.pm % 17;
;         const size_t latrow0 = (size_t)b * SEQ + (pt - 1) * 256;
;         if (pn < 8) epi_rope256(acc, p, brow, (bf16_t*)(p.ws + O_Q1), latrow0, pn * 256, 1.f);
;         else if (pn < 16) epi_rope256(acc, p, brow, (bf16_t*)(p.ws + O_K1), (size_t)brow, (pn - 8) * 256, 0.0625f);
;         else if (pn < 32) epi_T<32>(acc, (pn - 16) * 256, brow, (bf16_t*)(p.ws + O_V1T), 4096, nullptr);
;         else epi_plain(acc, 0, (bf16_t*)(p.ws + O_G1) + latrow0 * 4096, 4096, (pn - 32) * 256, nullptr);
	s_waitcnt lgkmcnt(0)
	v_mfma_f32_16x16x32_bf16 v[60:63], v[128:131], v[160:163], v[60:63]
	v_mfma_f32_16x16x32_bf16 v[52:55], v[136:139], v[160:163], v[52:55]
	v_mfma_f32_16x16x32_bf16 v[44:47], v[128:131], v[168:171], v[44:47]
	v_mfma_f32_16x16x32_bf16 v[36:39], v[136:139], v[168:171], v[36:39]
	v_mfma_f32_16x16x32_bf16 v[28:31], v[128:131], v[176:179], v[28:31]
	v_mfma_f32_16x16x32_bf16 v[20:23], v[136:139], v[176:179], v[20:23]
	v_mfma_f32_16x16x32_bf16 v[12:15], v[128:131], v[184:187], v[12:15]
	v_mfma_f32_16x16x32_bf16 v[4:7], v[136:139], v[184:187], v[4:7]
	v_mfma_f32_16x16x32_bf16 v[60:63], v[132:135], v[164:167], v[60:63]
	v_mfma_f32_16x16x32_bf16 v[52:55], v[156:159], v[164:167], v[52:55]
	v_mfma_f32_16x16x32_bf16 v[44:47], v[132:135], v[172:175], v[44:47]
	v_mfma_f32_16x16x32_bf16 v[36:39], v[156:159], v[172:175], v[36:39]
	v_mfma_f32_16x16x32_bf16 v[28:31], v[132:135], v[180:183], v[28:31]
	v_mfma_f32_16x16x32_bf16 v[20:23], v[156:159], v[180:183], v[20:23]
	v_mfma_f32_16x16x32_bf16 v[12:15], v[132:135], v[188:191], v[12:15]
	v_mfma_f32_16x16x32_bf16 v[4:7], v[156:159], v[188:191], v[4:7]
	s_barrier
	s_add_u32 s28, s74, 0x80080
	s_addc_u32 s29, s75, 0
	s_add_i32 s57, s63, s21
	v_lshl_add_u64 v[128:129], s[28:29], 0, v[142:143]
	s_mov_b32 m0, s57
	s_nop 0
	global_load_lds_dwordx4 v[128:129], off
	v_lshl_add_u64 v[128:129], s[28:29], 0, v[144:145]
	s_add_i32 m0, s57, 0x2000
	s_nop 0
	global_load_lds_dwordx4 v[128:129], off
	s_waitcnt vmcnt(6)
	s_barrier
	v_mfma_f32_16x16x32_bf16 v[56:59], v[192:195], v[160:163], v[56:59]
	v_mfma_f32_16x16x32_bf16 v[48:51], v[200:203], v[160:163], v[48:51]
	v_mfma_f32_16x16x32_bf16 v[40:43], v[192:195], v[168:171], v[40:43]
	v_mfma_f32_16x16x32_bf16 v[32:35], v[200:203], v[168:171], v[32:35]
	v_mfma_f32_16x16x32_bf16 v[24:27], v[192:195], v[176:179], v[24:27]
	v_mfma_f32_16x16x32_bf16 v[16:19], v[200:203], v[176:179], v[16:19]
	v_mfma_f32_16x16x32_bf16 v[8:11], v[192:195], v[184:187], v[8:11]
	v_mfma_f32_16x16x32_bf16 v[0:3], v[200:203], v[184:187], v[0:3]
	v_mfma_f32_16x16x32_bf16 v[56:59], v[196:199], v[164:167], v[56:59]
	v_mfma_f32_16x16x32_bf16 v[48:51], v[212:215], v[164:167], v[48:51]
	v_mfma_f32_16x16x32_bf16 v[40:43], v[196:199], v[172:175], v[40:43]
	v_mfma_f32_16x16x32_bf16 v[32:35], v[212:215], v[172:175], v[32:35]
	v_mfma_f32_16x16x32_bf16 v[24:27], v[196:199], v[180:183], v[24:27]
	v_mfma_f32_16x16x32_bf16 v[16:19], v[212:215], v[180:183], v[16:19]
	v_mfma_f32_16x16x32_bf16 v[8:11], v[196:199], v[188:191], v[8:11]
	v_mfma_f32_16x16x32_bf16 v[0:3], v[212:215], v[188:191], v[0:3]
	s_add_i32 s7, s7, 2
	s_add_u32 s64, s64, 0x100
	s_addc_u32 s65, s65, 0
	s_add_u32 s2, s2, 0x100
	s_addc_u32 s3, s3, 0
	s_cmp_gt_u32 s7, 29
	s_barrier
	s_cbranch_scc0 .LBB0_2102
	s_mul_hi_i32 s2, s6, 0x78787879
	s_lshr_b32 s3, s2, 31
	s_ashr_i32 s2, s2, 3
	s_add_i32 s76, s2, s3
	s_mul_i32 s2, s76, 17
	s_lshl_b32 s74, s6, 8
	s_sub_i32 s6, s6, s2
	s_lshl_b32 s6, s6, 8
	s_ashr_i32 s77, s76, 31
	s_addk_i32 s6, 0xff00
	s_lshl_b64 s[2:3], s[76:77], 12
	s_ashr_i32 s7, s6, 31
	s_add_u32 s64, s2, s6
	s_addc_u32 s65, s3, s7
	s_cmp_gt_i32 s62, 7
	s_mov_b64 s[6:7], -1
	s_cbranch_scc0 .LBB0_2145
	s_cmp_gt_u32 s62, 15
	s_cbranch_scc0 .LBB0_2110
	s_cmp_gt_u32 s62, 31
	v_cvt_pk_bf16_f32 v204, v124, v125
	v_cvt_pk_bf16_f32 v205, v126, v127
	v_cvt_pk_bf16_f32 v202, v116, v117
	v_cvt_pk_bf16_f32 v203, v118, v119
	v_cvt_pk_bf16_f32 v200, v120, v121
	v_cvt_pk_bf16_f32 v201, v122, v123
	v_cvt_pk_bf16_f32 v198, v112, v113
	v_cvt_pk_bf16_f32 v199, v114, v115
	v_cvt_pk_bf16_f32 v196, v108, v109
	v_cvt_pk_bf16_f32 v197, v110, v111
	v_cvt_pk_bf16_f32 v194, v100, v101
	v_cvt_pk_bf16_f32 v195, v102, v103
	v_cvt_pk_bf16_f32 v192, v104, v105
	v_cvt_pk_bf16_f32 v193, v106, v107
	v_cvt_pk_bf16_f32 v190, v96, v97
	v_cvt_pk_bf16_f32 v191, v98, v99
	v_cvt_pk_bf16_f32 v188, v92, v93
	v_cvt_pk_bf16_f32 v189, v94, v95
	v_cvt_pk_bf16_f32 v186, v84, v85
	v_cvt_pk_bf16_f32 v187, v86, v87
	v_cvt_pk_bf16_f32 v184, v88, v89
	v_cvt_pk_bf16_f32 v185, v90, v91
	v_cvt_pk_bf16_f32 v182, v80, v81
	v_cvt_pk_bf16_f32 v183, v82, v83
	v_cvt_pk_bf16_f32 v180, v76, v77
	v_cvt_pk_bf16_f32 v181, v78, v79
	v_cvt_pk_bf16_f32 v178, v68, v69
	v_cvt_pk_bf16_f32 v179, v70, v71
	v_cvt_pk_bf16_f32 v176, v72, v73
	v_cvt_pk_bf16_f32 v177, v74, v75
	v_cvt_pk_bf16_f32 v174, v64, v65
	v_cvt_pk_bf16_f32 v175, v66, v67
	v_cvt_pk_bf16_f32 v172, v60, v61
	v_cvt_pk_bf16_f32 v173, v62, v63
	v_cvt_pk_bf16_f32 v170, v52, v53
	v_cvt_pk_bf16_f32 v171, v54, v55
	v_cvt_pk_bf16_f32 v168, v56, v57
	v_cvt_pk_bf16_f32 v169, v58, v59
	v_cvt_pk_bf16_f32 v166, v48, v49
	v_cvt_pk_bf16_f32 v167, v50, v51
	v_cvt_pk_bf16_f32 v164, v44, v45
	v_cvt_pk_bf16_f32 v165, v46, v47
	v_cvt_pk_bf16_f32 v162, v36, v37
	v_cvt_pk_bf16_f32 v163, v38, v39
	v_cvt_pk_bf16_f32 v160, v40, v41
	v_cvt_pk_bf16_f32 v161, v42, v43
	v_cvt_pk_bf16_f32 v158, v32, v33
	v_cvt_pk_bf16_f32 v159, v34, v35
	v_cvt_pk_bf16_f32 v156, v28, v29
	v_cvt_pk_bf16_f32 v157, v30, v31
	v_cvt_pk_bf16_f32 v140, v20, v21
	v_cvt_pk_bf16_f32 v141, v22, v23
	v_cvt_pk_bf16_f32 v138, v24, v25
	v_cvt_pk_bf16_f32 v139, v26, v27
	v_cvt_pk_bf16_f32 v136, v16, v17
	v_cvt_pk_bf16_f32 v137, v18, v19
	v_cvt_pk_bf16_f32 v134, v12, v13
	v_cvt_pk_bf16_f32 v135, v14, v15
	v_cvt_pk_bf16_f32 v132, v4, v5
	v_cvt_pk_bf16_f32 v133, v6, v7
	v_cvt_pk_bf16_f32 v130, v8, v9
	v_cvt_pk_bf16_f32 v131, v10, v11
	v_cvt_pk_bf16_f32 v128, v0, v1
	v_cvt_pk_bf16_f32 v129, v2, v3
	s_cbranch_scc0 .LBB0_2107
; DI void epi_plain(const Acc& acc, int brow, bf16_t* dst, int ld, int coff, const float* rs) {
;     EPI_IDX
; #pragma unroll
;     for (int ai = 0; ai < 2; ++ai)
; #pragma unroll
;         for (int m = 0; m < 4; ++m) {
;             const int lr = ai * 128 + wr * 64 + m * 16 + fr;
;             const float s = rs ? rs[lr] : 1.f;
;             bf16_t* rp = dst + (size_t)(brow + lr) * ld + coff + wc * 32 + fq * 4;
; #pragma unroll
;             for (int bj = 0; bj < 2; ++bj)
; #pragma unroll
;                 for (int n = 0; n < 2; ++n) { const f32x4 v = acc[ai][bj][m][n]; st4(rp + bj * 128 + n * 16, v[0] * s, v[1] * s, v[2] * s, v[3] * s); }
;         }
; DI void phase_inproj1(const P& p, char* shm) {
;     ...
;         else epi_plain(acc, 0, (bf16_t*)(p.ws + O_G1) + latrow0 * 4096, 4096, (pn - 32) * 256, nullptr);
	s_lshl_b64 s[2:3], s[64:65], 13
	s_add_u32 s2, s26, s2
	s_addc_u32 s3, s27, s3
	v_mov_b32_e32 v146, v206
	s_lshl_b32 s6, s62, 9
	s_add_u32 s2, s2, s6
	v_and_b32_e32 v212, 15, v146
	v_ashrrev_i32_e32 v213, 2, v146
	v_and_or_b32 v212, v213, s92, v212
	s_addc_u32 s3, s3, 0
	v_lshrrev_b32_e32 v213, 1, v146
	v_and_b32_e32 v146, 0xc0, v146
	v_lshl_add_u64 v[214:215], s[2:3], 0, v[146:147]
	v_and_b32_e32 v146, 24, v213
	v_or_b32_e32 v218, 16, v212
	v_lshl_add_u64 v[214:215], v[214:215], 0, v[146:147]
	s_mov_b64 s[2:3], 0x1a3fc000
	v_ashrrev_i32_e32 v213, 31, v212
	v_ashrrev_i32_e32 v219, 31, v218
	v_lshl_add_u64 v[214:215], v[214:215], 0, s[2:3]
	v_lshlrev_b64 v[216:217], 13, v[212:213]
	v_lshlrev_b64 v[218:219], 13, v[218:219]
	v_lshl_add_u64 v[216:217], v[214:215], 0, v[216:217]
	v_lshl_add_u64 v[218:219], v[214:215], 0, v[218:219]
	global_store_dwordx2 v[216:217], v[204:205], off
	global_store_dwordx2 v[216:217], v[202:203], off offset:32
	global_store_dwordx2 v[216:217], v[200:201], off offset:256
	global_store_dwordx2 v[216:217], v[198:199], off offset:288
	global_store_dwordx2 v[218:219], v[196:197], off
	global_store_dwordx2 v[218:219], v[194:195], off offset:32
	global_store_dwordx2 v[218:219], v[192:193], off offset:256
	global_store_dwordx2 v[218:219], v[190:191], off offset:288
	v_or_b32_e32 v218, 32, v212
	v_or_b32_e32 v212, 48, v212
	v_ashrrev_i32_e32 v219, 31, v218
	v_ashrrev_i32_e32 v213, 31, v212
	v_lshlrev_b64 v[218:219], 13, v[218:219]
	v_lshlrev_b64 v[212:213], 13, v[212:213]
	v_lshl_add_u64 v[218:219], v[214:215], 0, v[218:219]
	v_lshl_add_u64 v[212:213], v[214:215], 0, v[212:213]
	s_mov_b64 s[2:3], 0x100000
	global_store_dwordx2 v[218:219], v[188:189], off
	global_store_dwordx2 v[218:219], v[186:187], off offset:32
	global_store_dwordx2 v[218:219], v[184:185], off offset:256
	global_store_dwordx2 v[218:219], v[182:183], off offset:288
	global_store_dwordx2 v[212:213], v[180:181], off
	global_store_dwordx2 v[212:213], v[178:179], off offset:32
	global_store_dwordx2 v[212:213], v[176:177], off offset:256
	global_store_dwordx2 v[212:213], v[174:175], off offset:288
	v_lshl_add_u64 v[212:213], v[216:217], 0, s[2:3]
	s_mov_b32 s2, 0x100000
	v_add_co_u32_e32 v214, vcc, s2, v216
	s_mov_b64 s[2:3], 0x120000
	s_nop 0
	v_addc_co_u32_e32 v215, vcc, 0, v217, vcc
	global_store_dwordx2 v[214:215], v[172:173], off
	global_store_dwordx2 v[212:213], v[170:171], off offset:32
	global_store_dwordx2 v[212:213], v[168:169], off offset:256
	global_store_dwordx2 v[212:213], v[166:167], off offset:288
	v_add_co_u32_e32 v214, vcc, s93, v216
	v_lshl_add_u64 v[212:213], v[216:217], 0, s[2:3]
	s_nop 0
	v_addc_co_u32_e32 v215, vcc, 0, v217, vcc
	global_store_dwordx2 v[214:215], v[164:165], off
	global_store_dwordx2 v[212:213], v[162:163], off offset:32
	global_store_dwordx2 v[212:213], v[160:161], off offset:256
	global_store_dwordx2 v[212:213], v[158:159], off offset:288
	v_add_co_u32_e32 v214, vcc, s94, v216
	v_lshl_add_u64 v[212:213], v[216:217], 0, s[16:17]
	s_nop 0
	v_addc_co_u32_e32 v215, vcc, 0, v217, vcc
	global_store_dwordx2 v[214:215], v[156:157], off
	global_store_dwordx2 v[212:213], v[140:141], off offset:32
	global_store_dwordx2 v[212:213], v[138:139], off offset:256
	global_store_dwordx2 v[212:213], v[136:137], off offset:288
	v_add_co_u32_e32 v214, vcc, s95, v216
	v_lshl_add_u64 v[212:213], v[216:217], 0, s[18:19]
	s_nop 0
	v_addc_co_u32_e32 v215, vcc, 0, v217, vcc
	global_store_dwordx2 v[214:215], v[134:135], off
	global_store_dwordx2 v[212:213], v[132:133], off offset:32
	global_store_dwordx2 v[212:213], v[130:131], off offset:256
	global_store_dwordx2 v[212:213], v[128:129], off offset:288
	s_mov_b64 s[6:7], 0

; #define WAIT_V(n) asm volatile("s_waitcnt vmcnt(" #n ")" ::: "memory")
; #define WAIT_L(n) asm volatile("s_waitcnt lgkmcnt(" #n ")" ::: "memory")
; #define BAR __builtin_amdgcn_s_barrier()
; #define SCHED __builtin_amdgcn_sched_barrier(0)
; template <class Get, class Epi>
; DI void gemm_stream(LAS unsigned char* lds, const int K, const int ld, Get get, Epi epi) {
;     ...
;         for (int t = 0; t < nt; t += 2) {
;             const bool last = (t == nt - 2);
;             const char* a1 = cA + (size_t)(t + 1) * kstep;
;             const char* a2 = last ? nA : cA + (size_t)(t + 2) * kstep;
;             const char* b2 = last ? nB : cB + (size_t)(t + 2) * kstep;
;             const char* a3 = a2 + kstep;
;             const char* b3 = b2 + kstep;
;             LDB(B0, 0, 0); SCHED; LDA(At, 0, 0); STAGE(SAo(1, 1), a1 + hstep);
;             WAIT_L(8); BAR; WAIT_L(0); MMA(0, 0, At, B0); BAR; SCHED;
;             LDB(B1, 0, 1); STAGE(SBo(0, 0), b2);
;             BAR; WAIT_L(0); MMA(0, 1, At, B1); BAR;
;             LDA(At, 0, 1); STAGE(SAo(0, 0), a2);
;             BAR; WAIT_L(0); MMA(1, 0, At, B0); BAR; SCHED;
;             STAGE(SBo(0, 1), b2 + hstep);
;             WAIT_V(6); BAR; MMA(1, 1, At, B1); BAR;
;             LDB(B0, 1, 0); SCHED; LDA(At, 1, 0); STAGE(SAo(0, 1), a2 + hstep);
;             WAIT_L(8); BAR; WAIT_L(0); MMA(0, 0, At, B0); BAR; SCHED;
;             LDB(B1, 1, 1); STAGE(SBo(1, 0), b3);
;             BAR; WAIT_L(0); MMA(0, 1, At, B1); BAR;
.LBB0_2670:
	ds_read_b128 v[128:131], v198
	ds_read_b128 v[132:135], v198 offset:1024
	ds_read_b128 v[136:139], v198 offset:2048
	ds_read_b128 v[140:143], v198 offset:3072
	s_add_u32 s8, s6, 0x100
	s_addc_u32 s9, s7, 0
	s_cmp_eq_u32 s16, 60
	s_cselect_b32 s13, s39, s9
	s_cselect_b32 s12, s38, s8
	s_cselect_b32 s11, s41, s15
	s_cselect_b32 s10, s40, s14
	s_mov_b32 m0, s52
	v_lshl_add_u64 v[186:187], s[6:7], 0, v[168:169]
	ds_read_b128 v[144:147], v199
	ds_read_b128 v[148:151], v199 offset:1024
	ds_read_b128 v[152:155], v199 offset:2048
	ds_read_b128 v[156:159], v199 offset:3072
	ds_read_b128 v[160:163], v199 offset:4096
	ds_read_b128 v[174:177], v199 offset:5120
	ds_read_b128 v[178:181], v199 offset:6144
	ds_read_b128 v[182:185], v199 offset:7168
	global_load_lds_dwordx4 v[186:187], off
	v_lshl_add_u64 v[186:187], s[6:7], 0, v[170:171]
	s_mov_b32 m0, s53
	s_nop 0
	global_load_lds_dwordx4 v[186:187], off
	s_waitcnt lgkmcnt(8)
	s_barrier
	s_waitcnt lgkmcnt(0)
	v_mfma_f32_16x16x32_bf16 v[124:127], v[128:131], v[144:147], v[124:127]
	v_mfma_f32_16x16x32_bf16 v[92:95], v[136:139], v[144:147], v[92:95]
	v_mfma_f32_16x16x32_bf16 v[120:123], v[128:131], v[152:155], v[120:123]
	v_mfma_f32_16x16x32_bf16 v[88:91], v[136:139], v[152:155], v[88:91]
	v_mfma_f32_16x16x32_bf16 v[116:119], v[128:131], v[160:163], v[116:119]
	v_mfma_f32_16x16x32_bf16 v[84:87], v[136:139], v[160:163], v[84:87]
	v_mfma_f32_16x16x32_bf16 v[112:115], v[128:131], v[178:181], v[112:115]
	v_mfma_f32_16x16x32_bf16 v[80:83], v[136:139], v[178:181], v[80:83]
	v_mfma_f32_16x16x32_bf16 v[124:127], v[132:135], v[148:151], v[124:127]
	v_mfma_f32_16x16x32_bf16 v[92:95], v[140:143], v[148:151], v[92:95]
	v_mfma_f32_16x16x32_bf16 v[120:123], v[132:135], v[156:159], v[120:123]
	v_mfma_f32_16x16x32_bf16 v[88:91], v[140:143], v[156:159], v[88:91]
	v_mfma_f32_16x16x32_bf16 v[116:119], v[132:135], v[174:177], v[116:119]
	v_mfma_f32_16x16x32_bf16 v[84:87], v[140:143], v[174:177], v[84:87]
	v_mfma_f32_16x16x32_bf16 v[112:115], v[132:135], v[182:185], v[112:115]
	v_mfma_f32_16x16x32_bf16 v[80:83], v[140:143], v[182:185], v[80:83]
	s_barrier
	s_mov_b32 m0, s58
	v_lshl_add_u64 v[204:205], s[10:11], 0, v[164:165]
	ds_read_b128 v[186:189], v200
	ds_read_b128 v[190:193], v200 offset:1024
	ds_read_b128 v[194:197], v200 offset:2048
	ds_read_b128 v[208:211], v200 offset:3072
	global_load_lds_dwordx4 v[204:205], off
	v_lshl_add_u64 v[212:213], s[10:11], 0, v[166:167]
	s_mov_b32 m0, s59
	s_nop 0
	global_load_lds_dwordx4 v[212:213], off
	s_barrier
	s_waitcnt lgkmcnt(0)
	v_mfma_f32_16x16x32_bf16 v[60:63], v[186:189], v[144:147], v[60:63]
	v_mfma_f32_16x16x32_bf16 v[28:31], v[194:197], v[144:147], v[28:31]
	v_mfma_f32_16x16x32_bf16 v[56:59], v[186:189], v[152:155], v[56:59]
	v_mfma_f32_16x16x32_bf16 v[24:27], v[194:197], v[152:155], v[24:27]
	v_mfma_f32_16x16x32_bf16 v[52:55], v[186:189], v[160:163], v[52:55]
	v_mfma_f32_16x16x32_bf16 v[20:23], v[194:197], v[160:163], v[20:23]
	v_mfma_f32_16x16x32_bf16 v[48:51], v[186:189], v[178:181], v[48:51]
	v_mfma_f32_16x16x32_bf16 v[16:19], v[194:197], v[178:181], v[16:19]
	v_mfma_f32_16x16x32_bf16 v[60:63], v[190:193], v[148:151], v[60:63]
	v_mfma_f32_16x16x32_bf16 v[28:31], v[208:211], v[148:151], v[28:31]
	v_mfma_f32_16x16x32_bf16 v[56:59], v[190:193], v[156:159], v[56:59]
	v_mfma_f32_16x16x32_bf16 v[24:27], v[208:211], v[156:159], v[24:27]
	v_mfma_f32_16x16x32_bf16 v[52:55], v[190:193], v[174:177], v[52:55]
	v_mfma_f32_16x16x32_bf16 v[20:23], v[208:211], v[174:177], v[20:23]
	v_mfma_f32_16x16x32_bf16 v[48:51], v[190:193], v[182:185], v[48:51]
	v_mfma_f32_16x16x32_bf16 v[16:19], v[208:211], v[182:185], v[16:19]
	s_mov_b32 m0, s35
	v_lshl_add_u64 v[214:215], s[12:13], 0, v[164:165]
	s_barrier
	ds_read_b128 v[144:147], v199 offset:16384
	ds_read_b128 v[148:151], v199 offset:17408
	ds_read_b128 v[152:155], v199 offset:18432
	ds_read_b128 v[156:159], v199 offset:19456
	ds_read_b128 v[160:163], v199 offset:20480
	ds_read_b128 v[174:177], v199 offset:21504
	ds_read_b128 v[178:181], v199 offset:22528
	ds_read_b128 v[182:185], v199 offset:23552
	global_load_lds_dwordx4 v[214:215], off
	v_lshl_add_u64 v[216:217], s[12:13], 0, v[166:167]
	s_mov_b32 m0, s44
	s_nop 0
	global_load_lds_dwordx4 v[216:217], off
	s_barrier
	s_waitcnt lgkmcnt(0)
	v_mfma_f32_16x16x32_bf16 v[108:111], v[128:131], v[144:147], v[108:111]
	v_mfma_f32_16x16x32_bf16 v[76:79], v[136:139], v[144:147], v[76:79]
	v_mfma_f32_16x16x32_bf16 v[104:107], v[128:131], v[152:155], v[104:107]
	v_mfma_f32_16x16x32_bf16 v[72:75], v[136:139], v[152:155], v[72:75]
	v_mfma_f32_16x16x32_bf16 v[100:103], v[128:131], v[160:163], v[100:103]
	v_mfma_f32_16x16x32_bf16 v[68:71], v[136:139], v[160:163], v[68:71]
	v_mfma_f32_16x16x32_bf16 v[96:99], v[128:131], v[178:181], v[96:99]
	v_mfma_f32_16x16x32_bf16 v[64:67], v[136:139], v[178:181], v[64:67]
	v_mfma_f32_16x16x32_bf16 v[108:111], v[132:135], v[148:151], v[108:111]
	v_mfma_f32_16x16x32_bf16 v[76:79], v[140:143], v[148:151], v[76:79]
	v_mfma_f32_16x16x32_bf16 v[104:107], v[132:135], v[156:159], v[104:107]
	v_mfma_f32_16x16x32_bf16 v[72:75], v[140:143], v[156:159], v[72:75]
	v_mfma_f32_16x16x32_bf16 v[100:103], v[132:135], v[174:177], v[100:103]
	v_mfma_f32_16x16x32_bf16 v[68:71], v[140:143], v[174:177], v[68:71]
	v_mfma_f32_16x16x32_bf16 v[96:99], v[132:135], v[182:185], v[96:99]
	v_mfma_f32_16x16x32_bf16 v[64:67], v[140:143], v[182:185], v[64:67]
	s_barrier
	s_add_u32 s6, s10, 0x100000
	s_addc_u32 s7, s11, 0
	s_mov_b32 m0, s60
	v_lshl_add_u64 v[128:129], s[6:7], 0, v[164:165]
	global_load_lds_dwordx4 v[128:129], off
	v_lshl_add_u64 v[128:129], s[6:7], 0, v[166:167]
	s_mov_b32 m0, s61
	s_nop 0
	global_load_lds_dwordx4 v[128:129], off
	s_waitcnt vmcnt(6)
	s_barrier
; #define WAIT_V(n) asm volatile("s_waitcnt vmcnt(" #n ")" ::: "memory")
; #define WAIT_L(n) asm volatile("s_waitcnt lgkmcnt(" #n ")" ::: "memory")
; #define BAR __builtin_amdgcn_s_barrier()
; #define SCHED __builtin_amdgcn_sched_barrier(0)
; template <class Get, class Epi>
; DI void gemm_stream(LAS unsigned char* lds, const int K, const int ld, Get get, Epi epi) {
;     ...
;             LDB(B0, 0, 0); SCHED; LDA(At, 0, 0); STAGE(SAo(1, 1), a1 + hstep);
;             WAIT_L(8); BAR; WAIT_L(0); MMA(0, 0, At, B0); BAR; SCHED;
;             LDB(B1, 0, 1); STAGE(SBo(0, 0), b2);
;             BAR; WAIT_L(0); MMA(0, 1, At, B1); BAR;
;             LDA(At, 0, 1); STAGE(SAo(0, 0), a2);
;             BAR; WAIT_L(0); MMA(1, 0, At, B0); BAR; SCHED;
;             STAGE(SBo(0, 1), b2 + hstep);
;             WAIT_V(6); BAR; MMA(1, 1, At, B1); BAR;
;             LDB(B0, 1, 0); SCHED; LDA(At, 1, 0); STAGE(SAo(0, 1), a2 + hstep);
;             WAIT_L(8); BAR; WAIT_L(0); MMA(0, 0, At, B0); BAR; SCHED;
;     ...
;             LDA(At, 1, 1); STAGE(SAo(1, 0), a3);
;             BAR; WAIT_L(0); MMA(1, 0, At, B0); BAR; SCHED;
;             STAGE(SBo(1, 1), b3 + hstep);
;             WAIT_V(6); BAR; MMA(1, 1, At, B1); BAR;
	v_mfma_f32_16x16x32_bf16 v[44:47], v[186:189], v[144:147], v[44:47]
	v_mfma_f32_16x16x32_bf16 v[12:15], v[194:197], v[144:147], v[12:15]
	v_mfma_f32_16x16x32_bf16 v[40:43], v[186:189], v[152:155], v[40:43]
	v_mfma_f32_16x16x32_bf16 v[8:11], v[194:197], v[152:155], v[8:11]
	v_mfma_f32_16x16x32_bf16 v[36:39], v[186:189], v[160:163], v[36:39]
	v_mfma_f32_16x16x32_bf16 v[4:7], v[194:197], v[160:163], v[4:7]
	v_mfma_f32_16x16x32_bf16 v[32:35], v[186:189], v[178:181], v[32:35]
	v_mfma_f32_16x16x32_bf16 v[0:3], v[194:197], v[178:181], v[0:3]
	v_mfma_f32_16x16x32_bf16 v[44:47], v[190:193], v[148:151], v[44:47]
	v_mfma_f32_16x16x32_bf16 v[12:15], v[208:211], v[148:151], v[12:15]
	v_mfma_f32_16x16x32_bf16 v[40:43], v[190:193], v[156:159], v[40:43]
	v_mfma_f32_16x16x32_bf16 v[8:11], v[208:211], v[156:159], v[8:11]
	v_mfma_f32_16x16x32_bf16 v[36:39], v[190:193], v[174:177], v[36:39]
	v_mfma_f32_16x16x32_bf16 v[4:7], v[208:211], v[174:177], v[4:7]
	v_mfma_f32_16x16x32_bf16 v[32:35], v[190:193], v[182:185], v[32:35]
	v_mfma_f32_16x16x32_bf16 v[0:3], v[208:211], v[182:185], v[0:3]
	s_barrier
	ds_read_b128 v[128:131], v201
	ds_read_b128 v[132:135], v201 offset:1024
	ds_read_b128 v[136:139], v201 offset:2048
	ds_read_b128 v[140:143], v201 offset:3072
	s_add_u32 s6, s12, 0x100000
	s_addc_u32 s7, s13, 0
	s_mov_b32 m0, s45
	v_lshl_add_u64 v[186:187], s[6:7], 0, v[164:165]
	ds_read_b128 v[144:147], v199 offset:32768
	ds_read_b128 v[148:151], v199 offset:33792
	ds_read_b128 v[152:155], v199 offset:34816
	ds_read_b128 v[156:159], v199 offset:35840
	ds_read_b128 v[160:163], v199 offset:36864
	ds_read_b128 v[174:177], v199 offset:37888
	ds_read_b128 v[178:181], v199 offset:38912
	ds_read_b128 v[182:185], v199 offset:39936
	global_load_lds_dwordx4 v[186:187], off
	v_lshl_add_u64 v[186:187], s[6:7], 0, v[166:167]
	s_mov_b32 m0, s46
	s_nop 0
	global_load_lds_dwordx4 v[186:187], off
	s_waitcnt lgkmcnt(8)
	s_barrier
	s_waitcnt lgkmcnt(0)
	v_mfma_f32_16x16x32_bf16 v[124:127], v[128:131], v[144:147], v[124:127]
	v_mfma_f32_16x16x32_bf16 v[92:95], v[136:139], v[144:147], v[92:95]
	v_mfma_f32_16x16x32_bf16 v[120:123], v[128:131], v[152:155], v[120:123]
	v_mfma_f32_16x16x32_bf16 v[88:91], v[136:139], v[152:155], v[88:91]
	v_mfma_f32_16x16x32_bf16 v[116:119], v[128:131], v[160:163], v[116:119]
	v_mfma_f32_16x16x32_bf16 v[84:87], v[136:139], v[160:163], v[84:87]
	v_mfma_f32_16x16x32_bf16 v[112:115], v[128:131], v[178:181], v[112:115]
	v_mfma_f32_16x16x32_bf16 v[80:83], v[136:139], v[178:181], v[80:83]
	v_mfma_f32_16x16x32_bf16 v[124:127], v[132:135], v[148:151], v[124:127]
	v_mfma_f32_16x16x32_bf16 v[92:95], v[140:143], v[148:151], v[92:95]
	v_mfma_f32_16x16x32_bf16 v[120:123], v[132:135], v[156:159], v[120:123]
	v_mfma_f32_16x16x32_bf16 v[88:91], v[140:143], v[156:159], v[88:91]
	v_mfma_f32_16x16x32_bf16 v[116:119], v[132:135], v[174:177], v[116:119]
	v_mfma_f32_16x16x32_bf16 v[84:87], v[140:143], v[174:177], v[84:87]
	v_mfma_f32_16x16x32_bf16 v[112:115], v[132:135], v[182:185], v[112:115]
	v_mfma_f32_16x16x32_bf16 v[80:83], v[140:143], v[182:185], v[80:83]
	s_barrier
	s_mov_b32 m0, s64
	v_lshl_add_u64 v[204:205], v[204:205], 0, s[0:1]
	ds_read_b128 v[186:189], v202
	ds_read_b128 v[190:193], v202 offset:1024
	ds_read_b128 v[194:197], v202 offset:2048
	ds_read_b128 v[208:211], v202 offset:3072
	global_load_lds_dwordx4 v[204:205], off
	v_lshl_add_u64 v[204:205], v[212:213], 0, s[0:1]
	s_mov_b32 m0, s65
	s_nop 0
	global_load_lds_dwordx4 v[204:205], off
	s_barrier
	s_waitcnt lgkmcnt(0)
	v_mfma_f32_16x16x32_bf16 v[60:63], v[186:189], v[144:147], v[60:63]
	v_mfma_f32_16x16x32_bf16 v[28:31], v[194:197], v[144:147], v[28:31]
	v_mfma_f32_16x16x32_bf16 v[56:59], v[186:189], v[152:155], v[56:59]
	v_mfma_f32_16x16x32_bf16 v[24:27], v[194:197], v[152:155], v[24:27]
	v_mfma_f32_16x16x32_bf16 v[52:55], v[186:189], v[160:163], v[52:55]
	v_mfma_f32_16x16x32_bf16 v[20:23], v[194:197], v[160:163], v[20:23]
	v_mfma_f32_16x16x32_bf16 v[48:51], v[186:189], v[178:181], v[48:51]
	v_mfma_f32_16x16x32_bf16 v[16:19], v[194:197], v[178:181], v[16:19]
	v_mfma_f32_16x16x32_bf16 v[60:63], v[190:193], v[148:151], v[60:63]
	v_mfma_f32_16x16x32_bf16 v[28:31], v[208:211], v[148:151], v[28:31]
	v_mfma_f32_16x16x32_bf16 v[56:59], v[190:193], v[156:159], v[56:59]
	v_mfma_f32_16x16x32_bf16 v[24:27], v[208:211], v[156:159], v[24:27]
	v_mfma_f32_16x16x32_bf16 v[52:55], v[190:193], v[174:177], v[52:55]
	v_mfma_f32_16x16x32_bf16 v[20:23], v[208:211], v[174:177], v[20:23]
	v_mfma_f32_16x16x32_bf16 v[48:51], v[190:193], v[182:185], v[48:51]
	v_mfma_f32_16x16x32_bf16 v[16:19], v[208:211], v[182:185], v[16:19]
	s_mov_b32 m0, s47
	v_lshl_add_u64 v[204:205], v[214:215], 0, s[0:1]
	s_barrier
	ds_read_b128 v[144:147], v199 offset:49152
	ds_read_b128 v[148:151], v199 offset:50176
	ds_read_b128 v[152:155], v199 offset:51200
	ds_read_b128 v[156:159], v199 offset:52224
	ds_read_b128 v[160:163], v199 offset:53248
	ds_read_b128 v[174:177], v199 offset:54272
	ds_read_b128 v[178:181], v199 offset:55296
	ds_read_b128 v[182:185], v199 offset:56320
	global_load_lds_dwordx4 v[204:205], off
	v_lshl_add_u64 v[204:205], v[216:217], 0, s[0:1]
	s_mov_b32 m0, s48
	s_nop 0
	global_load_lds_dwordx4 v[204:205], off
	s_barrier
; #define WAIT_V(n) asm volatile("s_waitcnt vmcnt(" #n ")" ::: "memory")
; #define WAIT_L(n) asm volatile("s_waitcnt lgkmcnt(" #n ")" ::: "memory")
; #define BAR __builtin_amdgcn_s_barrier()
; #define SCHED __builtin_amdgcn_sched_barrier(0)
; template <class Get, class Epi>
; DI void gemm_stream(LAS unsigned char* lds, const int K, const int ld, Get get, Epi epi) {
;     ...
;             LDB(B1, 1, 1); STAGE(SBo(1, 0), b3);
;             BAR; WAIT_L(0); MMA(0, 1, At, B1); BAR;
;             LDA(At, 1, 1); STAGE(SAo(1, 0), a3);
;             BAR; WAIT_L(0); MMA(1, 0, At, B0); BAR; SCHED;
;             STAGE(SBo(1, 1), b3 + hstep);
;             WAIT_V(6); BAR; MMA(1, 1, At, B1); BAR;
;         }
; DI void epi_resid(const Acc& acc, const P& p, int brow, int bcol, int layer, int gch, bool from_input) {
;     EPI_IDX
;     const float* gate = modv(p, layer, brow, gch);
; #pragma unroll
;     for (int bj = 0; bj < 2; ++bj)
; #pragma unroll
;         for (int n = 0; n < 2; ++n) {
;             const int c0 = bcol + bj * 128 + wc * 32 + n * 16 + fq * 4;
;             const f32x4 g = *(const f32x4*)(gate + c0);
;             f32x4 xv[2][4];
; #pragma unroll
;             for (int ai = 0; ai < 2; ++ai)
; #pragma unroll
;                 for (int m = 0; m < 4; ++m) {
;                     const int r = brow + ai * 128 + wr * 64 + m * 16 + fr;
;                     const float* sp = (from_input ? inrow(p, r) : xrow(p, r)) + c0;
;                     xv[ai][m] = *(const f32x4*)sp;
;                 }
	s_waitcnt lgkmcnt(0)
	v_mfma_f32_16x16x32_bf16 v[108:111], v[128:131], v[144:147], v[108:111]
	v_mfma_f32_16x16x32_bf16 v[76:79], v[136:139], v[144:147], v[76:79]
	v_mfma_f32_16x16x32_bf16 v[104:107], v[128:131], v[152:155], v[104:107]
	v_mfma_f32_16x16x32_bf16 v[72:75], v[136:139], v[152:155], v[72:75]
	v_mfma_f32_16x16x32_bf16 v[100:103], v[128:131], v[160:163], v[100:103]
	v_mfma_f32_16x16x32_bf16 v[68:71], v[136:139], v[160:163], v[68:71]
	v_mfma_f32_16x16x32_bf16 v[96:99], v[128:131], v[178:181], v[96:99]
	v_mfma_f32_16x16x32_bf16 v[64:67], v[136:139], v[178:181], v[64:67]
	v_mfma_f32_16x16x32_bf16 v[108:111], v[132:135], v[148:151], v[108:111]
	v_mfma_f32_16x16x32_bf16 v[76:79], v[140:143], v[148:151], v[76:79]
	v_mfma_f32_16x16x32_bf16 v[104:107], v[132:135], v[156:159], v[104:107]
	v_mfma_f32_16x16x32_bf16 v[72:75], v[140:143], v[156:159], v[72:75]
	v_mfma_f32_16x16x32_bf16 v[100:103], v[132:135], v[174:177], v[100:103]
	v_mfma_f32_16x16x32_bf16 v[68:71], v[140:143], v[174:177], v[68:71]
	v_mfma_f32_16x16x32_bf16 v[96:99], v[132:135], v[182:185], v[96:99]
	v_mfma_f32_16x16x32_bf16 v[64:67], v[140:143], v[182:185], v[64:67]
	s_barrier
	s_add_u32 s6, s10, 0x100080
	s_addc_u32 s7, s11, 0
	s_mov_b32 m0, s68
	v_lshl_add_u64 v[128:129], s[6:7], 0, v[164:165]
	global_load_lds_dwordx4 v[128:129], off
	v_lshl_add_u64 v[128:129], s[6:7], 0, v[166:167]
	s_mov_b32 m0, s69
	s_nop 0
	global_load_lds_dwordx4 v[128:129], off
	s_waitcnt vmcnt(6)
	s_barrier
	v_mfma_f32_16x16x32_bf16 v[44:47], v[186:189], v[144:147], v[44:47]
	v_mfma_f32_16x16x32_bf16 v[12:15], v[194:197], v[144:147], v[12:15]
	v_mfma_f32_16x16x32_bf16 v[40:43], v[186:189], v[152:155], v[40:43]
	v_mfma_f32_16x16x32_bf16 v[8:11], v[194:197], v[152:155], v[8:11]
	v_mfma_f32_16x16x32_bf16 v[36:39], v[186:189], v[160:163], v[36:39]
	v_mfma_f32_16x16x32_bf16 v[4:7], v[194:197], v[160:163], v[4:7]
	v_mfma_f32_16x16x32_bf16 v[32:35], v[186:189], v[178:181], v[32:35]
	v_mfma_f32_16x16x32_bf16 v[0:3], v[194:197], v[178:181], v[0:3]
	v_mfma_f32_16x16x32_bf16 v[44:47], v[190:193], v[148:151], v[44:47]
	v_mfma_f32_16x16x32_bf16 v[12:15], v[208:211], v[148:151], v[12:15]
	v_mfma_f32_16x16x32_bf16 v[40:43], v[190:193], v[156:159], v[40:43]
	v_mfma_f32_16x16x32_bf16 v[8:11], v[208:211], v[156:159], v[8:11]
	v_mfma_f32_16x16x32_bf16 v[36:39], v[190:193], v[174:177], v[36:39]
	v_mfma_f32_16x16x32_bf16 v[4:7], v[208:211], v[174:177], v[4:7]
	v_mfma_f32_16x16x32_bf16 v[32:35], v[190:193], v[182:185], v[32:35]
	v_mfma_f32_16x16x32_bf16 v[0:3], v[208:211], v[182:185], v[0:3]
	s_add_i32 s16, s16, 2
	s_add_u32 s14, s14, 0x100
	s_addc_u32 s15, s15, 0
	s_cmp_gt_u32 s16, 61
	s_mov_b64 s[6:7], s[8:9]
	s_barrier
	s_cbranch_scc0 .LBB0_2670
	s_lshr_b32 s6, s3, 4
	s_lshl_b32 s3, s3, 8
	s_mulk_i32 s6, 0x1100
	s_and_b32 s3, s3, 0xf00
	s_add_i32 s3, s6, s3
	s_add_i32 s6, s3, 0x100
	s_lshl_b32 s7, s2, 8
	s_mul_hi_i32 s2, s6, 0x78787879
	s_lshr_b32 s3, s2, 31
	s_ashr_i32 s2, s2, 11
	s_add_i32 s2, s2, s3
	s_mul_i32 s3, s2, 0xffffef00
	s_mul_i32 s2, s2, 6
	s_add_i32 s3, s3, s6
	s_add_i32 s2, s2, 32
	s_cmpk_gt_i32 s3, 0xff
	v_mov_b32_e32 v132, v206
	s_cselect_b32 s2, s2, 56
	s_ashr_i32 s3, s2, 31
	v_lshrrev_b32_e32 v128, 1, v132
	v_lshrrev_b32_e32 v129, 2, v132
	s_lshl_b64 s[2:3], s[2:3], 13
	v_and_b32_e32 v128, 0x60, v128
	v_and_b32_e32 v129, 12, v129
	s_add_u32 s2, s26, s2
	v_or3_b32 v174, v128, s7, v129
	s_addc_u32 s3, s27, s3
	v_ashrrev_i32_e32 v175, 31, v174
	v_lshl_add_u64 v[192:193], v[174:175], 2, s[2:3]
	global_load_dwordx4 v[128:131], v[192:193], off
	v_ashrrev_i32_e32 v133, 2, v132
	v_and_b32_e32 v133, 0xffffffc0, v133
	v_and_or_b32 v132, v132, 15, s6
	v_add_u32_e32 v176, v132, v133
	v_mul_hi_i32 v132, v176, s54
	v_lshrrev_b32_e32 v133, 31, v132
	v_ashrrev_i32_e32 v132, 11, v132
	v_add_u32_e32 v204, v132, v133
	v_mad_i32_i24 v203, v204, s55, v176
	v_lshlrev_b32_e32 v213, 12, v204
	v_cmp_lt_i32_e64 s[18:19], s56, v203
	v_add3_u32 v190, v213, v203, s57
	s_and_saveexec_b64 s[2:3], s[18:19]
	s_xor_b64 s[6:7], exec, s[2:3]
	v_add3_u32 v132, v213, v203, s57
	s_or_saveexec_b64 s[6:7], s[6:7]
	v_mov_b64_e32 v[134:135], s[24:25]
	v_lshl_add_u32 v191, v204, 8, v203
	s_xor_b64 exec, exec, s[6:7]
	v_lshl_add_u32 v132, v204, 8, v203
	v_mov_b64_e32 v[134:135], s[36:37]
	s_or_b64 exec, exec, s[6:7]
	v_ashrrev_i32_e32 v133, 31, v132
	v_lshlrev_b64 v[132:133], 13, v[132:133]
	v_lshl_add_u64 v[132:133], v[134:135], 0, v[132:133]
	v_lshl_add_u64 v[132:133], v[174:175], 2, v[132:133]
	global_load_dwordx4 v[160:163], v[132:133], off
	v_or_b32_e32 v132, 16, v176
	v_mul_hi_i32 v133, v132, s54
	v_lshrrev_b32_e32 v134, 31, v133
	v_ashrrev_i32_e32 v133, 11, v133
	v_add_u32_e32 v208, v133, v134
	v_mad_i32_i24 v205, v208, s55, v132
	v_lshlrev_b32_e32 v218, 12, v208
	v_cmp_lt_i32_e64 s[16:17], s56, v205
	v_add3_u32 v188, v218, v205, s57
	s_and_saveexec_b64 s[2:3], s[16:17]
	s_xor_b64 s[6:7], exec, s[2:3]
	v_add3_u32 v132, v218, v205, s57
	s_or_saveexec_b64 s[6:7], s[6:7]
	v_mov_b64_e32 v[134:135], s[24:25]
	v_lshl_add_u32 v189, v208, 8, v205
	s_xor_b64 exec, exec, s[6:7]
	v_lshl_add_u32 v132, v208, 8, v205
	v_mov_b64_e32 v[134:135], s[36:37]
	s_or_b64 exec, exec, s[6:7]
	v_ashrrev_i32_e32 v133, 31, v132
	v_lshlrev_b64 v[132:133], 13, v[132:133]
	v_lshl_add_u64 v[132:133], v[134:135], 0, v[132:133]
	v_lshl_add_u64 v[132:133], v[174:175], 2, v[132:133]
	global_load_dwordx4 v[156:159], v[132:133], off
	v_or_b32_e32 v132, 32, v176
	v_mul_hi_i32 v133, v132, s54
	v_lshrrev_b32_e32 v134, 31, v133
	v_ashrrev_i32_e32 v133, 11, v133
	v_add_u32_e32 v210, v133, v134
	v_mad_i32_i24 v209, v210, s55, v132
	v_lshlrev_b32_e32 v221, 12, v210
; DI void epi_resid(const Acc& acc, const P& p, int brow, int bcol, int layer, int gch, bool from_input) {
;     ...
;             for (int ai = 0; ai < 2; ++ai)
; #pragma unroll
;                 for (int m = 0; m < 4; ++m) {
;                     const int r = brow + ai * 128 + wr * 64 + m * 16 + fr;
;                     const float* sp = (from_input ? inrow(p, r) : xrow(p, r)) + c0;
;                     xv[ai][m] = *(const f32x4*)sp;
;                 }
	v_cmp_lt_i32_e64 s[14:15], s56, v209
	v_add3_u32 v186, v221, v209, s57
	s_and_saveexec_b64 s[2:3], s[14:15]
	s_xor_b64 s[6:7], exec, s[2:3]
	v_add3_u32 v132, v221, v209, s57
	s_or_saveexec_b64 s[6:7], s[6:7]
	v_mov_b64_e32 v[134:135], s[24:25]
	v_lshl_add_u32 v187, v210, 8, v209
	s_xor_b64 exec, exec, s[6:7]
	v_lshl_add_u32 v132, v210, 8, v209
	v_mov_b64_e32 v[134:135], s[36:37]
	s_or_b64 exec, exec, s[6:7]
	v_ashrrev_i32_e32 v133, 31, v132
	v_lshlrev_b64 v[132:133], 13, v[132:133]
	v_lshl_add_u64 v[132:133], v[134:135], 0, v[132:133]
	v_lshl_add_u64 v[132:133], v[174:175], 2, v[132:133]
	global_load_dwordx4 v[152:155], v[132:133], off
	v_or_b32_e32 v132, 48, v176
	v_mul_hi_i32 v133, v132, s54
	v_lshrrev_b32_e32 v134, 31, v133
	v_ashrrev_i32_e32 v133, 11, v133
	v_add_u32_e32 v212, v133, v134
	v_mad_i32_i24 v211, v212, s55, v132
	v_lshlrev_b32_e32 v224, 12, v212
	v_cmp_lt_i32_e64 s[12:13], s56, v211
	v_add3_u32 v184, v224, v211, s57
	s_and_saveexec_b64 s[2:3], s[12:13]
	s_xor_b64 s[6:7], exec, s[2:3]
	v_add3_u32 v132, v224, v211, s57
	s_or_saveexec_b64 s[6:7], s[6:7]
	v_mov_b64_e32 v[134:135], s[24:25]
	v_lshl_add_u32 v185, v212, 8, v211
	s_xor_b64 exec, exec, s[6:7]
	v_lshl_add_u32 v132, v212, 8, v211
	v_mov_b64_e32 v[134:135], s[36:37]
	s_or_b64 exec, exec, s[6:7]
	v_ashrrev_i32_e32 v133, 31, v132
	v_lshlrev_b64 v[132:133], 13, v[132:133]
	v_lshl_add_u64 v[132:133], v[134:135], 0, v[132:133]
	v_lshl_add_u64 v[132:133], v[174:175], 2, v[132:133]
	global_load_dwordx4 v[148:151], v[132:133], off
	v_add_u32_e32 v132, 0x80, v176
	v_mul_hi_i32 v133, v132, s54
	v_lshrrev_b32_e32 v134, 31, v133
	v_ashrrev_i32_e32 v133, 11, v133
	v_add_u32_e32 v215, v133, v134
	v_mad_i32_i24 v214, v215, s55, v132
	v_lshlrev_b32_e32 v225, 12, v215
	v_cmp_lt_i32_e64 s[10:11], s56, v214
	v_add3_u32 v182, v225, v214, s57
	s_and_saveexec_b64 s[2:3], s[10:11]
	s_xor_b64 s[6:7], exec, s[2:3]
	v_add3_u32 v132, v225, v214, s57
	s_or_saveexec_b64 s[6:7], s[6:7]
	v_mov_b64_e32 v[134:135], s[24:25]
	v_lshl_add_u32 v183, v215, 8, v214
	s_xor_b64 exec, exec, s[6:7]
	v_lshl_add_u32 v132, v215, 8, v214
	v_mov_b64_e32 v[134:135], s[36:37]
	s_or_b64 exec, exec, s[6:7]
	v_ashrrev_i32_e32 v133, 31, v132
	v_lshlrev_b64 v[132:133], 13, v[132:133]
	v_lshl_add_u64 v[132:133], v[134:135], 0, v[132:133]
	v_lshl_add_u64 v[132:133], v[174:175], 2, v[132:133]
	global_load_dwordx4 v[144:147], v[132:133], off
	v_add_u32_e32 v132, 0x90, v176
	v_mul_hi_i32 v133, v132, s54
	v_lshrrev_b32_e32 v134, 31, v133
	v_ashrrev_i32_e32 v133, 11, v133
	v_add_u32_e32 v217, v133, v134
	v_mad_i32_i24 v216, v217, s55, v132
	v_lshlrev_b32_e32 v226, 12, v217
	v_cmp_lt_i32_e64 s[8:9], s56, v216
	v_add3_u32 v180, v226, v216, s57
	s_and_saveexec_b64 s[2:3], s[8:9]
	s_xor_b64 s[6:7], exec, s[2:3]
	v_add3_u32 v132, v226, v216, s57
	s_or_saveexec_b64 s[6:7], s[6:7]
	v_mov_b64_e32 v[134:135], s[24:25]
	v_lshl_add_u32 v181, v217, 8, v216
	s_xor_b64 exec, exec, s[6:7]
	v_lshl_add_u32 v132, v217, 8, v216
	v_mov_b64_e32 v[134:135], s[36:37]
	s_or_b64 exec, exec, s[6:7]
	v_ashrrev_i32_e32 v133, 31, v132
	v_lshlrev_b64 v[132:133], 13, v[132:133]
	v_lshl_add_u64 v[132:133], v[134:135], 0, v[132:133]
	v_lshl_add_u64 v[132:133], v[174:175], 2, v[132:133]
	global_load_dwordx4 v[140:143], v[132:133], off
	v_add_u32_e32 v132, 0xa0, v176
	v_mul_hi_i32 v133, v132, s54
	v_lshrrev_b32_e32 v134, 31, v133
	v_ashrrev_i32_e32 v133, 11, v133
	v_add_u32_e32 v220, v133, v134
	v_mad_i32_i24 v219, v220, s55, v132
	v_lshlrev_b32_e32 v227, 12, v220
	v_cmp_lt_i32_e64 s[6:7], s56, v219
	v_add3_u32 v178, v227, v219, s57
	s_and_saveexec_b64 s[2:3], s[6:7]
	s_xor_b64 s[42:43], exec, s[2:3]
	v_add3_u32 v132, v227, v219, s57
	s_or_saveexec_b64 s[42:43], s[42:43]
	v_mov_b64_e32 v[134:135], s[24:25]
	v_lshl_add_u32 v179, v220, 8, v219
	s_xor_b64 exec, exec, s[42:43]
	v_lshl_add_u32 v132, v220, 8, v219
	v_mov_b64_e32 v[134:135], s[36:37]
	s_or_b64 exec, exec, s[42:43]
	v_ashrrev_i32_e32 v133, 31, v132
	v_lshlrev_b64 v[132:133], 13, v[132:133]
	v_lshl_add_u64 v[132:133], v[134:135], 0, v[132:133]
	v_lshl_add_u64 v[132:133], v[174:175], 2, v[132:133]
	global_load_dwordx4 v[136:139], v[132:133], off
	v_add_u32_e32 v132, 0xb0, v176
	v_mul_hi_i32 v133, v132, s54
	v_lshrrev_b32_e32 v134, 31, v133
	v_ashrrev_i32_e32 v133, 11, v133
	v_add_u32_e32 v223, v133, v134
	v_mad_i32_i24 v222, v223, s55, v132
	v_lshlrev_b32_e32 v228, 12, v223
	v_cmp_lt_i32_e32 vcc, s56, v222
	v_add3_u32 v176, v228, v222, s57
	s_and_saveexec_b64 s[2:3], vcc
	s_xor_b64 s[42:43], exec, s[2:3]
	v_add3_u32 v132, v228, v222, s57
	s_or_saveexec_b64 s[42:43], s[42:43]
	v_mov_b64_e32 v[134:135], s[24:25]
	v_lshl_add_u32 v177, v223, 8, v222
	s_xor_b64 exec, exec, s[42:43]
	v_lshl_add_u32 v132, v223, 8, v222
	v_mov_b64_e32 v[134:135], s[36:37]
	s_or_b64 exec, exec, s[42:43]
	v_ashrrev_i32_e32 v133, 31, v132
	v_lshlrev_b64 v[132:133], 13, v[132:133]
	v_lshl_add_u64 v[132:133], v[134:135], 0, v[132:133]
	v_lshl_add_u64 v[132:133], v[174:175], 2, v[132:133]
	global_load_dwordx4 v[132:135], v[132:133], off
	s_and_saveexec_b64 s[2:3], s[18:19]
	s_xor_b64 s[42:43], exec, s[2:3]
	v_add3_u32 v194, v213, v203, s57
	s_or_saveexec_b64 s[42:43], s[42:43]
	v_mov_b64_e32 v[196:197], s[24:25]
	s_xor_b64 exec, exec, s[42:43]
	v_lshl_add_u32 v194, v204, 8, v203
	v_mov_b64_e32 v[196:197], s[36:37]
	s_or_b64 exec, exec, s[42:43]
	v_ashrrev_i32_e32 v195, 31, v194
	s_waitcnt vmcnt(0)
; DI void epi_resid(const Acc& acc, const P& p, int brow, int bcol, int layer, int gch, bool from_input) {
;     ...
;             const f32x4 g = *(const f32x4*)(gate + c0);
;             f32x4 xv[2][4];
; #pragma unroll
;             for (int ai = 0; ai < 2; ++ai)
; #pragma unroll
;                 for (int m = 0; m < 4; ++m) {
;                     const int r = brow + ai * 128 + wr * 64 + m * 16 + fr;
;                     const float* sp = (from_input ? inrow(p, r) : xrow(p, r)) + c0;
;                     xv[ai][m] = *(const f32x4*)sp;
;     ...
;             for (int ai = 0; ai < 2; ++ai)
; #pragma unroll
;                 for (int m = 0; m < 4; ++m) {
;                     const int r = brow + ai * 128 + wr * 64 + m * 16 + fr;
;                     *(f32x4*)(xrow(p, r) + c0) = xv[ai][m] + g * acc[ai][bj][m][n];
	v_pk_fma_f32 v[124:125], v[124:125], v[128:129], v[160:161]
	v_lshlrev_b64 v[160:161], 13, v[194:195]
	v_lshl_add_u64 v[160:161], v[196:197], 0, v[160:161]
	v_pk_fma_f32 v[126:127], v[126:127], v[130:131], v[162:163]
	v_lshl_add_u64 v[160:161], v[174:175], 2, v[160:161]
	global_store_dwordx4 v[160:161], v[124:127], off
	s_and_saveexec_b64 s[2:3], s[16:17]
	s_xor_b64 s[42:43], exec, s[2:3]
	v_add3_u32 v124, v218, v205, s57
	s_or_saveexec_b64 s[42:43], s[42:43]
	v_mov_b64_e32 v[126:127], s[24:25]
	s_xor_b64 exec, exec, s[42:43]
	v_lshl_add_u32 v124, v208, 8, v205
	v_mov_b64_e32 v[126:127], s[36:37]
	s_or_b64 exec, exec, s[42:43]
	v_ashrrev_i32_e32 v125, 31, v124
	v_lshlrev_b64 v[124:125], 13, v[124:125]
	v_lshl_add_u64 v[124:125], v[126:127], 0, v[124:125]
	v_pk_fma_f32 v[122:123], v[122:123], v[130:131], v[158:159]
	v_pk_fma_f32 v[120:121], v[120:121], v[128:129], v[156:157]
	v_lshl_add_u64 v[124:125], v[174:175], 2, v[124:125]
	global_store_dwordx4 v[124:125], v[120:123], off
	s_and_saveexec_b64 s[2:3], s[14:15]
	s_xor_b64 s[42:43], exec, s[2:3]
	v_add3_u32 v120, v221, v209, s57
	s_or_saveexec_b64 s[42:43], s[42:43]
	v_mov_b64_e32 v[122:123], s[24:25]
	s_xor_b64 exec, exec, s[42:43]
	v_lshl_add_u32 v120, v210, 8, v209
	v_mov_b64_e32 v[122:123], s[36:37]
	s_or_b64 exec, exec, s[42:43]
	v_ashrrev_i32_e32 v121, 31, v120
	v_lshlrev_b64 v[120:121], 13, v[120:121]
	v_lshl_add_u64 v[120:121], v[122:123], 0, v[120:121]
	v_pk_fma_f32 v[118:119], v[118:119], v[130:131], v[154:155]
	v_pk_fma_f32 v[116:117], v[116:117], v[128:129], v[152:153]
	v_lshl_add_u64 v[120:121], v[174:175], 2, v[120:121]
	global_store_dwordx4 v[120:121], v[116:119], off
	s_and_saveexec_b64 s[2:3], s[12:13]
	s_xor_b64 s[42:43], exec, s[2:3]
	v_add3_u32 v116, v224, v211, s57
	s_or_saveexec_b64 s[42:43], s[42:43]
	v_mov_b64_e32 v[118:119], s[24:25]
	s_xor_b64 exec, exec, s[42:43]
	v_lshl_add_u32 v116, v212, 8, v211
	v_mov_b64_e32 v[118:119], s[36:37]
	s_or_b64 exec, exec, s[42:43]
	v_ashrrev_i32_e32 v117, 31, v116
	v_lshlrev_b64 v[116:117], 13, v[116:117]
	v_lshl_add_u64 v[116:117], v[118:119], 0, v[116:117]
	v_pk_fma_f32 v[114:115], v[114:115], v[130:131], v[150:151]
	v_pk_fma_f32 v[112:113], v[112:113], v[128:129], v[148:149]
	v_lshl_add_u64 v[116:117], v[174:175], 2, v[116:117]
	global_store_dwordx4 v[116:117], v[112:115], off
	s_and_saveexec_b64 s[2:3], s[10:11]
	s_xor_b64 s[42:43], exec, s[2:3]
	v_add3_u32 v112, v225, v214, s57
	s_or_saveexec_b64 s[42:43], s[42:43]
	v_mov_b64_e32 v[114:115], s[24:25]
	s_xor_b64 exec, exec, s[42:43]
	v_lshl_add_u32 v112, v215, 8, v214
	v_mov_b64_e32 v[114:115], s[36:37]
	s_or_b64 exec, exec, s[42:43]
	v_ashrrev_i32_e32 v113, 31, v112
	v_lshlrev_b64 v[112:113], 13, v[112:113]
	v_lshl_add_u64 v[112:113], v[114:115], 0, v[112:113]
	v_pk_fma_f32 v[110:111], v[110:111], v[130:131], v[146:147]
	v_pk_fma_f32 v[108:109], v[108:109], v[128:129], v[144:145]
	v_lshl_add_u64 v[112:113], v[174:175], 2, v[112:113]
	global_store_dwordx4 v[112:113], v[108:111], off
	s_and_saveexec_b64 s[2:3], s[8:9]
	s_xor_b64 s[42:43], exec, s[2:3]
	v_add3_u32 v108, v226, v216, s57
	s_or_saveexec_b64 s[42:43], s[42:43]
	v_mov_b64_e32 v[110:111], s[24:25]
	s_xor_b64 exec, exec, s[42:43]
	v_lshl_add_u32 v108, v217, 8, v216
	v_mov_b64_e32 v[110:111], s[36:37]
	s_or_b64 exec, exec, s[42:43]
	v_ashrrev_i32_e32 v109, 31, v108
	v_lshlrev_b64 v[108:109], 13, v[108:109]
	v_lshl_add_u64 v[108:109], v[110:111], 0, v[108:109]
	v_pk_fma_f32 v[106:107], v[106:107], v[130:131], v[142:143]
	v_pk_fma_f32 v[104:105], v[104:105], v[128:129], v[140:141]
	v_lshl_add_u64 v[108:109], v[174:175], 2, v[108:109]
	global_store_dwordx4 v[108:109], v[104:107], off
	s_and_saveexec_b64 s[2:3], s[6:7]
	s_xor_b64 s[42:43], exec, s[2:3]
	v_add3_u32 v104, v227, v219, s57
	s_or_saveexec_b64 s[42:43], s[42:43]
	v_mov_b64_e32 v[106:107], s[24:25]
	s_xor_b64 exec, exec, s[42:43]
	v_lshl_add_u32 v104, v220, 8, v219
	v_mov_b64_e32 v[106:107], s[36:37]
	s_or_b64 exec, exec, s[42:43]
	v_ashrrev_i32_e32 v105, 31, v104
	v_lshlrev_b64 v[104:105], 13, v[104:105]
	v_lshl_add_u64 v[104:105], v[106:107], 0, v[104:105]
	v_pk_fma_f32 v[102:103], v[102:103], v[130:131], v[138:139]
	v_pk_fma_f32 v[100:101], v[100:101], v[128:129], v[136:137]
	v_lshl_add_u64 v[104:105], v[174:175], 2, v[104:105]
	global_store_dwordx4 v[104:105], v[100:103], off
	s_and_saveexec_b64 s[2:3], vcc
	s_xor_b64 s[42:43], exec, s[2:3]
	v_add3_u32 v100, v228, v222, s57
	s_or_saveexec_b64 s[42:43], s[42:43]
	v_mov_b64_e32 v[102:103], s[24:25]
	s_xor_b64 exec, exec, s[42:43]
	v_lshl_add_u32 v100, v223, 8, v222
	v_mov_b64_e32 v[102:103], s[36:37]
	s_or_b64 exec, exec, s[42:43]
	v_ashrrev_i32_e32 v101, 31, v100
	v_lshlrev_b64 v[100:101], 13, v[100:101]
	v_lshl_add_u64 v[100:101], v[102:103], 0, v[100:101]
	v_pk_fma_f32 v[98:99], v[98:99], v[130:131], v[134:135]
	v_pk_fma_f32 v[96:97], v[96:97], v[128:129], v[132:133]
	v_lshl_add_u64 v[100:101], v[174:175], 2, v[100:101]
	global_store_dwordx4 v[100:101], v[96:99], off
	global_load_dwordx4 v[96:99], v[192:193], off offset:64
	s_and_saveexec_b64 s[2:3], s[18:19]
	s_xor_b64 s[42:43], exec, s[2:3]
	v_add3_u32 v100, v213, v203, s57
	s_or_saveexec_b64 s[42:43], s[42:43]
	v_mov_b64_e32 v[102:103], s[24:25]
	s_xor_b64 exec, exec, s[42:43]
	v_lshl_add_u32 v100, v204, 8, v203
	v_mov_b64_e32 v[102:103], s[36:37]
	s_or_b64 exec, exec, s[42:43]
	v_ashrrev_i32_e32 v101, 31, v100
	v_lshlrev_b64 v[100:101], 13, v[100:101]
	v_lshl_add_u64 v[100:101], v[102:103], 0, v[100:101]
	v_lshl_add_u64 v[100:101], v[174:175], 2, v[100:101]
	global_load_dwordx4 v[128:131], v[100:101], off offset:64
	s_and_saveexec_b64 s[2:3], s[16:17]
; DI void epi_resid(const Acc& acc, const P& p, int brow, int bcol, int layer, int gch, bool from_input) {
;     ...
;             for (int ai = 0; ai < 2; ++ai)
; #pragma unroll
;                 for (int m = 0; m < 4; ++m) {
;                     const int r = brow + ai * 128 + wr * 64 + m * 16 + fr;
;                     const float* sp = (from_input ? inrow(p, r) : xrow(p, r)) + c0;
;                     xv[ai][m] = *(const f32x4*)sp;
;                 }
;             __builtin_amdgcn_sched_barrier(0);
; #pragma unroll
;             for (int ai = 0; ai < 2; ++ai)
; #pragma unroll
;                 for (int m = 0; m < 4; ++m) {
;                     const int r = brow + ai * 128 + wr * 64 + m * 16 + fr;
;                     *(f32x4*)(xrow(p, r) + c0) = xv[ai][m] + g * acc[ai][bj][m][n];
	s_xor_b64 s[42:43], exec, s[2:3]
	v_add3_u32 v100, v218, v205, s57
	s_or_saveexec_b64 s[42:43], s[42:43]
	v_mov_b64_e32 v[102:103], s[24:25]
	s_xor_b64 exec, exec, s[42:43]
	v_lshl_add_u32 v100, v208, 8, v205
	v_mov_b64_e32 v[102:103], s[36:37]
	s_or_b64 exec, exec, s[42:43]
	v_ashrrev_i32_e32 v101, 31, v100
	v_lshlrev_b64 v[100:101], 13, v[100:101]
	v_lshl_add_u64 v[100:101], v[102:103], 0, v[100:101]
	v_lshl_add_u64 v[100:101], v[174:175], 2, v[100:101]
	global_load_dwordx4 v[124:127], v[100:101], off offset:64
	s_and_saveexec_b64 s[2:3], s[14:15]
	s_xor_b64 s[42:43], exec, s[2:3]
	v_add3_u32 v100, v221, v209, s57
	s_or_saveexec_b64 s[42:43], s[42:43]
	v_mov_b64_e32 v[102:103], s[24:25]
	s_xor_b64 exec, exec, s[42:43]
	v_lshl_add_u32 v100, v210, 8, v209
	v_mov_b64_e32 v[102:103], s[36:37]
	s_or_b64 exec, exec, s[42:43]
	v_ashrrev_i32_e32 v101, 31, v100
	v_lshlrev_b64 v[100:101], 13, v[100:101]
	v_lshl_add_u64 v[100:101], v[102:103], 0, v[100:101]
	v_lshl_add_u64 v[100:101], v[174:175], 2, v[100:101]
	global_load_dwordx4 v[120:123], v[100:101], off offset:64
	s_and_saveexec_b64 s[2:3], s[12:13]
	s_xor_b64 s[42:43], exec, s[2:3]
	v_add3_u32 v100, v224, v211, s57
	s_or_saveexec_b64 s[42:43], s[42:43]
	v_mov_b64_e32 v[102:103], s[24:25]
	s_xor_b64 exec, exec, s[42:43]
	v_lshl_add_u32 v100, v212, 8, v211
	v_mov_b64_e32 v[102:103], s[36:37]
	s_or_b64 exec, exec, s[42:43]
	v_ashrrev_i32_e32 v101, 31, v100
	v_lshlrev_b64 v[100:101], 13, v[100:101]
	v_lshl_add_u64 v[100:101], v[102:103], 0, v[100:101]
	v_lshl_add_u64 v[100:101], v[174:175], 2, v[100:101]
	global_load_dwordx4 v[116:119], v[100:101], off offset:64
	s_and_saveexec_b64 s[2:3], s[10:11]
	s_xor_b64 s[42:43], exec, s[2:3]
	v_add3_u32 v100, v225, v214, s57
	s_or_saveexec_b64 s[42:43], s[42:43]
	v_mov_b64_e32 v[102:103], s[24:25]
	s_xor_b64 exec, exec, s[42:43]
	v_lshl_add_u32 v100, v215, 8, v214
	v_mov_b64_e32 v[102:103], s[36:37]
	s_or_b64 exec, exec, s[42:43]
	v_ashrrev_i32_e32 v101, 31, v100
	v_lshlrev_b64 v[100:101], 13, v[100:101]
	v_lshl_add_u64 v[100:101], v[102:103], 0, v[100:101]
	v_lshl_add_u64 v[100:101], v[174:175], 2, v[100:101]
	global_load_dwordx4 v[112:115], v[100:101], off offset:64
	s_and_saveexec_b64 s[2:3], s[8:9]
	s_xor_b64 s[42:43], exec, s[2:3]
	v_add3_u32 v100, v226, v216, s57
	s_or_saveexec_b64 s[42:43], s[42:43]
	v_mov_b64_e32 v[102:103], s[24:25]
	s_xor_b64 exec, exec, s[42:43]
	v_lshl_add_u32 v100, v217, 8, v216
	v_mov_b64_e32 v[102:103], s[36:37]
	s_or_b64 exec, exec, s[42:43]
	v_ashrrev_i32_e32 v101, 31, v100
	v_lshlrev_b64 v[100:101], 13, v[100:101]
	v_lshl_add_u64 v[100:101], v[102:103], 0, v[100:101]
	v_lshl_add_u64 v[100:101], v[174:175], 2, v[100:101]
	global_load_dwordx4 v[108:111], v[100:101], off offset:64
	s_and_saveexec_b64 s[2:3], s[6:7]
	s_xor_b64 s[42:43], exec, s[2:3]
	v_add3_u32 v100, v227, v219, s57
	s_or_saveexec_b64 s[42:43], s[42:43]
	v_mov_b64_e32 v[102:103], s[24:25]
	s_xor_b64 exec, exec, s[42:43]
	v_lshl_add_u32 v100, v220, 8, v219
	v_mov_b64_e32 v[102:103], s[36:37]
	s_or_b64 exec, exec, s[42:43]
	v_ashrrev_i32_e32 v101, 31, v100
	v_lshlrev_b64 v[100:101], 13, v[100:101]
	v_lshl_add_u64 v[100:101], v[102:103], 0, v[100:101]
	v_lshl_add_u64 v[100:101], v[174:175], 2, v[100:101]
	global_load_dwordx4 v[104:107], v[100:101], off offset:64
	s_and_saveexec_b64 s[2:3], vcc
	s_xor_b64 s[42:43], exec, s[2:3]
	v_add3_u32 v100, v228, v222, s57
	s_or_saveexec_b64 s[42:43], s[42:43]
	v_mov_b64_e32 v[102:103], s[24:25]
	s_xor_b64 exec, exec, s[42:43]
	v_lshl_add_u32 v100, v223, 8, v222
	v_mov_b64_e32 v[102:103], s[36:37]
	s_or_b64 exec, exec, s[42:43]
	v_ashrrev_i32_e32 v101, 31, v100
	v_lshlrev_b64 v[100:101], 13, v[100:101]
	v_lshl_add_u64 v[100:101], v[102:103], 0, v[100:101]
	v_lshl_add_u64 v[100:101], v[174:175], 2, v[100:101]
	global_load_dwordx4 v[100:103], v[100:101], off offset:64
	s_and_saveexec_b64 s[2:3], s[18:19]
	s_xor_b64 s[42:43], exec, s[2:3]
	v_add3_u32 v132, v213, v203, s57
	s_or_saveexec_b64 s[42:43], s[42:43]
	v_mov_b64_e32 v[134:135], s[24:25]
	s_xor_b64 exec, exec, s[42:43]
	v_lshl_add_u32 v132, v204, 8, v203
	v_mov_b64_e32 v[134:135], s[36:37]
	s_or_b64 exec, exec, s[42:43]
	v_ashrrev_i32_e32 v133, 31, v132
	s_waitcnt vmcnt(0)
	v_pk_fma_f32 v[92:93], v[92:93], v[96:97], v[128:129]
	v_lshlrev_b64 v[128:129], 13, v[132:133]
	v_lshl_add_u64 v[128:129], v[134:135], 0, v[128:129]
	v_pk_fma_f32 v[94:95], v[94:95], v[98:99], v[130:131]
	v_lshl_add_u64 v[128:129], v[174:175], 2, v[128:129]
	global_store_dwordx4 v[128:129], v[92:95], off offset:64
	s_and_saveexec_b64 s[2:3], s[16:17]
	s_xor_b64 s[42:43], exec, s[2:3]
	v_add3_u32 v92, v218, v205, s57
	s_or_saveexec_b64 s[42:43], s[42:43]
	v_mov_b64_e32 v[94:95], s[24:25]
	s_xor_b64 exec, exec, s[42:43]
	v_lshl_add_u32 v92, v208, 8, v205
	v_mov_b64_e32 v[94:95], s[36:37]
	s_or_b64 exec, exec, s[42:43]
	v_ashrrev_i32_e32 v93, 31, v92
	v_lshlrev_b64 v[92:93], 13, v[92:93]
	v_lshl_add_u64 v[92:93], v[94:95], 0, v[92:93]
	v_pk_fma_f32 v[90:91], v[90:91], v[98:99], v[126:127]
	v_pk_fma_f32 v[88:89], v[88:89], v[96:97], v[124:125]
	v_lshl_add_u64 v[92:93], v[174:175], 2, v[92:93]
	global_store_dwordx4 v[92:93], v[88:91], off offset:64
	s_and_saveexec_b64 s[2:3], s[14:15]
	s_xor_b64 s[42:43], exec, s[2:3]
	v_add3_u32 v88, v221, v209, s57
	s_or_saveexec_b64 s[42:43], s[42:43]
	v_mov_b64_e32 v[90:91], s[24:25]
	s_xor_b64 exec, exec, s[42:43]
	v_lshl_add_u32 v88, v210, 8, v209
	v_mov_b64_e32 v[90:91], s[36:37]
	s_or_b64 exec, exec, s[42:43]
	v_ashrrev_i32_e32 v89, 31, v88
	v_lshlrev_b64 v[88:89], 13, v[88:89]
	v_lshl_add_u64 v[88:89], v[90:91], 0, v[88:89]
	v_pk_fma_f32 v[86:87], v[86:87], v[98:99], v[122:123]
; DI void epi_resid(const Acc& acc, const P& p, int brow, int bcol, int layer, int gch, bool from_input) {
;     ...
;             const f32x4 g = *(const f32x4*)(gate + c0);
;             f32x4 xv[2][4];
; #pragma unroll
;             for (int ai = 0; ai < 2; ++ai)
; #pragma unroll
;                 for (int m = 0; m < 4; ++m) {
;                     const int r = brow + ai * 128 + wr * 64 + m * 16 + fr;
;                     const float* sp = (from_input ? inrow(p, r) : xrow(p, r)) + c0;
;                     xv[ai][m] = *(const f32x4*)sp;
;     ...
;             for (int ai = 0; ai < 2; ++ai)
; #pragma unroll
;                 for (int m = 0; m < 4; ++m) {
;                     const int r = brow + ai * 128 + wr * 64 + m * 16 + fr;
;                     *(f32x4*)(xrow(p, r) + c0) = xv[ai][m] + g * acc[ai][bj][m][n];
	v_pk_fma_f32 v[84:85], v[84:85], v[96:97], v[120:121]
	v_lshl_add_u64 v[88:89], v[174:175], 2, v[88:89]
	global_store_dwordx4 v[88:89], v[84:87], off offset:64
	s_and_saveexec_b64 s[2:3], s[12:13]
	s_xor_b64 s[42:43], exec, s[2:3]
	v_add3_u32 v84, v224, v211, s57
	s_or_saveexec_b64 s[42:43], s[42:43]
	v_mov_b64_e32 v[86:87], s[24:25]
	s_xor_b64 exec, exec, s[42:43]
	v_lshl_add_u32 v84, v212, 8, v211
	v_mov_b64_e32 v[86:87], s[36:37]
	s_or_b64 exec, exec, s[42:43]
	v_ashrrev_i32_e32 v85, 31, v84
	v_lshlrev_b64 v[84:85], 13, v[84:85]
	v_lshl_add_u64 v[84:85], v[86:87], 0, v[84:85]
	v_pk_fma_f32 v[82:83], v[82:83], v[98:99], v[118:119]
	v_pk_fma_f32 v[80:81], v[80:81], v[96:97], v[116:117]
	v_lshl_add_u64 v[84:85], v[174:175], 2, v[84:85]
	global_store_dwordx4 v[84:85], v[80:83], off offset:64
	s_and_saveexec_b64 s[2:3], s[10:11]
	s_xor_b64 s[42:43], exec, s[2:3]
	v_add3_u32 v80, v225, v214, s57
	s_or_saveexec_b64 s[42:43], s[42:43]
	v_mov_b64_e32 v[82:83], s[24:25]
	s_xor_b64 exec, exec, s[42:43]
	v_lshl_add_u32 v80, v215, 8, v214
	v_mov_b64_e32 v[82:83], s[36:37]
	s_or_b64 exec, exec, s[42:43]
	v_ashrrev_i32_e32 v81, 31, v80
	v_lshlrev_b64 v[80:81], 13, v[80:81]
	v_lshl_add_u64 v[80:81], v[82:83], 0, v[80:81]
	v_pk_fma_f32 v[78:79], v[78:79], v[98:99], v[114:115]
	v_pk_fma_f32 v[76:77], v[76:77], v[96:97], v[112:113]
	v_lshl_add_u64 v[80:81], v[174:175], 2, v[80:81]
	global_store_dwordx4 v[80:81], v[76:79], off offset:64
	s_and_saveexec_b64 s[2:3], s[8:9]
	s_xor_b64 s[42:43], exec, s[2:3]
	v_add3_u32 v76, v226, v216, s57
	s_or_saveexec_b64 s[42:43], s[42:43]
	v_mov_b64_e32 v[78:79], s[24:25]
	s_xor_b64 exec, exec, s[42:43]
	v_lshl_add_u32 v76, v217, 8, v216
	v_mov_b64_e32 v[78:79], s[36:37]
	s_or_b64 exec, exec, s[42:43]
	v_ashrrev_i32_e32 v77, 31, v76
	v_lshlrev_b64 v[76:77], 13, v[76:77]
	v_lshl_add_u64 v[76:77], v[78:79], 0, v[76:77]
	v_pk_fma_f32 v[74:75], v[74:75], v[98:99], v[110:111]
	v_pk_fma_f32 v[72:73], v[72:73], v[96:97], v[108:109]
	v_lshl_add_u64 v[76:77], v[174:175], 2, v[76:77]
	global_store_dwordx4 v[76:77], v[72:75], off offset:64
	s_and_saveexec_b64 s[2:3], s[6:7]
	s_xor_b64 s[42:43], exec, s[2:3]
	v_add3_u32 v72, v227, v219, s57
	s_or_saveexec_b64 s[42:43], s[42:43]
	v_mov_b64_e32 v[74:75], s[24:25]
	s_xor_b64 exec, exec, s[42:43]
	v_lshl_add_u32 v72, v220, 8, v219
	v_mov_b64_e32 v[74:75], s[36:37]
	s_or_b64 exec, exec, s[42:43]
	v_ashrrev_i32_e32 v73, 31, v72
	v_lshlrev_b64 v[72:73], 13, v[72:73]
	v_lshl_add_u64 v[72:73], v[74:75], 0, v[72:73]
	v_pk_fma_f32 v[70:71], v[70:71], v[98:99], v[106:107]
	v_pk_fma_f32 v[68:69], v[68:69], v[96:97], v[104:105]
	v_lshl_add_u64 v[72:73], v[174:175], 2, v[72:73]
	global_store_dwordx4 v[72:73], v[68:71], off offset:64
	s_and_saveexec_b64 s[2:3], vcc
	s_xor_b64 s[42:43], exec, s[2:3]
	v_add3_u32 v68, v228, v222, s57
	s_or_saveexec_b64 s[42:43], s[42:43]
	v_mov_b64_e32 v[70:71], s[24:25]
	s_xor_b64 exec, exec, s[42:43]
	v_lshl_add_u32 v68, v223, 8, v222
	v_mov_b64_e32 v[70:71], s[36:37]
	s_or_b64 exec, exec, s[42:43]
	v_ashrrev_i32_e32 v69, 31, v68
	v_lshlrev_b64 v[68:69], 13, v[68:69]
	v_lshl_add_u64 v[68:69], v[70:71], 0, v[68:69]
	v_pk_fma_f32 v[66:67], v[66:67], v[98:99], v[102:103]
	v_pk_fma_f32 v[64:65], v[64:65], v[96:97], v[100:101]
	v_lshl_add_u64 v[68:69], v[174:175], 2, v[68:69]
	global_store_dwordx4 v[68:69], v[64:67], off offset:64
	global_load_dwordx4 v[64:67], v[192:193], off offset:512
	s_and_saveexec_b64 s[2:3], s[18:19]
	s_xor_b64 s[42:43], exec, s[2:3]
	v_add3_u32 v68, v213, v203, s57
	s_or_saveexec_b64 s[42:43], s[42:43]
	v_mov_b64_e32 v[70:71], s[24:25]
	s_xor_b64 exec, exec, s[42:43]
	v_lshl_add_u32 v68, v204, 8, v203
	v_mov_b64_e32 v[70:71], s[36:37]
	s_or_b64 exec, exec, s[42:43]
	v_ashrrev_i32_e32 v69, 31, v68
	v_lshlrev_b64 v[68:69], 13, v[68:69]
	v_lshl_add_u64 v[68:69], v[70:71], 0, v[68:69]
	v_lshl_add_u64 v[68:69], v[174:175], 2, v[68:69]
	global_load_dwordx4 v[96:99], v[68:69], off offset:512
	s_and_saveexec_b64 s[2:3], s[16:17]
	s_xor_b64 s[42:43], exec, s[2:3]
	v_add3_u32 v68, v218, v205, s57
	s_or_saveexec_b64 s[42:43], s[42:43]
	v_mov_b64_e32 v[70:71], s[24:25]
	s_xor_b64 exec, exec, s[42:43]
	v_lshl_add_u32 v68, v208, 8, v205
	v_mov_b64_e32 v[70:71], s[36:37]
	s_or_b64 exec, exec, s[42:43]
	v_ashrrev_i32_e32 v69, 31, v68
	v_lshlrev_b64 v[68:69], 13, v[68:69]
	v_lshl_add_u64 v[68:69], v[70:71], 0, v[68:69]
	v_lshl_add_u64 v[68:69], v[174:175], 2, v[68:69]
	global_load_dwordx4 v[92:95], v[68:69], off offset:512
	s_and_saveexec_b64 s[2:3], s[14:15]
	s_xor_b64 s[42:43], exec, s[2:3]
	v_add3_u32 v68, v221, v209, s57
	s_or_saveexec_b64 s[42:43], s[42:43]
	v_mov_b64_e32 v[70:71], s[24:25]
	s_xor_b64 exec, exec, s[42:43]
	v_lshl_add_u32 v68, v210, 8, v209
	v_mov_b64_e32 v[70:71], s[36:37]
	s_or_b64 exec, exec, s[42:43]
	v_ashrrev_i32_e32 v69, 31, v68
	v_lshlrev_b64 v[68:69], 13, v[68:69]
	v_lshl_add_u64 v[68:69], v[70:71], 0, v[68:69]
	v_lshl_add_u64 v[68:69], v[174:175], 2, v[68:69]
	global_load_dwordx4 v[88:91], v[68:69], off offset:512
	s_and_saveexec_b64 s[2:3], s[12:13]
	s_xor_b64 s[42:43], exec, s[2:3]
	v_add3_u32 v68, v224, v211, s57
	s_or_saveexec_b64 s[42:43], s[42:43]
	v_mov_b64_e32 v[70:71], s[24:25]
	s_xor_b64 exec, exec, s[42:43]
	v_lshl_add_u32 v68, v212, 8, v211
	v_mov_b64_e32 v[70:71], s[36:37]
	s_or_b64 exec, exec, s[42:43]
	v_ashrrev_i32_e32 v69, 31, v68
	v_lshlrev_b64 v[68:69], 13, v[68:69]
	v_lshl_add_u64 v[68:69], v[70:71], 0, v[68:69]
	v_lshl_add_u64 v[68:69], v[174:175], 2, v[68:69]
	global_load_dwordx4 v[84:87], v[68:69], off offset:512
	s_and_saveexec_b64 s[2:3], s[10:11]
	s_xor_b64 s[42:43], exec, s[2:3]
	v_add3_u32 v68, v225, v214, s57
; DI void epi_resid(const Acc& acc, const P& p, int brow, int bcol, int layer, int gch, bool from_input) {
;     ...
;             for (int ai = 0; ai < 2; ++ai)
; #pragma unroll
;                 for (int m = 0; m < 4; ++m) {
;                     const int r = brow + ai * 128 + wr * 64 + m * 16 + fr;
;                     const float* sp = (from_input ? inrow(p, r) : xrow(p, r)) + c0;
;                     xv[ai][m] = *(const f32x4*)sp;
;                 }
;             __builtin_amdgcn_sched_barrier(0);
; #pragma unroll
;             for (int ai = 0; ai < 2; ++ai)
; #pragma unroll
;                 for (int m = 0; m < 4; ++m) {
;                     const int r = brow + ai * 128 + wr * 64 + m * 16 + fr;
;                     *(f32x4*)(xrow(p, r) + c0) = xv[ai][m] + g * acc[ai][bj][m][n];
	s_or_saveexec_b64 s[42:43], s[42:43]
	v_mov_b64_e32 v[70:71], s[24:25]
	s_xor_b64 exec, exec, s[42:43]
	v_lshl_add_u32 v68, v215, 8, v214
	v_mov_b64_e32 v[70:71], s[36:37]
	s_or_b64 exec, exec, s[42:43]
	v_ashrrev_i32_e32 v69, 31, v68
	v_lshlrev_b64 v[68:69], 13, v[68:69]
	v_lshl_add_u64 v[68:69], v[70:71], 0, v[68:69]
	v_lshl_add_u64 v[68:69], v[174:175], 2, v[68:69]
	global_load_dwordx4 v[80:83], v[68:69], off offset:512
	s_and_saveexec_b64 s[2:3], s[8:9]
	s_xor_b64 s[42:43], exec, s[2:3]
	v_add3_u32 v68, v226, v216, s57
	s_or_saveexec_b64 s[42:43], s[42:43]
	v_mov_b64_e32 v[70:71], s[24:25]
	s_xor_b64 exec, exec, s[42:43]
	v_lshl_add_u32 v68, v217, 8, v216
	v_mov_b64_e32 v[70:71], s[36:37]
	s_or_b64 exec, exec, s[42:43]
	v_ashrrev_i32_e32 v69, 31, v68
	v_lshlrev_b64 v[68:69], 13, v[68:69]
	v_lshl_add_u64 v[68:69], v[70:71], 0, v[68:69]
	v_lshl_add_u64 v[68:69], v[174:175], 2, v[68:69]
	global_load_dwordx4 v[76:79], v[68:69], off offset:512
	s_and_saveexec_b64 s[2:3], s[6:7]
	s_xor_b64 s[42:43], exec, s[2:3]
	v_add3_u32 v68, v227, v219, s57
	s_or_saveexec_b64 s[42:43], s[42:43]
	v_mov_b64_e32 v[70:71], s[24:25]
	s_xor_b64 exec, exec, s[42:43]
	v_lshl_add_u32 v68, v220, 8, v219
	v_mov_b64_e32 v[70:71], s[36:37]
	s_or_b64 exec, exec, s[42:43]
	v_ashrrev_i32_e32 v69, 31, v68
	v_lshlrev_b64 v[68:69], 13, v[68:69]
	v_lshl_add_u64 v[68:69], v[70:71], 0, v[68:69]
	v_lshl_add_u64 v[68:69], v[174:175], 2, v[68:69]
	global_load_dwordx4 v[72:75], v[68:69], off offset:512
	s_and_saveexec_b64 s[2:3], vcc
	s_xor_b64 s[42:43], exec, s[2:3]
	v_add3_u32 v68, v228, v222, s57
	s_or_saveexec_b64 s[42:43], s[42:43]
	v_mov_b64_e32 v[70:71], s[24:25]
	s_xor_b64 exec, exec, s[42:43]
	v_lshl_add_u32 v68, v223, 8, v222
	v_mov_b64_e32 v[70:71], s[36:37]
	s_or_b64 exec, exec, s[42:43]
	v_ashrrev_i32_e32 v69, 31, v68
	v_lshlrev_b64 v[68:69], 13, v[68:69]
	v_lshl_add_u64 v[68:69], v[70:71], 0, v[68:69]
	v_lshl_add_u64 v[68:69], v[174:175], 2, v[68:69]
	global_load_dwordx4 v[68:71], v[68:69], off offset:512
	s_and_saveexec_b64 s[2:3], s[18:19]
	s_xor_b64 s[42:43], exec, s[2:3]
	v_add3_u32 v100, v213, v203, s57
	s_or_saveexec_b64 s[42:43], s[42:43]
	v_mov_b64_e32 v[102:103], s[24:25]
	s_xor_b64 exec, exec, s[42:43]
	v_lshl_add_u32 v100, v204, 8, v203
	v_mov_b64_e32 v[102:103], s[36:37]
	s_or_b64 exec, exec, s[42:43]
	v_ashrrev_i32_e32 v101, 31, v100
	s_waitcnt vmcnt(0)
	v_pk_fma_f32 v[60:61], v[60:61], v[64:65], v[96:97]
	v_lshlrev_b64 v[96:97], 13, v[100:101]
	v_lshl_add_u64 v[96:97], v[102:103], 0, v[96:97]
	v_pk_fma_f32 v[62:63], v[62:63], v[66:67], v[98:99]
	v_lshl_add_u64 v[96:97], v[174:175], 2, v[96:97]
	global_store_dwordx4 v[96:97], v[60:63], off offset:512
	s_and_saveexec_b64 s[2:3], s[16:17]
	s_xor_b64 s[42:43], exec, s[2:3]
	v_add3_u32 v60, v218, v205, s57
	s_or_saveexec_b64 s[42:43], s[42:43]
	v_mov_b64_e32 v[62:63], s[24:25]
	s_xor_b64 exec, exec, s[42:43]
	v_lshl_add_u32 v60, v208, 8, v205
	v_mov_b64_e32 v[62:63], s[36:37]
	s_or_b64 exec, exec, s[42:43]
	v_ashrrev_i32_e32 v61, 31, v60
	v_lshlrev_b64 v[60:61], 13, v[60:61]
	v_lshl_add_u64 v[60:61], v[62:63], 0, v[60:61]
	v_pk_fma_f32 v[58:59], v[58:59], v[66:67], v[94:95]
	v_pk_fma_f32 v[56:57], v[56:57], v[64:65], v[92:93]
	v_lshl_add_u64 v[60:61], v[174:175], 2, v[60:61]
	global_store_dwordx4 v[60:61], v[56:59], off offset:512
	s_and_saveexec_b64 s[2:3], s[14:15]
	s_xor_b64 s[42:43], exec, s[2:3]
	v_add3_u32 v56, v221, v209, s57
	s_or_saveexec_b64 s[42:43], s[42:43]
	v_mov_b64_e32 v[58:59], s[24:25]
	s_xor_b64 exec, exec, s[42:43]
	v_lshl_add_u32 v56, v210, 8, v209
	v_mov_b64_e32 v[58:59], s[36:37]
	s_or_b64 exec, exec, s[42:43]
	v_ashrrev_i32_e32 v57, 31, v56
	v_lshlrev_b64 v[56:57], 13, v[56:57]
	v_lshl_add_u64 v[56:57], v[58:59], 0, v[56:57]
	v_pk_fma_f32 v[54:55], v[54:55], v[66:67], v[90:91]
	v_pk_fma_f32 v[52:53], v[52:53], v[64:65], v[88:89]
	v_lshl_add_u64 v[56:57], v[174:175], 2, v[56:57]
	global_store_dwordx4 v[56:57], v[52:55], off offset:512
	s_and_saveexec_b64 s[2:3], s[12:13]
	s_xor_b64 s[42:43], exec, s[2:3]
	v_add3_u32 v52, v224, v211, s57
	s_or_saveexec_b64 s[42:43], s[42:43]
	v_mov_b64_e32 v[54:55], s[24:25]
	s_xor_b64 exec, exec, s[42:43]
	v_lshl_add_u32 v52, v212, 8, v211
	v_mov_b64_e32 v[54:55], s[36:37]
	s_or_b64 exec, exec, s[42:43]
	v_ashrrev_i32_e32 v53, 31, v52
	v_lshlrev_b64 v[52:53], 13, v[52:53]
	v_lshl_add_u64 v[52:53], v[54:55], 0, v[52:53]
	v_pk_fma_f32 v[50:51], v[50:51], v[66:67], v[86:87]
	v_pk_fma_f32 v[48:49], v[48:49], v[64:65], v[84:85]
	v_lshl_add_u64 v[52:53], v[174:175], 2, v[52:53]
	global_store_dwordx4 v[52:53], v[48:51], off offset:512
	s_and_saveexec_b64 s[2:3], s[10:11]
	s_xor_b64 s[42:43], exec, s[2:3]
	v_add3_u32 v48, v225, v214, s57
	s_or_saveexec_b64 s[42:43], s[42:43]
	v_mov_b64_e32 v[50:51], s[24:25]
	s_xor_b64 exec, exec, s[42:43]
	v_lshl_add_u32 v48, v215, 8, v214
	v_mov_b64_e32 v[50:51], s[36:37]
	s_or_b64 exec, exec, s[42:43]
	v_ashrrev_i32_e32 v49, 31, v48
	v_lshlrev_b64 v[48:49], 13, v[48:49]
	v_lshl_add_u64 v[48:49], v[50:51], 0, v[48:49]
	v_pk_fma_f32 v[46:47], v[46:47], v[66:67], v[82:83]
	v_pk_fma_f32 v[44:45], v[44:45], v[64:65], v[80:81]
	v_lshl_add_u64 v[48:49], v[174:175], 2, v[48:49]
	global_store_dwordx4 v[48:49], v[44:47], off offset:512
	s_and_saveexec_b64 s[2:3], s[8:9]
	s_xor_b64 s[42:43], exec, s[2:3]
	v_add3_u32 v44, v226, v216, s57
	s_or_saveexec_b64 s[42:43], s[42:43]
	v_mov_b64_e32 v[46:47], s[24:25]
	s_xor_b64 exec, exec, s[42:43]
	v_lshl_add_u32 v44, v217, 8, v216
	v_mov_b64_e32 v[46:47], s[36:37]
	s_or_b64 exec, exec, s[42:43]
	v_ashrrev_i32_e32 v45, 31, v44
	v_lshlrev_b64 v[44:45], 13, v[44:45]
; DI void epi_resid(const Acc& acc, const P& p, int brow, int bcol, int layer, int gch, bool from_input) {
;     ...
;             const f32x4 g = *(const f32x4*)(gate + c0);
;             f32x4 xv[2][4];
; #pragma unroll
;             for (int ai = 0; ai < 2; ++ai)
; #pragma unroll
;                 for (int m = 0; m < 4; ++m) {
;                     const int r = brow + ai * 128 + wr * 64 + m * 16 + fr;
;                     const float* sp = (from_input ? inrow(p, r) : xrow(p, r)) + c0;
;                     xv[ai][m] = *(const f32x4*)sp;
;     ...
;             for (int ai = 0; ai < 2; ++ai)
; #pragma unroll
;                 for (int m = 0; m < 4; ++m) {
;                     const int r = brow + ai * 128 + wr * 64 + m * 16 + fr;
;                     *(f32x4*)(xrow(p, r) + c0) = xv[ai][m] + g * acc[ai][bj][m][n];
	v_lshl_add_u64 v[44:45], v[46:47], 0, v[44:45]
	v_pk_fma_f32 v[42:43], v[42:43], v[66:67], v[78:79]
	v_pk_fma_f32 v[40:41], v[40:41], v[64:65], v[76:77]
	v_lshl_add_u64 v[44:45], v[174:175], 2, v[44:45]
	global_store_dwordx4 v[44:45], v[40:43], off offset:512
	s_and_saveexec_b64 s[2:3], s[6:7]
	s_xor_b64 s[42:43], exec, s[2:3]
	v_add3_u32 v40, v227, v219, s57
	s_or_saveexec_b64 s[42:43], s[42:43]
	v_mov_b64_e32 v[42:43], s[24:25]
	s_xor_b64 exec, exec, s[42:43]
	v_lshl_add_u32 v40, v220, 8, v219
	v_mov_b64_e32 v[42:43], s[36:37]
	s_or_b64 exec, exec, s[42:43]
	v_ashrrev_i32_e32 v41, 31, v40
	v_lshlrev_b64 v[40:41], 13, v[40:41]
	v_lshl_add_u64 v[40:41], v[42:43], 0, v[40:41]
	v_pk_fma_f32 v[38:39], v[38:39], v[66:67], v[74:75]
	v_pk_fma_f32 v[36:37], v[36:37], v[64:65], v[72:73]
	v_lshl_add_u64 v[40:41], v[174:175], 2, v[40:41]
	global_store_dwordx4 v[40:41], v[36:39], off offset:512
	s_and_saveexec_b64 s[2:3], vcc
	s_xor_b64 s[42:43], exec, s[2:3]
	v_add3_u32 v36, v228, v222, s57
	s_or_saveexec_b64 s[42:43], s[42:43]
	v_mov_b64_e32 v[38:39], s[24:25]
	s_xor_b64 exec, exec, s[42:43]
	v_lshl_add_u32 v36, v223, 8, v222
	v_mov_b64_e32 v[38:39], s[36:37]
	s_or_b64 exec, exec, s[42:43]
	v_ashrrev_i32_e32 v37, 31, v36
	v_lshlrev_b64 v[36:37], 13, v[36:37]
	v_lshl_add_u64 v[36:37], v[38:39], 0, v[36:37]
	v_pk_fma_f32 v[34:35], v[34:35], v[66:67], v[70:71]
	v_pk_fma_f32 v[32:33], v[32:33], v[64:65], v[68:69]
	v_lshl_add_u64 v[36:37], v[174:175], 2, v[36:37]
	global_store_dwordx4 v[36:37], v[32:35], off offset:512
	global_load_dwordx4 v[32:35], v[192:193], off offset:576
	s_and_saveexec_b64 s[2:3], s[18:19]
	s_xor_b64 s[42:43], exec, s[2:3]
	v_add3_u32 v36, v213, v203, s57
	s_or_saveexec_b64 s[42:43], s[42:43]
	v_mov_b64_e32 v[38:39], s[24:25]
	s_xor_b64 exec, exec, s[42:43]
	v_lshl_add_u32 v36, v204, 8, v203
	v_mov_b64_e32 v[38:39], s[36:37]
	s_or_b64 exec, exec, s[42:43]
	v_ashrrev_i32_e32 v37, 31, v36
	v_lshlrev_b64 v[36:37], 13, v[36:37]
	v_lshl_add_u64 v[36:37], v[38:39], 0, v[36:37]
	v_lshl_add_u64 v[36:37], v[174:175], 2, v[36:37]
	global_load_dwordx4 v[64:67], v[36:37], off offset:576
	s_and_saveexec_b64 s[2:3], s[16:17]
	s_xor_b64 s[42:43], exec, s[2:3]
	v_add3_u32 v36, v218, v205, s57
	s_or_saveexec_b64 s[42:43], s[42:43]
	v_mov_b64_e32 v[38:39], s[24:25]
	s_xor_b64 exec, exec, s[42:43]
	v_lshl_add_u32 v36, v208, 8, v205
	v_mov_b64_e32 v[38:39], s[36:37]
	s_or_b64 exec, exec, s[42:43]
	v_ashrrev_i32_e32 v37, 31, v36
	v_lshlrev_b64 v[36:37], 13, v[36:37]
	v_lshl_add_u64 v[36:37], v[38:39], 0, v[36:37]
	v_lshl_add_u64 v[36:37], v[174:175], 2, v[36:37]
	global_load_dwordx4 v[60:63], v[36:37], off offset:576
	s_and_saveexec_b64 s[2:3], s[14:15]
	s_xor_b64 s[42:43], exec, s[2:3]
	v_add3_u32 v36, v221, v209, s57
	s_or_saveexec_b64 s[42:43], s[42:43]
	v_mov_b64_e32 v[38:39], s[24:25]
	s_xor_b64 exec, exec, s[42:43]
	v_lshl_add_u32 v36, v210, 8, v209
	v_mov_b64_e32 v[38:39], s[36:37]
	s_or_b64 exec, exec, s[42:43]
	v_ashrrev_i32_e32 v37, 31, v36
	v_lshlrev_b64 v[36:37], 13, v[36:37]
	v_lshl_add_u64 v[36:37], v[38:39], 0, v[36:37]
	v_lshl_add_u64 v[36:37], v[174:175], 2, v[36:37]
	global_load_dwordx4 v[56:59], v[36:37], off offset:576
	s_and_saveexec_b64 s[2:3], s[12:13]
	s_xor_b64 s[42:43], exec, s[2:3]
	v_add3_u32 v36, v224, v211, s57
	s_or_saveexec_b64 s[42:43], s[42:43]
	v_mov_b64_e32 v[38:39], s[24:25]
	s_xor_b64 exec, exec, s[42:43]
	v_lshl_add_u32 v36, v212, 8, v211
	v_mov_b64_e32 v[38:39], s[36:37]
	s_or_b64 exec, exec, s[42:43]
	v_ashrrev_i32_e32 v37, 31, v36
	v_lshlrev_b64 v[36:37], 13, v[36:37]
	v_lshl_add_u64 v[36:37], v[38:39], 0, v[36:37]
	v_lshl_add_u64 v[36:37], v[174:175], 2, v[36:37]
	global_load_dwordx4 v[52:55], v[36:37], off offset:576
	s_and_saveexec_b64 s[2:3], s[10:11]
	s_xor_b64 s[42:43], exec, s[2:3]
	v_add3_u32 v36, v225, v214, s57
	s_or_saveexec_b64 s[42:43], s[42:43]
	v_mov_b64_e32 v[38:39], s[24:25]
	s_xor_b64 exec, exec, s[42:43]
	v_lshl_add_u32 v36, v215, 8, v214
	v_mov_b64_e32 v[38:39], s[36:37]
	s_or_b64 exec, exec, s[42:43]
	v_ashrrev_i32_e32 v37, 31, v36
	v_lshlrev_b64 v[36:37], 13, v[36:37]
	v_lshl_add_u64 v[36:37], v[38:39], 0, v[36:37]
	v_lshl_add_u64 v[36:37], v[174:175], 2, v[36:37]
	global_load_dwordx4 v[48:51], v[36:37], off offset:576
	s_and_saveexec_b64 s[2:3], s[8:9]
	s_xor_b64 s[42:43], exec, s[2:3]
	v_add3_u32 v36, v226, v216, s57
	s_or_saveexec_b64 s[42:43], s[42:43]
	v_mov_b64_e32 v[38:39], s[24:25]
	s_xor_b64 exec, exec, s[42:43]
	v_lshl_add_u32 v36, v217, 8, v216
	v_mov_b64_e32 v[38:39], s[36:37]
	s_or_b64 exec, exec, s[42:43]
	v_ashrrev_i32_e32 v37, 31, v36
	v_lshlrev_b64 v[36:37], 13, v[36:37]
	v_lshl_add_u64 v[36:37], v[38:39], 0, v[36:37]
	v_lshl_add_u64 v[36:37], v[174:175], 2, v[36:37]
	global_load_dwordx4 v[44:47], v[36:37], off offset:576
	s_and_saveexec_b64 s[2:3], s[6:7]
	s_xor_b64 s[42:43], exec, s[2:3]
	v_add3_u32 v36, v227, v219, s57
	s_or_saveexec_b64 s[42:43], s[42:43]
	v_mov_b64_e32 v[38:39], s[24:25]
	s_xor_b64 exec, exec, s[42:43]
	v_lshl_add_u32 v36, v220, 8, v219
	v_mov_b64_e32 v[38:39], s[36:37]
	s_or_b64 exec, exec, s[42:43]
	v_ashrrev_i32_e32 v37, 31, v36
	v_lshlrev_b64 v[36:37], 13, v[36:37]
	v_lshl_add_u64 v[36:37], v[38:39], 0, v[36:37]
	v_lshl_add_u64 v[36:37], v[174:175], 2, v[36:37]
	global_load_dwordx4 v[40:43], v[36:37], off offset:576
	s_and_saveexec_b64 s[2:3], vcc
	s_xor_b64 s[42:43], exec, s[2:3]
	v_add3_u32 v36, v228, v222, s57
	s_or_saveexec_b64 s[42:43], s[42:43]
	v_mov_b64_e32 v[38:39], s[24:25]
	s_xor_b64 exec, exec, s[42:43]
	v_lshl_add_u32 v36, v223, 8, v222
	v_mov_b64_e32 v[38:39], s[36:37]
	s_or_b64 exec, exec, s[42:43]
	v_ashrrev_i32_e32 v37, 31, v36
	v_lshlrev_b64 v[36:37], 13, v[36:37]
	v_lshl_add_u64 v[36:37], v[38:39], 0, v[36:37]
	v_lshl_add_u64 v[36:37], v[174:175], 2, v[36:37]
	global_load_dwordx4 v[36:39], v[36:37], off offset:576
	s_and_saveexec_b64 s[2:3], s[18:19]
	s_xor_b64 s[18:19], exec, s[2:3]
	s_or_saveexec_b64 s[18:19], s[18:19]
	v_mov_b64_e32 v[68:69], s[24:25]
	s_xor_b64 exec, exec, s[18:19]
	v_mov_b64_e32 v[68:69], s[36:37]
	v_mov_b32_e32 v190, v191
	s_or_b64 exec, exec, s[18:19]
	v_ashrrev_i32_e32 v191, 31, v190
	s_waitcnt vmcnt(0)
; DI void epi_resid(const Acc& acc, const P& p, int brow, int bcol, int layer, int gch, bool from_input) {
;     ...
;             for (int ai = 0; ai < 2; ++ai)
; #pragma unroll
;                 for (int m = 0; m < 4; ++m) {
;                     const int r = brow + ai * 128 + wr * 64 + m * 16 + fr;
;                     *(f32x4*)(xrow(p, r) + c0) = xv[ai][m] + g * acc[ai][bj][m][n];
	v_pk_fma_f32 v[28:29], v[28:29], v[32:33], v[64:65]
	v_lshlrev_b64 v[64:65], 13, v[190:191]
	v_lshl_add_u64 v[64:65], v[68:69], 0, v[64:65]
	v_pk_fma_f32 v[30:31], v[30:31], v[34:35], v[66:67]
	v_lshl_add_u64 v[64:65], v[174:175], 2, v[64:65]
	global_store_dwordx4 v[64:65], v[28:31], off offset:576
	s_and_saveexec_b64 s[2:3], s[16:17]
	s_xor_b64 s[16:17], exec, s[2:3]
	s_or_saveexec_b64 s[16:17], s[16:17]
	v_mov_b64_e32 v[28:29], s[24:25]
	s_xor_b64 exec, exec, s[16:17]
	v_mov_b64_e32 v[28:29], s[36:37]
	v_mov_b32_e32 v188, v189
	s_or_b64 exec, exec, s[16:17]
	v_ashrrev_i32_e32 v189, 31, v188
	v_lshlrev_b64 v[30:31], 13, v[188:189]
	v_lshl_add_u64 v[28:29], v[28:29], 0, v[30:31]
	v_pk_fma_f32 v[26:27], v[26:27], v[34:35], v[62:63]
	v_pk_fma_f32 v[24:25], v[24:25], v[32:33], v[60:61]
	v_lshl_add_u64 v[28:29], v[174:175], 2, v[28:29]
	global_store_dwordx4 v[28:29], v[24:27], off offset:576
	s_and_saveexec_b64 s[2:3], s[14:15]
	s_xor_b64 s[14:15], exec, s[2:3]
	s_or_saveexec_b64 s[14:15], s[14:15]
	v_mov_b64_e32 v[24:25], s[24:25]
	s_xor_b64 exec, exec, s[14:15]
	v_mov_b64_e32 v[24:25], s[36:37]
	v_mov_b32_e32 v186, v187
	s_or_b64 exec, exec, s[14:15]
	v_ashrrev_i32_e32 v187, 31, v186
	v_lshlrev_b64 v[26:27], 13, v[186:187]
	v_lshl_add_u64 v[24:25], v[24:25], 0, v[26:27]
	v_pk_fma_f32 v[22:23], v[22:23], v[34:35], v[58:59]
	v_pk_fma_f32 v[20:21], v[20:21], v[32:33], v[56:57]
	v_lshl_add_u64 v[24:25], v[174:175], 2, v[24:25]
	global_store_dwordx4 v[24:25], v[20:23], off offset:576
	s_and_saveexec_b64 s[2:3], s[12:13]
	s_xor_b64 s[12:13], exec, s[2:3]
	s_or_saveexec_b64 s[12:13], s[12:13]
	v_mov_b64_e32 v[20:21], s[24:25]
	s_xor_b64 exec, exec, s[12:13]
	v_mov_b64_e32 v[20:21], s[36:37]
	v_mov_b32_e32 v184, v185
	s_or_b64 exec, exec, s[12:13]
	v_ashrrev_i32_e32 v185, 31, v184
	v_lshlrev_b64 v[22:23], 13, v[184:185]
	v_lshl_add_u64 v[20:21], v[20:21], 0, v[22:23]
	v_pk_fma_f32 v[18:19], v[18:19], v[34:35], v[54:55]
	v_pk_fma_f32 v[16:17], v[16:17], v[32:33], v[52:53]
	v_lshl_add_u64 v[20:21], v[174:175], 2, v[20:21]
	global_store_dwordx4 v[20:21], v[16:19], off offset:576
	s_and_saveexec_b64 s[2:3], s[10:11]
	s_xor_b64 s[10:11], exec, s[2:3]
	s_or_saveexec_b64 s[10:11], s[10:11]
	v_mov_b64_e32 v[16:17], s[24:25]
	s_xor_b64 exec, exec, s[10:11]
	v_mov_b64_e32 v[16:17], s[36:37]
	v_mov_b32_e32 v182, v183
	s_or_b64 exec, exec, s[10:11]
	v_ashrrev_i32_e32 v183, 31, v182
	v_lshlrev_b64 v[18:19], 13, v[182:183]
	v_lshl_add_u64 v[16:17], v[16:17], 0, v[18:19]
	v_pk_fma_f32 v[14:15], v[14:15], v[34:35], v[50:51]
	v_pk_fma_f32 v[12:13], v[12:13], v[32:33], v[48:49]
	v_lshl_add_u64 v[16:17], v[174:175], 2, v[16:17]
	global_store_dwordx4 v[16:17], v[12:15], off offset:576
	s_and_saveexec_b64 s[2:3], s[8:9]
	s_xor_b64 s[8:9], exec, s[2:3]
	s_or_saveexec_b64 s[8:9], s[8:9]
	v_mov_b64_e32 v[12:13], s[24:25]
	s_xor_b64 exec, exec, s[8:9]
	v_mov_b64_e32 v[12:13], s[36:37]
	v_mov_b32_e32 v180, v181
	s_or_b64 exec, exec, s[8:9]
	v_ashrrev_i32_e32 v181, 31, v180
	v_lshlrev_b64 v[14:15], 13, v[180:181]
	v_lshl_add_u64 v[12:13], v[12:13], 0, v[14:15]
	v_pk_fma_f32 v[10:11], v[10:11], v[34:35], v[46:47]
	v_pk_fma_f32 v[8:9], v[8:9], v[32:33], v[44:45]
	v_lshl_add_u64 v[12:13], v[174:175], 2, v[12:13]
	global_store_dwordx4 v[12:13], v[8:11], off offset:576
	s_and_saveexec_b64 s[2:3], s[6:7]
	s_xor_b64 s[6:7], exec, s[2:3]
	s_or_saveexec_b64 s[6:7], s[6:7]
	v_mov_b64_e32 v[8:9], s[24:25]
	s_xor_b64 exec, exec, s[6:7]
	v_mov_b64_e32 v[8:9], s[36:37]
	v_mov_b32_e32 v178, v179
	s_or_b64 exec, exec, s[6:7]
	v_ashrrev_i32_e32 v179, 31, v178
	v_lshlrev_b64 v[10:11], 13, v[178:179]
	v_lshl_add_u64 v[8:9], v[8:9], 0, v[10:11]
	v_pk_fma_f32 v[6:7], v[6:7], v[34:35], v[42:43]
	v_pk_fma_f32 v[4:5], v[4:5], v[32:33], v[40:41]
	v_lshl_add_u64 v[8:9], v[174:175], 2, v[8:9]
	global_store_dwordx4 v[8:9], v[4:7], off offset:576
	s_and_saveexec_b64 s[2:3], vcc
	s_xor_b64 s[6:7], exec, s[2:3]
	s_or_saveexec_b64 s[6:7], s[6:7]
	v_mov_b64_e32 v[4:5], s[24:25]
	s_xor_b64 exec, exec, s[6:7]
	s_cbranch_execz .LBB0_2666
	v_mov_b64_e32 v[4:5], s[36:37]
	v_mov_b32_e32 v176, v177
	s_branch .LBB0_2666

; #define WAIT_V(n) asm volatile("s_waitcnt vmcnt(" #n ")" ::: "memory")
; #define WAIT_L(n) asm volatile("s_waitcnt lgkmcnt(" #n ")" ::: "memory")
; #define BAR __builtin_amdgcn_s_barrier()
; #define SCHED __builtin_amdgcn_sched_barrier(0)
; template <class Get, class Epi>
; DI void gemm_stream(LAS unsigned char* lds, const int K, const int ld, Get get, Epi epi) {
;     ...
;         for (int t = 0; t < nt; t += 2) {
;             const bool last = (t == nt - 2);
;             const char* a1 = cA + (size_t)(t + 1) * kstep;
;             const char* a2 = last ? nA : cA + (size_t)(t + 2) * kstep;
;             const char* b2 = last ? nB : cB + (size_t)(t + 2) * kstep;
;             const char* a3 = a2 + kstep;
;             const char* b3 = b2 + kstep;
;             LDB(B0, 0, 0); SCHED; LDA(At, 0, 0); STAGE(SAo(1, 1), a1 + hstep);
;             WAIT_L(8); BAR; WAIT_L(0); MMA(0, 0, At, B0); BAR; SCHED;
;             LDB(B1, 0, 1); STAGE(SBo(0, 0), b2);
;             BAR; WAIT_L(0); MMA(0, 1, At, B1); BAR;
;             LDA(At, 0, 1); STAGE(SAo(0, 0), a2);
;             BAR; WAIT_L(0); MMA(1, 0, At, B0); BAR; SCHED;
;             STAGE(SBo(0, 1), b2 + hstep);
;             WAIT_V(6); BAR; MMA(1, 1, At, B1); BAR;
;             LDB(B0, 1, 0); SCHED; LDA(At, 1, 0); STAGE(SAo(0, 1), a2 + hstep);
;             WAIT_L(8); BAR; WAIT_L(0); MMA(0, 0, At, B0); BAR; SCHED;
;             LDB(B1, 1, 1); STAGE(SBo(1, 0), b3);
;             BAR; WAIT_L(0); MMA(0, 1, At, B1); BAR;
.LBB0_3046:
	ds_read_b128 v[148:151], v142
	ds_read_b128 v[152:155], v142 offset:1024
	ds_read_b128 v[156:159], v142 offset:2048
	ds_read_b128 v[160:163], v142 offset:3072
	s_add_u32 s14, s12, 0xfff80080
	s_addc_u32 s15, s13, -1
	s_cmp_eq_u32 s56, 28
	s_cselect_b32 s17, s9, s15
	s_cselect_b32 s16, s8, s14
	s_cselect_b32 s15, s11, s55
	s_cselect_b32 s14, s10, s0
	s_mov_b32 m0, s38
	v_lshl_add_u64 v[140:141], s[12:13], 0, v[134:135]
	ds_read_b128 v[164:167], v143
	ds_read_b128 v[168:171], v143 offset:1024
	ds_read_b128 v[172:175], v143 offset:2048
	ds_read_b128 v[176:179], v143 offset:3072
	ds_read_b128 v[180:183], v143 offset:4096
	ds_read_b128 v[184:187], v143 offset:5120
	ds_read_b128 v[188:191], v143 offset:6144
	ds_read_b128 v[192:195], v143 offset:7168
	global_load_lds_dwordx4 v[140:141], off
	v_lshl_add_u64 v[140:141], s[12:13], 0, v[136:137]
	s_mov_b32 m0, s39
	s_nop 0
	global_load_lds_dwordx4 v[140:141], off
	s_waitcnt lgkmcnt(8)
	s_barrier
	s_waitcnt lgkmcnt(0)
	v_mfma_f32_16x16x32_bf16 v[124:127], v[148:151], v[164:167], v[124:127]
	v_mfma_f32_16x16x32_bf16 v[116:119], v[156:159], v[164:167], v[116:119]
	v_mfma_f32_16x16x32_bf16 v[108:111], v[148:151], v[172:175], v[108:111]
	v_mfma_f32_16x16x32_bf16 v[100:103], v[156:159], v[172:175], v[100:103]
	v_mfma_f32_16x16x32_bf16 v[92:95], v[148:151], v[180:183], v[92:95]
	v_mfma_f32_16x16x32_bf16 v[84:87], v[156:159], v[180:183], v[84:87]
	v_mfma_f32_16x16x32_bf16 v[76:79], v[148:151], v[188:191], v[76:79]
	v_mfma_f32_16x16x32_bf16 v[68:71], v[156:159], v[188:191], v[68:71]
	v_mfma_f32_16x16x32_bf16 v[124:127], v[152:155], v[168:171], v[124:127]
	v_mfma_f32_16x16x32_bf16 v[116:119], v[160:163], v[168:171], v[116:119]
	v_mfma_f32_16x16x32_bf16 v[108:111], v[152:155], v[176:179], v[108:111]
	v_mfma_f32_16x16x32_bf16 v[100:103], v[160:163], v[176:179], v[100:103]
	v_mfma_f32_16x16x32_bf16 v[92:95], v[152:155], v[184:187], v[92:95]
	v_mfma_f32_16x16x32_bf16 v[84:87], v[160:163], v[184:187], v[84:87]
	v_mfma_f32_16x16x32_bf16 v[76:79], v[152:155], v[192:195], v[76:79]
	v_mfma_f32_16x16x32_bf16 v[68:71], v[160:163], v[192:195], v[68:71]
	s_barrier
	s_mov_b32 m0, s40
	v_lshl_add_u64 v[140:141], s[14:15], 0, v[130:131]
	ds_read_b128 v[196:199], v144
	ds_read_b128 v[200:203], v144 offset:1024
	ds_read_b128 v[208:211], v144 offset:2048
	ds_read_b128 v[212:215], v144 offset:3072
	global_load_lds_dwordx4 v[140:141], off
	v_lshl_add_u64 v[204:205], s[14:15], 0, v[128:129]
	s_mov_b32 m0, s41
	s_nop 0
	global_load_lds_dwordx4 v[204:205], off
	s_barrier
	s_waitcnt lgkmcnt(0)
	v_mfma_f32_16x16x32_bf16 v[120:123], v[196:199], v[164:167], v[120:123]
	v_mfma_f32_16x16x32_bf16 v[112:115], v[208:211], v[164:167], v[112:115]
	v_mfma_f32_16x16x32_bf16 v[104:107], v[196:199], v[172:175], v[104:107]
	v_mfma_f32_16x16x32_bf16 v[96:99], v[208:211], v[172:175], v[96:99]
	v_mfma_f32_16x16x32_bf16 v[88:91], v[196:199], v[180:183], v[88:91]
	v_mfma_f32_16x16x32_bf16 v[80:83], v[208:211], v[180:183], v[80:83]
	v_mfma_f32_16x16x32_bf16 v[72:75], v[196:199], v[188:191], v[72:75]
	v_mfma_f32_16x16x32_bf16 v[64:67], v[208:211], v[188:191], v[64:67]
	v_mfma_f32_16x16x32_bf16 v[120:123], v[200:203], v[168:171], v[120:123]
	v_mfma_f32_16x16x32_bf16 v[112:115], v[212:215], v[168:171], v[112:115]
	v_mfma_f32_16x16x32_bf16 v[104:107], v[200:203], v[176:179], v[104:107]
	v_mfma_f32_16x16x32_bf16 v[96:99], v[212:215], v[176:179], v[96:99]
	v_mfma_f32_16x16x32_bf16 v[88:91], v[200:203], v[184:187], v[88:91]
	v_mfma_f32_16x16x32_bf16 v[80:83], v[212:215], v[184:187], v[80:83]
	v_mfma_f32_16x16x32_bf16 v[72:75], v[200:203], v[192:195], v[72:75]
	v_mfma_f32_16x16x32_bf16 v[64:67], v[212:215], v[192:195], v[64:67]
	s_mov_b32 m0, s19
	v_lshl_add_u64 v[216:217], s[16:17], 0, v[130:131]
	s_barrier
	ds_read_b128 v[164:167], v143 offset:16384
	ds_read_b128 v[168:171], v143 offset:17408
	ds_read_b128 v[172:175], v143 offset:18432
	ds_read_b128 v[176:179], v143 offset:19456
	ds_read_b128 v[180:183], v143 offset:20480
	ds_read_b128 v[184:187], v143 offset:21504
	ds_read_b128 v[188:191], v143 offset:22528
	ds_read_b128 v[192:195], v143 offset:23552
	global_load_lds_dwordx4 v[216:217], off
	v_lshl_add_u64 v[218:219], s[16:17], 0, v[128:129]
	s_mov_b32 m0, s20
	s_nop 0
	global_load_lds_dwordx4 v[218:219], off
	s_barrier
	s_waitcnt lgkmcnt(0)
	v_mfma_f32_16x16x32_bf16 v[60:63], v[148:151], v[164:167], v[60:63]
	v_mfma_f32_16x16x32_bf16 v[52:55], v[156:159], v[164:167], v[52:55]
	v_mfma_f32_16x16x32_bf16 v[44:47], v[148:151], v[172:175], v[44:47]
	v_mfma_f32_16x16x32_bf16 v[36:39], v[156:159], v[172:175], v[36:39]
	v_mfma_f32_16x16x32_bf16 v[28:31], v[148:151], v[180:183], v[28:31]
	v_mfma_f32_16x16x32_bf16 v[20:23], v[156:159], v[180:183], v[20:23]
	v_mfma_f32_16x16x32_bf16 v[12:15], v[148:151], v[188:191], v[12:15]
	v_mfma_f32_16x16x32_bf16 v[4:7], v[156:159], v[188:191], v[4:7]
	v_mfma_f32_16x16x32_bf16 v[60:63], v[152:155], v[168:171], v[60:63]
	v_mfma_f32_16x16x32_bf16 v[52:55], v[160:163], v[168:171], v[52:55]
	v_mfma_f32_16x16x32_bf16 v[44:47], v[152:155], v[176:179], v[44:47]
	v_mfma_f32_16x16x32_bf16 v[36:39], v[160:163], v[176:179], v[36:39]
	v_mfma_f32_16x16x32_bf16 v[28:31], v[152:155], v[184:187], v[28:31]
	v_mfma_f32_16x16x32_bf16 v[20:23], v[160:163], v[184:187], v[20:23]
	v_mfma_f32_16x16x32_bf16 v[12:15], v[152:155], v[192:195], v[12:15]
	v_mfma_f32_16x16x32_bf16 v[4:7], v[160:163], v[192:195], v[4:7]
	s_barrier
	s_add_u32 s58, s14, 0x80000
	s_addc_u32 s59, s15, 0
	s_mov_b32 m0, s42
	v_lshl_add_u64 v[148:149], s[58:59], 0, v[130:131]
	global_load_lds_dwordx4 v[148:149], off
	v_lshl_add_u64 v[148:149], s[58:59], 0, v[128:129]
	s_mov_b32 m0, s43
	s_nop 0
	global_load_lds_dwordx4 v[148:149], off
	s_waitcnt vmcnt(6)
	s_barrier
; #define WAIT_V(n) asm volatile("s_waitcnt vmcnt(" #n ")" ::: "memory")
; #define WAIT_L(n) asm volatile("s_waitcnt lgkmcnt(" #n ")" ::: "memory")
; #define BAR __builtin_amdgcn_s_barrier()
; #define SCHED __builtin_amdgcn_sched_barrier(0)
; template <class Get, class Epi>
; DI void gemm_stream(LAS unsigned char* lds, const int K, const int ld, Get get, Epi epi) {
;     ...
;             LDB(B0, 0, 0); SCHED; LDA(At, 0, 0); STAGE(SAo(1, 1), a1 + hstep);
;             WAIT_L(8); BAR; WAIT_L(0); MMA(0, 0, At, B0); BAR; SCHED;
;             LDB(B1, 0, 1); STAGE(SBo(0, 0), b2);
;             BAR; WAIT_L(0); MMA(0, 1, At, B1); BAR;
;             LDA(At, 0, 1); STAGE(SAo(0, 0), a2);
;             BAR; WAIT_L(0); MMA(1, 0, At, B0); BAR; SCHED;
;             STAGE(SBo(0, 1), b2 + hstep);
;             WAIT_V(6); BAR; MMA(1, 1, At, B1); BAR;
;             LDB(B0, 1, 0); SCHED; LDA(At, 1, 0); STAGE(SAo(0, 1), a2 + hstep);
;             WAIT_L(8); BAR; WAIT_L(0); MMA(0, 0, At, B0); BAR; SCHED;
;     ...
;             LDA(At, 1, 1); STAGE(SAo(1, 0), a3);
;             BAR; WAIT_L(0); MMA(1, 0, At, B0); BAR; SCHED;
;             STAGE(SBo(1, 1), b3 + hstep);
;             WAIT_V(6); BAR; MMA(1, 1, At, B1); BAR;
	v_mfma_f32_16x16x32_bf16 v[56:59], v[196:199], v[164:167], v[56:59]
	v_mfma_f32_16x16x32_bf16 v[48:51], v[208:211], v[164:167], v[48:51]
	v_mfma_f32_16x16x32_bf16 v[40:43], v[196:199], v[172:175], v[40:43]
	v_mfma_f32_16x16x32_bf16 v[32:35], v[208:211], v[172:175], v[32:35]
	v_mfma_f32_16x16x32_bf16 v[24:27], v[196:199], v[180:183], v[24:27]
	v_mfma_f32_16x16x32_bf16 v[16:19], v[208:211], v[180:183], v[16:19]
	v_mfma_f32_16x16x32_bf16 v[8:11], v[196:199], v[188:191], v[8:11]
	v_mfma_f32_16x16x32_bf16 v[0:3], v[208:211], v[188:191], v[0:3]
	v_mfma_f32_16x16x32_bf16 v[56:59], v[200:203], v[168:171], v[56:59]
	v_mfma_f32_16x16x32_bf16 v[48:51], v[212:215], v[168:171], v[48:51]
	v_mfma_f32_16x16x32_bf16 v[40:43], v[200:203], v[176:179], v[40:43]
	v_mfma_f32_16x16x32_bf16 v[32:35], v[212:215], v[176:179], v[32:35]
	v_mfma_f32_16x16x32_bf16 v[24:27], v[200:203], v[184:187], v[24:27]
	v_mfma_f32_16x16x32_bf16 v[16:19], v[212:215], v[184:187], v[16:19]
	v_mfma_f32_16x16x32_bf16 v[8:11], v[200:203], v[192:195], v[8:11]
	v_mfma_f32_16x16x32_bf16 v[0:3], v[212:215], v[192:195], v[0:3]
	s_barrier
	ds_read_b128 v[148:151], v145
	ds_read_b128 v[152:155], v145 offset:1024
	ds_read_b128 v[156:159], v145 offset:2048
	ds_read_b128 v[160:163], v145 offset:3072
	s_add_u32 s16, s16, 0x80000
	s_addc_u32 s17, s17, 0
	s_mov_b32 m0, s21
	v_lshl_add_u64 v[196:197], s[16:17], 0, v[130:131]
	ds_read_b128 v[164:167], v143 offset:32768
	ds_read_b128 v[168:171], v143 offset:33792
	ds_read_b128 v[172:175], v143 offset:34816
	ds_read_b128 v[176:179], v143 offset:35840
	ds_read_b128 v[180:183], v143 offset:36864
	ds_read_b128 v[184:187], v143 offset:37888
	ds_read_b128 v[188:191], v143 offset:38912
	ds_read_b128 v[192:195], v143 offset:39936
	global_load_lds_dwordx4 v[196:197], off
	v_lshl_add_u64 v[196:197], s[16:17], 0, v[128:129]
	s_mov_b32 m0, s28
	s_nop 0
	global_load_lds_dwordx4 v[196:197], off
	s_waitcnt lgkmcnt(8)
	s_barrier
	s_waitcnt lgkmcnt(0)
	v_mfma_f32_16x16x32_bf16 v[124:127], v[148:151], v[164:167], v[124:127]
	v_mfma_f32_16x16x32_bf16 v[116:119], v[156:159], v[164:167], v[116:119]
	v_mfma_f32_16x16x32_bf16 v[108:111], v[148:151], v[172:175], v[108:111]
	v_mfma_f32_16x16x32_bf16 v[100:103], v[156:159], v[172:175], v[100:103]
	v_mfma_f32_16x16x32_bf16 v[92:95], v[148:151], v[180:183], v[92:95]
	v_mfma_f32_16x16x32_bf16 v[84:87], v[156:159], v[180:183], v[84:87]
	v_mfma_f32_16x16x32_bf16 v[76:79], v[148:151], v[188:191], v[76:79]
	v_mfma_f32_16x16x32_bf16 v[68:71], v[156:159], v[188:191], v[68:71]
	v_mfma_f32_16x16x32_bf16 v[124:127], v[152:155], v[168:171], v[124:127]
	v_mfma_f32_16x16x32_bf16 v[116:119], v[160:163], v[168:171], v[116:119]
	v_mfma_f32_16x16x32_bf16 v[108:111], v[152:155], v[176:179], v[108:111]
	v_mfma_f32_16x16x32_bf16 v[100:103], v[160:163], v[176:179], v[100:103]
	v_mfma_f32_16x16x32_bf16 v[92:95], v[152:155], v[184:187], v[92:95]
	v_mfma_f32_16x16x32_bf16 v[84:87], v[160:163], v[184:187], v[84:87]
	v_mfma_f32_16x16x32_bf16 v[76:79], v[152:155], v[192:195], v[76:79]
	v_mfma_f32_16x16x32_bf16 v[68:71], v[160:163], v[192:195], v[68:71]
	s_barrier
	s_mov_b32 m0, s44
	v_lshl_add_u64 v[140:141], v[140:141], 0, s[6:7]
	ds_read_b128 v[196:199], v146
	ds_read_b128 v[200:203], v146 offset:1024
	ds_read_b128 v[208:211], v146 offset:2048
	ds_read_b128 v[212:215], v146 offset:3072
	global_load_lds_dwordx4 v[140:141], off
	v_lshl_add_u64 v[140:141], v[204:205], 0, s[6:7]
	s_mov_b32 m0, s45
	s_nop 0
	global_load_lds_dwordx4 v[140:141], off
	s_barrier
	s_waitcnt lgkmcnt(0)
	v_mfma_f32_16x16x32_bf16 v[120:123], v[196:199], v[164:167], v[120:123]
	v_mfma_f32_16x16x32_bf16 v[112:115], v[208:211], v[164:167], v[112:115]
	v_mfma_f32_16x16x32_bf16 v[104:107], v[196:199], v[172:175], v[104:107]
	v_mfma_f32_16x16x32_bf16 v[96:99], v[208:211], v[172:175], v[96:99]
	v_mfma_f32_16x16x32_bf16 v[88:91], v[196:199], v[180:183], v[88:91]
	v_mfma_f32_16x16x32_bf16 v[80:83], v[208:211], v[180:183], v[80:83]
	v_mfma_f32_16x16x32_bf16 v[72:75], v[196:199], v[188:191], v[72:75]
	v_mfma_f32_16x16x32_bf16 v[64:67], v[208:211], v[188:191], v[64:67]
	v_mfma_f32_16x16x32_bf16 v[120:123], v[200:203], v[168:171], v[120:123]
	v_mfma_f32_16x16x32_bf16 v[112:115], v[212:215], v[168:171], v[112:115]
	v_mfma_f32_16x16x32_bf16 v[104:107], v[200:203], v[176:179], v[104:107]
	v_mfma_f32_16x16x32_bf16 v[96:99], v[212:215], v[176:179], v[96:99]
	v_mfma_f32_16x16x32_bf16 v[88:91], v[200:203], v[184:187], v[88:91]
	v_mfma_f32_16x16x32_bf16 v[80:83], v[212:215], v[184:187], v[80:83]
	v_mfma_f32_16x16x32_bf16 v[72:75], v[200:203], v[192:195], v[72:75]
	v_mfma_f32_16x16x32_bf16 v[64:67], v[212:215], v[192:195], v[64:67]
	s_mov_b32 m0, s29
	v_lshl_add_u64 v[140:141], v[216:217], 0, s[6:7]
	s_barrier
	ds_read_b128 v[164:167], v143 offset:49152
	ds_read_b128 v[168:171], v143 offset:50176
	ds_read_b128 v[172:175], v143 offset:51200
	ds_read_b128 v[176:179], v143 offset:52224
	ds_read_b128 v[180:183], v143 offset:53248
	ds_read_b128 v[184:187], v143 offset:54272
	ds_read_b128 v[188:191], v143 offset:55296
	ds_read_b128 v[192:195], v143 offset:56320
	global_load_lds_dwordx4 v[140:141], off
	v_lshl_add_u64 v[140:141], v[218:219], 0, s[6:7]
	s_mov_b32 m0, s36
	s_nop 0
	global_load_lds_dwordx4 v[140:141], off
	s_barrier
; DI float silu_f(float g) { return g * __builtin_amdgcn_rcpf(1.f + __builtin_amdgcn_exp2f(-LOG2E * g)); }
; #define WAIT_V(n) asm volatile("s_waitcnt vmcnt(" #n ")" ::: "memory")
; #define WAIT_L(n) asm volatile("s_waitcnt lgkmcnt(" #n ")" ::: "memory")
; #define BAR __builtin_amdgcn_s_barrier()
; #define SCHED __builtin_amdgcn_sched_barrier(0)
; template <class Get, class Epi>
; DI void gemm_stream(LAS unsigned char* lds, const int K, const int ld, Get get, Epi epi) {
;     ...
;             LDA(At, 1, 1); STAGE(SAo(1, 0), a3);
;             BAR; WAIT_L(0); MMA(1, 0, At, B0); BAR; SCHED;
;             STAGE(SBo(1, 1), b3 + hstep);
;             WAIT_V(6); BAR; MMA(1, 1, At, B1); BAR;
;         }
;         epi(acc, cur);
;         if (!has_next) break;
;         ZERO_ACC;
;         cur = nxt; cA = nA; cB = nB; ++ui;
;     }
; DI void epi_swiglu(const Acc& acc, int brow, int pn, bf16_t* hid) {
;     ...
;     for (int ai = 0; ai < 2; ++ai)
; #pragma unroll
;         for (int m = 0; m < 4; ++m) {
;             const int r = brow + ai * 128 + wr * 64 + m * 16 + fr;
;             bf16_t* rp = hid + (size_t)r * FF + pn * 128 + wc * 32 + fq * 4;
; #pragma unroll
;             for (int n = 0; n < 2; ++n) {
;                 const f32x4 g = acc[ai][0][m][n], u = acc[ai][1][m][n];
;                 float o[4];
; #pragma unroll
;                 for (int j = 0; j < 4; ++j) o[j] = silu_f(g[j]) * u[j];
;                 st4(rp + n * 16, o[0], o[1], o[2], o[3]);
;             }
	s_waitcnt lgkmcnt(0)
	v_mfma_f32_16x16x32_bf16 v[60:63], v[148:151], v[164:167], v[60:63]
	v_mfma_f32_16x16x32_bf16 v[52:55], v[156:159], v[164:167], v[52:55]
	v_mfma_f32_16x16x32_bf16 v[44:47], v[148:151], v[172:175], v[44:47]
	v_mfma_f32_16x16x32_bf16 v[36:39], v[156:159], v[172:175], v[36:39]
	v_mfma_f32_16x16x32_bf16 v[28:31], v[148:151], v[180:183], v[28:31]
	v_mfma_f32_16x16x32_bf16 v[20:23], v[156:159], v[180:183], v[20:23]
	v_mfma_f32_16x16x32_bf16 v[12:15], v[148:151], v[188:191], v[12:15]
	v_mfma_f32_16x16x32_bf16 v[4:7], v[156:159], v[188:191], v[4:7]
	v_mfma_f32_16x16x32_bf16 v[60:63], v[152:155], v[168:171], v[60:63]
	v_mfma_f32_16x16x32_bf16 v[52:55], v[160:163], v[168:171], v[52:55]
	v_mfma_f32_16x16x32_bf16 v[44:47], v[152:155], v[176:179], v[44:47]
	v_mfma_f32_16x16x32_bf16 v[36:39], v[160:163], v[176:179], v[36:39]
	v_mfma_f32_16x16x32_bf16 v[28:31], v[152:155], v[184:187], v[28:31]
	v_mfma_f32_16x16x32_bf16 v[20:23], v[160:163], v[184:187], v[20:23]
	v_mfma_f32_16x16x32_bf16 v[12:15], v[152:155], v[192:195], v[12:15]
	v_mfma_f32_16x16x32_bf16 v[4:7], v[160:163], v[192:195], v[4:7]
	s_barrier
	s_add_u32 s14, s14, 0x80080
	s_addc_u32 s15, s15, 0
	s_mov_b32 m0, s46
	v_lshl_add_u64 v[140:141], s[14:15], 0, v[130:131]
	global_load_lds_dwordx4 v[140:141], off
	v_lshl_add_u64 v[140:141], s[14:15], 0, v[128:129]
	s_mov_b32 m0, s47
	s_nop 0
	global_load_lds_dwordx4 v[140:141], off
	s_waitcnt vmcnt(6)
	s_barrier
	v_mfma_f32_16x16x32_bf16 v[56:59], v[196:199], v[164:167], v[56:59]
	v_mfma_f32_16x16x32_bf16 v[48:51], v[208:211], v[164:167], v[48:51]
	v_mfma_f32_16x16x32_bf16 v[40:43], v[196:199], v[172:175], v[40:43]
	v_mfma_f32_16x16x32_bf16 v[32:35], v[208:211], v[172:175], v[32:35]
	v_mfma_f32_16x16x32_bf16 v[24:27], v[196:199], v[180:183], v[24:27]
	v_mfma_f32_16x16x32_bf16 v[16:19], v[208:211], v[180:183], v[16:19]
	v_mfma_f32_16x16x32_bf16 v[8:11], v[196:199], v[188:191], v[8:11]
	v_mfma_f32_16x16x32_bf16 v[0:3], v[208:211], v[188:191], v[0:3]
	v_mfma_f32_16x16x32_bf16 v[56:59], v[200:203], v[168:171], v[56:59]
	v_mfma_f32_16x16x32_bf16 v[48:51], v[212:215], v[168:171], v[48:51]
	v_mfma_f32_16x16x32_bf16 v[40:43], v[200:203], v[176:179], v[40:43]
	v_mfma_f32_16x16x32_bf16 v[32:35], v[212:215], v[176:179], v[32:35]
	v_mfma_f32_16x16x32_bf16 v[24:27], v[200:203], v[184:187], v[24:27]
	v_mfma_f32_16x16x32_bf16 v[16:19], v[212:215], v[184:187], v[16:19]
	v_mfma_f32_16x16x32_bf16 v[8:11], v[200:203], v[192:195], v[8:11]
	v_mfma_f32_16x16x32_bf16 v[0:3], v[212:215], v[192:195], v[0:3]
	s_add_i32 s56, s56, 2
	s_add_u32 s12, s12, 0x100
	s_addc_u32 s13, s13, 0
	s_add_u32 s0, s0, 0x100
	s_addc_u32 s55, s55, 0
	s_cmp_gt_u32 s56, 29
	s_barrier
	s_cbranch_scc0 .LBB0_3046
	s_lshr_b32 s0, s53, 4
	s_lshl_b32 s12, s53, 8
	s_mulk_i32 s0, 0x1100
	s_and_b32 s12, s12, 0xf00
	s_add_i32 s0, s0, s12
	s_lshl_b32 s12, s54, 7
	s_ashr_i32 s13, s12, 31
	s_addk_i32 s0, 0x100
	v_mov_b32_e32 v132, v206
	s_lshl_b64 s[12:13], s[12:13], 1
	s_add_u32 s12, s23, s12
	v_ashrrev_i32_e32 v140, 2, v132
	v_and_b32_e32 v140, 0xffffffc0, v140
	v_and_or_b32 v141, v132, 15, s0
	s_addc_u32 s13, s35, s13
	v_lshrrev_b32_e32 v148, 1, v132
	v_and_b32_e32 v132, 0xc0, v132
	v_add_u32_e32 v147, v141, v140
	v_lshl_add_u64 v[140:141], s[12:13], 0, v[132:133]
	v_and_b32_e32 v132, 24, v148
	v_mul_f32_e32 v148, 0xbfb8aa3b, v124
	v_exp_f32_e32 v148, v148
	v_mul_f32_e32 v149, 0xbfb8aa3b, v125
	v_exp_f32_e32 v149, v149
	v_lshl_add_u64 v[140:141], v[140:141], 0, v[132:133]
	v_add_f32_e32 v132, 1.0, v148
	v_rcp_f32_e32 v148, v132
	v_add_f32_e32 v132, 1.0, v149
	v_mul_f32_e32 v149, 0xbfb8aa3b, v126
	v_exp_f32_e32 v150, v149
	v_mul_f32_e32 v149, 0xbfb8aa3b, v127
	v_exp_f32_e32 v151, v149
	v_rcp_f32_e32 v149, v132
	v_add_f32_e32 v132, 1.0, v150
	v_rcp_f32_e32 v150, v132
	v_add_f32_e32 v132, 1.0, v151
	v_rcp_f32_e32 v151, v132
	v_pk_mul_f32 v[124:125], v[124:125], v[148:149]
	v_mad_i64_i32 v[152:153], s[12:13], v147, s37, v[140:141]
	v_pk_mul_f32 v[120:121], v[124:125], v[120:121]
	v_pk_mul_f32 v[124:125], v[126:127], v[150:151]
	v_cvt_pk_bf16_f32 v120, v120, v121
	v_mul_f32_e32 v121, 0xbfb8aa3b, v116
	v_pk_mul_f32 v[122:123], v[124:125], v[122:123]
	v_exp_f32_e32 v124, v121
	v_mul_f32_e32 v121, 0xbfb8aa3b, v117
	v_exp_f32_e32 v125, v121
	v_cvt_pk_bf16_f32 v121, v122, v123
	v_add_f32_e32 v122, 1.0, v124
	v_mul_f32_e32 v124, 0xbfb8aa3b, v118
	v_add_f32_e32 v123, 1.0, v125
	v_mul_f32_e32 v125, 0xbfb8aa3b, v119
	v_exp_f32_e32 v124, v124
	v_exp_f32_e32 v125, v125
	v_rcp_f32_e32 v122, v122
	v_rcp_f32_e32 v123, v123
	v_add_f32_e32 v124, 1.0, v124
	v_add_f32_e32 v125, 1.0, v125
	v_rcp_f32_e32 v124, v124
	v_rcp_f32_e32 v125, v125
	v_pk_mul_f32 v[116:117], v[116:117], v[122:123]
	s_and_b64 vcc, exec, s[4:5]
	v_pk_mul_f32 v[112:113], v[116:117], v[112:113]
	v_pk_mul_f32 v[116:117], v[118:119], v[124:125]
	v_cvt_pk_bf16_f32 v112, v112, v113
	v_pk_mul_f32 v[114:115], v[116:117], v[114:115]
	v_or_b32_e32 v116, 16, v147
	v_cvt_pk_bf16_f32 v113, v114, v115
	global_store_dwordx2 v[152:153], v[112:113], off offset:32
	v_mul_f32_e32 v112, 0xbfb8aa3b, v108
	v_mul_f32_e32 v113, 0xbfb8aa3b, v109
	v_exp_f32_e32 v112, v112
	v_exp_f32_e32 v113, v113
	v_mul_f32_e32 v114, 0xbfb8aa3b, v110
	v_mul_f32_e32 v115, 0xbfb8aa3b, v111
	v_exp_f32_e32 v114, v114
	v_exp_f32_e32 v115, v115
	v_add_f32_e32 v112, 1.0, v112
	v_add_f32_e32 v113, 1.0, v113
	v_rcp_f32_e32 v112, v112
	v_rcp_f32_e32 v113, v113
	v_add_f32_e32 v114, 1.0, v114
	v_add_f32_e32 v115, 1.0, v115
	v_rcp_f32_e32 v114, v114
	v_rcp_f32_e32 v115, v115
	v_pk_mul_f32 v[108:109], v[108:109], v[112:113]
	v_mad_i64_i32 v[116:117], s[12:13], v116, s37, v[140:141]
; DI float silu_f(float g) { return g * __builtin_amdgcn_rcpf(1.f + __builtin_amdgcn_exp2f(-LOG2E * g)); }
; DI void epi_swiglu(const Acc& acc, int brow, int pn, bf16_t* hid) {
;     ...
;     for (int ai = 0; ai < 2; ++ai)
; #pragma unroll
;         for (int m = 0; m < 4; ++m) {
;             const int r = brow + ai * 128 + wr * 64 + m * 16 + fr;
;             bf16_t* rp = hid + (size_t)r * FF + pn * 128 + wc * 32 + fq * 4;
; #pragma unroll
;             for (int n = 0; n < 2; ++n) {
;                 const f32x4 g = acc[ai][0][m][n], u = acc[ai][1][m][n];
;                 float o[4];
; #pragma unroll
;                 for (int j = 0; j < 4; ++j) o[j] = silu_f(g[j]) * u[j];
;                 st4(rp + n * 16, o[0], o[1], o[2], o[3]);
;             }
	v_pk_mul_f32 v[104:105], v[108:109], v[104:105]
	v_pk_mul_f32 v[108:109], v[110:111], v[114:115]
	v_cvt_pk_bf16_f32 v104, v104, v105
	v_mul_f32_e32 v105, 0xbfb8aa3b, v100
	v_pk_mul_f32 v[106:107], v[108:109], v[106:107]
	v_exp_f32_e32 v108, v105
	v_mul_f32_e32 v105, 0xbfb8aa3b, v101
	v_exp_f32_e32 v109, v105
	v_cvt_pk_bf16_f32 v105, v106, v107
	v_add_f32_e32 v106, 1.0, v108
	v_mul_f32_e32 v108, 0xbfb8aa3b, v102
	v_add_f32_e32 v107, 1.0, v109
	v_mul_f32_e32 v109, 0xbfb8aa3b, v103
	v_exp_f32_e32 v108, v108
	v_exp_f32_e32 v109, v109
	v_rcp_f32_e32 v106, v106
	v_rcp_f32_e32 v107, v107
	v_add_f32_e32 v108, 1.0, v108
	v_add_f32_e32 v109, 1.0, v109
	v_rcp_f32_e32 v108, v108
	v_rcp_f32_e32 v109, v109
	v_pk_mul_f32 v[100:101], v[100:101], v[106:107]
	s_mov_b32 s54, s49
	v_pk_mul_f32 v[96:97], v[100:101], v[96:97]
	v_pk_mul_f32 v[100:101], v[102:103], v[108:109]
	v_cvt_pk_bf16_f32 v96, v96, v97
	v_pk_mul_f32 v[98:99], v[100:101], v[98:99]
	v_or_b32_e32 v100, 32, v147
	v_cvt_pk_bf16_f32 v97, v98, v99
	global_store_dwordx2 v[116:117], v[96:97], off offset:32
	v_mul_f32_e32 v96, 0xbfb8aa3b, v92
	v_mul_f32_e32 v97, 0xbfb8aa3b, v93
	v_exp_f32_e32 v96, v96
	v_exp_f32_e32 v97, v97
	v_mul_f32_e32 v98, 0xbfb8aa3b, v94
	v_mul_f32_e32 v99, 0xbfb8aa3b, v95
	v_exp_f32_e32 v98, v98
	v_exp_f32_e32 v99, v99
	v_add_f32_e32 v96, 1.0, v96
	v_add_f32_e32 v97, 1.0, v97
	v_rcp_f32_e32 v96, v96
	v_rcp_f32_e32 v97, v97
	v_add_f32_e32 v98, 1.0, v98
	v_add_f32_e32 v99, 1.0, v99
	v_rcp_f32_e32 v98, v98
	v_rcp_f32_e32 v99, v99
	v_pk_mul_f32 v[92:93], v[92:93], v[96:97]
	v_mad_i64_i32 v[100:101], s[12:13], v100, s37, v[140:141]
	v_pk_mul_f32 v[88:89], v[92:93], v[88:89]
	v_pk_mul_f32 v[92:93], v[94:95], v[98:99]
	v_cvt_pk_bf16_f32 v88, v88, v89
	v_mul_f32_e32 v89, 0xbfb8aa3b, v84
	v_pk_mul_f32 v[90:91], v[92:93], v[90:91]
	v_exp_f32_e32 v92, v89
	v_mul_f32_e32 v89, 0xbfb8aa3b, v85
	v_exp_f32_e32 v93, v89
	v_cvt_pk_bf16_f32 v89, v90, v91
	v_add_f32_e32 v90, 1.0, v92
	v_mul_f32_e32 v92, 0xbfb8aa3b, v86
	v_add_f32_e32 v91, 1.0, v93
	v_mul_f32_e32 v93, 0xbfb8aa3b, v87
	v_exp_f32_e32 v92, v92
	v_exp_f32_e32 v93, v93
	v_rcp_f32_e32 v90, v90
	v_rcp_f32_e32 v91, v91
	v_add_f32_e32 v92, 1.0, v92
	v_add_f32_e32 v93, 1.0, v93
	v_rcp_f32_e32 v92, v92
	v_rcp_f32_e32 v93, v93
	v_pk_mul_f32 v[84:85], v[84:85], v[90:91]
	s_mov_b32 s53, s52
	v_pk_mul_f32 v[80:81], v[84:85], v[80:81]
	v_pk_mul_f32 v[84:85], v[86:87], v[92:93]
	v_cvt_pk_bf16_f32 v80, v80, v81
	v_pk_mul_f32 v[82:83], v[84:85], v[82:83]
	v_or_b32_e32 v84, 48, v147
	v_cvt_pk_bf16_f32 v81, v82, v83
	global_store_dwordx2 v[100:101], v[80:81], off offset:32
	v_mul_f32_e32 v80, 0xbfb8aa3b, v76
	v_mul_f32_e32 v81, 0xbfb8aa3b, v77
	v_exp_f32_e32 v80, v80
	v_exp_f32_e32 v81, v81
	v_mul_f32_e32 v82, 0xbfb8aa3b, v78
	v_mul_f32_e32 v83, 0xbfb8aa3b, v79
	v_exp_f32_e32 v82, v82
	v_exp_f32_e32 v83, v83
	v_add_f32_e32 v80, 1.0, v80
	v_add_f32_e32 v81, 1.0, v81
	v_rcp_f32_e32 v80, v80
	v_rcp_f32_e32 v81, v81
	v_add_f32_e32 v82, 1.0, v82
	v_add_f32_e32 v83, 1.0, v83
	v_rcp_f32_e32 v82, v82
	v_rcp_f32_e32 v83, v83
	v_pk_mul_f32 v[76:77], v[76:77], v[80:81]
	v_mad_i64_i32 v[84:85], s[12:13], v84, s37, v[140:141]
	v_pk_mul_f32 v[72:73], v[76:77], v[72:73]
	v_pk_mul_f32 v[76:77], v[78:79], v[82:83]
	v_cvt_pk_bf16_f32 v72, v72, v73
	v_mul_f32_e32 v73, 0xbfb8aa3b, v68
	v_pk_mul_f32 v[74:75], v[76:77], v[74:75]
	v_exp_f32_e32 v76, v73
	v_mul_f32_e32 v73, 0xbfb8aa3b, v69
	v_exp_f32_e32 v77, v73
	v_cvt_pk_bf16_f32 v73, v74, v75
	v_add_f32_e32 v74, 1.0, v76
	v_mul_f32_e32 v76, 0xbfb8aa3b, v70
	v_add_f32_e32 v75, 1.0, v77
	v_mul_f32_e32 v77, 0xbfb8aa3b, v71
	v_exp_f32_e32 v76, v76
	v_exp_f32_e32 v77, v77
	v_rcp_f32_e32 v74, v74
	v_rcp_f32_e32 v75, v75
	v_add_f32_e32 v76, 1.0, v76
	v_add_f32_e32 v77, 1.0, v77
	v_rcp_f32_e32 v76, v76
	v_rcp_f32_e32 v77, v77
	v_pk_mul_f32 v[68:69], v[68:69], v[74:75]
	s_mov_b64 s[14:15], s[10:11]
	v_pk_mul_f32 v[64:65], v[68:69], v[64:65]
	v_pk_mul_f32 v[68:69], v[70:71], v[76:77]
	v_cvt_pk_bf16_f32 v64, v64, v65
	v_pk_mul_f32 v[66:67], v[68:69], v[66:67]
	v_add_u32_e32 v68, 0x80, v147
	v_cvt_pk_bf16_f32 v65, v66, v67
	global_store_dwordx2 v[84:85], v[64:65], off offset:32
	v_mul_f32_e32 v64, 0xbfb8aa3b, v60
	v_mul_f32_e32 v65, 0xbfb8aa3b, v61
	v_exp_f32_e32 v64, v64
	v_exp_f32_e32 v65, v65
	v_mul_f32_e32 v66, 0xbfb8aa3b, v62
	v_mul_f32_e32 v67, 0xbfb8aa3b, v63
	v_exp_f32_e32 v66, v66
	v_exp_f32_e32 v67, v67
	v_add_f32_e32 v64, 1.0, v64
	v_add_f32_e32 v65, 1.0, v65
	v_rcp_f32_e32 v64, v64
	v_rcp_f32_e32 v65, v65
	v_add_f32_e32 v66, 1.0, v66
	v_add_f32_e32 v67, 1.0, v67
	v_rcp_f32_e32 v66, v66
	v_rcp_f32_e32 v67, v67
	v_pk_mul_f32 v[60:61], v[60:61], v[64:65]
	v_mad_i64_i32 v[68:69], s[12:13], v68, s37, v[140:141]
	v_pk_mul_f32 v[56:57], v[60:61], v[56:57]
	v_pk_mul_f32 v[60:61], v[62:63], v[66:67]
	v_cvt_pk_bf16_f32 v56, v56, v57
	v_mul_f32_e32 v57, 0xbfb8aa3b, v52
	v_pk_mul_f32 v[58:59], v[60:61], v[58:59]
	v_exp_f32_e32 v60, v57
	v_mul_f32_e32 v57, 0xbfb8aa3b, v53
	v_exp_f32_e32 v61, v57
	v_cvt_pk_bf16_f32 v57, v58, v59
	v_add_f32_e32 v58, 1.0, v60
	v_mul_f32_e32 v60, 0xbfb8aa3b, v54
	v_add_f32_e32 v59, 1.0, v61
	v_mul_f32_e32 v61, 0xbfb8aa3b, v55
	v_exp_f32_e32 v60, v60
	v_exp_f32_e32 v61, v61
	v_rcp_f32_e32 v58, v58
	v_rcp_f32_e32 v59, v59
	v_add_f32_e32 v60, 1.0, v60
	v_add_f32_e32 v61, 1.0, v61
	v_rcp_f32_e32 v60, v60
; DI float silu_f(float g) { return g * __builtin_amdgcn_rcpf(1.f + __builtin_amdgcn_exp2f(-LOG2E * g)); }
; #define WAIT_V(n) asm volatile("s_waitcnt vmcnt(" #n ")" ::: "memory")
; #define BAR __builtin_amdgcn_s_barrier()
; template <class Get, class Epi>
; DI void gemm_stream(LAS unsigned char* lds, const int K, const int ld, Get get, Epi epi) {
;     ...
;         epi(acc, cur);
;         if (!has_next) break;
;         ZERO_ACC;
;         cur = nxt; cA = nA; cB = nB; ++ui;
;     }
;     WAIT_V(0);
;     if (wr == 0) BAR;
; DI void epi_swiglu(const Acc& acc, int brow, int pn, bf16_t* hid) {
;     ...
;     for (int ai = 0; ai < 2; ++ai)
; #pragma unroll
;         for (int m = 0; m < 4; ++m) {
;             const int r = brow + ai * 128 + wr * 64 + m * 16 + fr;
;             bf16_t* rp = hid + (size_t)r * FF + pn * 128 + wc * 32 + fq * 4;
; #pragma unroll
;             for (int n = 0; n < 2; ++n) {
;                 const f32x4 g = acc[ai][0][m][n], u = acc[ai][1][m][n];
;                 float o[4];
; #pragma unroll
;                 for (int j = 0; j < 4; ++j) o[j] = silu_f(g[j]) * u[j];
;                 st4(rp + n * 16, o[0], o[1], o[2], o[3]);
;             }
	v_rcp_f32_e32 v61, v61
	v_pk_mul_f32 v[52:53], v[52:53], v[58:59]
	global_store_dwordx2 v[152:153], v[120:121], off
	v_pk_mul_f32 v[48:49], v[52:53], v[48:49]
	v_pk_mul_f32 v[52:53], v[54:55], v[60:61]
	v_cvt_pk_bf16_f32 v48, v48, v49
	v_pk_mul_f32 v[50:51], v[52:53], v[50:51]
	v_add_u32_e32 v52, 0x90, v147
	v_cvt_pk_bf16_f32 v49, v50, v51
	global_store_dwordx2 v[68:69], v[48:49], off offset:32
	v_mul_f32_e32 v48, 0xbfb8aa3b, v44
	v_mul_f32_e32 v49, 0xbfb8aa3b, v45
	v_exp_f32_e32 v48, v48
	v_exp_f32_e32 v49, v49
	v_mul_f32_e32 v50, 0xbfb8aa3b, v46
	v_mul_f32_e32 v51, 0xbfb8aa3b, v47
	v_exp_f32_e32 v50, v50
	v_exp_f32_e32 v51, v51
	v_add_f32_e32 v48, 1.0, v48
	v_add_f32_e32 v49, 1.0, v49
	v_rcp_f32_e32 v48, v48
	v_rcp_f32_e32 v49, v49
	v_add_f32_e32 v50, 1.0, v50
	v_add_f32_e32 v51, 1.0, v51
	v_rcp_f32_e32 v50, v50
	v_rcp_f32_e32 v51, v51
	v_pk_mul_f32 v[44:45], v[44:45], v[48:49]
	v_mad_i64_i32 v[52:53], s[12:13], v52, s37, v[140:141]
	v_pk_mul_f32 v[40:41], v[44:45], v[40:41]
	v_pk_mul_f32 v[44:45], v[46:47], v[50:51]
	v_cvt_pk_bf16_f32 v40, v40, v41
	v_mul_f32_e32 v41, 0xbfb8aa3b, v36
	v_pk_mul_f32 v[42:43], v[44:45], v[42:43]
	v_exp_f32_e32 v44, v41
	v_mul_f32_e32 v41, 0xbfb8aa3b, v37
	v_exp_f32_e32 v45, v41
	v_cvt_pk_bf16_f32 v41, v42, v43
	v_add_f32_e32 v42, 1.0, v44
	v_mul_f32_e32 v44, 0xbfb8aa3b, v38
	v_add_f32_e32 v43, 1.0, v45
	v_mul_f32_e32 v45, 0xbfb8aa3b, v39
	v_exp_f32_e32 v44, v44
	v_exp_f32_e32 v45, v45
	v_rcp_f32_e32 v42, v42
	v_rcp_f32_e32 v43, v43
	v_add_f32_e32 v44, 1.0, v44
	v_add_f32_e32 v45, 1.0, v45
	v_rcp_f32_e32 v44, v44
	v_rcp_f32_e32 v45, v45
	v_pk_mul_f32 v[36:37], v[36:37], v[42:43]
	global_store_dwordx2 v[116:117], v[104:105], off
	v_pk_mul_f32 v[32:33], v[36:37], v[32:33]
	v_pk_mul_f32 v[36:37], v[38:39], v[44:45]
	v_cvt_pk_bf16_f32 v32, v32, v33
	v_pk_mul_f32 v[34:35], v[36:37], v[34:35]
	v_add_u32_e32 v36, 0xa0, v147
	v_cvt_pk_bf16_f32 v33, v34, v35
	global_store_dwordx2 v[52:53], v[32:33], off offset:32
	v_mul_f32_e32 v32, 0xbfb8aa3b, v28
	v_mul_f32_e32 v33, 0xbfb8aa3b, v29
	v_exp_f32_e32 v32, v32
	v_exp_f32_e32 v33, v33
	v_mul_f32_e32 v34, 0xbfb8aa3b, v30
	v_mul_f32_e32 v35, 0xbfb8aa3b, v31
	v_exp_f32_e32 v34, v34
	v_exp_f32_e32 v35, v35
	v_add_f32_e32 v32, 1.0, v32
	v_add_f32_e32 v33, 1.0, v33
	v_rcp_f32_e32 v32, v32
	v_rcp_f32_e32 v33, v33
	v_add_f32_e32 v34, 1.0, v34
	v_add_f32_e32 v35, 1.0, v35
	v_rcp_f32_e32 v34, v34
	v_rcp_f32_e32 v35, v35
	v_pk_mul_f32 v[28:29], v[28:29], v[32:33]
	v_mad_i64_i32 v[36:37], s[12:13], v36, s37, v[140:141]
	v_pk_mul_f32 v[24:25], v[28:29], v[24:25]
	v_pk_mul_f32 v[28:29], v[30:31], v[34:35]
	v_cvt_pk_bf16_f32 v24, v24, v25
	v_mul_f32_e32 v25, 0xbfb8aa3b, v20
	v_pk_mul_f32 v[26:27], v[28:29], v[26:27]
	v_exp_f32_e32 v28, v25
	v_mul_f32_e32 v25, 0xbfb8aa3b, v21
	v_exp_f32_e32 v29, v25
	v_cvt_pk_bf16_f32 v25, v26, v27
	v_add_f32_e32 v26, 1.0, v28
	v_mul_f32_e32 v28, 0xbfb8aa3b, v22
	v_add_f32_e32 v27, 1.0, v29
	v_mul_f32_e32 v29, 0xbfb8aa3b, v23
	v_exp_f32_e32 v28, v28
	v_exp_f32_e32 v29, v29
	v_rcp_f32_e32 v26, v26
	v_rcp_f32_e32 v27, v27
	v_add_f32_e32 v28, 1.0, v28
	v_add_f32_e32 v29, 1.0, v29
	v_rcp_f32_e32 v28, v28
	v_rcp_f32_e32 v29, v29
	v_pk_mul_f32 v[20:21], v[20:21], v[26:27]
	global_store_dwordx2 v[100:101], v[88:89], off
	v_pk_mul_f32 v[16:17], v[20:21], v[16:17]
	v_pk_mul_f32 v[20:21], v[22:23], v[28:29]
	v_cvt_pk_bf16_f32 v16, v16, v17
	v_pk_mul_f32 v[18:19], v[20:21], v[18:19]
	v_add_u32_e32 v20, 0xb0, v147
	v_cvt_pk_bf16_f32 v17, v18, v19
	global_store_dwordx2 v[36:37], v[16:17], off offset:32
	v_mul_f32_e32 v16, 0xbfb8aa3b, v12
	v_mul_f32_e32 v17, 0xbfb8aa3b, v13
	v_exp_f32_e32 v16, v16
	v_exp_f32_e32 v17, v17
	v_mul_f32_e32 v18, 0xbfb8aa3b, v14
	v_mul_f32_e32 v19, 0xbfb8aa3b, v15
	v_exp_f32_e32 v18, v18
	v_exp_f32_e32 v19, v19
	v_add_f32_e32 v16, 1.0, v16
	v_add_f32_e32 v17, 1.0, v17
	v_rcp_f32_e32 v16, v16
	v_rcp_f32_e32 v17, v17
	v_add_f32_e32 v18, 1.0, v18
	v_add_f32_e32 v19, 1.0, v19
	v_rcp_f32_e32 v18, v18
	v_rcp_f32_e32 v19, v19
	v_pk_mul_f32 v[12:13], v[12:13], v[16:17]
	v_mad_i64_i32 v[20:21], s[12:13], v20, s37, v[140:141]
	v_pk_mul_f32 v[8:9], v[12:13], v[8:9]
	v_pk_mul_f32 v[12:13], v[14:15], v[18:19]
	v_cvt_pk_bf16_f32 v8, v8, v9
	v_mul_f32_e32 v9, 0xbfb8aa3b, v4
	v_pk_mul_f32 v[10:11], v[12:13], v[10:11]
	v_exp_f32_e32 v12, v9
	v_mul_f32_e32 v9, 0xbfb8aa3b, v5
	v_exp_f32_e32 v13, v9
	v_cvt_pk_bf16_f32 v9, v10, v11
	v_add_f32_e32 v10, 1.0, v12
	v_mul_f32_e32 v12, 0xbfb8aa3b, v6
	v_add_f32_e32 v11, 1.0, v13
	v_mul_f32_e32 v13, 0xbfb8aa3b, v7
	v_exp_f32_e32 v12, v12
	v_exp_f32_e32 v13, v13
	v_rcp_f32_e32 v10, v10
	v_rcp_f32_e32 v11, v11
	v_add_f32_e32 v12, 1.0, v12
	v_add_f32_e32 v13, 1.0, v13
	v_rcp_f32_e32 v12, v12
	v_rcp_f32_e32 v13, v13
	v_pk_mul_f32 v[4:5], v[4:5], v[10:11]
	s_mov_b64 s[12:13], s[8:9]
	v_pk_mul_f32 v[0:1], v[4:5], v[0:1]
	v_pk_mul_f32 v[4:5], v[6:7], v[12:13]
	v_cvt_pk_bf16_f32 v0, v0, v1
	v_pk_mul_f32 v[2:3], v[4:5], v[2:3]
	global_store_dwordx2 v[84:85], v[72:73], off
	v_cvt_pk_bf16_f32 v1, v2, v3
	global_store_dwordx2 v[68:69], v[56:57], off
	global_store_dwordx2 v[52:53], v[40:41], off
	global_store_dwordx2 v[36:37], v[24:25], off
	global_store_dwordx2 v[20:21], v[8:9], off
	global_store_dwordx2 v[20:21], v[0:1], off offset:32
	s_cbranch_vccz .LBB0_3043
	s_waitcnt vmcnt(0)
	s_cmpk_gt_u32 s2, 0xff
	s_cbranch_scc1 .LBB0_3050
	s_barrier

; #define WAIT_V(n) asm volatile("s_waitcnt vmcnt(" #n ")" ::: "memory")
; #define WAIT_L(n) asm volatile("s_waitcnt lgkmcnt(" #n ")" ::: "memory")
; #define BAR __builtin_amdgcn_s_barrier()
; #define SCHED __builtin_amdgcn_sched_barrier(0)
; template <class Get, class Epi>
; DI void gemm_stream(LAS unsigned char* lds, const int K, const int ld, Get get, Epi epi) {
;     ...
;             const bool last = (t == nt - 2);
;             const char* a1 = cA + (size_t)(t + 1) * kstep;
;             const char* a2 = last ? nA : cA + (size_t)(t + 2) * kstep;
;             const char* b2 = last ? nB : cB + (size_t)(t + 2) * kstep;
;             const char* a3 = a2 + kstep;
;             const char* b3 = b2 + kstep;
;             LDB(B0, 0, 0); SCHED; LDA(At, 0, 0); STAGE(SAo(1, 1), a1 + hstep);
;             WAIT_L(8); BAR; WAIT_L(0); MMA(0, 0, At, B0); BAR; SCHED;
;             LDB(B1, 0, 1); STAGE(SBo(0, 0), b2);
;             BAR; WAIT_L(0); MMA(0, 1, At, B1); BAR;
;             LDA(At, 0, 1); STAGE(SAo(0, 0), a2);
;             BAR; WAIT_L(0); MMA(1, 0, At, B0); BAR; SCHED;
;             STAGE(SBo(0, 1), b2 + hstep);
;             WAIT_V(6); BAR; MMA(1, 1, At, B1); BAR;
;             LDB(B0, 1, 0); SCHED; LDA(At, 1, 0); STAGE(SAo(0, 1), a2 + hstep);
;             WAIT_L(8); BAR; WAIT_L(0); MMA(0, 0, At, B0); BAR; SCHED;
;             LDB(B1, 1, 1); STAGE(SBo(1, 0), b3);
;             BAR; WAIT_L(0); MMA(0, 1, At, B1); BAR;
.LBB0_3113:
	ds_read_b128 v[128:131], v199
	ds_read_b128 v[132:135], v199 offset:1024
	ds_read_b128 v[136:139], v199 offset:2048
	ds_read_b128 v[140:143], v199 offset:3072
	s_add_u32 s6, s4, 0x100
	s_addc_u32 s7, s5, 0
	s_cmpk_eq_i32 s16, 0x54
	s_cselect_b32 s11, s37, s7
	s_cselect_b32 s10, s36, s6
	s_cselect_b32 s9, s39, s15
	s_cselect_b32 s8, s38, s14
	s_mov_b32 m0, s54
	v_lshl_add_u64 v[186:187], s[4:5], 0, v[168:169]
	ds_read_b128 v[144:147], v200
	ds_read_b128 v[148:151], v200 offset:1024
	ds_read_b128 v[152:155], v200 offset:2048
	ds_read_b128 v[156:159], v200 offset:3072
	ds_read_b128 v[160:163], v200 offset:4096
	ds_read_b128 v[174:177], v200 offset:5120
	ds_read_b128 v[178:181], v200 offset:6144
	ds_read_b128 v[182:185], v200 offset:7168
	global_load_lds_dwordx4 v[186:187], off
	v_lshl_add_u64 v[186:187], s[4:5], 0, v[170:171]
	s_mov_b32 m0, s55
	s_nop 0
	global_load_lds_dwordx4 v[186:187], off
	s_waitcnt lgkmcnt(8)
	s_barrier
	s_waitcnt lgkmcnt(0)
	v_mfma_f32_16x16x32_bf16 v[124:127], v[128:131], v[144:147], v[124:127]
	v_mfma_f32_16x16x32_bf16 v[92:95], v[136:139], v[144:147], v[92:95]
	v_mfma_f32_16x16x32_bf16 v[120:123], v[128:131], v[152:155], v[120:123]
	v_mfma_f32_16x16x32_bf16 v[88:91], v[136:139], v[152:155], v[88:91]
	v_mfma_f32_16x16x32_bf16 v[116:119], v[128:131], v[160:163], v[116:119]
	v_mfma_f32_16x16x32_bf16 v[84:87], v[136:139], v[160:163], v[84:87]
	v_mfma_f32_16x16x32_bf16 v[112:115], v[128:131], v[178:181], v[112:115]
	v_mfma_f32_16x16x32_bf16 v[80:83], v[136:139], v[178:181], v[80:83]
	v_mfma_f32_16x16x32_bf16 v[124:127], v[132:135], v[148:151], v[124:127]
	v_mfma_f32_16x16x32_bf16 v[92:95], v[140:143], v[148:151], v[92:95]
	v_mfma_f32_16x16x32_bf16 v[120:123], v[132:135], v[156:159], v[120:123]
	v_mfma_f32_16x16x32_bf16 v[88:91], v[140:143], v[156:159], v[88:91]
	v_mfma_f32_16x16x32_bf16 v[116:119], v[132:135], v[174:177], v[116:119]
	v_mfma_f32_16x16x32_bf16 v[84:87], v[140:143], v[174:177], v[84:87]
	v_mfma_f32_16x16x32_bf16 v[112:115], v[132:135], v[182:185], v[112:115]
	v_mfma_f32_16x16x32_bf16 v[80:83], v[140:143], v[182:185], v[80:83]
	s_barrier
	s_mov_b32 m0, s56
	v_lshl_add_u64 v[208:209], s[8:9], 0, v[164:165]
	ds_read_b128 v[186:189], v201
	ds_read_b128 v[190:193], v201 offset:1024
	ds_read_b128 v[194:197], v201 offset:2048
	ds_read_b128 v[202:205], v201 offset:3072
	global_load_lds_dwordx4 v[208:209], off
	v_lshl_add_u64 v[210:211], s[8:9], 0, v[166:167]
	s_mov_b32 m0, s57
	s_nop 0
	global_load_lds_dwordx4 v[210:211], off
	s_barrier
	s_waitcnt lgkmcnt(0)
	v_mfma_f32_16x16x32_bf16 v[60:63], v[186:189], v[144:147], v[60:63]
	v_mfma_f32_16x16x32_bf16 v[28:31], v[194:197], v[144:147], v[28:31]
	v_mfma_f32_16x16x32_bf16 v[56:59], v[186:189], v[152:155], v[56:59]
	v_mfma_f32_16x16x32_bf16 v[24:27], v[194:197], v[152:155], v[24:27]
	v_mfma_f32_16x16x32_bf16 v[52:55], v[186:189], v[160:163], v[52:55]
	v_mfma_f32_16x16x32_bf16 v[20:23], v[194:197], v[160:163], v[20:23]
	v_mfma_f32_16x16x32_bf16 v[48:51], v[186:189], v[178:181], v[48:51]
	v_mfma_f32_16x16x32_bf16 v[16:19], v[194:197], v[178:181], v[16:19]
	v_mfma_f32_16x16x32_bf16 v[60:63], v[190:193], v[148:151], v[60:63]
	v_mfma_f32_16x16x32_bf16 v[28:31], v[202:205], v[148:151], v[28:31]
	v_mfma_f32_16x16x32_bf16 v[56:59], v[190:193], v[156:159], v[56:59]
	v_mfma_f32_16x16x32_bf16 v[24:27], v[202:205], v[156:159], v[24:27]
	v_mfma_f32_16x16x32_bf16 v[52:55], v[190:193], v[174:177], v[52:55]
	v_mfma_f32_16x16x32_bf16 v[20:23], v[202:205], v[174:177], v[20:23]
	v_mfma_f32_16x16x32_bf16 v[48:51], v[190:193], v[182:185], v[48:51]
	v_mfma_f32_16x16x32_bf16 v[16:19], v[202:205], v[182:185], v[16:19]
	s_mov_b32 m0, s33
	v_lshl_add_u64 v[212:213], s[10:11], 0, v[164:165]
	s_barrier
	ds_read_b128 v[144:147], v200 offset:16384
	ds_read_b128 v[148:151], v200 offset:17408
	ds_read_b128 v[152:155], v200 offset:18432
	ds_read_b128 v[156:159], v200 offset:19456
	ds_read_b128 v[160:163], v200 offset:20480
	ds_read_b128 v[174:177], v200 offset:21504
	ds_read_b128 v[178:181], v200 offset:22528
	ds_read_b128 v[182:185], v200 offset:23552
	global_load_lds_dwordx4 v[212:213], off
	v_lshl_add_u64 v[214:215], s[10:11], 0, v[166:167]
	s_mov_b32 m0, s42
	s_nop 0
	global_load_lds_dwordx4 v[214:215], off
	s_barrier
	s_waitcnt lgkmcnt(0)
	v_mfma_f32_16x16x32_bf16 v[108:111], v[128:131], v[144:147], v[108:111]
	v_mfma_f32_16x16x32_bf16 v[76:79], v[136:139], v[144:147], v[76:79]
	v_mfma_f32_16x16x32_bf16 v[104:107], v[128:131], v[152:155], v[104:107]
	v_mfma_f32_16x16x32_bf16 v[72:75], v[136:139], v[152:155], v[72:75]
	v_mfma_f32_16x16x32_bf16 v[100:103], v[128:131], v[160:163], v[100:103]
	v_mfma_f32_16x16x32_bf16 v[68:71], v[136:139], v[160:163], v[68:71]
	v_mfma_f32_16x16x32_bf16 v[96:99], v[128:131], v[178:181], v[96:99]
	v_mfma_f32_16x16x32_bf16 v[64:67], v[136:139], v[178:181], v[64:67]
	v_mfma_f32_16x16x32_bf16 v[108:111], v[132:135], v[148:151], v[108:111]
	v_mfma_f32_16x16x32_bf16 v[76:79], v[140:143], v[148:151], v[76:79]
	v_mfma_f32_16x16x32_bf16 v[104:107], v[132:135], v[156:159], v[104:107]
	v_mfma_f32_16x16x32_bf16 v[72:75], v[140:143], v[156:159], v[72:75]
	v_mfma_f32_16x16x32_bf16 v[100:103], v[132:135], v[174:177], v[100:103]
	v_mfma_f32_16x16x32_bf16 v[68:71], v[140:143], v[174:177], v[68:71]
	v_mfma_f32_16x16x32_bf16 v[96:99], v[132:135], v[182:185], v[96:99]
	v_mfma_f32_16x16x32_bf16 v[64:67], v[140:143], v[182:185], v[64:67]
	s_barrier
	s_add_u32 s4, s8, 0x160000
	s_addc_u32 s5, s9, 0
	s_mov_b32 m0, s58
	v_lshl_add_u64 v[128:129], s[4:5], 0, v[164:165]
	global_load_lds_dwordx4 v[128:129], off
	v_lshl_add_u64 v[128:129], s[4:5], 0, v[166:167]
	s_mov_b32 m0, s59
	s_nop 0
	global_load_lds_dwordx4 v[128:129], off
	s_waitcnt vmcnt(6)
	s_barrier
; #define WAIT_V(n) asm volatile("s_waitcnt vmcnt(" #n ")" ::: "memory")
; #define WAIT_L(n) asm volatile("s_waitcnt lgkmcnt(" #n ")" ::: "memory")
; #define BAR __builtin_amdgcn_s_barrier()
; #define SCHED __builtin_amdgcn_sched_barrier(0)
; template <class Get, class Epi>
; DI void gemm_stream(LAS unsigned char* lds, const int K, const int ld, Get get, Epi epi) {
;     ...
;             WAIT_V(6); BAR; MMA(1, 1, At, B1); BAR;
;             LDB(B0, 1, 0); SCHED; LDA(At, 1, 0); STAGE(SAo(0, 1), a2 + hstep);
;             WAIT_L(8); BAR; WAIT_L(0); MMA(0, 0, At, B0); BAR; SCHED;
;             LDB(B1, 1, 1); STAGE(SBo(1, 0), b3);
;             BAR; WAIT_L(0); MMA(0, 1, At, B1); BAR;
;             LDA(At, 1, 1); STAGE(SAo(1, 0), a3);
;             BAR; WAIT_L(0); MMA(1, 0, At, B0); BAR; SCHED;
;             STAGE(SBo(1, 1), b3 + hstep);
;             WAIT_V(6); BAR; MMA(1, 1, At, B1); BAR;
	v_mfma_f32_16x16x32_bf16 v[44:47], v[186:189], v[144:147], v[44:47]
	v_mfma_f32_16x16x32_bf16 v[12:15], v[194:197], v[144:147], v[12:15]
	v_mfma_f32_16x16x32_bf16 v[40:43], v[186:189], v[152:155], v[40:43]
	v_mfma_f32_16x16x32_bf16 v[8:11], v[194:197], v[152:155], v[8:11]
	v_mfma_f32_16x16x32_bf16 v[36:39], v[186:189], v[160:163], v[36:39]
	v_mfma_f32_16x16x32_bf16 v[4:7], v[194:197], v[160:163], v[4:7]
	v_mfma_f32_16x16x32_bf16 v[32:35], v[186:189], v[178:181], v[32:35]
	v_mfma_f32_16x16x32_bf16 v[0:3], v[194:197], v[178:181], v[0:3]
	v_mfma_f32_16x16x32_bf16 v[44:47], v[190:193], v[148:151], v[44:47]
	v_mfma_f32_16x16x32_bf16 v[12:15], v[202:205], v[148:151], v[12:15]
	v_mfma_f32_16x16x32_bf16 v[40:43], v[190:193], v[156:159], v[40:43]
	v_mfma_f32_16x16x32_bf16 v[8:11], v[202:205], v[156:159], v[8:11]
	v_mfma_f32_16x16x32_bf16 v[36:39], v[190:193], v[174:177], v[36:39]
	v_mfma_f32_16x16x32_bf16 v[4:7], v[202:205], v[174:177], v[4:7]
	v_mfma_f32_16x16x32_bf16 v[32:35], v[190:193], v[182:185], v[32:35]
	v_mfma_f32_16x16x32_bf16 v[0:3], v[202:205], v[182:185], v[0:3]
	s_add_i32 s17, 16, 0x18000
	v_add_u32_e32 v140, s17, v198
	s_barrier
	ds_read_b128 v[128:131], v140
	ds_read_b128 v[132:135], v140 offset:1024
	ds_read_b128 v[136:139], v140 offset:2048
	ds_read_b128 v[140:143], v140 offset:3072
	s_add_u32 s4, s10, 0x160000
	s_addc_u32 s5, s11, 0
	s_mov_b32 m0, s43
	v_lshl_add_u64 v[186:187], s[4:5], 0, v[164:165]
	ds_read_b128 v[144:147], v200 offset:32768
	ds_read_b128 v[148:151], v200 offset:33792
	ds_read_b128 v[152:155], v200 offset:34816
	ds_read_b128 v[156:159], v200 offset:35840
	ds_read_b128 v[160:163], v200 offset:36864
	ds_read_b128 v[174:177], v200 offset:37888
	ds_read_b128 v[178:181], v200 offset:38912
	ds_read_b128 v[182:185], v200 offset:39936
	global_load_lds_dwordx4 v[186:187], off
	v_lshl_add_u64 v[186:187], s[4:5], 0, v[166:167]
	s_mov_b32 m0, s44
	s_nop 0
	global_load_lds_dwordx4 v[186:187], off
	s_waitcnt lgkmcnt(8)
	s_barrier
	s_waitcnt lgkmcnt(0)
	v_mfma_f32_16x16x32_bf16 v[124:127], v[128:131], v[144:147], v[124:127]
	v_mfma_f32_16x16x32_bf16 v[92:95], v[136:139], v[144:147], v[92:95]
	v_mfma_f32_16x16x32_bf16 v[120:123], v[128:131], v[152:155], v[120:123]
	v_mfma_f32_16x16x32_bf16 v[88:91], v[136:139], v[152:155], v[88:91]
	v_mfma_f32_16x16x32_bf16 v[116:119], v[128:131], v[160:163], v[116:119]
	v_mfma_f32_16x16x32_bf16 v[84:87], v[136:139], v[160:163], v[84:87]
	v_mfma_f32_16x16x32_bf16 v[112:115], v[128:131], v[178:181], v[112:115]
	v_mfma_f32_16x16x32_bf16 v[80:83], v[136:139], v[178:181], v[80:83]
	v_mfma_f32_16x16x32_bf16 v[124:127], v[132:135], v[148:151], v[124:127]
	v_mfma_f32_16x16x32_bf16 v[92:95], v[140:143], v[148:151], v[92:95]
	v_mfma_f32_16x16x32_bf16 v[120:123], v[132:135], v[156:159], v[120:123]
	v_mfma_f32_16x16x32_bf16 v[88:91], v[140:143], v[156:159], v[88:91]
	v_mfma_f32_16x16x32_bf16 v[116:119], v[132:135], v[174:177], v[116:119]
	v_mfma_f32_16x16x32_bf16 v[84:87], v[140:143], v[174:177], v[84:87]
	v_mfma_f32_16x16x32_bf16 v[112:115], v[132:135], v[182:185], v[112:115]
	v_mfma_f32_16x16x32_bf16 v[80:83], v[140:143], v[182:185], v[80:83]
	s_barrier
	s_add_i32 s10, 16, 0x1c000
	s_add_i32 s4, s17, s21
	v_add_u32_e32 v202, s10, v198
	v_lshl_add_u64 v[208:209], v[208:209], 0, s[0:1]
	s_mov_b32 m0, s4
	ds_read_b128 v[186:189], v202
	ds_read_b128 v[190:193], v202 offset:1024
	ds_read_b128 v[194:197], v202 offset:2048
	ds_read_b128 v[202:205], v202 offset:3072
	global_load_lds_dwordx4 v[208:209], off
	v_lshl_add_u64 v[208:209], v[210:211], 0, s[0:1]
	s_add_i32 m0, s4, 0x2000
	s_nop 0
	global_load_lds_dwordx4 v[208:209], off
	s_barrier
	s_waitcnt lgkmcnt(0)
	v_mfma_f32_16x16x32_bf16 v[60:63], v[186:189], v[144:147], v[60:63]
	v_mfma_f32_16x16x32_bf16 v[28:31], v[194:197], v[144:147], v[28:31]
	v_mfma_f32_16x16x32_bf16 v[56:59], v[186:189], v[152:155], v[56:59]
	v_mfma_f32_16x16x32_bf16 v[24:27], v[194:197], v[152:155], v[24:27]
	v_mfma_f32_16x16x32_bf16 v[52:55], v[186:189], v[160:163], v[52:55]
	v_mfma_f32_16x16x32_bf16 v[20:23], v[194:197], v[160:163], v[20:23]
	v_mfma_f32_16x16x32_bf16 v[48:51], v[186:189], v[178:181], v[48:51]
	v_mfma_f32_16x16x32_bf16 v[16:19], v[194:197], v[178:181], v[16:19]
	v_mfma_f32_16x16x32_bf16 v[60:63], v[190:193], v[148:151], v[60:63]
	v_mfma_f32_16x16x32_bf16 v[28:31], v[202:205], v[148:151], v[28:31]
	v_mfma_f32_16x16x32_bf16 v[56:59], v[190:193], v[156:159], v[56:59]
	v_mfma_f32_16x16x32_bf16 v[24:27], v[202:205], v[156:159], v[24:27]
	v_mfma_f32_16x16x32_bf16 v[52:55], v[190:193], v[174:177], v[52:55]
	v_mfma_f32_16x16x32_bf16 v[20:23], v[202:205], v[174:177], v[20:23]
	v_mfma_f32_16x16x32_bf16 v[48:51], v[190:193], v[182:185], v[48:51]
	v_mfma_f32_16x16x32_bf16 v[16:19], v[202:205], v[182:185], v[16:19]
	s_mov_b32 m0, s45
	v_lshl_add_u64 v[208:209], v[212:213], 0, s[0:1]
	s_barrier
	ds_read_b128 v[144:147], v200 offset:49152
	ds_read_b128 v[148:151], v200 offset:50176
	ds_read_b128 v[152:155], v200 offset:51200
	ds_read_b128 v[156:159], v200 offset:52224
	ds_read_b128 v[160:163], v200 offset:53248
	ds_read_b128 v[174:177], v200 offset:54272
	ds_read_b128 v[178:181], v200 offset:55296
	ds_read_b128 v[182:185], v200 offset:56320
	global_load_lds_dwordx4 v[208:209], off
	v_lshl_add_u64 v[208:209], v[214:215], 0, s[0:1]
	s_mov_b32 m0, s46
	s_nop 0
	global_load_lds_dwordx4 v[208:209], off
	s_barrier
; #define WAIT_V(n) asm volatile("s_waitcnt vmcnt(" #n ")" ::: "memory")
; #define WAIT_L(n) asm volatile("s_waitcnt lgkmcnt(" #n ")" ::: "memory")
; #define BAR __builtin_amdgcn_s_barrier()
; #define SCHED __builtin_amdgcn_sched_barrier(0)
; template <class Get, class Epi>
; DI void gemm_stream(LAS unsigned char* lds, const int K, const int ld, Get get, Epi epi) {
;     ...
;             BAR; WAIT_L(0); MMA(1, 0, At, B0); BAR; SCHED;
;             STAGE(SBo(1, 1), b3 + hstep);
;             WAIT_V(6); BAR; MMA(1, 1, At, B1); BAR;
;         }
;         epi(acc, cur);
; DI void epi_resid(const Acc& acc, const P& p, int brow, int bcol, int layer, int gch, bool from_input) {
;     ...
;     const float* gate = modv(p, layer, brow, gch);
; #pragma unroll
;     for (int bj = 0; bj < 2; ++bj)
; #pragma unroll
;         for (int n = 0; n < 2; ++n) {
;             const int c0 = bcol + bj * 128 + wc * 32 + n * 16 + fq * 4;
;             const f32x4 g = *(const f32x4*)(gate + c0);
;             f32x4 xv[2][4];
; #pragma unroll
;             for (int ai = 0; ai < 2; ++ai)
; #pragma unroll
;                 for (int m = 0; m < 4; ++m) {
;                     const int r = brow + ai * 128 + wr * 64 + m * 16 + fr;
;                     const float* sp = (from_input ? inrow(p, r) : xrow(p, r)) + c0;
;                     xv[ai][m] = *(const f32x4*)sp;
;                 }
	s_waitcnt lgkmcnt(0)
	v_mfma_f32_16x16x32_bf16 v[108:111], v[128:131], v[144:147], v[108:111]
	v_mfma_f32_16x16x32_bf16 v[76:79], v[136:139], v[144:147], v[76:79]
	v_mfma_f32_16x16x32_bf16 v[104:107], v[128:131], v[152:155], v[104:107]
	v_mfma_f32_16x16x32_bf16 v[72:75], v[136:139], v[152:155], v[72:75]
	v_mfma_f32_16x16x32_bf16 v[100:103], v[128:131], v[160:163], v[100:103]
	v_mfma_f32_16x16x32_bf16 v[68:71], v[136:139], v[160:163], v[68:71]
	v_mfma_f32_16x16x32_bf16 v[96:99], v[128:131], v[178:181], v[96:99]
	v_mfma_f32_16x16x32_bf16 v[64:67], v[136:139], v[178:181], v[64:67]
	v_mfma_f32_16x16x32_bf16 v[108:111], v[132:135], v[148:151], v[108:111]
	v_mfma_f32_16x16x32_bf16 v[76:79], v[140:143], v[148:151], v[76:79]
	v_mfma_f32_16x16x32_bf16 v[104:107], v[132:135], v[156:159], v[104:107]
	v_mfma_f32_16x16x32_bf16 v[72:75], v[140:143], v[156:159], v[72:75]
	v_mfma_f32_16x16x32_bf16 v[100:103], v[132:135], v[174:177], v[100:103]
	v_mfma_f32_16x16x32_bf16 v[68:71], v[140:143], v[174:177], v[68:71]
	v_mfma_f32_16x16x32_bf16 v[96:99], v[132:135], v[182:185], v[96:99]
	v_mfma_f32_16x16x32_bf16 v[64:67], v[140:143], v[182:185], v[64:67]
	s_barrier
	s_add_u32 s4, s8, 0x160080
	s_addc_u32 s5, s9, 0
	s_add_i32 s8, s10, s21
	v_lshl_add_u64 v[128:129], s[4:5], 0, v[164:165]
	s_mov_b32 m0, s8
	s_nop 0
	global_load_lds_dwordx4 v[128:129], off
	v_lshl_add_u64 v[128:129], s[4:5], 0, v[166:167]
	s_add_i32 m0, s8, 0x2000
	s_nop 0
	global_load_lds_dwordx4 v[128:129], off
	s_waitcnt vmcnt(6)
	s_barrier
	v_mfma_f32_16x16x32_bf16 v[44:47], v[186:189], v[144:147], v[44:47]
	v_mfma_f32_16x16x32_bf16 v[12:15], v[194:197], v[144:147], v[12:15]
	v_mfma_f32_16x16x32_bf16 v[40:43], v[186:189], v[152:155], v[40:43]
	v_mfma_f32_16x16x32_bf16 v[8:11], v[194:197], v[152:155], v[8:11]
	v_mfma_f32_16x16x32_bf16 v[36:39], v[186:189], v[160:163], v[36:39]
	v_mfma_f32_16x16x32_bf16 v[4:7], v[194:197], v[160:163], v[4:7]
	v_mfma_f32_16x16x32_bf16 v[32:35], v[186:189], v[178:181], v[32:35]
	v_mfma_f32_16x16x32_bf16 v[0:3], v[194:197], v[178:181], v[0:3]
	v_mfma_f32_16x16x32_bf16 v[44:47], v[190:193], v[148:151], v[44:47]
	v_mfma_f32_16x16x32_bf16 v[12:15], v[202:205], v[148:151], v[12:15]
	v_mfma_f32_16x16x32_bf16 v[40:43], v[190:193], v[156:159], v[40:43]
	v_mfma_f32_16x16x32_bf16 v[8:11], v[202:205], v[156:159], v[8:11]
	v_mfma_f32_16x16x32_bf16 v[36:39], v[190:193], v[174:177], v[36:39]
	v_mfma_f32_16x16x32_bf16 v[4:7], v[202:205], v[174:177], v[4:7]
	v_mfma_f32_16x16x32_bf16 v[32:35], v[190:193], v[182:185], v[32:35]
	v_mfma_f32_16x16x32_bf16 v[0:3], v[202:205], v[182:185], v[0:3]
	s_add_i32 s16, s16, 2
	s_add_u32 s14, s14, 0x100
	s_addc_u32 s15, s15, 0
	s_cmpk_gt_u32 s16, 0x55
	s_mov_b64 s[4:5], s[6:7]
	s_barrier
	s_cbranch_scc0 .LBB0_3113
	s_lshr_b32 s4, s13, 4
	s_lshl_b32 s5, s13, 8
	s_mulk_i32 s4, 0x1100
	s_and_b32 s5, s5, 0xf00
	s_add_i32 s4, s4, s5
	s_add_i32 s6, s4, 0x100
	s_mul_hi_i32 s4, s6, 0x78787879
	s_lshr_b32 s5, s4, 31
	s_ashr_i32 s4, s4, 11
	s_add_i32 s4, s4, s5
	s_mul_i32 s5, s4, 0xffffef00
	s_mul_i32 s4, s4, 6
	s_lshl_b32 s7, s12, 8
	s_add_i32 s5, s5, s6
	s_add_i32 s4, s4, 35
	s_cmpk_gt_i32 s5, 0xff
	v_mov_b32_e32 v132, v206
	s_cselect_b32 s4, s4, 59
	s_ashr_i32 s5, s4, 31
	v_lshrrev_b32_e32 v128, 1, v132
	v_lshrrev_b32_e32 v129, 2, v132
	s_lshl_b64 s[4:5], s[4:5], 13
	v_and_b32_e32 v128, 0x60, v128
	v_and_b32_e32 v129, 12, v129
	s_add_u32 s4, s26, s4
	v_or3_b32 v174, v128, s7, v129
	s_addc_u32 s5, s27, s5
	v_ashrrev_i32_e32 v175, 31, v174
	v_lshl_add_u64 v[192:193], v[174:175], 2, s[4:5]
	global_load_dwordx4 v[128:131], v[192:193], off
	v_ashrrev_i32_e32 v133, 2, v132
	v_and_b32_e32 v133, 0xffffffc0, v133
	v_and_or_b32 v132, v132, 15, s6
	v_add_u32_e32 v176, v132, v133
	v_mul_hi_i32 v132, v176, s48
	v_lshrrev_b32_e32 v133, 31, v132
	v_ashrrev_i32_e32 v132, 11, v132
	v_add_u32_e32 v203, v132, v133
	v_mad_i32_i24 v202, v203, s49, v176
	v_lshlrev_b32_e32 v212, 12, v203
	v_cmp_lt_i32_e64 s[16:17], s52, v202
	v_add3_u32 v190, v212, v202, s53
	s_and_saveexec_b64 s[4:5], s[16:17]
	s_xor_b64 s[4:5], exec, s[4:5]
	v_add3_u32 v132, v212, v202, s53
	s_or_saveexec_b64 s[4:5], s[4:5]
	v_mov_b64_e32 v[134:135], s[24:25]
	v_lshl_add_u32 v191, v203, 8, v202
	s_xor_b64 exec, exec, s[4:5]
	v_lshl_add_u32 v132, v203, 8, v202
	v_mov_b64_e32 v[134:135], s[18:19]
	s_or_b64 exec, exec, s[4:5]
	v_ashrrev_i32_e32 v133, 31, v132
	v_lshlrev_b64 v[132:133], 13, v[132:133]
	v_lshl_add_u64 v[132:133], v[134:135], 0, v[132:133]
	v_lshl_add_u64 v[132:133], v[174:175], 2, v[132:133]
	global_load_dwordx4 v[160:163], v[132:133], off
	v_or_b32_e32 v132, 16, v176
	v_mul_hi_i32 v133, v132, s48
	v_lshrrev_b32_e32 v134, 31, v133
	v_ashrrev_i32_e32 v133, 11, v133
	v_add_u32_e32 v205, v133, v134
	v_mad_i32_i24 v204, v205, s49, v132
	v_lshlrev_b32_e32 v217, 12, v205
	v_cmp_lt_i32_e64 s[14:15], s52, v204
	v_add3_u32 v188, v217, v204, s53
	s_and_saveexec_b64 s[4:5], s[14:15]
	s_xor_b64 s[4:5], exec, s[4:5]
	v_add3_u32 v132, v217, v204, s53
	s_or_saveexec_b64 s[4:5], s[4:5]
	v_mov_b64_e32 v[134:135], s[24:25]
	v_lshl_add_u32 v189, v205, 8, v204
	s_xor_b64 exec, exec, s[4:5]
	v_lshl_add_u32 v132, v205, 8, v204
	v_mov_b64_e32 v[134:135], s[18:19]
	s_or_b64 exec, exec, s[4:5]
	v_ashrrev_i32_e32 v133, 31, v132
	v_lshlrev_b64 v[132:133], 13, v[132:133]
	v_lshl_add_u64 v[132:133], v[134:135], 0, v[132:133]
	v_lshl_add_u64 v[132:133], v[174:175], 2, v[132:133]
	global_load_dwordx4 v[156:159], v[132:133], off
	v_or_b32_e32 v132, 32, v176
	v_mul_hi_i32 v133, v132, s48
	v_lshrrev_b32_e32 v134, 31, v133
	v_ashrrev_i32_e32 v133, 11, v133
	v_add_u32_e32 v209, v133, v134
	v_mad_i32_i24 v208, v209, s49, v132
; DI void epi_resid(const Acc& acc, const P& p, int brow, int bcol, int layer, int gch, bool from_input) {
;     ...
;             for (int ai = 0; ai < 2; ++ai)
; #pragma unroll
;                 for (int m = 0; m < 4; ++m) {
;                     const int r = brow + ai * 128 + wr * 64 + m * 16 + fr;
;                     const float* sp = (from_input ? inrow(p, r) : xrow(p, r)) + c0;
;                     xv[ai][m] = *(const f32x4*)sp;
;                 }
	v_lshlrev_b32_e32 v220, 12, v209
	v_cmp_lt_i32_e64 s[12:13], s52, v208
	v_add3_u32 v186, v220, v208, s53
	s_and_saveexec_b64 s[4:5], s[12:13]
	s_xor_b64 s[4:5], exec, s[4:5]
	v_add3_u32 v132, v220, v208, s53
	s_or_saveexec_b64 s[4:5], s[4:5]
	v_mov_b64_e32 v[134:135], s[24:25]
	v_lshl_add_u32 v187, v209, 8, v208
	s_xor_b64 exec, exec, s[4:5]
	v_lshl_add_u32 v132, v209, 8, v208
	v_mov_b64_e32 v[134:135], s[18:19]
	s_or_b64 exec, exec, s[4:5]
	v_ashrrev_i32_e32 v133, 31, v132
	v_lshlrev_b64 v[132:133], 13, v[132:133]
	v_lshl_add_u64 v[132:133], v[134:135], 0, v[132:133]
	v_lshl_add_u64 v[132:133], v[174:175], 2, v[132:133]
	global_load_dwordx4 v[152:155], v[132:133], off
	v_or_b32_e32 v132, 48, v176
	v_mul_hi_i32 v133, v132, s48
	v_lshrrev_b32_e32 v134, 31, v133
	v_ashrrev_i32_e32 v133, 11, v133
	v_add_u32_e32 v211, v133, v134
	v_mad_i32_i24 v210, v211, s49, v132
	v_lshlrev_b32_e32 v223, 12, v211
	v_cmp_lt_i32_e64 s[10:11], s52, v210
	v_add3_u32 v184, v223, v210, s53
	s_and_saveexec_b64 s[4:5], s[10:11]
	s_xor_b64 s[4:5], exec, s[4:5]
	v_add3_u32 v132, v223, v210, s53
	s_or_saveexec_b64 s[4:5], s[4:5]
	v_mov_b64_e32 v[134:135], s[24:25]
	v_lshl_add_u32 v185, v211, 8, v210
	s_xor_b64 exec, exec, s[4:5]
	v_lshl_add_u32 v132, v211, 8, v210
	v_mov_b64_e32 v[134:135], s[18:19]
	s_or_b64 exec, exec, s[4:5]
	v_ashrrev_i32_e32 v133, 31, v132
	v_lshlrev_b64 v[132:133], 13, v[132:133]
	v_lshl_add_u64 v[132:133], v[134:135], 0, v[132:133]
	v_lshl_add_u64 v[132:133], v[174:175], 2, v[132:133]
	global_load_dwordx4 v[148:151], v[132:133], off
	v_add_u32_e32 v132, 0x80, v176
	v_mul_hi_i32 v133, v132, s48
	v_lshrrev_b32_e32 v134, 31, v133
	v_ashrrev_i32_e32 v133, 11, v133
	v_add_u32_e32 v214, v133, v134
	v_mad_i32_i24 v213, v214, s49, v132
	v_lshlrev_b32_e32 v224, 12, v214
	v_cmp_lt_i32_e64 s[8:9], s52, v213
	v_add3_u32 v182, v224, v213, s53
	s_and_saveexec_b64 s[4:5], s[8:9]
	s_xor_b64 s[4:5], exec, s[4:5]
	v_add3_u32 v132, v224, v213, s53
	s_or_saveexec_b64 s[4:5], s[4:5]
	v_mov_b64_e32 v[134:135], s[24:25]
	v_lshl_add_u32 v183, v214, 8, v213
	s_xor_b64 exec, exec, s[4:5]
	v_lshl_add_u32 v132, v214, 8, v213
	v_mov_b64_e32 v[134:135], s[18:19]
	s_or_b64 exec, exec, s[4:5]
	v_ashrrev_i32_e32 v133, 31, v132
	v_lshlrev_b64 v[132:133], 13, v[132:133]
	v_lshl_add_u64 v[132:133], v[134:135], 0, v[132:133]
	v_lshl_add_u64 v[132:133], v[174:175], 2, v[132:133]
	global_load_dwordx4 v[144:147], v[132:133], off
	v_add_u32_e32 v132, 0x90, v176
	v_mul_hi_i32 v133, v132, s48
	v_lshrrev_b32_e32 v134, 31, v133
	v_ashrrev_i32_e32 v133, 11, v133
	v_add_u32_e32 v216, v133, v134
	v_mad_i32_i24 v215, v216, s49, v132
	v_lshlrev_b32_e32 v225, 12, v216
	v_cmp_lt_i32_e64 s[6:7], s52, v215
	v_add3_u32 v180, v225, v215, s53
	s_and_saveexec_b64 s[4:5], s[6:7]
	s_xor_b64 s[4:5], exec, s[4:5]
	v_add3_u32 v132, v225, v215, s53
	s_or_saveexec_b64 s[4:5], s[4:5]
	v_mov_b64_e32 v[134:135], s[24:25]
	v_lshl_add_u32 v181, v216, 8, v215
	s_xor_b64 exec, exec, s[4:5]
	v_lshl_add_u32 v132, v216, 8, v215
	v_mov_b64_e32 v[134:135], s[18:19]
	s_or_b64 exec, exec, s[4:5]
	v_ashrrev_i32_e32 v133, 31, v132
	v_lshlrev_b64 v[132:133], 13, v[132:133]
	v_lshl_add_u64 v[132:133], v[134:135], 0, v[132:133]
	v_lshl_add_u64 v[132:133], v[174:175], 2, v[132:133]
	global_load_dwordx4 v[140:143], v[132:133], off
	v_add_u32_e32 v132, 0xa0, v176
	v_mul_hi_i32 v133, v132, s48
	v_lshrrev_b32_e32 v134, 31, v133
	v_ashrrev_i32_e32 v133, 11, v133
	v_add_u32_e32 v219, v133, v134
	v_mad_i32_i24 v218, v219, s49, v132
	v_lshlrev_b32_e32 v226, 12, v219
	v_cmp_lt_i32_e64 s[4:5], s52, v218
	v_add3_u32 v178, v226, v218, s53
	s_and_saveexec_b64 s[28:29], s[4:5]
	s_xor_b64 s[40:41], exec, s[28:29]
	v_add3_u32 v132, v226, v218, s53
	s_or_saveexec_b64 s[40:41], s[40:41]
	v_mov_b64_e32 v[134:135], s[24:25]
	v_lshl_add_u32 v179, v219, 8, v218
	s_xor_b64 exec, exec, s[40:41]
	v_lshl_add_u32 v132, v219, 8, v218
	v_mov_b64_e32 v[134:135], s[18:19]
	s_or_b64 exec, exec, s[40:41]
	v_ashrrev_i32_e32 v133, 31, v132
	v_lshlrev_b64 v[132:133], 13, v[132:133]
	v_lshl_add_u64 v[132:133], v[134:135], 0, v[132:133]
	v_lshl_add_u64 v[132:133], v[174:175], 2, v[132:133]
	global_load_dwordx4 v[136:139], v[132:133], off
	v_add_u32_e32 v132, 0xb0, v176
	v_mul_hi_i32 v133, v132, s48
	v_lshrrev_b32_e32 v134, 31, v133
	v_ashrrev_i32_e32 v133, 11, v133
	v_add_u32_e32 v222, v133, v134
	v_mad_i32_i24 v221, v222, s49, v132
	v_lshlrev_b32_e32 v227, 12, v222
	v_cmp_lt_i32_e32 vcc, s52, v221
	v_add3_u32 v176, v227, v221, s53
	s_and_saveexec_b64 s[28:29], vcc
	s_xor_b64 s[40:41], exec, s[28:29]
	v_add3_u32 v132, v227, v221, s53
	s_or_saveexec_b64 s[40:41], s[40:41]
	v_mov_b64_e32 v[134:135], s[24:25]
	v_lshl_add_u32 v177, v222, 8, v221
	s_xor_b64 exec, exec, s[40:41]
	v_lshl_add_u32 v132, v222, 8, v221
	v_mov_b64_e32 v[134:135], s[18:19]
	s_or_b64 exec, exec, s[40:41]
	v_ashrrev_i32_e32 v133, 31, v132
	v_lshlrev_b64 v[132:133], 13, v[132:133]
	v_lshl_add_u64 v[132:133], v[134:135], 0, v[132:133]
	v_lshl_add_u64 v[132:133], v[174:175], 2, v[132:133]
	global_load_dwordx4 v[132:135], v[132:133], off
	s_and_saveexec_b64 s[28:29], s[16:17]
	s_xor_b64 s[40:41], exec, s[28:29]
	v_add3_u32 v194, v212, v202, s53
	s_or_saveexec_b64 s[40:41], s[40:41]
	v_mov_b64_e32 v[196:197], s[24:25]
	s_xor_b64 exec, exec, s[40:41]
	v_lshl_add_u32 v194, v203, 8, v202
	v_mov_b64_e32 v[196:197], s[18:19]
	s_or_b64 exec, exec, s[40:41]
	v_ashrrev_i32_e32 v195, 31, v194
	s_waitcnt vmcnt(0)
; DI void epi_resid(const Acc& acc, const P& p, int brow, int bcol, int layer, int gch, bool from_input) {
;     ...
; #pragma unroll
;             for (int ai = 0; ai < 2; ++ai)
; #pragma unroll
;                 for (int m = 0; m < 4; ++m) {
;                     const int r = brow + ai * 128 + wr * 64 + m * 16 + fr;
;                     *(f32x4*)(xrow(p, r) + c0) = xv[ai][m] + g * acc[ai][bj][m][n];
;                 }
;             __builtin_amdgcn_sched_barrier(0);
	v_pk_fma_f32 v[124:125], v[124:125], v[128:129], v[160:161]
	v_lshlrev_b64 v[160:161], 13, v[194:195]
	v_lshl_add_u64 v[160:161], v[196:197], 0, v[160:161]
	v_pk_fma_f32 v[126:127], v[126:127], v[130:131], v[162:163]
	v_lshl_add_u64 v[160:161], v[174:175], 2, v[160:161]
	global_store_dwordx4 v[160:161], v[124:127], off
	s_and_saveexec_b64 s[28:29], s[14:15]
	s_xor_b64 s[40:41], exec, s[28:29]
	v_add3_u32 v124, v217, v204, s53
	s_or_saveexec_b64 s[40:41], s[40:41]
	v_mov_b64_e32 v[126:127], s[24:25]
	s_xor_b64 exec, exec, s[40:41]
	v_lshl_add_u32 v124, v205, 8, v204
	v_mov_b64_e32 v[126:127], s[18:19]
	s_or_b64 exec, exec, s[40:41]
	v_ashrrev_i32_e32 v125, 31, v124
	v_lshlrev_b64 v[124:125], 13, v[124:125]
	v_lshl_add_u64 v[124:125], v[126:127], 0, v[124:125]
	v_pk_fma_f32 v[122:123], v[122:123], v[130:131], v[158:159]
	v_pk_fma_f32 v[120:121], v[120:121], v[128:129], v[156:157]
	v_lshl_add_u64 v[124:125], v[174:175], 2, v[124:125]
	global_store_dwordx4 v[124:125], v[120:123], off
	s_and_saveexec_b64 s[28:29], s[12:13]
	s_xor_b64 s[40:41], exec, s[28:29]
	v_add3_u32 v120, v220, v208, s53
	s_or_saveexec_b64 s[40:41], s[40:41]
	v_mov_b64_e32 v[122:123], s[24:25]
	s_xor_b64 exec, exec, s[40:41]
	v_lshl_add_u32 v120, v209, 8, v208
	v_mov_b64_e32 v[122:123], s[18:19]
	s_or_b64 exec, exec, s[40:41]
	v_ashrrev_i32_e32 v121, 31, v120
	v_lshlrev_b64 v[120:121], 13, v[120:121]
	v_lshl_add_u64 v[120:121], v[122:123], 0, v[120:121]
	v_pk_fma_f32 v[118:119], v[118:119], v[130:131], v[154:155]
	v_pk_fma_f32 v[116:117], v[116:117], v[128:129], v[152:153]
	v_lshl_add_u64 v[120:121], v[174:175], 2, v[120:121]
	global_store_dwordx4 v[120:121], v[116:119], off
	s_and_saveexec_b64 s[28:29], s[10:11]
	s_xor_b64 s[40:41], exec, s[28:29]
	v_add3_u32 v116, v223, v210, s53
	s_or_saveexec_b64 s[40:41], s[40:41]
	v_mov_b64_e32 v[118:119], s[24:25]
	s_xor_b64 exec, exec, s[40:41]
	v_lshl_add_u32 v116, v211, 8, v210
	v_mov_b64_e32 v[118:119], s[18:19]
	s_or_b64 exec, exec, s[40:41]
	v_ashrrev_i32_e32 v117, 31, v116
	v_lshlrev_b64 v[116:117], 13, v[116:117]
	v_lshl_add_u64 v[116:117], v[118:119], 0, v[116:117]
	v_pk_fma_f32 v[114:115], v[114:115], v[130:131], v[150:151]
	v_pk_fma_f32 v[112:113], v[112:113], v[128:129], v[148:149]
	v_lshl_add_u64 v[116:117], v[174:175], 2, v[116:117]
	global_store_dwordx4 v[116:117], v[112:115], off
	s_and_saveexec_b64 s[28:29], s[8:9]
	s_xor_b64 s[40:41], exec, s[28:29]
	v_add3_u32 v112, v224, v213, s53
	s_or_saveexec_b64 s[40:41], s[40:41]
	v_mov_b64_e32 v[114:115], s[24:25]
	s_xor_b64 exec, exec, s[40:41]
	v_lshl_add_u32 v112, v214, 8, v213
	v_mov_b64_e32 v[114:115], s[18:19]
	s_or_b64 exec, exec, s[40:41]
	v_ashrrev_i32_e32 v113, 31, v112
	v_lshlrev_b64 v[112:113], 13, v[112:113]
	v_lshl_add_u64 v[112:113], v[114:115], 0, v[112:113]
	v_pk_fma_f32 v[110:111], v[110:111], v[130:131], v[146:147]
	v_pk_fma_f32 v[108:109], v[108:109], v[128:129], v[144:145]
	v_lshl_add_u64 v[112:113], v[174:175], 2, v[112:113]
	global_store_dwordx4 v[112:113], v[108:111], off
	s_and_saveexec_b64 s[28:29], s[6:7]
	s_xor_b64 s[40:41], exec, s[28:29]
	v_add3_u32 v108, v225, v215, s53
	s_or_saveexec_b64 s[40:41], s[40:41]
	v_mov_b64_e32 v[110:111], s[24:25]
	s_xor_b64 exec, exec, s[40:41]
	v_lshl_add_u32 v108, v216, 8, v215
	v_mov_b64_e32 v[110:111], s[18:19]
	s_or_b64 exec, exec, s[40:41]
	v_ashrrev_i32_e32 v109, 31, v108
	v_lshlrev_b64 v[108:109], 13, v[108:109]
	v_lshl_add_u64 v[108:109], v[110:111], 0, v[108:109]
	v_pk_fma_f32 v[106:107], v[106:107], v[130:131], v[142:143]
	v_pk_fma_f32 v[104:105], v[104:105], v[128:129], v[140:141]
	v_lshl_add_u64 v[108:109], v[174:175], 2, v[108:109]
	global_store_dwordx4 v[108:109], v[104:107], off
	s_and_saveexec_b64 s[28:29], s[4:5]
	s_xor_b64 s[40:41], exec, s[28:29]
	v_add3_u32 v104, v226, v218, s53
	s_or_saveexec_b64 s[40:41], s[40:41]
	v_mov_b64_e32 v[106:107], s[24:25]
	s_xor_b64 exec, exec, s[40:41]
	v_lshl_add_u32 v104, v219, 8, v218
	v_mov_b64_e32 v[106:107], s[18:19]
	s_or_b64 exec, exec, s[40:41]
	v_ashrrev_i32_e32 v105, 31, v104
	v_lshlrev_b64 v[104:105], 13, v[104:105]
	v_lshl_add_u64 v[104:105], v[106:107], 0, v[104:105]
	v_pk_fma_f32 v[102:103], v[102:103], v[130:131], v[138:139]
	v_pk_fma_f32 v[100:101], v[100:101], v[128:129], v[136:137]
	v_lshl_add_u64 v[104:105], v[174:175], 2, v[104:105]
	global_store_dwordx4 v[104:105], v[100:103], off
	s_and_saveexec_b64 s[28:29], vcc
	s_xor_b64 s[40:41], exec, s[28:29]
	v_add3_u32 v100, v227, v221, s53
	s_or_saveexec_b64 s[40:41], s[40:41]
	v_mov_b64_e32 v[102:103], s[24:25]
	s_xor_b64 exec, exec, s[40:41]
	v_lshl_add_u32 v100, v222, 8, v221
	v_mov_b64_e32 v[102:103], s[18:19]
	s_or_b64 exec, exec, s[40:41]
	v_ashrrev_i32_e32 v101, 31, v100
	v_lshlrev_b64 v[100:101], 13, v[100:101]
	v_lshl_add_u64 v[100:101], v[102:103], 0, v[100:101]
	v_pk_fma_f32 v[98:99], v[98:99], v[130:131], v[134:135]
	v_pk_fma_f32 v[96:97], v[96:97], v[128:129], v[132:133]
	v_lshl_add_u64 v[100:101], v[174:175], 2, v[100:101]
	global_store_dwordx4 v[100:101], v[96:99], off
	global_load_dwordx4 v[96:99], v[192:193], off offset:64
	s_and_saveexec_b64 s[28:29], s[16:17]
	s_xor_b64 s[40:41], exec, s[28:29]
	v_add3_u32 v100, v212, v202, s53
	s_or_saveexec_b64 s[40:41], s[40:41]
	v_mov_b64_e32 v[102:103], s[24:25]
	s_xor_b64 exec, exec, s[40:41]
	v_lshl_add_u32 v100, v203, 8, v202
	v_mov_b64_e32 v[102:103], s[18:19]
	s_or_b64 exec, exec, s[40:41]
	v_ashrrev_i32_e32 v101, 31, v100
	v_lshlrev_b64 v[100:101], 13, v[100:101]
	v_lshl_add_u64 v[100:101], v[102:103], 0, v[100:101]
	v_lshl_add_u64 v[100:101], v[174:175], 2, v[100:101]
	global_load_dwordx4 v[128:131], v[100:101], off offset:64
; DI void epi_resid(const Acc& acc, const P& p, int brow, int bcol, int layer, int gch, bool from_input) {
;     ...
;             f32x4 xv[2][4];
; #pragma unroll
;             for (int ai = 0; ai < 2; ++ai)
; #pragma unroll
;                 for (int m = 0; m < 4; ++m) {
;                     const int r = brow + ai * 128 + wr * 64 + m * 16 + fr;
;                     const float* sp = (from_input ? inrow(p, r) : xrow(p, r)) + c0;
;                     xv[ai][m] = *(const f32x4*)sp;
;                 }
	s_and_saveexec_b64 s[28:29], s[14:15]
	s_xor_b64 s[40:41], exec, s[28:29]
	v_add3_u32 v100, v217, v204, s53
	s_or_saveexec_b64 s[40:41], s[40:41]
	v_mov_b64_e32 v[102:103], s[24:25]
	s_xor_b64 exec, exec, s[40:41]
	v_lshl_add_u32 v100, v205, 8, v204
	v_mov_b64_e32 v[102:103], s[18:19]
	s_or_b64 exec, exec, s[40:41]
	v_ashrrev_i32_e32 v101, 31, v100
	v_lshlrev_b64 v[100:101], 13, v[100:101]
	v_lshl_add_u64 v[100:101], v[102:103], 0, v[100:101]
	v_lshl_add_u64 v[100:101], v[174:175], 2, v[100:101]
	global_load_dwordx4 v[124:127], v[100:101], off offset:64
	s_and_saveexec_b64 s[28:29], s[12:13]
	s_xor_b64 s[40:41], exec, s[28:29]
	v_add3_u32 v100, v220, v208, s53
	s_or_saveexec_b64 s[40:41], s[40:41]
	v_mov_b64_e32 v[102:103], s[24:25]
	s_xor_b64 exec, exec, s[40:41]
	v_lshl_add_u32 v100, v209, 8, v208
	v_mov_b64_e32 v[102:103], s[18:19]
	s_or_b64 exec, exec, s[40:41]
	v_ashrrev_i32_e32 v101, 31, v100
	v_lshlrev_b64 v[100:101], 13, v[100:101]
	v_lshl_add_u64 v[100:101], v[102:103], 0, v[100:101]
	v_lshl_add_u64 v[100:101], v[174:175], 2, v[100:101]
	global_load_dwordx4 v[120:123], v[100:101], off offset:64
	s_and_saveexec_b64 s[28:29], s[10:11]
	s_xor_b64 s[40:41], exec, s[28:29]
	v_add3_u32 v100, v223, v210, s53
	s_or_saveexec_b64 s[40:41], s[40:41]
	v_mov_b64_e32 v[102:103], s[24:25]
	s_xor_b64 exec, exec, s[40:41]
	v_lshl_add_u32 v100, v211, 8, v210
	v_mov_b64_e32 v[102:103], s[18:19]
	s_or_b64 exec, exec, s[40:41]
	v_ashrrev_i32_e32 v101, 31, v100
	v_lshlrev_b64 v[100:101], 13, v[100:101]
	v_lshl_add_u64 v[100:101], v[102:103], 0, v[100:101]
	v_lshl_add_u64 v[100:101], v[174:175], 2, v[100:101]
	global_load_dwordx4 v[116:119], v[100:101], off offset:64
	s_and_saveexec_b64 s[28:29], s[8:9]
	s_xor_b64 s[40:41], exec, s[28:29]
	v_add3_u32 v100, v224, v213, s53
	s_or_saveexec_b64 s[40:41], s[40:41]
	v_mov_b64_e32 v[102:103], s[24:25]
	s_xor_b64 exec, exec, s[40:41]
	v_lshl_add_u32 v100, v214, 8, v213
	v_mov_b64_e32 v[102:103], s[18:19]
	s_or_b64 exec, exec, s[40:41]
	v_ashrrev_i32_e32 v101, 31, v100
	v_lshlrev_b64 v[100:101], 13, v[100:101]
	v_lshl_add_u64 v[100:101], v[102:103], 0, v[100:101]
	v_lshl_add_u64 v[100:101], v[174:175], 2, v[100:101]
	global_load_dwordx4 v[112:115], v[100:101], off offset:64
	s_and_saveexec_b64 s[28:29], s[6:7]
	s_xor_b64 s[40:41], exec, s[28:29]
	v_add3_u32 v100, v225, v215, s53
	s_or_saveexec_b64 s[40:41], s[40:41]
	v_mov_b64_e32 v[102:103], s[24:25]
	s_xor_b64 exec, exec, s[40:41]
	v_lshl_add_u32 v100, v216, 8, v215
	v_mov_b64_e32 v[102:103], s[18:19]
	s_or_b64 exec, exec, s[40:41]
	v_ashrrev_i32_e32 v101, 31, v100
	v_lshlrev_b64 v[100:101], 13, v[100:101]
	v_lshl_add_u64 v[100:101], v[102:103], 0, v[100:101]
	v_lshl_add_u64 v[100:101], v[174:175], 2, v[100:101]
	global_load_dwordx4 v[108:111], v[100:101], off offset:64
	s_and_saveexec_b64 s[28:29], s[4:5]
	s_xor_b64 s[40:41], exec, s[28:29]
	v_add3_u32 v100, v226, v218, s53
	s_or_saveexec_b64 s[40:41], s[40:41]
	v_mov_b64_e32 v[102:103], s[24:25]
	s_xor_b64 exec, exec, s[40:41]
	v_lshl_add_u32 v100, v219, 8, v218
	v_mov_b64_e32 v[102:103], s[18:19]
	s_or_b64 exec, exec, s[40:41]
	v_ashrrev_i32_e32 v101, 31, v100
	v_lshlrev_b64 v[100:101], 13, v[100:101]
	v_lshl_add_u64 v[100:101], v[102:103], 0, v[100:101]
	v_lshl_add_u64 v[100:101], v[174:175], 2, v[100:101]
	global_load_dwordx4 v[104:107], v[100:101], off offset:64
	s_and_saveexec_b64 s[28:29], vcc
	s_xor_b64 s[40:41], exec, s[28:29]
	v_add3_u32 v100, v227, v221, s53
	s_or_saveexec_b64 s[40:41], s[40:41]
	v_mov_b64_e32 v[102:103], s[24:25]
	s_xor_b64 exec, exec, s[40:41]
	v_lshl_add_u32 v100, v222, 8, v221
	v_mov_b64_e32 v[102:103], s[18:19]
	s_or_b64 exec, exec, s[40:41]
	v_ashrrev_i32_e32 v101, 31, v100
	v_lshlrev_b64 v[100:101], 13, v[100:101]
	v_lshl_add_u64 v[100:101], v[102:103], 0, v[100:101]
	v_lshl_add_u64 v[100:101], v[174:175], 2, v[100:101]
	global_load_dwordx4 v[100:103], v[100:101], off offset:64
	s_and_saveexec_b64 s[28:29], s[16:17]
	s_xor_b64 s[40:41], exec, s[28:29]
	v_add3_u32 v132, v212, v202, s53
	s_or_saveexec_b64 s[40:41], s[40:41]
	v_mov_b64_e32 v[134:135], s[24:25]
	s_xor_b64 exec, exec, s[40:41]
	v_lshl_add_u32 v132, v203, 8, v202
	v_mov_b64_e32 v[134:135], s[18:19]
	s_or_b64 exec, exec, s[40:41]
	v_ashrrev_i32_e32 v133, 31, v132
	s_waitcnt vmcnt(0)
; DI void epi_resid(const Acc& acc, const P& p, int brow, int bcol, int layer, int gch, bool from_input) {
;     ...
;             const f32x4 g = *(const f32x4*)(gate + c0);
;             f32x4 xv[2][4];
; #pragma unroll
;             for (int ai = 0; ai < 2; ++ai)
; #pragma unroll
;                 for (int m = 0; m < 4; ++m) {
;                     const int r = brow + ai * 128 + wr * 64 + m * 16 + fr;
;                     const float* sp = (from_input ? inrow(p, r) : xrow(p, r)) + c0;
;                     xv[ai][m] = *(const f32x4*)sp;
;                 }
;     ...
; #pragma unroll
;             for (int ai = 0; ai < 2; ++ai)
; #pragma unroll
;                 for (int m = 0; m < 4; ++m) {
;                     const int r = brow + ai * 128 + wr * 64 + m * 16 + fr;
;                     *(f32x4*)(xrow(p, r) + c0) = xv[ai][m] + g * acc[ai][bj][m][n];
;                 }
;             __builtin_amdgcn_sched_barrier(0);
	v_pk_fma_f32 v[92:93], v[92:93], v[96:97], v[128:129]
	v_lshlrev_b64 v[128:129], 13, v[132:133]
	v_lshl_add_u64 v[128:129], v[134:135], 0, v[128:129]
	v_pk_fma_f32 v[94:95], v[94:95], v[98:99], v[130:131]
	v_lshl_add_u64 v[128:129], v[174:175], 2, v[128:129]
	global_store_dwordx4 v[128:129], v[92:95], off offset:64
	s_and_saveexec_b64 s[28:29], s[14:15]
	s_xor_b64 s[40:41], exec, s[28:29]
	v_add3_u32 v92, v217, v204, s53
	s_or_saveexec_b64 s[40:41], s[40:41]
	v_mov_b64_e32 v[94:95], s[24:25]
	s_xor_b64 exec, exec, s[40:41]
	v_lshl_add_u32 v92, v205, 8, v204
	v_mov_b64_e32 v[94:95], s[18:19]
	s_or_b64 exec, exec, s[40:41]
	v_ashrrev_i32_e32 v93, 31, v92
	v_lshlrev_b64 v[92:93], 13, v[92:93]
	v_lshl_add_u64 v[92:93], v[94:95], 0, v[92:93]
	v_pk_fma_f32 v[90:91], v[90:91], v[98:99], v[126:127]
	v_pk_fma_f32 v[88:89], v[88:89], v[96:97], v[124:125]
	v_lshl_add_u64 v[92:93], v[174:175], 2, v[92:93]
	global_store_dwordx4 v[92:93], v[88:91], off offset:64
	s_and_saveexec_b64 s[28:29], s[12:13]
	s_xor_b64 s[40:41], exec, s[28:29]
	v_add3_u32 v88, v220, v208, s53
	s_or_saveexec_b64 s[40:41], s[40:41]
	v_mov_b64_e32 v[90:91], s[24:25]
	s_xor_b64 exec, exec, s[40:41]
	v_lshl_add_u32 v88, v209, 8, v208
	v_mov_b64_e32 v[90:91], s[18:19]
	s_or_b64 exec, exec, s[40:41]
	v_ashrrev_i32_e32 v89, 31, v88
	v_lshlrev_b64 v[88:89], 13, v[88:89]
	v_lshl_add_u64 v[88:89], v[90:91], 0, v[88:89]
	v_pk_fma_f32 v[86:87], v[86:87], v[98:99], v[122:123]
	v_pk_fma_f32 v[84:85], v[84:85], v[96:97], v[120:121]
	v_lshl_add_u64 v[88:89], v[174:175], 2, v[88:89]
	global_store_dwordx4 v[88:89], v[84:87], off offset:64
	s_and_saveexec_b64 s[28:29], s[10:11]
	s_xor_b64 s[40:41], exec, s[28:29]
	v_add3_u32 v84, v223, v210, s53
	s_or_saveexec_b64 s[40:41], s[40:41]
	v_mov_b64_e32 v[86:87], s[24:25]
	s_xor_b64 exec, exec, s[40:41]
	v_lshl_add_u32 v84, v211, 8, v210
	v_mov_b64_e32 v[86:87], s[18:19]
	s_or_b64 exec, exec, s[40:41]
	v_ashrrev_i32_e32 v85, 31, v84
	v_lshlrev_b64 v[84:85], 13, v[84:85]
	v_lshl_add_u64 v[84:85], v[86:87], 0, v[84:85]
	v_pk_fma_f32 v[82:83], v[82:83], v[98:99], v[118:119]
	v_pk_fma_f32 v[80:81], v[80:81], v[96:97], v[116:117]
	v_lshl_add_u64 v[84:85], v[174:175], 2, v[84:85]
	global_store_dwordx4 v[84:85], v[80:83], off offset:64
	s_and_saveexec_b64 s[28:29], s[8:9]
	s_xor_b64 s[40:41], exec, s[28:29]
	v_add3_u32 v80, v224, v213, s53
	s_or_saveexec_b64 s[40:41], s[40:41]
	v_mov_b64_e32 v[82:83], s[24:25]
	s_xor_b64 exec, exec, s[40:41]
	v_lshl_add_u32 v80, v214, 8, v213
	v_mov_b64_e32 v[82:83], s[18:19]
	s_or_b64 exec, exec, s[40:41]
	v_ashrrev_i32_e32 v81, 31, v80
	v_lshlrev_b64 v[80:81], 13, v[80:81]
	v_lshl_add_u64 v[80:81], v[82:83], 0, v[80:81]
	v_pk_fma_f32 v[78:79], v[78:79], v[98:99], v[114:115]
	v_pk_fma_f32 v[76:77], v[76:77], v[96:97], v[112:113]
	v_lshl_add_u64 v[80:81], v[174:175], 2, v[80:81]
	global_store_dwordx4 v[80:81], v[76:79], off offset:64
	s_and_saveexec_b64 s[28:29], s[6:7]
	s_xor_b64 s[40:41], exec, s[28:29]
	v_add3_u32 v76, v225, v215, s53
	s_or_saveexec_b64 s[40:41], s[40:41]
	v_mov_b64_e32 v[78:79], s[24:25]
	s_xor_b64 exec, exec, s[40:41]
	v_lshl_add_u32 v76, v216, 8, v215
	v_mov_b64_e32 v[78:79], s[18:19]
	s_or_b64 exec, exec, s[40:41]
	v_ashrrev_i32_e32 v77, 31, v76
	v_lshlrev_b64 v[76:77], 13, v[76:77]
	v_lshl_add_u64 v[76:77], v[78:79], 0, v[76:77]
	v_pk_fma_f32 v[74:75], v[74:75], v[98:99], v[110:111]
	v_pk_fma_f32 v[72:73], v[72:73], v[96:97], v[108:109]
	v_lshl_add_u64 v[76:77], v[174:175], 2, v[76:77]
	global_store_dwordx4 v[76:77], v[72:75], off offset:64
	s_and_saveexec_b64 s[28:29], s[4:5]
	s_xor_b64 s[40:41], exec, s[28:29]
	v_add3_u32 v72, v226, v218, s53
	s_or_saveexec_b64 s[40:41], s[40:41]
	v_mov_b64_e32 v[74:75], s[24:25]
	s_xor_b64 exec, exec, s[40:41]
	v_lshl_add_u32 v72, v219, 8, v218
	v_mov_b64_e32 v[74:75], s[18:19]
	s_or_b64 exec, exec, s[40:41]
	v_ashrrev_i32_e32 v73, 31, v72
	v_lshlrev_b64 v[72:73], 13, v[72:73]
	v_lshl_add_u64 v[72:73], v[74:75], 0, v[72:73]
	v_pk_fma_f32 v[70:71], v[70:71], v[98:99], v[106:107]
	v_pk_fma_f32 v[68:69], v[68:69], v[96:97], v[104:105]
	v_lshl_add_u64 v[72:73], v[174:175], 2, v[72:73]
	global_store_dwordx4 v[72:73], v[68:71], off offset:64
	s_and_saveexec_b64 s[28:29], vcc
	s_xor_b64 s[40:41], exec, s[28:29]
	v_add3_u32 v68, v227, v221, s53
	s_or_saveexec_b64 s[40:41], s[40:41]
	v_mov_b64_e32 v[70:71], s[24:25]
	s_xor_b64 exec, exec, s[40:41]
	v_lshl_add_u32 v68, v222, 8, v221
	v_mov_b64_e32 v[70:71], s[18:19]
	s_or_b64 exec, exec, s[40:41]
	v_ashrrev_i32_e32 v69, 31, v68
	v_lshlrev_b64 v[68:69], 13, v[68:69]
	v_lshl_add_u64 v[68:69], v[70:71], 0, v[68:69]
	v_pk_fma_f32 v[66:67], v[66:67], v[98:99], v[102:103]
	v_pk_fma_f32 v[64:65], v[64:65], v[96:97], v[100:101]
	v_lshl_add_u64 v[68:69], v[174:175], 2, v[68:69]
	global_store_dwordx4 v[68:69], v[64:67], off offset:64
	global_load_dwordx4 v[64:67], v[192:193], off offset:512
	s_and_saveexec_b64 s[28:29], s[16:17]
	s_xor_b64 s[40:41], exec, s[28:29]
	v_add3_u32 v68, v212, v202, s53
	s_or_saveexec_b64 s[40:41], s[40:41]
	v_mov_b64_e32 v[70:71], s[24:25]
	s_xor_b64 exec, exec, s[40:41]
	v_lshl_add_u32 v68, v203, 8, v202
	v_mov_b64_e32 v[70:71], s[18:19]
	s_or_b64 exec, exec, s[40:41]
	v_ashrrev_i32_e32 v69, 31, v68
	v_lshlrev_b64 v[68:69], 13, v[68:69]
	v_lshl_add_u64 v[68:69], v[70:71], 0, v[68:69]
	v_lshl_add_u64 v[68:69], v[174:175], 2, v[68:69]
	global_load_dwordx4 v[96:99], v[68:69], off offset:512
	s_and_saveexec_b64 s[28:29], s[14:15]
	s_xor_b64 s[40:41], exec, s[28:29]
	v_add3_u32 v68, v217, v204, s53
	s_or_saveexec_b64 s[40:41], s[40:41]
	v_mov_b64_e32 v[70:71], s[24:25]
	s_xor_b64 exec, exec, s[40:41]
; DI void epi_resid(const Acc& acc, const P& p, int brow, int bcol, int layer, int gch, bool from_input) {
;     ...
;             f32x4 xv[2][4];
; #pragma unroll
;             for (int ai = 0; ai < 2; ++ai)
; #pragma unroll
;                 for (int m = 0; m < 4; ++m) {
;                     const int r = brow + ai * 128 + wr * 64 + m * 16 + fr;
;                     const float* sp = (from_input ? inrow(p, r) : xrow(p, r)) + c0;
;                     xv[ai][m] = *(const f32x4*)sp;
;                 }
;             __builtin_amdgcn_sched_barrier(0);
; #pragma unroll
;             for (int ai = 0; ai < 2; ++ai)
; #pragma unroll
;                 for (int m = 0; m < 4; ++m) {
;                     const int r = brow + ai * 128 + wr * 64 + m * 16 + fr;
;                     *(f32x4*)(xrow(p, r) + c0) = xv[ai][m] + g * acc[ai][bj][m][n];
;                 }
;             __builtin_amdgcn_sched_barrier(0);
	v_lshl_add_u32 v68, v205, 8, v204
	v_mov_b64_e32 v[70:71], s[18:19]
	s_or_b64 exec, exec, s[40:41]
	v_ashrrev_i32_e32 v69, 31, v68
	v_lshlrev_b64 v[68:69], 13, v[68:69]
	v_lshl_add_u64 v[68:69], v[70:71], 0, v[68:69]
	v_lshl_add_u64 v[68:69], v[174:175], 2, v[68:69]
	global_load_dwordx4 v[92:95], v[68:69], off offset:512
	s_and_saveexec_b64 s[28:29], s[12:13]
	s_xor_b64 s[40:41], exec, s[28:29]
	v_add3_u32 v68, v220, v208, s53
	s_or_saveexec_b64 s[40:41], s[40:41]
	v_mov_b64_e32 v[70:71], s[24:25]
	s_xor_b64 exec, exec, s[40:41]
	v_lshl_add_u32 v68, v209, 8, v208
	v_mov_b64_e32 v[70:71], s[18:19]
	s_or_b64 exec, exec, s[40:41]
	v_ashrrev_i32_e32 v69, 31, v68
	v_lshlrev_b64 v[68:69], 13, v[68:69]
	v_lshl_add_u64 v[68:69], v[70:71], 0, v[68:69]
	v_lshl_add_u64 v[68:69], v[174:175], 2, v[68:69]
	global_load_dwordx4 v[88:91], v[68:69], off offset:512
	s_and_saveexec_b64 s[28:29], s[10:11]
	s_xor_b64 s[40:41], exec, s[28:29]
	v_add3_u32 v68, v223, v210, s53
	s_or_saveexec_b64 s[40:41], s[40:41]
	v_mov_b64_e32 v[70:71], s[24:25]
	s_xor_b64 exec, exec, s[40:41]
	v_lshl_add_u32 v68, v211, 8, v210
	v_mov_b64_e32 v[70:71], s[18:19]
	s_or_b64 exec, exec, s[40:41]
	v_ashrrev_i32_e32 v69, 31, v68
	v_lshlrev_b64 v[68:69], 13, v[68:69]
	v_lshl_add_u64 v[68:69], v[70:71], 0, v[68:69]
	v_lshl_add_u64 v[68:69], v[174:175], 2, v[68:69]
	global_load_dwordx4 v[84:87], v[68:69], off offset:512
	s_and_saveexec_b64 s[28:29], s[8:9]
	s_xor_b64 s[40:41], exec, s[28:29]
	v_add3_u32 v68, v224, v213, s53
	s_or_saveexec_b64 s[40:41], s[40:41]
	v_mov_b64_e32 v[70:71], s[24:25]
	s_xor_b64 exec, exec, s[40:41]
	v_lshl_add_u32 v68, v214, 8, v213
	v_mov_b64_e32 v[70:71], s[18:19]
	s_or_b64 exec, exec, s[40:41]
	v_ashrrev_i32_e32 v69, 31, v68
	v_lshlrev_b64 v[68:69], 13, v[68:69]
	v_lshl_add_u64 v[68:69], v[70:71], 0, v[68:69]
	v_lshl_add_u64 v[68:69], v[174:175], 2, v[68:69]
	global_load_dwordx4 v[80:83], v[68:69], off offset:512
	s_and_saveexec_b64 s[28:29], s[6:7]
	s_xor_b64 s[40:41], exec, s[28:29]
	v_add3_u32 v68, v225, v215, s53
	s_or_saveexec_b64 s[40:41], s[40:41]
	v_mov_b64_e32 v[70:71], s[24:25]
	s_xor_b64 exec, exec, s[40:41]
	v_lshl_add_u32 v68, v216, 8, v215
	v_mov_b64_e32 v[70:71], s[18:19]
	s_or_b64 exec, exec, s[40:41]
	v_ashrrev_i32_e32 v69, 31, v68
	v_lshlrev_b64 v[68:69], 13, v[68:69]
	v_lshl_add_u64 v[68:69], v[70:71], 0, v[68:69]
	v_lshl_add_u64 v[68:69], v[174:175], 2, v[68:69]
	global_load_dwordx4 v[76:79], v[68:69], off offset:512
	s_and_saveexec_b64 s[28:29], s[4:5]
	s_xor_b64 s[40:41], exec, s[28:29]
	v_add3_u32 v68, v226, v218, s53
	s_or_saveexec_b64 s[40:41], s[40:41]
	v_mov_b64_e32 v[70:71], s[24:25]
	s_xor_b64 exec, exec, s[40:41]
	v_lshl_add_u32 v68, v219, 8, v218
	v_mov_b64_e32 v[70:71], s[18:19]
	s_or_b64 exec, exec, s[40:41]
	v_ashrrev_i32_e32 v69, 31, v68
	v_lshlrev_b64 v[68:69], 13, v[68:69]
	v_lshl_add_u64 v[68:69], v[70:71], 0, v[68:69]
	v_lshl_add_u64 v[68:69], v[174:175], 2, v[68:69]
	global_load_dwordx4 v[72:75], v[68:69], off offset:512
	s_and_saveexec_b64 s[28:29], vcc
	s_xor_b64 s[40:41], exec, s[28:29]
	v_add3_u32 v68, v227, v221, s53
	s_or_saveexec_b64 s[40:41], s[40:41]
	v_mov_b64_e32 v[70:71], s[24:25]
	s_xor_b64 exec, exec, s[40:41]
	v_lshl_add_u32 v68, v222, 8, v221
	v_mov_b64_e32 v[70:71], s[18:19]
	s_or_b64 exec, exec, s[40:41]
	v_ashrrev_i32_e32 v69, 31, v68
	v_lshlrev_b64 v[68:69], 13, v[68:69]
	v_lshl_add_u64 v[68:69], v[70:71], 0, v[68:69]
	v_lshl_add_u64 v[68:69], v[174:175], 2, v[68:69]
	global_load_dwordx4 v[68:71], v[68:69], off offset:512
	s_and_saveexec_b64 s[28:29], s[16:17]
	s_xor_b64 s[40:41], exec, s[28:29]
	v_add3_u32 v100, v212, v202, s53
	s_or_saveexec_b64 s[40:41], s[40:41]
	v_mov_b64_e32 v[102:103], s[24:25]
	s_xor_b64 exec, exec, s[40:41]
	v_lshl_add_u32 v100, v203, 8, v202
	v_mov_b64_e32 v[102:103], s[18:19]
	s_or_b64 exec, exec, s[40:41]
	v_ashrrev_i32_e32 v101, 31, v100
	s_waitcnt vmcnt(0)
	v_pk_fma_f32 v[60:61], v[60:61], v[64:65], v[96:97]
	v_lshlrev_b64 v[96:97], 13, v[100:101]
	v_lshl_add_u64 v[96:97], v[102:103], 0, v[96:97]
	v_pk_fma_f32 v[62:63], v[62:63], v[66:67], v[98:99]
	v_lshl_add_u64 v[96:97], v[174:175], 2, v[96:97]
	global_store_dwordx4 v[96:97], v[60:63], off offset:512
	s_and_saveexec_b64 s[28:29], s[14:15]
	s_xor_b64 s[40:41], exec, s[28:29]
	v_add3_u32 v60, v217, v204, s53
	s_or_saveexec_b64 s[40:41], s[40:41]
	v_mov_b64_e32 v[62:63], s[24:25]
	s_xor_b64 exec, exec, s[40:41]
	v_lshl_add_u32 v60, v205, 8, v204
	v_mov_b64_e32 v[62:63], s[18:19]
	s_or_b64 exec, exec, s[40:41]
	v_ashrrev_i32_e32 v61, 31, v60
	v_lshlrev_b64 v[60:61], 13, v[60:61]
	v_lshl_add_u64 v[60:61], v[62:63], 0, v[60:61]
	v_pk_fma_f32 v[58:59], v[58:59], v[66:67], v[94:95]
	v_pk_fma_f32 v[56:57], v[56:57], v[64:65], v[92:93]
	v_lshl_add_u64 v[60:61], v[174:175], 2, v[60:61]
	global_store_dwordx4 v[60:61], v[56:59], off offset:512
	s_and_saveexec_b64 s[28:29], s[12:13]
	s_xor_b64 s[40:41], exec, s[28:29]
	v_add3_u32 v56, v220, v208, s53
	s_or_saveexec_b64 s[40:41], s[40:41]
	v_mov_b64_e32 v[58:59], s[24:25]
	s_xor_b64 exec, exec, s[40:41]
	v_lshl_add_u32 v56, v209, 8, v208
	v_mov_b64_e32 v[58:59], s[18:19]
	s_or_b64 exec, exec, s[40:41]
	v_ashrrev_i32_e32 v57, 31, v56
	v_lshlrev_b64 v[56:57], 13, v[56:57]
	v_lshl_add_u64 v[56:57], v[58:59], 0, v[56:57]
	v_pk_fma_f32 v[54:55], v[54:55], v[66:67], v[90:91]
	v_pk_fma_f32 v[52:53], v[52:53], v[64:65], v[88:89]
	v_lshl_add_u64 v[56:57], v[174:175], 2, v[56:57]
	global_store_dwordx4 v[56:57], v[52:55], off offset:512
	s_and_saveexec_b64 s[28:29], s[10:11]
	s_xor_b64 s[40:41], exec, s[28:29]
	v_add3_u32 v52, v223, v210, s53
	s_or_saveexec_b64 s[40:41], s[40:41]
; DI void epi_resid(const Acc& acc, const P& p, int brow, int bcol, int layer, int gch, bool from_input) {
;     ...
;             const f32x4 g = *(const f32x4*)(gate + c0);
;             f32x4 xv[2][4];
; #pragma unroll
;             for (int ai = 0; ai < 2; ++ai)
; #pragma unroll
;                 for (int m = 0; m < 4; ++m) {
;                     const int r = brow + ai * 128 + wr * 64 + m * 16 + fr;
;                     const float* sp = (from_input ? inrow(p, r) : xrow(p, r)) + c0;
;                     xv[ai][m] = *(const f32x4*)sp;
;                 }
;     ...
; #pragma unroll
;             for (int ai = 0; ai < 2; ++ai)
; #pragma unroll
;                 for (int m = 0; m < 4; ++m) {
;                     const int r = brow + ai * 128 + wr * 64 + m * 16 + fr;
;                     *(f32x4*)(xrow(p, r) + c0) = xv[ai][m] + g * acc[ai][bj][m][n];
;                 }
;             __builtin_amdgcn_sched_barrier(0);
	v_mov_b64_e32 v[54:55], s[24:25]
	s_xor_b64 exec, exec, s[40:41]
	v_lshl_add_u32 v52, v211, 8, v210
	v_mov_b64_e32 v[54:55], s[18:19]
	s_or_b64 exec, exec, s[40:41]
	v_ashrrev_i32_e32 v53, 31, v52
	v_lshlrev_b64 v[52:53], 13, v[52:53]
	v_lshl_add_u64 v[52:53], v[54:55], 0, v[52:53]
	v_pk_fma_f32 v[50:51], v[50:51], v[66:67], v[86:87]
	v_pk_fma_f32 v[48:49], v[48:49], v[64:65], v[84:85]
	v_lshl_add_u64 v[52:53], v[174:175], 2, v[52:53]
	global_store_dwordx4 v[52:53], v[48:51], off offset:512
	s_and_saveexec_b64 s[28:29], s[8:9]
	s_xor_b64 s[40:41], exec, s[28:29]
	v_add3_u32 v48, v224, v213, s53
	s_or_saveexec_b64 s[40:41], s[40:41]
	v_mov_b64_e32 v[50:51], s[24:25]
	s_xor_b64 exec, exec, s[40:41]
	v_lshl_add_u32 v48, v214, 8, v213
	v_mov_b64_e32 v[50:51], s[18:19]
	s_or_b64 exec, exec, s[40:41]
	v_ashrrev_i32_e32 v49, 31, v48
	v_lshlrev_b64 v[48:49], 13, v[48:49]
	v_lshl_add_u64 v[48:49], v[50:51], 0, v[48:49]
	v_pk_fma_f32 v[46:47], v[46:47], v[66:67], v[82:83]
	v_pk_fma_f32 v[44:45], v[44:45], v[64:65], v[80:81]
	v_lshl_add_u64 v[48:49], v[174:175], 2, v[48:49]
	global_store_dwordx4 v[48:49], v[44:47], off offset:512
	s_and_saveexec_b64 s[28:29], s[6:7]
	s_xor_b64 s[40:41], exec, s[28:29]
	v_add3_u32 v44, v225, v215, s53
	s_or_saveexec_b64 s[40:41], s[40:41]
	v_mov_b64_e32 v[46:47], s[24:25]
	s_xor_b64 exec, exec, s[40:41]
	v_lshl_add_u32 v44, v216, 8, v215
	v_mov_b64_e32 v[46:47], s[18:19]
	s_or_b64 exec, exec, s[40:41]
	v_ashrrev_i32_e32 v45, 31, v44
	v_lshlrev_b64 v[44:45], 13, v[44:45]
	v_lshl_add_u64 v[44:45], v[46:47], 0, v[44:45]
	v_pk_fma_f32 v[42:43], v[42:43], v[66:67], v[78:79]
	v_pk_fma_f32 v[40:41], v[40:41], v[64:65], v[76:77]
	v_lshl_add_u64 v[44:45], v[174:175], 2, v[44:45]
	global_store_dwordx4 v[44:45], v[40:43], off offset:512
	s_and_saveexec_b64 s[28:29], s[4:5]
	s_xor_b64 s[40:41], exec, s[28:29]
	v_add3_u32 v40, v226, v218, s53
	s_or_saveexec_b64 s[40:41], s[40:41]
	v_mov_b64_e32 v[42:43], s[24:25]
	s_xor_b64 exec, exec, s[40:41]
	v_lshl_add_u32 v40, v219, 8, v218
	v_mov_b64_e32 v[42:43], s[18:19]
	s_or_b64 exec, exec, s[40:41]
	v_ashrrev_i32_e32 v41, 31, v40
	v_lshlrev_b64 v[40:41], 13, v[40:41]
	v_lshl_add_u64 v[40:41], v[42:43], 0, v[40:41]
	v_pk_fma_f32 v[38:39], v[38:39], v[66:67], v[74:75]
	v_pk_fma_f32 v[36:37], v[36:37], v[64:65], v[72:73]
	v_lshl_add_u64 v[40:41], v[174:175], 2, v[40:41]
	global_store_dwordx4 v[40:41], v[36:39], off offset:512
	s_and_saveexec_b64 s[28:29], vcc
	s_xor_b64 s[40:41], exec, s[28:29]
	v_add3_u32 v36, v227, v221, s53
	s_or_saveexec_b64 s[40:41], s[40:41]
	v_mov_b64_e32 v[38:39], s[24:25]
	s_xor_b64 exec, exec, s[40:41]
	v_lshl_add_u32 v36, v222, 8, v221
	v_mov_b64_e32 v[38:39], s[18:19]
	s_or_b64 exec, exec, s[40:41]
	v_ashrrev_i32_e32 v37, 31, v36
	v_lshlrev_b64 v[36:37], 13, v[36:37]
	v_lshl_add_u64 v[36:37], v[38:39], 0, v[36:37]
	v_pk_fma_f32 v[34:35], v[34:35], v[66:67], v[70:71]
	v_pk_fma_f32 v[32:33], v[32:33], v[64:65], v[68:69]
	v_lshl_add_u64 v[36:37], v[174:175], 2, v[36:37]
	global_store_dwordx4 v[36:37], v[32:35], off offset:512
	global_load_dwordx4 v[32:35], v[192:193], off offset:576
	s_and_saveexec_b64 s[28:29], s[16:17]
	s_xor_b64 s[40:41], exec, s[28:29]
	v_add3_u32 v36, v212, v202, s53
	s_or_saveexec_b64 s[40:41], s[40:41]
	v_mov_b64_e32 v[38:39], s[24:25]
	s_xor_b64 exec, exec, s[40:41]
	v_lshl_add_u32 v36, v203, 8, v202
	v_mov_b64_e32 v[38:39], s[18:19]
	s_or_b64 exec, exec, s[40:41]
	v_ashrrev_i32_e32 v37, 31, v36
	v_lshlrev_b64 v[36:37], 13, v[36:37]
	v_lshl_add_u64 v[36:37], v[38:39], 0, v[36:37]
	v_lshl_add_u64 v[36:37], v[174:175], 2, v[36:37]
	global_load_dwordx4 v[64:67], v[36:37], off offset:576
	s_and_saveexec_b64 s[28:29], s[14:15]
	s_xor_b64 s[40:41], exec, s[28:29]
	v_add3_u32 v36, v217, v204, s53
	s_or_saveexec_b64 s[40:41], s[40:41]
	v_mov_b64_e32 v[38:39], s[24:25]
	s_xor_b64 exec, exec, s[40:41]
	v_lshl_add_u32 v36, v205, 8, v204
	v_mov_b64_e32 v[38:39], s[18:19]
	s_or_b64 exec, exec, s[40:41]
	v_ashrrev_i32_e32 v37, 31, v36
	v_lshlrev_b64 v[36:37], 13, v[36:37]
	v_lshl_add_u64 v[36:37], v[38:39], 0, v[36:37]
	v_lshl_add_u64 v[36:37], v[174:175], 2, v[36:37]
	global_load_dwordx4 v[60:63], v[36:37], off offset:576
	s_and_saveexec_b64 s[28:29], s[12:13]
	s_xor_b64 s[40:41], exec, s[28:29]
	v_add3_u32 v36, v220, v208, s53
	s_or_saveexec_b64 s[40:41], s[40:41]
	v_mov_b64_e32 v[38:39], s[24:25]
	s_xor_b64 exec, exec, s[40:41]
	v_lshl_add_u32 v36, v209, 8, v208
	v_mov_b64_e32 v[38:39], s[18:19]
	s_or_b64 exec, exec, s[40:41]
	v_ashrrev_i32_e32 v37, 31, v36
	v_lshlrev_b64 v[36:37], 13, v[36:37]
	v_lshl_add_u64 v[36:37], v[38:39], 0, v[36:37]
	v_lshl_add_u64 v[36:37], v[174:175], 2, v[36:37]
	global_load_dwordx4 v[56:59], v[36:37], off offset:576
	s_and_saveexec_b64 s[28:29], s[10:11]
	s_xor_b64 s[40:41], exec, s[28:29]
	v_add3_u32 v36, v223, v210, s53
	s_or_saveexec_b64 s[40:41], s[40:41]
	v_mov_b64_e32 v[38:39], s[24:25]
	s_xor_b64 exec, exec, s[40:41]
	v_lshl_add_u32 v36, v211, 8, v210
	v_mov_b64_e32 v[38:39], s[18:19]
	s_or_b64 exec, exec, s[40:41]
	v_ashrrev_i32_e32 v37, 31, v36
	v_lshlrev_b64 v[36:37], 13, v[36:37]
	v_lshl_add_u64 v[36:37], v[38:39], 0, v[36:37]
	v_lshl_add_u64 v[36:37], v[174:175], 2, v[36:37]
	global_load_dwordx4 v[52:55], v[36:37], off offset:576
	s_and_saveexec_b64 s[28:29], s[8:9]
	s_xor_b64 s[40:41], exec, s[28:29]
	v_add3_u32 v36, v224, v213, s53
	s_or_saveexec_b64 s[40:41], s[40:41]
	v_mov_b64_e32 v[38:39], s[24:25]
	s_xor_b64 exec, exec, s[40:41]
	v_lshl_add_u32 v36, v214, 8, v213
	v_mov_b64_e32 v[38:39], s[18:19]
	s_or_b64 exec, exec, s[40:41]
	v_ashrrev_i32_e32 v37, 31, v36
	v_lshlrev_b64 v[36:37], 13, v[36:37]
; DI void epi_resid(const Acc& acc, const P& p, int brow, int bcol, int layer, int gch, bool from_input) {
;     ...
;             f32x4 xv[2][4];
; #pragma unroll
;             for (int ai = 0; ai < 2; ++ai)
; #pragma unroll
;                 for (int m = 0; m < 4; ++m) {
;                     const int r = brow + ai * 128 + wr * 64 + m * 16 + fr;
;                     const float* sp = (from_input ? inrow(p, r) : xrow(p, r)) + c0;
;                     xv[ai][m] = *(const f32x4*)sp;
;                 }
;             __builtin_amdgcn_sched_barrier(0);
; #pragma unroll
;             for (int ai = 0; ai < 2; ++ai)
; #pragma unroll
;                 for (int m = 0; m < 4; ++m) {
;                     const int r = brow + ai * 128 + wr * 64 + m * 16 + fr;
;                     *(f32x4*)(xrow(p, r) + c0) = xv[ai][m] + g * acc[ai][bj][m][n];
;                 }
;             __builtin_amdgcn_sched_barrier(0);
;         }
	v_lshl_add_u64 v[36:37], v[38:39], 0, v[36:37]
	v_lshl_add_u64 v[36:37], v[174:175], 2, v[36:37]
	global_load_dwordx4 v[48:51], v[36:37], off offset:576
	s_and_saveexec_b64 s[28:29], s[6:7]
	s_xor_b64 s[40:41], exec, s[28:29]
	v_add3_u32 v36, v225, v215, s53
	s_or_saveexec_b64 s[40:41], s[40:41]
	v_mov_b64_e32 v[38:39], s[24:25]
	s_xor_b64 exec, exec, s[40:41]
	v_lshl_add_u32 v36, v216, 8, v215
	v_mov_b64_e32 v[38:39], s[18:19]
	s_or_b64 exec, exec, s[40:41]
	v_ashrrev_i32_e32 v37, 31, v36
	v_lshlrev_b64 v[36:37], 13, v[36:37]
	v_lshl_add_u64 v[36:37], v[38:39], 0, v[36:37]
	v_lshl_add_u64 v[36:37], v[174:175], 2, v[36:37]
	global_load_dwordx4 v[44:47], v[36:37], off offset:576
	s_and_saveexec_b64 s[28:29], s[4:5]
	s_xor_b64 s[40:41], exec, s[28:29]
	v_add3_u32 v36, v226, v218, s53
	s_or_saveexec_b64 s[40:41], s[40:41]
	v_mov_b64_e32 v[38:39], s[24:25]
	s_xor_b64 exec, exec, s[40:41]
	v_lshl_add_u32 v36, v219, 8, v218
	v_mov_b64_e32 v[38:39], s[18:19]
	s_or_b64 exec, exec, s[40:41]
	v_ashrrev_i32_e32 v37, 31, v36
	v_lshlrev_b64 v[36:37], 13, v[36:37]
	v_lshl_add_u64 v[36:37], v[38:39], 0, v[36:37]
	v_lshl_add_u64 v[36:37], v[174:175], 2, v[36:37]
	global_load_dwordx4 v[40:43], v[36:37], off offset:576
	s_and_saveexec_b64 s[28:29], vcc
	s_xor_b64 s[40:41], exec, s[28:29]
	v_add3_u32 v36, v227, v221, s53
	s_or_saveexec_b64 s[40:41], s[40:41]
	v_mov_b64_e32 v[38:39], s[24:25]
	s_xor_b64 exec, exec, s[40:41]
	v_lshl_add_u32 v36, v222, 8, v221
	v_mov_b64_e32 v[38:39], s[18:19]
	s_or_b64 exec, exec, s[40:41]
	v_ashrrev_i32_e32 v37, 31, v36
	v_lshlrev_b64 v[36:37], 13, v[36:37]
	v_lshl_add_u64 v[36:37], v[38:39], 0, v[36:37]
	v_lshl_add_u64 v[36:37], v[174:175], 2, v[36:37]
	global_load_dwordx4 v[36:39], v[36:37], off offset:576
	s_and_saveexec_b64 s[28:29], s[16:17]
	s_xor_b64 s[16:17], exec, s[28:29]
	s_or_saveexec_b64 s[16:17], s[16:17]
	v_mov_b64_e32 v[68:69], s[24:25]
	s_xor_b64 exec, exec, s[16:17]
	v_mov_b64_e32 v[68:69], s[18:19]
	v_mov_b32_e32 v190, v191
	s_or_b64 exec, exec, s[16:17]
	v_ashrrev_i32_e32 v191, 31, v190
	s_waitcnt vmcnt(0)
	v_pk_fma_f32 v[28:29], v[28:29], v[32:33], v[64:65]
	v_lshlrev_b64 v[64:65], 13, v[190:191]
	v_lshl_add_u64 v[64:65], v[68:69], 0, v[64:65]
	v_pk_fma_f32 v[30:31], v[30:31], v[34:35], v[66:67]
	v_lshl_add_u64 v[64:65], v[174:175], 2, v[64:65]
	global_store_dwordx4 v[64:65], v[28:31], off offset:576
	s_and_saveexec_b64 s[16:17], s[14:15]
	s_xor_b64 s[14:15], exec, s[16:17]
	s_or_saveexec_b64 s[14:15], s[14:15]
	v_mov_b64_e32 v[28:29], s[24:25]
	s_xor_b64 exec, exec, s[14:15]
	v_mov_b64_e32 v[28:29], s[18:19]
	v_mov_b32_e32 v188, v189
	s_or_b64 exec, exec, s[14:15]
	v_ashrrev_i32_e32 v189, 31, v188
	v_lshlrev_b64 v[30:31], 13, v[188:189]
	v_lshl_add_u64 v[28:29], v[28:29], 0, v[30:31]
	v_pk_fma_f32 v[26:27], v[26:27], v[34:35], v[62:63]
	v_pk_fma_f32 v[24:25], v[24:25], v[32:33], v[60:61]
	v_lshl_add_u64 v[28:29], v[174:175], 2, v[28:29]
	global_store_dwordx4 v[28:29], v[24:27], off offset:576
	s_and_saveexec_b64 s[16:17], s[12:13]
	s_xor_b64 s[12:13], exec, s[16:17]
	s_mov_b64 s[14:15], s[24:25]
	s_or_saveexec_b64 s[12:13], s[12:13]
	v_mov_b64_e32 v[24:25], s[14:15]
	s_xor_b64 exec, exec, s[12:13]
	v_mov_b64_e32 v[24:25], s[18:19]
	v_mov_b32_e32 v186, v187
	s_or_b64 exec, exec, s[12:13]
	v_ashrrev_i32_e32 v187, 31, v186
	v_lshlrev_b64 v[26:27], 13, v[186:187]
	v_lshl_add_u64 v[24:25], v[24:25], 0, v[26:27]
	v_pk_fma_f32 v[22:23], v[22:23], v[34:35], v[58:59]
	v_pk_fma_f32 v[20:21], v[20:21], v[32:33], v[56:57]
	v_lshl_add_u64 v[24:25], v[174:175], 2, v[24:25]
	global_store_dwordx4 v[24:25], v[20:23], off offset:576
	s_and_saveexec_b64 s[14:15], s[10:11]
	s_xor_b64 s[10:11], exec, s[14:15]
	s_mov_b64 s[12:13], s[24:25]
	s_or_saveexec_b64 s[10:11], s[10:11]
	v_mov_b64_e32 v[20:21], s[12:13]
	s_xor_b64 exec, exec, s[10:11]
	v_mov_b64_e32 v[20:21], s[18:19]
	v_mov_b32_e32 v184, v185
	s_or_b64 exec, exec, s[10:11]
	v_ashrrev_i32_e32 v185, 31, v184
	v_lshlrev_b64 v[22:23], 13, v[184:185]
	v_lshl_add_u64 v[20:21], v[20:21], 0, v[22:23]
	v_pk_fma_f32 v[18:19], v[18:19], v[34:35], v[54:55]
	v_pk_fma_f32 v[16:17], v[16:17], v[32:33], v[52:53]
	v_lshl_add_u64 v[20:21], v[174:175], 2, v[20:21]
	global_store_dwordx4 v[20:21], v[16:19], off offset:576
	s_and_saveexec_b64 s[12:13], s[8:9]
	s_xor_b64 s[8:9], exec, s[12:13]
	s_mov_b64 s[10:11], s[24:25]
	s_or_saveexec_b64 s[8:9], s[8:9]
	v_mov_b64_e32 v[16:17], s[10:11]
	s_xor_b64 exec, exec, s[8:9]
	v_mov_b64_e32 v[16:17], s[18:19]
	v_mov_b32_e32 v182, v183
	s_or_b64 exec, exec, s[8:9]
	v_ashrrev_i32_e32 v183, 31, v182
	v_lshlrev_b64 v[18:19], 13, v[182:183]
	v_lshl_add_u64 v[16:17], v[16:17], 0, v[18:19]
	v_pk_fma_f32 v[14:15], v[14:15], v[34:35], v[50:51]
	v_pk_fma_f32 v[12:13], v[12:13], v[32:33], v[48:49]
	v_lshl_add_u64 v[16:17], v[174:175], 2, v[16:17]
	global_store_dwordx4 v[16:17], v[12:15], off offset:576
	s_and_saveexec_b64 s[10:11], s[6:7]
	s_xor_b64 s[6:7], exec, s[10:11]
	s_mov_b64 s[8:9], s[24:25]
	s_or_saveexec_b64 s[6:7], s[6:7]
	v_mov_b64_e32 v[12:13], s[8:9]
	s_xor_b64 exec, exec, s[6:7]
	v_mov_b64_e32 v[12:13], s[18:19]
	v_mov_b32_e32 v180, v181
	s_or_b64 exec, exec, s[6:7]
	v_ashrrev_i32_e32 v181, 31, v180
	v_lshlrev_b64 v[14:15], 13, v[180:181]
	v_lshl_add_u64 v[12:13], v[12:13], 0, v[14:15]
	v_pk_fma_f32 v[10:11], v[10:11], v[34:35], v[46:47]
	v_pk_fma_f32 v[8:9], v[8:9], v[32:33], v[44:45]
	v_lshl_add_u64 v[12:13], v[174:175], 2, v[12:13]
	global_store_dwordx4 v[12:13], v[8:11], off offset:576
	s_and_saveexec_b64 s[8:9], s[4:5]
	s_xor_b64 s[4:5], exec, s[8:9]
	s_mov_b64 s[6:7], s[24:25]
	s_or_saveexec_b64 s[4:5], s[4:5]
	v_mov_b64_e32 v[8:9], s[6:7]
	s_xor_b64 exec, exec, s[4:5]
	v_mov_b64_e32 v[8:9], s[18:19]
	v_mov_b32_e32 v178, v179
	s_or_b64 exec, exec, s[4:5]
	v_ashrrev_i32_e32 v179, 31, v178
	v_lshlrev_b64 v[10:11], 13, v[178:179]
	v_lshl_add_u64 v[8:9], v[8:9], 0, v[10:11]
	v_pk_fma_f32 v[6:7], v[6:7], v[34:35], v[42:43]
	v_pk_fma_f32 v[4:5], v[4:5], v[32:33], v[40:41]
	v_lshl_add_u64 v[8:9], v[174:175], 2, v[8:9]
	global_store_dwordx4 v[8:9], v[4:7], off offset:576
	s_and_saveexec_b64 s[6:7], vcc
	s_xor_b64 s[6:7], exec, s[6:7]
	s_mov_b64 s[4:5], s[24:25]
	s_or_saveexec_b64 s[6:7], s[6:7]
	v_mov_b64_e32 v[4:5], s[4:5]
	s_xor_b64 exec, exec, s[6:7]
	s_cbranch_execz .LBB0_3109
	v_mov_b64_e32 v[4:5], s[18:19]
	v_mov_b32_e32 v176, v177
	s_branch .LBB0_3109
